# GEMM K loops: s_setprio 0 moved behind each MFMA segment's closing barrier (one instruction less before barrier arrival), on top of the stacked file
# speedup vs baseline: 1.0149x; 1.0149x over previous
; #define PG8_STAGE(bufoff, gbase, voff) do { _Pragma("unroll") for (int _i = 0; _i < 2; ++_i) \
;         __builtin_amdgcn_global_load_lds((const unsigned*)((const char*)(gbase) + (voff)[_i]), (PG8_LAS unsigned*)(lds + (bufoff) + ldsw + _i * 8192), 16, 0, 0); } while (0)
; #define PG8_LDA(dst, b, h) do { _Pragma("unroll") for (int m = 0; m < 4; ++m) _Pragma("unroll") for (int k = 0; k < 2; ++k) dst[m][k] = *(const PG8_LAS bf16x8*)(lds + PG8_SA(b, h) + aoff + m * 2048 + k * 1024); } while (0)
; #define PG8_LDB(dst, b, h) do { _Pragma("unroll") for (int n = 0; n < 2; ++n) _Pragma("unroll") for (int k = 0; k < 2; ++k) dst[n][k] = *(const PG8_LAS bf16x8*)(lds + PG8_SB(b, h) + boff + n * 2048 + k * 1024); } while (0)
; #define PG8_MMA(ai, bj, At, Bt) do { __builtin_amdgcn_s_setprio(1); _Pragma("unroll") for (int m = 0; m < 4; ++m) _Pragma("unroll") for (int n = 0; n < 2; ++n) _Pragma("unroll") for (int k = 0; k < 2; ++k) \
;         acc[ai][bj][m][n] = __builtin_amdgcn_mfma_f32_16x16x32_bf16(Bt[n][k], At[m][k], acc[ai][bj][m][n], 0, 0, 0); __builtin_amdgcn_s_setprio(0); } while (0)
; #define PG8_WAIT_V(n) asm volatile("s_waitcnt vmcnt(" #n ")" ::: "memory")
; #define PG8_WAIT_L(n) asm volatile("s_waitcnt lgkmcnt(" #n ")" ::: "memory")
; #define PG8_BAR __builtin_amdgcn_s_barrier()
; #define PG8_SCHED __builtin_amdgcn_sched_barrier(0)
; template <class Epi, class Sched, bool ALIGN_EPI = false, bool SP2 = false>
; __device__ __forceinline__ void gemm_phase(PG8_LAS unsigned char* lds, const Gemm g, const Sched& S, const Epi& E) {
;     ...
;             const bool last = (t == nt - 2);
;             const char* a1 = cA + (size_t)(t + 1) * kstep;
;             const char* a2 = last ? nA : cA + (size_t)(t + 2) * kstep; const char* b2 = last ? nB : cB + (size_t)(t + 2) * kstep;
;             const char* a3 = a2 + kstep; const char* b3 = b2 + kstep;
;             if (last && has_next) S.a_ready(nxt);
;             if constexpr (SP2) {
;             PG8_LDB(B0, 0, 0); PG8_LDB(B1, 0, 1); PG8_SCHED; PG8_LDA(At, 0, 0); PG8_STAGE(PG8_SA(1, 1), a1 + hstep, voffA);
;             PG8_WAIT_V(8); PG8_WAIT_L(0); PG8_BAR; PG8_MMA(0, 0, At, B0); PG8_MMA(0, 1, At, B1); PG8_BAR; PG8_SCHED;
;             PG8_LDA(At, 0, 1); PG8_STAGE(PG8_SB(0, 0), b2, voffB); PG8_STAGE(PG8_SB(0, 1), b2 + hstep, voffB); PG8_STAGE(PG8_SA(0, 0), a2, voffA);
.LBB0_85:
	ds_read_b128 v[146:149], v152
	ds_read_b128 v[156:159], v152 offset:1024
	ds_read_b128 v[160:163], v152 offset:2048
	ds_read_b128 v[164:167], v152 offset:3072
	ds_read_b128 v[168:171], v153
	ds_read_b128 v[172:175], v153 offset:1024
	ds_read_b128 v[176:179], v153 offset:2048
	ds_read_b128 v[180:183], v153 offset:3072
	s_add_u32 s22, s20, 0xfffc0080
	s_addc_u32 s23, s21, -1
	s_cmp_eq_u32 s50, 12
	s_cselect_b32 s25, s13, s23
	s_cselect_b32 s24, s42, s22
	s_cselect_b32 s23, s11, s49
	s_cselect_b32 s22, s43, s48
	v_lshl_add_u64 v[184:185], s[20:21], 0, v[138:139]
	s_add_i32 m0, s19, 0xc000
	ds_read_b128 v[188:191], v154
	ds_read_b128 v[192:195], v154 offset:1024
	ds_read_b128 v[196:199], v154 offset:2048
	ds_read_b128 v[200:203], v154 offset:3072
	ds_read_b128 v[204:207], v154 offset:4096
	ds_read_b128 v[208:211], v154 offset:5120
	ds_read_b128 v[212:215], v154 offset:6144
	ds_read_b128 v[216:219], v154 offset:7168
	global_load_lds_dwordx4 v[184:185], off
	v_lshl_add_u64 v[184:185], s[20:21], 0, v[140:141]
	s_add_i32 m0, s19, 0xe000
	s_nop 0
	global_load_lds_dwordx4 v[184:185], off
	s_waitcnt vmcnt(8)
	s_waitcnt lgkmcnt(0)
	s_barrier
	s_setprio 1
	s_waitcnt lgkmcnt(0)
	v_mfma_f32_16x16x32_bf16 v[126:129], v[146:149], v[188:191], v[126:129]
	v_mfma_f32_16x16x32_bf16 v[122:125], v[160:163], v[188:191], v[122:125]
	v_mfma_f32_16x16x32_bf16 v[110:113], v[146:149], v[196:199], v[110:113]
	v_mfma_f32_16x16x32_bf16 v[106:109], v[160:163], v[196:199], v[106:109]
	v_mfma_f32_16x16x32_bf16 v[94:97], v[146:149], v[204:207], v[94:97]
	v_mfma_f32_16x16x32_bf16 v[90:93], v[160:163], v[204:207], v[90:93]
	v_mfma_f32_16x16x32_bf16 v[78:81], v[146:149], v[212:215], v[78:81]
	v_mfma_f32_16x16x32_bf16 v[74:77], v[160:163], v[212:215], v[74:77]
	v_mfma_f32_16x16x32_bf16 v[126:129], v[156:159], v[192:195], v[126:129]
	v_mfma_f32_16x16x32_bf16 v[122:125], v[164:167], v[192:195], v[122:125]
	v_mfma_f32_16x16x32_bf16 v[110:113], v[156:159], v[200:203], v[110:113]
	v_mfma_f32_16x16x32_bf16 v[106:109], v[164:167], v[200:203], v[106:109]
	v_mfma_f32_16x16x32_bf16 v[94:97], v[156:159], v[208:211], v[94:97]
	v_mfma_f32_16x16x32_bf16 v[90:93], v[164:167], v[208:211], v[90:93]
	v_mfma_f32_16x16x32_bf16 v[78:81], v[156:159], v[216:219], v[78:81]
	v_mfma_f32_16x16x32_bf16 v[74:77], v[164:167], v[216:219], v[74:77]
	s_setprio 0
	s_setprio 1
	v_mfma_f32_16x16x32_bf16 v[118:121], v[168:171], v[188:191], v[118:121]
	v_mfma_f32_16x16x32_bf16 v[114:117], v[176:179], v[188:191], v[114:117]
	v_mfma_f32_16x16x32_bf16 v[102:105], v[168:171], v[196:199], v[102:105]
	v_mfma_f32_16x16x32_bf16 v[98:101], v[176:179], v[196:199], v[98:101]
	v_mfma_f32_16x16x32_bf16 v[86:89], v[168:171], v[204:207], v[86:89]
	v_mfma_f32_16x16x32_bf16 v[82:85], v[176:179], v[204:207], v[82:85]
	v_mfma_f32_16x16x32_bf16 v[70:73], v[168:171], v[212:215], v[70:73]
	v_mfma_f32_16x16x32_bf16 v[66:69], v[176:179], v[212:215], v[66:69]
	v_mfma_f32_16x16x32_bf16 v[118:121], v[172:175], v[192:195], v[118:121]
	v_mfma_f32_16x16x32_bf16 v[114:117], v[180:183], v[192:195], v[114:117]
	v_mfma_f32_16x16x32_bf16 v[102:105], v[172:175], v[200:203], v[102:105]
	v_mfma_f32_16x16x32_bf16 v[98:101], v[180:183], v[200:203], v[98:101]
	v_mfma_f32_16x16x32_bf16 v[86:89], v[172:175], v[208:211], v[86:89]
	v_mfma_f32_16x16x32_bf16 v[82:85], v[180:183], v[208:211], v[82:85]
	v_mfma_f32_16x16x32_bf16 v[70:73], v[172:175], v[216:219], v[70:73]
	v_mfma_f32_16x16x32_bf16 v[66:69], v[180:183], v[216:219], v[66:69]
	s_barrier
	s_setprio 0
	s_add_i32 s51, s38, s26
	v_lshl_add_u64 v[184:185], s[22:23], 0, v[134:135]
	s_mov_b32 m0, s51
	ds_read_b128 v[188:191], v154 offset:16384
	ds_read_b128 v[192:195], v154 offset:17408
	ds_read_b128 v[196:199], v154 offset:18432
	ds_read_b128 v[200:203], v154 offset:19456
	ds_read_b128 v[204:207], v154 offset:20480
	ds_read_b128 v[208:211], v154 offset:21504
	ds_read_b128 v[212:215], v154 offset:22528
	ds_read_b128 v[216:219], v154 offset:23552
	global_load_lds_dwordx4 v[184:185], off
	s_add_i32 m0, s51, 0x2000
	s_add_u32 s52, s22, 0x40000
	v_lshl_add_u64 v[220:221], s[22:23], 0, v[130:131]
	s_addc_u32 s53, s23, 0
	s_add_i32 s51, s39, s26
	global_load_lds_dwordx4 v[220:221], off
	v_lshl_add_u64 v[222:223], s[52:53], 0, v[134:135]
	s_mov_b32 m0, s51
	v_lshl_add_u64 v[224:225], s[24:25], 0, v[132:133]
	global_load_lds_dwordx4 v[222:223], off
	v_lshl_add_u64 v[222:223], s[52:53], 0, v[130:131]
	s_add_i32 m0, s51, 0x2000
	s_nop 0
	global_load_lds_dwordx4 v[222:223], off
	v_lshl_add_u64 v[222:223], s[24:25], 0, v[136:137]
	s_mov_b32 m0, s19
	s_nop 0
	global_load_lds_dwordx4 v[222:223], off
	s_mov_b32 m0, s29
	s_nop 0
	global_load_lds_dwordx4 v[224:225], off
	s_waitcnt vmcnt(8)
	s_waitcnt lgkmcnt(0)
	s_barrier
; #define PG8_STAGE(bufoff, gbase, voff) do { _Pragma("unroll") for (int _i = 0; _i < 2; ++_i) \
;         __builtin_amdgcn_global_load_lds((const unsigned*)((const char*)(gbase) + (voff)[_i]), (PG8_LAS unsigned*)(lds + (bufoff) + ldsw + _i * 8192), 16, 0, 0); } while (0)
; #define PG8_LDA(dst, b, h) do { _Pragma("unroll") for (int m = 0; m < 4; ++m) _Pragma("unroll") for (int k = 0; k < 2; ++k) dst[m][k] = *(const PG8_LAS bf16x8*)(lds + PG8_SA(b, h) + aoff + m * 2048 + k * 1024); } while (0)
; #define PG8_LDB(dst, b, h) do { _Pragma("unroll") for (int n = 0; n < 2; ++n) _Pragma("unroll") for (int k = 0; k < 2; ++k) dst[n][k] = *(const PG8_LAS bf16x8*)(lds + PG8_SB(b, h) + boff + n * 2048 + k * 1024); } while (0)
; #define PG8_MMA(ai, bj, At, Bt) do { __builtin_amdgcn_s_setprio(1); _Pragma("unroll") for (int m = 0; m < 4; ++m) _Pragma("unroll") for (int n = 0; n < 2; ++n) _Pragma("unroll") for (int k = 0; k < 2; ++k) \
;         acc[ai][bj][m][n] = __builtin_amdgcn_mfma_f32_16x16x32_bf16(Bt[n][k], At[m][k], acc[ai][bj][m][n], 0, 0, 0); __builtin_amdgcn_s_setprio(0); } while (0)
; #define PG8_WAIT_V(n) asm volatile("s_waitcnt vmcnt(" #n ")" ::: "memory")
; #define PG8_WAIT_L(n) asm volatile("s_waitcnt lgkmcnt(" #n ")" ::: "memory")
; #define PG8_BAR __builtin_amdgcn_s_barrier()
; #define PG8_SCHED __builtin_amdgcn_sched_barrier(0)
; template <class Epi, class Sched, bool ALIGN_EPI = false, bool SP2 = false>
; __device__ __forceinline__ void gemm_phase(PG8_LAS unsigned char* lds, const Gemm g, const Sched& S, const Epi& E) {
;     ...
;             PG8_WAIT_V(8); PG8_WAIT_L(0); PG8_BAR; PG8_MMA(1, 0, At, B0); PG8_MMA(1, 1, At, B1); PG8_BAR; PG8_SCHED;
;             PG8_LDB(B0, 1, 0); PG8_LDB(B1, 1, 1); PG8_SCHED; PG8_LDA(At, 1, 0); PG8_STAGE(PG8_SA(0, 1), a2 + hstep, voffA);
;             PG8_WAIT_V(8); PG8_WAIT_L(0); PG8_BAR; PG8_MMA(0, 0, At, B0); PG8_MMA(0, 1, At, B1); PG8_BAR; PG8_SCHED;
	s_setprio 1
	s_waitcnt lgkmcnt(0)
	v_mfma_f32_16x16x32_bf16 v[62:65], v[146:149], v[188:191], v[62:65]
	v_mfma_f32_16x16x32_bf16 v[58:61], v[160:163], v[188:191], v[58:61]
	v_mfma_f32_16x16x32_bf16 v[46:49], v[146:149], v[196:199], v[46:49]
	v_mfma_f32_16x16x32_bf16 v[42:45], v[160:163], v[196:199], v[42:45]
	v_mfma_f32_16x16x32_bf16 v[30:33], v[146:149], v[204:207], v[30:33]
	v_mfma_f32_16x16x32_bf16 v[26:29], v[160:163], v[204:207], v[26:29]
	v_mfma_f32_16x16x32_bf16 v[14:17], v[146:149], v[212:215], v[14:17]
	v_mfma_f32_16x16x32_bf16 v[10:13], v[160:163], v[212:215], v[10:13]
	v_mfma_f32_16x16x32_bf16 v[62:65], v[156:159], v[192:195], v[62:65]
	v_mfma_f32_16x16x32_bf16 v[58:61], v[164:167], v[192:195], v[58:61]
	v_mfma_f32_16x16x32_bf16 v[46:49], v[156:159], v[200:203], v[46:49]
	v_mfma_f32_16x16x32_bf16 v[42:45], v[164:167], v[200:203], v[42:45]
	v_mfma_f32_16x16x32_bf16 v[30:33], v[156:159], v[208:211], v[30:33]
	v_mfma_f32_16x16x32_bf16 v[26:29], v[164:167], v[208:211], v[26:29]
	v_mfma_f32_16x16x32_bf16 v[14:17], v[156:159], v[216:219], v[14:17]
	v_mfma_f32_16x16x32_bf16 v[10:13], v[164:167], v[216:219], v[10:13]
	s_setprio 0
	s_setprio 1
	v_mfma_f32_16x16x32_bf16 v[54:57], v[168:171], v[188:191], v[54:57]
	v_mfma_f32_16x16x32_bf16 v[50:53], v[176:179], v[188:191], v[50:53]
	v_mfma_f32_16x16x32_bf16 v[38:41], v[168:171], v[196:199], v[38:41]
	v_mfma_f32_16x16x32_bf16 v[34:37], v[176:179], v[196:199], v[34:37]
	v_mfma_f32_16x16x32_bf16 v[22:25], v[168:171], v[204:207], v[22:25]
	v_mfma_f32_16x16x32_bf16 v[18:21], v[176:179], v[204:207], v[18:21]
	v_mfma_f32_16x16x32_bf16 v[6:9], v[168:171], v[212:215], v[6:9]
	v_mfma_f32_16x16x32_bf16 v[2:5], v[176:179], v[212:215], v[2:5]
	v_mfma_f32_16x16x32_bf16 v[54:57], v[172:175], v[192:195], v[54:57]
	v_mfma_f32_16x16x32_bf16 v[50:53], v[180:183], v[192:195], v[50:53]
	v_mfma_f32_16x16x32_bf16 v[38:41], v[172:175], v[200:203], v[38:41]
	v_mfma_f32_16x16x32_bf16 v[34:37], v[180:183], v[200:203], v[34:37]
	v_mfma_f32_16x16x32_bf16 v[22:25], v[172:175], v[208:211], v[22:25]
	v_mfma_f32_16x16x32_bf16 v[18:21], v[180:183], v[208:211], v[18:21]
	v_mfma_f32_16x16x32_bf16 v[6:9], v[172:175], v[216:219], v[6:9]
	v_mfma_f32_16x16x32_bf16 v[2:5], v[180:183], v[216:219], v[2:5]
	s_barrier
	s_setprio 0
	s_add_i32 s51, 0, 0x18000
	v_add_u32_e32 v155, s51, v150
	s_add_i32 s52, 0, 0x1c000
	ds_read_b128 v[146:149], v155
	ds_read_b128 v[156:159], v155 offset:1024
	ds_read_b128 v[160:163], v155 offset:2048
	ds_read_b128 v[164:167], v155 offset:3072
	v_add_u32_e32 v155, s52, v150
	ds_read_b128 v[168:171], v155
	ds_read_b128 v[172:175], v155 offset:1024
	ds_read_b128 v[176:179], v155 offset:2048
	ds_read_b128 v[180:183], v155 offset:3072
	s_add_u32 s24, s24, 0x40000
	s_addc_u32 s25, s25, 0
	s_mov_b32 m0, s30
	v_lshl_add_u64 v[226:227], s[24:25], 0, v[136:137]
	ds_read_b128 v[188:191], v154 offset:32768
	ds_read_b128 v[192:195], v154 offset:33792
	ds_read_b128 v[196:199], v154 offset:34816
	ds_read_b128 v[200:203], v154 offset:35840
	ds_read_b128 v[204:207], v154 offset:36864
	ds_read_b128 v[208:211], v154 offset:37888
	ds_read_b128 v[212:215], v154 offset:38912
	ds_read_b128 v[216:219], v154 offset:39936
	global_load_lds_dwordx4 v[226:227], off
	v_lshl_add_u64 v[226:227], s[24:25], 0, v[132:133]
	s_mov_b32 m0, s31
	s_nop 0
	global_load_lds_dwordx4 v[226:227], off
	s_waitcnt vmcnt(8)
	s_waitcnt lgkmcnt(0)
	s_barrier
	s_setprio 1
	s_waitcnt lgkmcnt(0)
	v_mfma_f32_16x16x32_bf16 v[126:129], v[146:149], v[188:191], v[126:129]
	v_mfma_f32_16x16x32_bf16 v[122:125], v[160:163], v[188:191], v[122:125]
	v_mfma_f32_16x16x32_bf16 v[110:113], v[146:149], v[196:199], v[110:113]
	v_mfma_f32_16x16x32_bf16 v[106:109], v[160:163], v[196:199], v[106:109]
	v_mfma_f32_16x16x32_bf16 v[94:97], v[146:149], v[204:207], v[94:97]
	v_mfma_f32_16x16x32_bf16 v[90:93], v[160:163], v[204:207], v[90:93]
	v_mfma_f32_16x16x32_bf16 v[78:81], v[146:149], v[212:215], v[78:81]
	v_mfma_f32_16x16x32_bf16 v[74:77], v[160:163], v[212:215], v[74:77]
	v_mfma_f32_16x16x32_bf16 v[126:129], v[156:159], v[192:195], v[126:129]
	v_mfma_f32_16x16x32_bf16 v[122:125], v[164:167], v[192:195], v[122:125]
	v_mfma_f32_16x16x32_bf16 v[110:113], v[156:159], v[200:203], v[110:113]
	v_mfma_f32_16x16x32_bf16 v[106:109], v[164:167], v[200:203], v[106:109]
	v_mfma_f32_16x16x32_bf16 v[94:97], v[156:159], v[208:211], v[94:97]
	v_mfma_f32_16x16x32_bf16 v[90:93], v[164:167], v[208:211], v[90:93]
	v_mfma_f32_16x16x32_bf16 v[78:81], v[156:159], v[216:219], v[78:81]
	v_mfma_f32_16x16x32_bf16 v[74:77], v[164:167], v[216:219], v[74:77]
	s_setprio 0
	s_setprio 1
	v_mfma_f32_16x16x32_bf16 v[118:121], v[168:171], v[188:191], v[118:121]
	v_mfma_f32_16x16x32_bf16 v[114:117], v[176:179], v[188:191], v[114:117]
	v_mfma_f32_16x16x32_bf16 v[102:105], v[168:171], v[196:199], v[102:105]
	v_mfma_f32_16x16x32_bf16 v[98:101], v[176:179], v[196:199], v[98:101]
	v_mfma_f32_16x16x32_bf16 v[86:89], v[168:171], v[204:207], v[86:89]
	v_mfma_f32_16x16x32_bf16 v[82:85], v[176:179], v[204:207], v[82:85]
	v_mfma_f32_16x16x32_bf16 v[70:73], v[168:171], v[212:215], v[70:73]
	v_mfma_f32_16x16x32_bf16 v[66:69], v[176:179], v[212:215], v[66:69]
	v_mfma_f32_16x16x32_bf16 v[118:121], v[172:175], v[192:195], v[118:121]
	v_mfma_f32_16x16x32_bf16 v[114:117], v[180:183], v[192:195], v[114:117]
	v_mfma_f32_16x16x32_bf16 v[102:105], v[172:175], v[200:203], v[102:105]
	v_mfma_f32_16x16x32_bf16 v[98:101], v[180:183], v[200:203], v[98:101]
	v_mfma_f32_16x16x32_bf16 v[86:89], v[172:175], v[208:211], v[86:89]
	v_mfma_f32_16x16x32_bf16 v[82:85], v[180:183], v[208:211], v[82:85]
	v_mfma_f32_16x16x32_bf16 v[70:73], v[172:175], v[216:219], v[70:73]
	v_mfma_f32_16x16x32_bf16 v[66:69], v[180:183], v[216:219], v[66:69]
	s_barrier
; #define PG8_STAGE(bufoff, gbase, voff) do { _Pragma("unroll") for (int _i = 0; _i < 2; ++_i) \
;         __builtin_amdgcn_global_load_lds((const unsigned*)((const char*)(gbase) + (voff)[_i]), (PG8_LAS unsigned*)(lds + (bufoff) + ldsw + _i * 8192), 16, 0, 0); } while (0)
; #define PG8_LDA(dst, b, h) do { _Pragma("unroll") for (int m = 0; m < 4; ++m) _Pragma("unroll") for (int k = 0; k < 2; ++k) dst[m][k] = *(const PG8_LAS bf16x8*)(lds + PG8_SA(b, h) + aoff + m * 2048 + k * 1024); } while (0)
; #define PG8_MMA(ai, bj, At, Bt) do { __builtin_amdgcn_s_setprio(1); _Pragma("unroll") for (int m = 0; m < 4; ++m) _Pragma("unroll") for (int n = 0; n < 2; ++n) _Pragma("unroll") for (int k = 0; k < 2; ++k) \
;         acc[ai][bj][m][n] = __builtin_amdgcn_mfma_f32_16x16x32_bf16(Bt[n][k], At[m][k], acc[ai][bj][m][n], 0, 0, 0); __builtin_amdgcn_s_setprio(0); } while (0)
; #define PG8_WAIT_V(n) asm volatile("s_waitcnt vmcnt(" #n ")" ::: "memory")
; #define PG8_WAIT_L(n) asm volatile("s_waitcnt lgkmcnt(" #n ")" ::: "memory")
; #define PG8_BAR __builtin_amdgcn_s_barrier()
; #define PG8_SCHED __builtin_amdgcn_sched_barrier(0)
; template <class Epi, class Sched, bool ALIGN_EPI = false, bool SP2 = false>
; __device__ __forceinline__ void gemm_phase(PG8_LAS unsigned char* lds, const Gemm g, const Sched& S, const Epi& E) {
;     ...
;             PG8_LDA(At, 1, 1); PG8_STAGE(PG8_SB(1, 0), b3, voffB); PG8_STAGE(PG8_SB(1, 1), b3 + hstep, voffB); PG8_STAGE(PG8_SA(1, 0), a3, voffA);
;             PG8_WAIT_V(8); PG8_WAIT_L(0); PG8_BAR; PG8_MMA(1, 0, At, B0); PG8_MMA(1, 1, At, B1); PG8_BAR; PG8_SCHED;
;     ...
;         if constexpr (ALIGN_EPI) { if (wr == 0) PG8_BAR; }
	s_setprio 0
	s_add_i32 s24, s51, s26
	v_lshl_add_u64 v[184:185], v[184:185], 0, s[6:7]
	s_mov_b32 m0, s24
	ds_read_b128 v[188:191], v154 offset:49152
	ds_read_b128 v[192:195], v154 offset:50176
	ds_read_b128 v[196:199], v154 offset:51200
	ds_read_b128 v[200:203], v154 offset:52224
	ds_read_b128 v[204:207], v154 offset:53248
	ds_read_b128 v[208:211], v154 offset:54272
	ds_read_b128 v[212:215], v154 offset:55296
	ds_read_b128 v[216:219], v154 offset:56320
	global_load_lds_dwordx4 v[184:185], off
	s_add_i32 m0, s24, 0x2000
	s_add_u32 s22, s22, 0x40080
	v_lshl_add_u64 v[184:185], v[220:221], 0, s[6:7]
	s_addc_u32 s23, s23, 0
	s_add_i32 s24, s52, s26
	global_load_lds_dwordx4 v[184:185], off
	v_lshl_add_u64 v[184:185], s[22:23], 0, v[134:135]
	s_mov_b32 m0, s24
	s_nop 0
	global_load_lds_dwordx4 v[184:185], off
	v_lshl_add_u64 v[184:185], s[22:23], 0, v[130:131]
	s_add_i32 m0, s24, 0x2000
	s_nop 0
	global_load_lds_dwordx4 v[184:185], off
	v_lshl_add_u64 v[184:185], v[222:223], 0, s[6:7]
	s_mov_b32 m0, s35
	s_nop 0
	global_load_lds_dwordx4 v[184:185], off
	v_lshl_add_u64 v[184:185], v[224:225], 0, s[6:7]
	s_mov_b32 m0, s36
	s_nop 0
	global_load_lds_dwordx4 v[184:185], off
	s_waitcnt vmcnt(8)
	s_waitcnt lgkmcnt(0)
	s_barrier
	s_setprio 1
	s_waitcnt lgkmcnt(0)
	v_mfma_f32_16x16x32_bf16 v[62:65], v[146:149], v[188:191], v[62:65]
	v_mfma_f32_16x16x32_bf16 v[58:61], v[160:163], v[188:191], v[58:61]
	v_mfma_f32_16x16x32_bf16 v[46:49], v[146:149], v[196:199], v[46:49]
	v_mfma_f32_16x16x32_bf16 v[42:45], v[160:163], v[196:199], v[42:45]
	v_mfma_f32_16x16x32_bf16 v[30:33], v[146:149], v[204:207], v[30:33]
	v_mfma_f32_16x16x32_bf16 v[26:29], v[160:163], v[204:207], v[26:29]
	v_mfma_f32_16x16x32_bf16 v[14:17], v[146:149], v[212:215], v[14:17]
	v_mfma_f32_16x16x32_bf16 v[10:13], v[160:163], v[212:215], v[10:13]
	v_mfma_f32_16x16x32_bf16 v[62:65], v[156:159], v[192:195], v[62:65]
	v_mfma_f32_16x16x32_bf16 v[58:61], v[164:167], v[192:195], v[58:61]
	v_mfma_f32_16x16x32_bf16 v[46:49], v[156:159], v[200:203], v[46:49]
	v_mfma_f32_16x16x32_bf16 v[42:45], v[164:167], v[200:203], v[42:45]
	v_mfma_f32_16x16x32_bf16 v[30:33], v[156:159], v[208:211], v[30:33]
	v_mfma_f32_16x16x32_bf16 v[26:29], v[164:167], v[208:211], v[26:29]
	v_mfma_f32_16x16x32_bf16 v[14:17], v[156:159], v[216:219], v[14:17]
	v_mfma_f32_16x16x32_bf16 v[10:13], v[164:167], v[216:219], v[10:13]
	s_setprio 0
	s_setprio 1
	v_mfma_f32_16x16x32_bf16 v[54:57], v[168:171], v[188:191], v[54:57]
	v_mfma_f32_16x16x32_bf16 v[50:53], v[176:179], v[188:191], v[50:53]
	v_mfma_f32_16x16x32_bf16 v[38:41], v[168:171], v[196:199], v[38:41]
	v_mfma_f32_16x16x32_bf16 v[34:37], v[176:179], v[196:199], v[34:37]
	v_mfma_f32_16x16x32_bf16 v[22:25], v[168:171], v[204:207], v[22:25]
	v_mfma_f32_16x16x32_bf16 v[18:21], v[176:179], v[204:207], v[18:21]
	v_mfma_f32_16x16x32_bf16 v[6:9], v[168:171], v[212:215], v[6:9]
	v_mfma_f32_16x16x32_bf16 v[2:5], v[176:179], v[212:215], v[2:5]
	v_mfma_f32_16x16x32_bf16 v[54:57], v[172:175], v[192:195], v[54:57]
	v_mfma_f32_16x16x32_bf16 v[50:53], v[180:183], v[192:195], v[50:53]
	v_mfma_f32_16x16x32_bf16 v[38:41], v[172:175], v[200:203], v[38:41]
	v_mfma_f32_16x16x32_bf16 v[34:37], v[180:183], v[200:203], v[34:37]
	v_mfma_f32_16x16x32_bf16 v[22:25], v[172:175], v[208:211], v[22:25]
	v_mfma_f32_16x16x32_bf16 v[18:21], v[180:183], v[208:211], v[18:21]
	v_mfma_f32_16x16x32_bf16 v[6:9], v[172:175], v[216:219], v[6:9]
	v_mfma_f32_16x16x32_bf16 v[2:5], v[180:183], v[216:219], v[2:5]
	s_barrier
	s_setprio 0
	s_add_i32 s50, s50, 2
	s_add_u32 s20, s20, 0x100
	s_addc_u32 s21, s21, 0
	s_add_u32 s48, s48, 0x100
	s_addc_u32 s49, s49, 0
	s_cmp_gt_u32 s50, 13
	s_cbranch_scc0 .LBB0_85
	s_and_b64 vcc, exec, s[8:9]
	s_cbranch_vccz .LBB0_88
	s_barrier

; #define PG8_STAGE(bufoff, gbase, voff) do { _Pragma("unroll") for (int _i = 0; _i < 2; ++_i) \
;         __builtin_amdgcn_global_load_lds((const unsigned*)((const char*)(gbase) + (voff)[_i]), (PG8_LAS unsigned*)(lds + (bufoff) + ldsw + _i * 8192), 16, 0, 0); } while (0)
; #define PG8_LDA(dst, b, h) do { _Pragma("unroll") for (int m = 0; m < 4; ++m) _Pragma("unroll") for (int k = 0; k < 2; ++k) dst[m][k] = *(const PG8_LAS bf16x8*)(lds + PG8_SA(b, h) + aoff + m * 2048 + k * 1024); } while (0)
; #define PG8_LDB(dst, b, h) do { _Pragma("unroll") for (int n = 0; n < 2; ++n) _Pragma("unroll") for (int k = 0; k < 2; ++k) dst[n][k] = *(const PG8_LAS bf16x8*)(lds + PG8_SB(b, h) + boff + n * 2048 + k * 1024); } while (0)
; #define PG8_MMA(ai, bj, At, Bt) do { __builtin_amdgcn_s_setprio(1); _Pragma("unroll") for (int m = 0; m < 4; ++m) _Pragma("unroll") for (int n = 0; n < 2; ++n) _Pragma("unroll") for (int k = 0; k < 2; ++k) \
;         acc[ai][bj][m][n] = __builtin_amdgcn_mfma_f32_16x16x32_bf16(Bt[n][k], At[m][k], acc[ai][bj][m][n], 0, 0, 0); __builtin_amdgcn_s_setprio(0); } while (0)
; #define PG8_WAIT_V(n) asm volatile("s_waitcnt vmcnt(" #n ")" ::: "memory")
; #define PG8_WAIT_L(n) asm volatile("s_waitcnt lgkmcnt(" #n ")" ::: "memory")
; #define PG8_BAR __builtin_amdgcn_s_barrier()
; #define PG8_SCHED __builtin_amdgcn_sched_barrier(0)
; template <class Epi, class Sched, bool ALIGN_EPI = false, bool SP2 = false>
; __device__ __forceinline__ void gemm_phase(PG8_LAS unsigned char* lds, const Gemm g, const Sched& S, const Epi& E) {
;     ...
;             const bool last = (t == nt - 2);
;             const char* a1 = cA + (size_t)(t + 1) * kstep;
;             const char* a2 = last ? nA : cA + (size_t)(t + 2) * kstep; const char* b2 = last ? nB : cB + (size_t)(t + 2) * kstep;
;             const char* a3 = a2 + kstep; const char* b3 = b2 + kstep;
;             if (last && has_next) S.a_ready(nxt);
;             if constexpr (SP2) {
;             PG8_LDB(B0, 0, 0); PG8_LDB(B1, 0, 1); PG8_SCHED; PG8_LDA(At, 0, 0); PG8_STAGE(PG8_SA(1, 1), a1 + hstep, voffA);
;             PG8_WAIT_V(8); PG8_WAIT_L(0); PG8_BAR; PG8_MMA(0, 0, At, B0); PG8_MMA(0, 1, At, B1); PG8_BAR; PG8_SCHED;
;             PG8_LDA(At, 0, 1); PG8_STAGE(PG8_SB(0, 0), b2, voffB); PG8_STAGE(PG8_SB(0, 1), b2 + hstep, voffB); PG8_STAGE(PG8_SA(0, 0), a2, voffA);
.LBB0_207:
	ds_read_b128 v[144:147], v140
	ds_read_b128 v[148:151], v140 offset:1024
	ds_read_b128 v[152:155], v140 offset:2048
	ds_read_b128 v[156:159], v140 offset:3072
	ds_read_b128 v[160:163], v141
	ds_read_b128 v[164:167], v141 offset:1024
	ds_read_b128 v[168:171], v141 offset:2048
	ds_read_b128 v[172:175], v141 offset:3072
	s_add_i32 s68, s36, 2
	s_add_u32 s34, s30, 0x100
	s_addc_u32 s35, s31, 0
	s_cmp_eq_u32 s53, s36
	s_cselect_b32 s36, s28, s66
	s_cselect_b32 s39, s27, s35
	s_cselect_b32 s38, s26, s34
	s_cselect_b32 s37, s29, s67
	s_mov_b32 m0, s60
	v_lshl_add_u64 v[184:185], s[30:31], 0, v[134:135]
	ds_read_b128 v[176:179], v142
	ds_read_b128 v[180:183], v142 offset:1024
	ds_read_b128 v[188:191], v142 offset:2048
	ds_read_b128 v[192:195], v142 offset:3072
	ds_read_b128 v[196:199], v142 offset:4096
	ds_read_b128 v[200:203], v142 offset:5120
	ds_read_b128 v[204:207], v142 offset:6144
	ds_read_b128 v[208:211], v142 offset:7168
	global_load_lds_dwordx4 v[184:185], off
	v_lshl_add_u64 v[184:185], s[30:31], 0, v[136:137]
	s_add_i32 m0, s41, 0xe000
	s_nop 0
	global_load_lds_dwordx4 v[184:185], off
	s_waitcnt vmcnt(8)
	s_waitcnt lgkmcnt(0)
	s_barrier
	s_setprio 1
	s_waitcnt lgkmcnt(0)
	v_mfma_f32_16x16x32_bf16 v[126:129], v[144:147], v[176:179], v[126:129]
	v_mfma_f32_16x16x32_bf16 v[122:125], v[152:155], v[176:179], v[122:125]
	v_mfma_f32_16x16x32_bf16 v[110:113], v[144:147], v[188:191], v[110:113]
	v_mfma_f32_16x16x32_bf16 v[106:109], v[152:155], v[188:191], v[106:109]
	v_mfma_f32_16x16x32_bf16 v[94:97], v[144:147], v[196:199], v[94:97]
	v_mfma_f32_16x16x32_bf16 v[90:93], v[152:155], v[196:199], v[90:93]
	v_mfma_f32_16x16x32_bf16 v[78:81], v[144:147], v[204:207], v[78:81]
	v_mfma_f32_16x16x32_bf16 v[74:77], v[152:155], v[204:207], v[74:77]
	v_mfma_f32_16x16x32_bf16 v[126:129], v[148:151], v[180:183], v[126:129]
	v_mfma_f32_16x16x32_bf16 v[122:125], v[156:159], v[180:183], v[122:125]
	v_mfma_f32_16x16x32_bf16 v[110:113], v[148:151], v[192:195], v[110:113]
	v_mfma_f32_16x16x32_bf16 v[106:109], v[156:159], v[192:195], v[106:109]
	v_mfma_f32_16x16x32_bf16 v[94:97], v[148:151], v[200:203], v[94:97]
	v_mfma_f32_16x16x32_bf16 v[90:93], v[156:159], v[200:203], v[90:93]
	v_mfma_f32_16x16x32_bf16 v[78:81], v[148:151], v[208:211], v[78:81]
	v_mfma_f32_16x16x32_bf16 v[74:77], v[156:159], v[208:211], v[74:77]
	s_setprio 0
	s_setprio 1
	v_mfma_f32_16x16x32_bf16 v[118:121], v[160:163], v[176:179], v[118:121]
	v_mfma_f32_16x16x32_bf16 v[114:117], v[168:171], v[176:179], v[114:117]
	v_mfma_f32_16x16x32_bf16 v[102:105], v[160:163], v[188:191], v[102:105]
	v_mfma_f32_16x16x32_bf16 v[98:101], v[168:171], v[188:191], v[98:101]
	v_mfma_f32_16x16x32_bf16 v[86:89], v[160:163], v[196:199], v[86:89]
	v_mfma_f32_16x16x32_bf16 v[82:85], v[168:171], v[196:199], v[82:85]
	v_mfma_f32_16x16x32_bf16 v[70:73], v[160:163], v[204:207], v[70:73]
	v_mfma_f32_16x16x32_bf16 v[66:69], v[168:171], v[204:207], v[66:69]
	v_mfma_f32_16x16x32_bf16 v[118:121], v[164:167], v[180:183], v[118:121]
	v_mfma_f32_16x16x32_bf16 v[114:117], v[172:175], v[180:183], v[114:117]
	v_mfma_f32_16x16x32_bf16 v[102:105], v[164:167], v[192:195], v[102:105]
	v_mfma_f32_16x16x32_bf16 v[98:101], v[172:175], v[192:195], v[98:101]
	v_mfma_f32_16x16x32_bf16 v[86:89], v[164:167], v[200:203], v[86:89]
	v_mfma_f32_16x16x32_bf16 v[82:85], v[172:175], v[200:203], v[82:85]
	v_mfma_f32_16x16x32_bf16 v[70:73], v[164:167], v[208:211], v[70:73]
	v_mfma_f32_16x16x32_bf16 v[66:69], v[172:175], v[208:211], v[66:69]
	s_barrier
	s_setprio 0
	s_add_i32 s30, s54, s40
	v_lshl_add_u64 v[184:185], s[36:37], 0, v[132:133]
	s_mov_b32 m0, s30
	ds_read_b128 v[176:179], v142 offset:16384
	ds_read_b128 v[180:183], v142 offset:17408
	ds_read_b128 v[188:191], v142 offset:18432
	ds_read_b128 v[192:195], v142 offset:19456
	ds_read_b128 v[196:199], v142 offset:20480
	ds_read_b128 v[200:203], v142 offset:21504
	ds_read_b128 v[204:207], v142 offset:22528
	ds_read_b128 v[208:211], v142 offset:23552
	global_load_lds_dwordx4 v[184:185], off
	s_add_i32 m0, s30, 0x2000
	s_add_u32 s30, s36, 0xb0000
	v_lshl_add_u64 v[212:213], s[36:37], 0, v[130:131]
	s_addc_u32 s31, s37, 0
	s_add_i32 s69, s55, s40
	global_load_lds_dwordx4 v[212:213], off
	v_lshl_add_u64 v[214:215], s[30:31], 0, v[132:133]
	s_mov_b32 m0, s69
	v_lshl_add_u64 v[216:217], s[38:39], 0, v[130:131]
	global_load_lds_dwordx4 v[214:215], off
	v_lshl_add_u64 v[214:215], s[30:31], 0, v[130:131]
	s_add_i32 m0, s69, 0x2000
	s_nop 0
	global_load_lds_dwordx4 v[214:215], off
	v_lshl_add_u64 v[214:215], s[38:39], 0, v[132:133]
	s_mov_b32 m0, s41
	s_nop 0
	global_load_lds_dwordx4 v[214:215], off
	s_mov_b32 m0, s42
	s_nop 0
	global_load_lds_dwordx4 v[216:217], off
	s_waitcnt vmcnt(8)
	s_waitcnt lgkmcnt(0)
	s_barrier
; #define PG8_STAGE(bufoff, gbase, voff) do { _Pragma("unroll") for (int _i = 0; _i < 2; ++_i) \
;         __builtin_amdgcn_global_load_lds((const unsigned*)((const char*)(gbase) + (voff)[_i]), (PG8_LAS unsigned*)(lds + (bufoff) + ldsw + _i * 8192), 16, 0, 0); } while (0)
; #define PG8_LDA(dst, b, h) do { _Pragma("unroll") for (int m = 0; m < 4; ++m) _Pragma("unroll") for (int k = 0; k < 2; ++k) dst[m][k] = *(const PG8_LAS bf16x8*)(lds + PG8_SA(b, h) + aoff + m * 2048 + k * 1024); } while (0)
; #define PG8_LDB(dst, b, h) do { _Pragma("unroll") for (int n = 0; n < 2; ++n) _Pragma("unroll") for (int k = 0; k < 2; ++k) dst[n][k] = *(const PG8_LAS bf16x8*)(lds + PG8_SB(b, h) + boff + n * 2048 + k * 1024); } while (0)
; #define PG8_MMA(ai, bj, At, Bt) do { __builtin_amdgcn_s_setprio(1); _Pragma("unroll") for (int m = 0; m < 4; ++m) _Pragma("unroll") for (int n = 0; n < 2; ++n) _Pragma("unroll") for (int k = 0; k < 2; ++k) \
;         acc[ai][bj][m][n] = __builtin_amdgcn_mfma_f32_16x16x32_bf16(Bt[n][k], At[m][k], acc[ai][bj][m][n], 0, 0, 0); __builtin_amdgcn_s_setprio(0); } while (0)
; #define PG8_WAIT_V(n) asm volatile("s_waitcnt vmcnt(" #n ")" ::: "memory")
; #define PG8_WAIT_L(n) asm volatile("s_waitcnt lgkmcnt(" #n ")" ::: "memory")
; #define PG8_BAR __builtin_amdgcn_s_barrier()
; #define PG8_SCHED __builtin_amdgcn_sched_barrier(0)
; template <class Epi, class Sched, bool ALIGN_EPI = false, bool SP2 = false>
; __device__ __forceinline__ void gemm_phase(PG8_LAS unsigned char* lds, const Gemm g, const Sched& S, const Epi& E) {
;     ...
;             PG8_WAIT_V(8); PG8_WAIT_L(0); PG8_BAR; PG8_MMA(1, 0, At, B0); PG8_MMA(1, 1, At, B1); PG8_BAR; PG8_SCHED;
;             PG8_LDB(B0, 1, 0); PG8_LDB(B1, 1, 1); PG8_SCHED; PG8_LDA(At, 1, 0); PG8_STAGE(PG8_SA(0, 1), a2 + hstep, voffA);
;             PG8_WAIT_V(8); PG8_WAIT_L(0); PG8_BAR; PG8_MMA(0, 0, At, B0); PG8_MMA(0, 1, At, B1); PG8_BAR; PG8_SCHED;
	s_setprio 1
	s_waitcnt lgkmcnt(0)
	v_mfma_f32_16x16x32_bf16 v[62:65], v[144:147], v[176:179], v[62:65]
	v_mfma_f32_16x16x32_bf16 v[58:61], v[152:155], v[176:179], v[58:61]
	v_mfma_f32_16x16x32_bf16 v[46:49], v[144:147], v[188:191], v[46:49]
	v_mfma_f32_16x16x32_bf16 v[42:45], v[152:155], v[188:191], v[42:45]
	v_mfma_f32_16x16x32_bf16 v[30:33], v[144:147], v[196:199], v[30:33]
	v_mfma_f32_16x16x32_bf16 v[26:29], v[152:155], v[196:199], v[26:29]
	v_mfma_f32_16x16x32_bf16 v[14:17], v[144:147], v[204:207], v[14:17]
	v_mfma_f32_16x16x32_bf16 v[10:13], v[152:155], v[204:207], v[10:13]
	v_mfma_f32_16x16x32_bf16 v[62:65], v[148:151], v[180:183], v[62:65]
	v_mfma_f32_16x16x32_bf16 v[58:61], v[156:159], v[180:183], v[58:61]
	v_mfma_f32_16x16x32_bf16 v[46:49], v[148:151], v[192:195], v[46:49]
	v_mfma_f32_16x16x32_bf16 v[42:45], v[156:159], v[192:195], v[42:45]
	v_mfma_f32_16x16x32_bf16 v[30:33], v[148:151], v[200:203], v[30:33]
	v_mfma_f32_16x16x32_bf16 v[26:29], v[156:159], v[200:203], v[26:29]
	v_mfma_f32_16x16x32_bf16 v[14:17], v[148:151], v[208:211], v[14:17]
	v_mfma_f32_16x16x32_bf16 v[10:13], v[156:159], v[208:211], v[10:13]
	s_setprio 0
	s_setprio 1
	v_mfma_f32_16x16x32_bf16 v[54:57], v[160:163], v[176:179], v[54:57]
	v_mfma_f32_16x16x32_bf16 v[50:53], v[168:171], v[176:179], v[50:53]
	v_mfma_f32_16x16x32_bf16 v[38:41], v[160:163], v[188:191], v[38:41]
	v_mfma_f32_16x16x32_bf16 v[34:37], v[168:171], v[188:191], v[34:37]
	v_mfma_f32_16x16x32_bf16 v[22:25], v[160:163], v[196:199], v[22:25]
	v_mfma_f32_16x16x32_bf16 v[18:21], v[168:171], v[196:199], v[18:21]
	v_mfma_f32_16x16x32_bf16 v[6:9], v[160:163], v[204:207], v[6:9]
	v_mfma_f32_16x16x32_bf16 v[2:5], v[168:171], v[204:207], v[2:5]
	v_mfma_f32_16x16x32_bf16 v[54:57], v[164:167], v[180:183], v[54:57]
	v_mfma_f32_16x16x32_bf16 v[50:53], v[172:175], v[180:183], v[50:53]
	v_mfma_f32_16x16x32_bf16 v[38:41], v[164:167], v[192:195], v[38:41]
	v_mfma_f32_16x16x32_bf16 v[34:37], v[172:175], v[192:195], v[34:37]
	v_mfma_f32_16x16x32_bf16 v[22:25], v[164:167], v[200:203], v[22:25]
	v_mfma_f32_16x16x32_bf16 v[18:21], v[172:175], v[200:203], v[18:21]
	v_mfma_f32_16x16x32_bf16 v[6:9], v[164:167], v[208:211], v[6:9]
	v_mfma_f32_16x16x32_bf16 v[2:5], v[172:175], v[208:211], v[2:5]
	s_barrier
	s_setprio 0
	s_add_i32 s69, 0, 0x18000
	v_add_u32_e32 v143, s69, v1
	s_add_i32 s70, 0, 0x1c000
	ds_read_b128 v[144:147], v143
	ds_read_b128 v[148:151], v143 offset:1024
	ds_read_b128 v[152:155], v143 offset:2048
	ds_read_b128 v[156:159], v143 offset:3072
	v_add_u32_e32 v143, s70, v1
	ds_read_b128 v[160:163], v143
	ds_read_b128 v[164:167], v143 offset:1024
	ds_read_b128 v[168:171], v143 offset:2048
	ds_read_b128 v[172:175], v143 offset:3072
	s_add_u32 s30, s38, 0xb0000
	s_addc_u32 s31, s39, 0
	s_mov_b32 m0, s43
	v_lshl_add_u64 v[218:219], s[30:31], 0, v[132:133]
	ds_read_b128 v[176:179], v142 offset:32768
	ds_read_b128 v[180:183], v142 offset:33792
	ds_read_b128 v[188:191], v142 offset:34816
	ds_read_b128 v[192:195], v142 offset:35840
	ds_read_b128 v[196:199], v142 offset:36864
	ds_read_b128 v[200:203], v142 offset:37888
	ds_read_b128 v[204:207], v142 offset:38912
	ds_read_b128 v[208:211], v142 offset:39936
	global_load_lds_dwordx4 v[218:219], off
	v_lshl_add_u64 v[218:219], s[30:31], 0, v[130:131]
	s_mov_b32 m0, s48
	s_nop 0
	global_load_lds_dwordx4 v[218:219], off
	s_waitcnt vmcnt(8)
	s_waitcnt lgkmcnt(0)
	s_barrier
	s_setprio 1
	s_waitcnt lgkmcnt(0)
	v_mfma_f32_16x16x32_bf16 v[126:129], v[144:147], v[176:179], v[126:129]
	v_mfma_f32_16x16x32_bf16 v[122:125], v[152:155], v[176:179], v[122:125]
	v_mfma_f32_16x16x32_bf16 v[110:113], v[144:147], v[188:191], v[110:113]
	v_mfma_f32_16x16x32_bf16 v[106:109], v[152:155], v[188:191], v[106:109]
	v_mfma_f32_16x16x32_bf16 v[94:97], v[144:147], v[196:199], v[94:97]
	v_mfma_f32_16x16x32_bf16 v[90:93], v[152:155], v[196:199], v[90:93]
	v_mfma_f32_16x16x32_bf16 v[78:81], v[144:147], v[204:207], v[78:81]
	v_mfma_f32_16x16x32_bf16 v[74:77], v[152:155], v[204:207], v[74:77]
	v_mfma_f32_16x16x32_bf16 v[126:129], v[148:151], v[180:183], v[126:129]
	v_mfma_f32_16x16x32_bf16 v[122:125], v[156:159], v[180:183], v[122:125]
	v_mfma_f32_16x16x32_bf16 v[110:113], v[148:151], v[192:195], v[110:113]
	v_mfma_f32_16x16x32_bf16 v[106:109], v[156:159], v[192:195], v[106:109]
	v_mfma_f32_16x16x32_bf16 v[94:97], v[148:151], v[200:203], v[94:97]
	v_mfma_f32_16x16x32_bf16 v[90:93], v[156:159], v[200:203], v[90:93]
	v_mfma_f32_16x16x32_bf16 v[78:81], v[148:151], v[208:211], v[78:81]
	v_mfma_f32_16x16x32_bf16 v[74:77], v[156:159], v[208:211], v[74:77]
	s_setprio 0
	s_setprio 1
	v_mfma_f32_16x16x32_bf16 v[118:121], v[160:163], v[176:179], v[118:121]
	v_mfma_f32_16x16x32_bf16 v[114:117], v[168:171], v[176:179], v[114:117]
	v_mfma_f32_16x16x32_bf16 v[102:105], v[160:163], v[188:191], v[102:105]
	v_mfma_f32_16x16x32_bf16 v[98:101], v[168:171], v[188:191], v[98:101]
	v_mfma_f32_16x16x32_bf16 v[86:89], v[160:163], v[196:199], v[86:89]
	v_mfma_f32_16x16x32_bf16 v[82:85], v[168:171], v[196:199], v[82:85]
	v_mfma_f32_16x16x32_bf16 v[70:73], v[160:163], v[204:207], v[70:73]
	v_mfma_f32_16x16x32_bf16 v[66:69], v[168:171], v[204:207], v[66:69]
	v_mfma_f32_16x16x32_bf16 v[118:121], v[164:167], v[180:183], v[118:121]
	v_mfma_f32_16x16x32_bf16 v[114:117], v[172:175], v[180:183], v[114:117]
	v_mfma_f32_16x16x32_bf16 v[102:105], v[164:167], v[192:195], v[102:105]
	v_mfma_f32_16x16x32_bf16 v[98:101], v[172:175], v[192:195], v[98:101]
	v_mfma_f32_16x16x32_bf16 v[86:89], v[164:167], v[200:203], v[86:89]
	v_mfma_f32_16x16x32_bf16 v[82:85], v[172:175], v[200:203], v[82:85]
	v_mfma_f32_16x16x32_bf16 v[70:73], v[164:167], v[208:211], v[70:73]
	v_mfma_f32_16x16x32_bf16 v[66:69], v[172:175], v[208:211], v[66:69]
	s_barrier
; #define PG8_STAGE(bufoff, gbase, voff) do { _Pragma("unroll") for (int _i = 0; _i < 2; ++_i) \
;         __builtin_amdgcn_global_load_lds((const unsigned*)((const char*)(gbase) + (voff)[_i]), (PG8_LAS unsigned*)(lds + (bufoff) + ldsw + _i * 8192), 16, 0, 0); } while (0)
; #define PG8_LDA(dst, b, h) do { _Pragma("unroll") for (int m = 0; m < 4; ++m) _Pragma("unroll") for (int k = 0; k < 2; ++k) dst[m][k] = *(const PG8_LAS bf16x8*)(lds + PG8_SA(b, h) + aoff + m * 2048 + k * 1024); } while (0)
; #define PG8_MMA(ai, bj, At, Bt) do { __builtin_amdgcn_s_setprio(1); _Pragma("unroll") for (int m = 0; m < 4; ++m) _Pragma("unroll") for (int n = 0; n < 2; ++n) _Pragma("unroll") for (int k = 0; k < 2; ++k) \
;         acc[ai][bj][m][n] = __builtin_amdgcn_mfma_f32_16x16x32_bf16(Bt[n][k], At[m][k], acc[ai][bj][m][n], 0, 0, 0); __builtin_amdgcn_s_setprio(0); } while (0)
; #define PG8_WAIT_V(n) asm volatile("s_waitcnt vmcnt(" #n ")" ::: "memory")
; #define PG8_WAIT_L(n) asm volatile("s_waitcnt lgkmcnt(" #n ")" ::: "memory")
; #define PG8_BAR __builtin_amdgcn_s_barrier()
; #define PG8_SCHED __builtin_amdgcn_sched_barrier(0)
; template <class Epi, class Sched, bool ALIGN_EPI = false, bool SP2 = false>
; __device__ __forceinline__ void gemm_phase(PG8_LAS unsigned char* lds, const Gemm g, const Sched& S, const Epi& E) {
;     ...
;             PG8_LDA(At, 1, 1); PG8_STAGE(PG8_SB(1, 0), b3, voffB); PG8_STAGE(PG8_SB(1, 1), b3 + hstep, voffB); PG8_STAGE(PG8_SA(1, 0), a3, voffA);
;             PG8_WAIT_V(8); PG8_WAIT_L(0); PG8_BAR; PG8_MMA(1, 0, At, B0); PG8_MMA(1, 1, At, B1); PG8_BAR; PG8_SCHED;
	s_setprio 0
	s_add_i32 s30, s69, s40
	v_lshl_add_u64 v[184:185], v[184:185], 0, s[14:15]
	s_mov_b32 m0, s30
	ds_read_b128 v[176:179], v142 offset:49152
	ds_read_b128 v[180:183], v142 offset:50176
	ds_read_b128 v[188:191], v142 offset:51200
	ds_read_b128 v[192:195], v142 offset:52224
	ds_read_b128 v[196:199], v142 offset:53248
	ds_read_b128 v[200:203], v142 offset:54272
	ds_read_b128 v[204:207], v142 offset:55296
	ds_read_b128 v[208:211], v142 offset:56320
	global_load_lds_dwordx4 v[184:185], off
	s_add_i32 m0, s30, 0x2000
	s_add_u32 s30, s36, 0xb0080
	v_lshl_add_u64 v[184:185], v[212:213], 0, s[14:15]
	s_addc_u32 s31, s37, 0
	s_add_i32 s36, s70, s40
	global_load_lds_dwordx4 v[184:185], off
	v_lshl_add_u64 v[184:185], s[30:31], 0, v[132:133]
	s_mov_b32 m0, s36
	s_nop 0
	global_load_lds_dwordx4 v[184:185], off
	v_lshl_add_u64 v[184:185], s[30:31], 0, v[130:131]
	s_add_i32 m0, s36, 0x2000
	s_nop 0
	global_load_lds_dwordx4 v[184:185], off
	v_lshl_add_u64 v[184:185], v[214:215], 0, s[14:15]
	s_mov_b32 m0, s51
	s_nop 0
	global_load_lds_dwordx4 v[184:185], off
	v_lshl_add_u64 v[184:185], v[216:217], 0, s[14:15]
	s_mov_b32 m0, s52
	s_nop 0
	global_load_lds_dwordx4 v[184:185], off
	s_waitcnt vmcnt(8)
	s_waitcnt lgkmcnt(0)
	s_barrier
	s_setprio 1
	s_waitcnt lgkmcnt(0)
	v_mfma_f32_16x16x32_bf16 v[62:65], v[144:147], v[176:179], v[62:65]
	v_mfma_f32_16x16x32_bf16 v[58:61], v[152:155], v[176:179], v[58:61]
	v_mfma_f32_16x16x32_bf16 v[46:49], v[144:147], v[188:191], v[46:49]
	v_mfma_f32_16x16x32_bf16 v[42:45], v[152:155], v[188:191], v[42:45]
	v_mfma_f32_16x16x32_bf16 v[30:33], v[144:147], v[196:199], v[30:33]
	v_mfma_f32_16x16x32_bf16 v[26:29], v[152:155], v[196:199], v[26:29]
	v_mfma_f32_16x16x32_bf16 v[14:17], v[144:147], v[204:207], v[14:17]
	v_mfma_f32_16x16x32_bf16 v[10:13], v[152:155], v[204:207], v[10:13]
	v_mfma_f32_16x16x32_bf16 v[62:65], v[148:151], v[180:183], v[62:65]
	v_mfma_f32_16x16x32_bf16 v[58:61], v[156:159], v[180:183], v[58:61]
	v_mfma_f32_16x16x32_bf16 v[46:49], v[148:151], v[192:195], v[46:49]
	v_mfma_f32_16x16x32_bf16 v[42:45], v[156:159], v[192:195], v[42:45]
	v_mfma_f32_16x16x32_bf16 v[30:33], v[148:151], v[200:203], v[30:33]
	v_mfma_f32_16x16x32_bf16 v[26:29], v[156:159], v[200:203], v[26:29]
	v_mfma_f32_16x16x32_bf16 v[14:17], v[148:151], v[208:211], v[14:17]
	v_mfma_f32_16x16x32_bf16 v[10:13], v[156:159], v[208:211], v[10:13]
	s_setprio 0
	s_setprio 1
	v_mfma_f32_16x16x32_bf16 v[54:57], v[160:163], v[176:179], v[54:57]
	v_mfma_f32_16x16x32_bf16 v[50:53], v[168:171], v[176:179], v[50:53]
	v_mfma_f32_16x16x32_bf16 v[38:41], v[160:163], v[188:191], v[38:41]
	v_mfma_f32_16x16x32_bf16 v[34:37], v[168:171], v[188:191], v[34:37]
	v_mfma_f32_16x16x32_bf16 v[22:25], v[160:163], v[196:199], v[22:25]
	v_mfma_f32_16x16x32_bf16 v[18:21], v[168:171], v[196:199], v[18:21]
	v_mfma_f32_16x16x32_bf16 v[6:9], v[160:163], v[204:207], v[6:9]
	v_mfma_f32_16x16x32_bf16 v[2:5], v[168:171], v[204:207], v[2:5]
	v_mfma_f32_16x16x32_bf16 v[54:57], v[164:167], v[180:183], v[54:57]
	v_mfma_f32_16x16x32_bf16 v[50:53], v[172:175], v[180:183], v[50:53]
	v_mfma_f32_16x16x32_bf16 v[38:41], v[164:167], v[192:195], v[38:41]
	v_mfma_f32_16x16x32_bf16 v[34:37], v[172:175], v[192:195], v[34:37]
	v_mfma_f32_16x16x32_bf16 v[22:25], v[164:167], v[200:203], v[22:25]
	v_mfma_f32_16x16x32_bf16 v[18:21], v[172:175], v[200:203], v[18:21]
	v_mfma_f32_16x16x32_bf16 v[6:9], v[164:167], v[208:211], v[6:9]
	v_mfma_f32_16x16x32_bf16 v[2:5], v[172:175], v[208:211], v[2:5]
	s_barrier
	s_setprio 0
	s_add_u32 s66, s66, 0x100
	s_addc_u32 s67, s67, 0
	s_cmp_ge_i32 s68, s50
	s_mov_b64 s[30:31], s[34:35]
	s_mov_b32 s36, s68
	s_cbranch_scc0 .LBB0_207

; #define PG8_STAGE(bufoff, gbase, voff) do { _Pragma("unroll") for (int _i = 0; _i < 2; ++_i) \
;         __builtin_amdgcn_global_load_lds((const unsigned*)((const char*)(gbase) + (voff)[_i]), (PG8_LAS unsigned*)(lds + (bufoff) + ldsw + _i * 8192), 16, 0, 0); } while (0)
; #define PG8_LDA(dst, b, h) do { _Pragma("unroll") for (int m = 0; m < 4; ++m) _Pragma("unroll") for (int k = 0; k < 2; ++k) dst[m][k] = *(const PG8_LAS bf16x8*)(lds + PG8_SA(b, h) + aoff + m * 2048 + k * 1024); } while (0)
; #define PG8_LDB(dst, b, h) do { _Pragma("unroll") for (int n = 0; n < 2; ++n) _Pragma("unroll") for (int k = 0; k < 2; ++k) dst[n][k] = *(const PG8_LAS bf16x8*)(lds + PG8_SB(b, h) + boff + n * 2048 + k * 1024); } while (0)
; #define PG8_MMA(ai, bj, At, Bt) do { __builtin_amdgcn_s_setprio(1); _Pragma("unroll") for (int m = 0; m < 4; ++m) _Pragma("unroll") for (int n = 0; n < 2; ++n) _Pragma("unroll") for (int k = 0; k < 2; ++k) \
;         acc[ai][bj][m][n] = __builtin_amdgcn_mfma_f32_16x16x32_bf16(Bt[n][k], At[m][k], acc[ai][bj][m][n], 0, 0, 0); __builtin_amdgcn_s_setprio(0); } while (0)
; #define PG8_WAIT_V(n) asm volatile("s_waitcnt vmcnt(" #n ")" ::: "memory")
; #define PG8_WAIT_L(n) asm volatile("s_waitcnt lgkmcnt(" #n ")" ::: "memory")
; #define PG8_BAR __builtin_amdgcn_s_barrier()
; #define PG8_SCHED __builtin_amdgcn_sched_barrier(0)
; template <class Epi, class Sched, bool ALIGN_EPI = false, bool SP2 = false>
; __device__ __forceinline__ void gemm_phase(PG8_LAS unsigned char* lds, const Gemm g, const Sched& S, const Epi& E) {
;     ...
;             const bool last = (t == nt - 2);
;             const char* a1 = cA + (size_t)(t + 1) * kstep;
;             const char* a2 = last ? nA : cA + (size_t)(t + 2) * kstep; const char* b2 = last ? nB : cB + (size_t)(t + 2) * kstep;
;             const char* a3 = a2 + kstep; const char* b3 = b2 + kstep;
;             if (last && has_next) S.a_ready(nxt);
;             if constexpr (SP2) {
;             PG8_LDB(B0, 0, 0); PG8_LDB(B1, 0, 1); PG8_SCHED; PG8_LDA(At, 0, 0); PG8_STAGE(PG8_SA(1, 1), a1 + hstep, voffA);
;             PG8_WAIT_V(8); PG8_WAIT_L(0); PG8_BAR; PG8_MMA(0, 0, At, B0); PG8_MMA(0, 1, At, B1); PG8_BAR; PG8_SCHED;
;             PG8_LDA(At, 0, 1); PG8_STAGE(PG8_SB(0, 0), b2, voffB); PG8_STAGE(PG8_SB(0, 1), b2 + hstep, voffB); PG8_STAGE(PG8_SA(0, 0), a2, voffA);
.LBB0_252:
	v_add_u32_e32 v162, s52, v148
	v_add_u32_e32 v178, s53, v148
	s_add_u32 s28, s20, s26
	ds_read_b128 v[150:153], v162
	ds_read_b128 v[154:157], v162 offset:1024
	ds_read_b128 v[158:161], v162 offset:2048
	ds_read_b128 v[162:165], v162 offset:3072
	ds_read_b128 v[166:169], v178
	ds_read_b128 v[170:173], v178 offset:1024
	ds_read_b128 v[174:177], v178 offset:2048
	ds_read_b128 v[178:181], v178 offset:3072
	s_addc_u32 s29, s21, s27
	s_add_u32 s28, s28, 0x100
	s_addc_u32 s29, s29, 0
	s_add_u32 s60, s57, s26
	s_addc_u32 s61, s58, s27
	s_cmpk_eq_i32 s26, 0x1500
	s_cselect_b32 s31, s25, s29
	s_cselect_b32 s30, s24, s28
	s_cselect_b32 s29, s9, s61
	s_cselect_b32 s28, s8, s60
	v_lshl_add_u64 v[216:217], v[142:143], 0, s[26:27]
	s_add_i32 m0, s40, 0xc000
	ds_read_b128 v[182:185], v149
	ds_read_b128 v[188:191], v149 offset:1024
	ds_read_b128 v[192:195], v149 offset:2048
	ds_read_b128 v[196:199], v149 offset:3072
	ds_read_b128 v[200:203], v149 offset:4096
	ds_read_b128 v[204:207], v149 offset:5120
	ds_read_b128 v[208:211], v149 offset:6144
	ds_read_b128 v[212:215], v149 offset:7168
	global_load_lds_dwordx4 v[216:217], off
	v_lshl_add_u64 v[216:217], v[144:145], 0, s[26:27]
	s_add_i32 m0, s40, 0xe000
	s_nop 0
	global_load_lds_dwordx4 v[216:217], off
	s_waitcnt vmcnt(8)
	s_waitcnt lgkmcnt(0)
	s_barrier
	s_setprio 1
	s_waitcnt lgkmcnt(0)
	v_mfma_f32_16x16x32_bf16 v[106:109], v[150:153], v[182:185], v[106:109]
	v_mfma_f32_16x16x32_bf16 v[66:69], v[158:161], v[182:185], v[66:69]
	v_mfma_f32_16x16x32_bf16 v[114:117], v[150:153], v[192:195], v[114:117]
	v_mfma_f32_16x16x32_bf16 v[86:89], v[158:161], v[192:195], v[86:89]
	v_mfma_f32_16x16x32_bf16 v[126:129], v[150:153], v[200:203], v[126:129]
	v_mfma_f32_16x16x32_bf16 v[110:113], v[158:161], v[200:203], v[110:113]
	v_mfma_f32_16x16x32_bf16 v[122:125], v[150:153], v[208:211], v[122:125]
	v_mfma_f32_16x16x32_bf16 v[118:121], v[158:161], v[208:211], v[118:121]
	v_mfma_f32_16x16x32_bf16 v[106:109], v[154:157], v[188:191], v[106:109]
	v_mfma_f32_16x16x32_bf16 v[66:69], v[162:165], v[188:191], v[66:69]
	v_mfma_f32_16x16x32_bf16 v[114:117], v[154:157], v[196:199], v[114:117]
	v_mfma_f32_16x16x32_bf16 v[86:89], v[162:165], v[196:199], v[86:89]
	v_mfma_f32_16x16x32_bf16 v[126:129], v[154:157], v[204:207], v[126:129]
	v_mfma_f32_16x16x32_bf16 v[110:113], v[162:165], v[204:207], v[110:113]
	v_mfma_f32_16x16x32_bf16 v[122:125], v[154:157], v[212:215], v[122:125]
	v_mfma_f32_16x16x32_bf16 v[118:121], v[162:165], v[212:215], v[118:121]
	s_setprio 0
	s_setprio 1
	v_mfma_f32_16x16x32_bf16 v[42:45], v[166:169], v[182:185], v[42:45]
	v_mfma_f32_16x16x32_bf16 v[18:21], v[174:177], v[182:185], v[18:21]
	v_mfma_f32_16x16x32_bf16 v[50:53], v[166:169], v[192:195], v[50:53]
	v_mfma_f32_16x16x32_bf16 v[30:33], v[174:177], v[192:195], v[30:33]
	v_mfma_f32_16x16x32_bf16 v[74:77], v[166:169], v[200:203], v[74:77]
	v_mfma_f32_16x16x32_bf16 v[46:49], v[174:177], v[200:203], v[46:49]
	v_mfma_f32_16x16x32_bf16 v[94:97], v[166:169], v[208:211], v[94:97]
	v_mfma_f32_16x16x32_bf16 v[54:57], v[174:177], v[208:211], v[54:57]
	v_mfma_f32_16x16x32_bf16 v[42:45], v[170:173], v[188:191], v[42:45]
	v_mfma_f32_16x16x32_bf16 v[18:21], v[178:181], v[188:191], v[18:21]
	v_mfma_f32_16x16x32_bf16 v[50:53], v[170:173], v[196:199], v[50:53]
	v_mfma_f32_16x16x32_bf16 v[30:33], v[178:181], v[196:199], v[30:33]
	v_mfma_f32_16x16x32_bf16 v[74:77], v[170:173], v[204:207], v[74:77]
	v_mfma_f32_16x16x32_bf16 v[46:49], v[178:181], v[204:207], v[46:49]
	v_mfma_f32_16x16x32_bf16 v[94:97], v[170:173], v[212:215], v[94:97]
	v_mfma_f32_16x16x32_bf16 v[54:57], v[178:181], v[212:215], v[54:57]
	s_barrier
	s_setprio 0
	s_add_i32 s60, s52, s39
	v_lshl_add_u64 v[216:217], s[28:29], 0, v[130:131]
	s_mov_b32 m0, s60
	ds_read_b128 v[182:185], v149 offset:16384
	ds_read_b128 v[188:191], v149 offset:17408
	ds_read_b128 v[192:195], v149 offset:18432
	ds_read_b128 v[196:199], v149 offset:19456
	ds_read_b128 v[200:203], v149 offset:20480
	ds_read_b128 v[204:207], v149 offset:21504
	ds_read_b128 v[208:211], v149 offset:22528
	ds_read_b128 v[212:215], v149 offset:23552
	global_load_lds_dwordx4 v[216:217], off
	s_add_i32 m0, s60, 0x2000
	s_add_u32 s60, s28, 0xb0000
	v_lshl_add_u64 v[218:219], s[28:29], 0, v[132:133]
	s_addc_u32 s61, s29, 0
	s_add_i32 s62, s53, s39
	global_load_lds_dwordx4 v[218:219], off
	v_lshl_add_u64 v[220:221], s[60:61], 0, v[130:131]
	s_mov_b32 m0, s62
	v_lshl_add_u64 v[222:223], s[30:31], 0, v[132:133]
	global_load_lds_dwordx4 v[220:221], off
	v_lshl_add_u64 v[220:221], s[60:61], 0, v[132:133]
	s_add_i32 m0, s62, 0x2000
	s_nop 0
	global_load_lds_dwordx4 v[220:221], off
	v_lshl_add_u64 v[220:221], s[30:31], 0, v[130:131]
	s_mov_b32 m0, s40
	s_nop 0
	global_load_lds_dwordx4 v[220:221], off
	s_mov_b32 m0, s41
	s_nop 0
	global_load_lds_dwordx4 v[222:223], off
	s_waitcnt vmcnt(8)
	s_waitcnt lgkmcnt(0)
	s_barrier
; #define PG8_STAGE(bufoff, gbase, voff) do { _Pragma("unroll") for (int _i = 0; _i < 2; ++_i) \
;         __builtin_amdgcn_global_load_lds((const unsigned*)((const char*)(gbase) + (voff)[_i]), (PG8_LAS unsigned*)(lds + (bufoff) + ldsw + _i * 8192), 16, 0, 0); } while (0)
; #define PG8_LDA(dst, b, h) do { _Pragma("unroll") for (int m = 0; m < 4; ++m) _Pragma("unroll") for (int k = 0; k < 2; ++k) dst[m][k] = *(const PG8_LAS bf16x8*)(lds + PG8_SA(b, h) + aoff + m * 2048 + k * 1024); } while (0)
; #define PG8_LDB(dst, b, h) do { _Pragma("unroll") for (int n = 0; n < 2; ++n) _Pragma("unroll") for (int k = 0; k < 2; ++k) dst[n][k] = *(const PG8_LAS bf16x8*)(lds + PG8_SB(b, h) + boff + n * 2048 + k * 1024); } while (0)
; #define PG8_MMA(ai, bj, At, Bt) do { __builtin_amdgcn_s_setprio(1); _Pragma("unroll") for (int m = 0; m < 4; ++m) _Pragma("unroll") for (int n = 0; n < 2; ++n) _Pragma("unroll") for (int k = 0; k < 2; ++k) \
;         acc[ai][bj][m][n] = __builtin_amdgcn_mfma_f32_16x16x32_bf16(Bt[n][k], At[m][k], acc[ai][bj][m][n], 0, 0, 0); __builtin_amdgcn_s_setprio(0); } while (0)
; #define PG8_WAIT_V(n) asm volatile("s_waitcnt vmcnt(" #n ")" ::: "memory")
; #define PG8_WAIT_L(n) asm volatile("s_waitcnt lgkmcnt(" #n ")" ::: "memory")
; #define PG8_BAR __builtin_amdgcn_s_barrier()
; #define PG8_SCHED __builtin_amdgcn_sched_barrier(0)
; template <class Epi, class Sched, bool ALIGN_EPI = false, bool SP2 = false>
; __device__ __forceinline__ void gemm_phase(PG8_LAS unsigned char* lds, const Gemm g, const Sched& S, const Epi& E) {
;     ...
;             PG8_WAIT_V(8); PG8_WAIT_L(0); PG8_BAR; PG8_MMA(1, 0, At, B0); PG8_MMA(1, 1, At, B1); PG8_BAR; PG8_SCHED;
;             PG8_LDB(B0, 1, 0); PG8_LDB(B1, 1, 1); PG8_SCHED; PG8_LDA(At, 1, 0); PG8_STAGE(PG8_SA(0, 1), a2 + hstep, voffA);
;             PG8_WAIT_V(8); PG8_WAIT_L(0); PG8_BAR; PG8_MMA(0, 0, At, B0); PG8_MMA(0, 1, At, B1); PG8_BAR; PG8_SCHED;
	s_setprio 1
	s_waitcnt lgkmcnt(0)
	v_mfma_f32_16x16x32_bf16 v[102:105], v[150:153], v[182:185], v[102:105]
	v_mfma_f32_16x16x32_bf16 v[98:101], v[158:161], v[182:185], v[98:101]
	v_mfma_f32_16x16x32_bf16 v[78:81], v[150:153], v[192:195], v[78:81]
	v_mfma_f32_16x16x32_bf16 v[70:73], v[158:161], v[192:195], v[70:73]
	v_mfma_f32_16x16x32_bf16 v[38:41], v[150:153], v[200:203], v[38:41]
	v_mfma_f32_16x16x32_bf16 v[34:37], v[158:161], v[200:203], v[34:37]
	v_mfma_f32_16x16x32_bf16 v[14:17], v[150:153], v[208:211], v[14:17]
	v_mfma_f32_16x16x32_bf16 v[10:13], v[158:161], v[208:211], v[10:13]
	v_mfma_f32_16x16x32_bf16 v[102:105], v[154:157], v[188:191], v[102:105]
	v_mfma_f32_16x16x32_bf16 v[98:101], v[162:165], v[188:191], v[98:101]
	v_mfma_f32_16x16x32_bf16 v[78:81], v[154:157], v[196:199], v[78:81]
	v_mfma_f32_16x16x32_bf16 v[70:73], v[162:165], v[196:199], v[70:73]
	v_mfma_f32_16x16x32_bf16 v[38:41], v[154:157], v[204:207], v[38:41]
	v_mfma_f32_16x16x32_bf16 v[34:37], v[162:165], v[204:207], v[34:37]
	v_mfma_f32_16x16x32_bf16 v[14:17], v[154:157], v[212:215], v[14:17]
	v_mfma_f32_16x16x32_bf16 v[10:13], v[162:165], v[212:215], v[10:13]
	s_setprio 0
	s_setprio 1
	v_mfma_f32_16x16x32_bf16 v[90:93], v[166:169], v[182:185], v[90:93]
	v_mfma_f32_16x16x32_bf16 v[82:85], v[174:177], v[182:185], v[82:85]
	v_mfma_f32_16x16x32_bf16 v[62:65], v[166:169], v[192:195], v[62:65]
	v_mfma_f32_16x16x32_bf16 v[58:61], v[174:177], v[192:195], v[58:61]
	v_mfma_f32_16x16x32_bf16 v[26:29], v[166:169], v[200:203], v[26:29]
	v_mfma_f32_16x16x32_bf16 v[22:25], v[174:177], v[200:203], v[22:25]
	v_mfma_f32_16x16x32_bf16 v[6:9], v[166:169], v[208:211], v[6:9]
	v_mfma_f32_16x16x32_bf16 v[2:5], v[174:177], v[208:211], v[2:5]
	v_mfma_f32_16x16x32_bf16 v[90:93], v[170:173], v[188:191], v[90:93]
	v_mfma_f32_16x16x32_bf16 v[82:85], v[178:181], v[188:191], v[82:85]
	v_mfma_f32_16x16x32_bf16 v[62:65], v[170:173], v[196:199], v[62:65]
	v_mfma_f32_16x16x32_bf16 v[58:61], v[178:181], v[196:199], v[58:61]
	v_mfma_f32_16x16x32_bf16 v[26:29], v[170:173], v[204:207], v[26:29]
	v_mfma_f32_16x16x32_bf16 v[22:25], v[178:181], v[204:207], v[22:25]
	v_mfma_f32_16x16x32_bf16 v[6:9], v[170:173], v[212:215], v[6:9]
	v_mfma_f32_16x16x32_bf16 v[2:5], v[178:181], v[212:215], v[2:5]
	s_barrier
	s_setprio 0
	s_add_i32 s60, 0, 0x18000
	s_add_i32 s61, 0, 0x1c000
	v_add_u32_e32 v162, s60, v148
	v_add_u32_e32 v178, s61, v148
	ds_read_b128 v[150:153], v162
	ds_read_b128 v[154:157], v162 offset:1024
	ds_read_b128 v[158:161], v162 offset:2048
	ds_read_b128 v[162:165], v162 offset:3072
	ds_read_b128 v[166:169], v178
	ds_read_b128 v[170:173], v178 offset:1024
	ds_read_b128 v[174:177], v178 offset:2048
	ds_read_b128 v[178:181], v178 offset:3072
	s_add_u32 s30, s30, 0xb0000
	s_addc_u32 s31, s31, 0
	s_mov_b32 m0, s42
	v_lshl_add_u64 v[224:225], s[30:31], 0, v[130:131]
	ds_read_b128 v[182:185], v149 offset:32768
	ds_read_b128 v[188:191], v149 offset:33792
	ds_read_b128 v[192:195], v149 offset:34816
	ds_read_b128 v[196:199], v149 offset:35840
	ds_read_b128 v[200:203], v149 offset:36864
	ds_read_b128 v[204:207], v149 offset:37888
	ds_read_b128 v[208:211], v149 offset:38912
	ds_read_b128 v[212:215], v149 offset:39936
	global_load_lds_dwordx4 v[224:225], off
	v_lshl_add_u64 v[224:225], s[30:31], 0, v[132:133]
	s_mov_b32 m0, s43
	s_nop 0
	global_load_lds_dwordx4 v[224:225], off
	s_waitcnt vmcnt(8)
	s_waitcnt lgkmcnt(0)
	s_barrier
	s_setprio 1
	s_waitcnt lgkmcnt(0)
	v_mfma_f32_16x16x32_bf16 v[106:109], v[150:153], v[182:185], v[106:109]
	v_mfma_f32_16x16x32_bf16 v[66:69], v[158:161], v[182:185], v[66:69]
	v_mfma_f32_16x16x32_bf16 v[114:117], v[150:153], v[192:195], v[114:117]
	v_mfma_f32_16x16x32_bf16 v[86:89], v[158:161], v[192:195], v[86:89]
	v_mfma_f32_16x16x32_bf16 v[126:129], v[150:153], v[200:203], v[126:129]
	v_mfma_f32_16x16x32_bf16 v[110:113], v[158:161], v[200:203], v[110:113]
	v_mfma_f32_16x16x32_bf16 v[122:125], v[150:153], v[208:211], v[122:125]
	v_mfma_f32_16x16x32_bf16 v[118:121], v[158:161], v[208:211], v[118:121]
	v_mfma_f32_16x16x32_bf16 v[106:109], v[154:157], v[188:191], v[106:109]
	v_mfma_f32_16x16x32_bf16 v[66:69], v[162:165], v[188:191], v[66:69]
	v_mfma_f32_16x16x32_bf16 v[114:117], v[154:157], v[196:199], v[114:117]
	v_mfma_f32_16x16x32_bf16 v[86:89], v[162:165], v[196:199], v[86:89]
	v_mfma_f32_16x16x32_bf16 v[126:129], v[154:157], v[204:207], v[126:129]
	v_mfma_f32_16x16x32_bf16 v[110:113], v[162:165], v[204:207], v[110:113]
	v_mfma_f32_16x16x32_bf16 v[122:125], v[154:157], v[212:215], v[122:125]
	v_mfma_f32_16x16x32_bf16 v[118:121], v[162:165], v[212:215], v[118:121]
	s_setprio 0
	s_setprio 1
	v_mfma_f32_16x16x32_bf16 v[42:45], v[166:169], v[182:185], v[42:45]
	v_mfma_f32_16x16x32_bf16 v[18:21], v[174:177], v[182:185], v[18:21]
	v_mfma_f32_16x16x32_bf16 v[50:53], v[166:169], v[192:195], v[50:53]
	v_mfma_f32_16x16x32_bf16 v[30:33], v[174:177], v[192:195], v[30:33]
	v_mfma_f32_16x16x32_bf16 v[74:77], v[166:169], v[200:203], v[74:77]
	v_mfma_f32_16x16x32_bf16 v[46:49], v[174:177], v[200:203], v[46:49]
	v_mfma_f32_16x16x32_bf16 v[94:97], v[166:169], v[208:211], v[94:97]
	v_mfma_f32_16x16x32_bf16 v[54:57], v[174:177], v[208:211], v[54:57]
	v_mfma_f32_16x16x32_bf16 v[42:45], v[170:173], v[188:191], v[42:45]
	v_mfma_f32_16x16x32_bf16 v[18:21], v[178:181], v[188:191], v[18:21]
	v_mfma_f32_16x16x32_bf16 v[50:53], v[170:173], v[196:199], v[50:53]
	v_mfma_f32_16x16x32_bf16 v[30:33], v[178:181], v[196:199], v[30:33]
	v_mfma_f32_16x16x32_bf16 v[74:77], v[170:173], v[204:207], v[74:77]
	v_mfma_f32_16x16x32_bf16 v[46:49], v[178:181], v[204:207], v[46:49]
	v_mfma_f32_16x16x32_bf16 v[94:97], v[170:173], v[212:215], v[94:97]
	v_mfma_f32_16x16x32_bf16 v[54:57], v[178:181], v[212:215], v[54:57]
	s_barrier
; #define PG8_STAGE(bufoff, gbase, voff) do { _Pragma("unroll") for (int _i = 0; _i < 2; ++_i) \
;         __builtin_amdgcn_global_load_lds((const unsigned*)((const char*)(gbase) + (voff)[_i]), (PG8_LAS unsigned*)(lds + (bufoff) + ldsw + _i * 8192), 16, 0, 0); } while (0)
; #define PG8_LDA(dst, b, h) do { _Pragma("unroll") for (int m = 0; m < 4; ++m) _Pragma("unroll") for (int k = 0; k < 2; ++k) dst[m][k] = *(const PG8_LAS bf16x8*)(lds + PG8_SA(b, h) + aoff + m * 2048 + k * 1024); } while (0)
; #define PG8_MMA(ai, bj, At, Bt) do { __builtin_amdgcn_s_setprio(1); _Pragma("unroll") for (int m = 0; m < 4; ++m) _Pragma("unroll") for (int n = 0; n < 2; ++n) _Pragma("unroll") for (int k = 0; k < 2; ++k) \
;         acc[ai][bj][m][n] = __builtin_amdgcn_mfma_f32_16x16x32_bf16(Bt[n][k], At[m][k], acc[ai][bj][m][n], 0, 0, 0); __builtin_amdgcn_s_setprio(0); } while (0)
; #define PG8_WAIT_V(n) asm volatile("s_waitcnt vmcnt(" #n ")" ::: "memory")
; #define PG8_WAIT_L(n) asm volatile("s_waitcnt lgkmcnt(" #n ")" ::: "memory")
; #define PG8_BAR __builtin_amdgcn_s_barrier()
; #define PG8_SCHED __builtin_amdgcn_sched_barrier(0)
; template <class Epi, class Sched, bool ALIGN_EPI = false, bool SP2 = false>
; __device__ __forceinline__ void gemm_phase(PG8_LAS unsigned char* lds, const Gemm g, const Sched& S, const Epi& E) {
;     ...
;             PG8_LDA(At, 1, 1); PG8_STAGE(PG8_SB(1, 0), b3, voffB); PG8_STAGE(PG8_SB(1, 1), b3 + hstep, voffB); PG8_STAGE(PG8_SA(1, 0), a3, voffA);
;             PG8_WAIT_V(8); PG8_WAIT_L(0); PG8_BAR; PG8_MMA(1, 0, At, B0); PG8_MMA(1, 1, At, B1); PG8_BAR; PG8_SCHED;
;     ...
; #pragma unroll
;         for (int a = 0; a < 2; ++a)
; #pragma unroll
;             for (int b = 0; b < 2; ++b)
; #pragma unroll
;                 for (int m = 0; m < 4; ++m)
; #pragma unroll
;                     for (int n = 0; n < 2; ++n) acc[a][b][m][n] = (f32x4){0.f, 0.f, 0.f, 0.f};
;         cur = nxt; cA = nA; cB = nB; ++ui;
	s_setprio 0
	s_add_i32 s30, s60, s39
	v_lshl_add_u64 v[216:217], v[216:217], 0, s[22:23]
	s_mov_b32 m0, s30
	ds_read_b128 v[182:185], v149 offset:49152
	ds_read_b128 v[188:191], v149 offset:50176
	ds_read_b128 v[192:195], v149 offset:51200
	ds_read_b128 v[196:199], v149 offset:52224
	ds_read_b128 v[200:203], v149 offset:53248
	ds_read_b128 v[204:207], v149 offset:54272
	ds_read_b128 v[208:211], v149 offset:55296
	ds_read_b128 v[212:215], v149 offset:56320
	global_load_lds_dwordx4 v[216:217], off
	s_add_i32 m0, s30, 0x2000
	s_add_u32 s28, s28, 0xb0080
	v_lshl_add_u64 v[216:217], v[218:219], 0, s[22:23]
	s_addc_u32 s29, s29, 0
	s_add_i32 s30, s61, s39
	global_load_lds_dwordx4 v[216:217], off
	v_lshl_add_u64 v[216:217], s[28:29], 0, v[130:131]
	s_mov_b32 m0, s30
	s_nop 0
	global_load_lds_dwordx4 v[216:217], off
	v_lshl_add_u64 v[216:217], s[28:29], 0, v[132:133]
	s_add_i32 m0, s30, 0x2000
	s_nop 0
	global_load_lds_dwordx4 v[216:217], off
	v_lshl_add_u64 v[216:217], v[220:221], 0, s[22:23]
	s_mov_b32 m0, s50
	s_nop 0
	global_load_lds_dwordx4 v[216:217], off
	v_lshl_add_u64 v[216:217], v[222:223], 0, s[22:23]
	s_mov_b32 m0, s51
	s_nop 0
	global_load_lds_dwordx4 v[216:217], off
	s_waitcnt vmcnt(8)
	s_waitcnt lgkmcnt(0)
	s_barrier
	s_setprio 1
	s_waitcnt lgkmcnt(0)
	v_mfma_f32_16x16x32_bf16 v[102:105], v[150:153], v[182:185], v[102:105]
	v_mfma_f32_16x16x32_bf16 v[98:101], v[158:161], v[182:185], v[98:101]
	v_mfma_f32_16x16x32_bf16 v[78:81], v[150:153], v[192:195], v[78:81]
	v_mfma_f32_16x16x32_bf16 v[70:73], v[158:161], v[192:195], v[70:73]
	v_mfma_f32_16x16x32_bf16 v[38:41], v[150:153], v[200:203], v[38:41]
	v_mfma_f32_16x16x32_bf16 v[34:37], v[158:161], v[200:203], v[34:37]
	v_mfma_f32_16x16x32_bf16 v[14:17], v[150:153], v[208:211], v[14:17]
	v_mfma_f32_16x16x32_bf16 v[10:13], v[158:161], v[208:211], v[10:13]
	v_mfma_f32_16x16x32_bf16 v[102:105], v[154:157], v[188:191], v[102:105]
	v_mfma_f32_16x16x32_bf16 v[98:101], v[162:165], v[188:191], v[98:101]
	v_mfma_f32_16x16x32_bf16 v[78:81], v[154:157], v[196:199], v[78:81]
	v_mfma_f32_16x16x32_bf16 v[70:73], v[162:165], v[196:199], v[70:73]
	v_mfma_f32_16x16x32_bf16 v[38:41], v[154:157], v[204:207], v[38:41]
	v_mfma_f32_16x16x32_bf16 v[34:37], v[162:165], v[204:207], v[34:37]
	v_mfma_f32_16x16x32_bf16 v[14:17], v[154:157], v[212:215], v[14:17]
	v_mfma_f32_16x16x32_bf16 v[10:13], v[162:165], v[212:215], v[10:13]
	s_setprio 0
	s_setprio 1
	v_mfma_f32_16x16x32_bf16 v[90:93], v[166:169], v[182:185], v[90:93]
	v_mfma_f32_16x16x32_bf16 v[82:85], v[174:177], v[182:185], v[82:85]
	v_mfma_f32_16x16x32_bf16 v[62:65], v[166:169], v[192:195], v[62:65]
	v_mfma_f32_16x16x32_bf16 v[58:61], v[174:177], v[192:195], v[58:61]
	v_mfma_f32_16x16x32_bf16 v[26:29], v[166:169], v[200:203], v[26:29]
	v_mfma_f32_16x16x32_bf16 v[22:25], v[174:177], v[200:203], v[22:25]
	v_mfma_f32_16x16x32_bf16 v[6:9], v[166:169], v[208:211], v[6:9]
	v_mfma_f32_16x16x32_bf16 v[2:5], v[174:177], v[208:211], v[2:5]
	v_mfma_f32_16x16x32_bf16 v[90:93], v[170:173], v[188:191], v[90:93]
	v_mfma_f32_16x16x32_bf16 v[82:85], v[178:181], v[188:191], v[82:85]
	v_mfma_f32_16x16x32_bf16 v[62:65], v[170:173], v[196:199], v[62:65]
	v_mfma_f32_16x16x32_bf16 v[58:61], v[178:181], v[196:199], v[58:61]
	v_mfma_f32_16x16x32_bf16 v[26:29], v[170:173], v[204:207], v[26:29]
	v_mfma_f32_16x16x32_bf16 v[22:25], v[178:181], v[204:207], v[22:25]
	v_mfma_f32_16x16x32_bf16 v[6:9], v[170:173], v[212:215], v[6:9]
	v_mfma_f32_16x16x32_bf16 v[2:5], v[178:181], v[212:215], v[2:5]
	s_barrier
	s_setprio 0
	s_add_i32 s59, s59, 2
	s_add_u32 s26, s26, 0x100
	s_addc_u32 s27, s27, 0
	s_cmp_gt_u32 s59, 41
	s_cbranch_scc0 .LBB0_252
	s_add_u32 s26, s57, 0xffffff00
	s_addc_u32 s27, s58, -1
	s_and_b64 vcc, exec, s[6:7]
	s_cbranch_vccnz .LBB0_255
	v_mov_b32_e32 v2, 0
	s_mov_b32 s18, s54
	s_mov_b32 s35, s55
	s_mov_b64 s[20:21], s[24:25]
	s_mov_b32 s49, s56
	v_mov_b32_e32 v3, v2
	v_mov_b32_e32 v4, v2
	v_mov_b32_e32 v5, v2
	v_mov_b32_e32 v6, v2
	v_mov_b32_e32 v7, v2
	v_mov_b32_e32 v8, v2
	v_mov_b32_e32 v9, v2
	v_mov_b32_e32 v22, v2
	v_mov_b32_e32 v23, v2
	v_mov_b32_e32 v24, v2
	v_mov_b32_e32 v25, v2
	v_mov_b32_e32 v26, v2
	v_mov_b32_e32 v27, v2
	v_mov_b32_e32 v28, v2
	v_mov_b32_e32 v29, v2
	v_mov_b32_e32 v58, v2
	v_mov_b32_e32 v59, v2
	v_mov_b32_e32 v60, v2
	v_mov_b32_e32 v61, v2
	v_mov_b32_e32 v62, v2
	v_mov_b32_e32 v63, v2
	v_mov_b32_e32 v64, v2
	v_mov_b32_e32 v65, v2
	v_mov_b32_e32 v82, v2
	v_mov_b32_e32 v83, v2
	v_mov_b32_e32 v84, v2
	v_mov_b32_e32 v85, v2
	v_mov_b32_e32 v90, v2
	v_mov_b32_e32 v91, v2
	v_mov_b32_e32 v92, v2
	v_mov_b32_e32 v93, v2
	v_mov_b32_e32 v10, v2
	v_mov_b32_e32 v11, v2
	v_mov_b32_e32 v12, v2
	v_mov_b32_e32 v13, v2
	v_mov_b32_e32 v14, v2
	v_mov_b32_e32 v15, v2
	v_mov_b32_e32 v16, v2
	v_mov_b32_e32 v17, v2
	v_mov_b32_e32 v34, v2
	v_mov_b32_e32 v35, v2
	v_mov_b32_e32 v36, v2
	v_mov_b32_e32 v37, v2
	v_mov_b32_e32 v38, v2
	v_mov_b32_e32 v39, v2
	v_mov_b32_e32 v40, v2
	v_mov_b32_e32 v41, v2
	v_mov_b32_e32 v70, v2
	v_mov_b32_e32 v71, v2
	v_mov_b32_e32 v72, v2
	v_mov_b32_e32 v73, v2
	v_mov_b32_e32 v78, v2
	v_mov_b32_e32 v79, v2
	v_mov_b32_e32 v80, v2
	v_mov_b32_e32 v81, v2
	v_mov_b32_e32 v98, v2
	v_mov_b32_e32 v99, v2
	v_mov_b32_e32 v100, v2
	v_mov_b32_e32 v101, v2
	v_mov_b32_e32 v102, v2
	v_mov_b32_e32 v103, v2
	v_mov_b32_e32 v104, v2
	v_mov_b32_e32 v105, v2
	v_mov_b32_e32 v54, v2
	v_mov_b32_e32 v55, v2
	v_mov_b32_e32 v56, v2
	v_mov_b32_e32 v57, v2
	v_mov_b32_e32 v94, v2
	v_mov_b32_e32 v95, v2
	v_mov_b32_e32 v96, v2
	v_mov_b32_e32 v97, v2
	v_mov_b32_e32 v46, v2
	v_mov_b32_e32 v47, v2
	v_mov_b32_e32 v48, v2
	v_mov_b32_e32 v49, v2
	v_mov_b32_e32 v74, v2
	v_mov_b32_e32 v75, v2
	v_mov_b32_e32 v76, v2
	v_mov_b32_e32 v77, v2
	v_mov_b32_e32 v30, v2
	v_mov_b32_e32 v31, v2
	v_mov_b32_e32 v32, v2
	v_mov_b32_e32 v33, v2
	v_mov_b32_e32 v50, v2
	v_mov_b32_e32 v51, v2
	v_mov_b32_e32 v52, v2
	v_mov_b32_e32 v53, v2
	v_mov_b32_e32 v18, v2
	v_mov_b32_e32 v19, v2
	v_mov_b32_e32 v20, v2
	v_mov_b32_e32 v21, v2
	v_mov_b32_e32 v42, v2
	v_mov_b32_e32 v43, v2
	v_mov_b32_e32 v44, v2
	v_mov_b32_e32 v45, v2
	v_mov_b32_e32 v118, v2
	v_mov_b32_e32 v119, v2
	v_mov_b32_e32 v120, v2
	v_mov_b32_e32 v121, v2
	v_mov_b32_e32 v122, v2
	v_mov_b32_e32 v123, v2
	v_mov_b32_e32 v124, v2
	v_mov_b32_e32 v125, v2
	v_mov_b32_e32 v110, v2
	v_mov_b32_e32 v111, v2
	v_mov_b32_e32 v112, v2
	v_mov_b32_e32 v113, v2
	v_mov_b32_e32 v126, v2
	v_mov_b32_e32 v127, v2
	v_mov_b32_e32 v128, v2
	v_mov_b32_e32 v129, v2
	v_mov_b32_e32 v86, v2
	v_mov_b32_e32 v87, v2
	v_mov_b32_e32 v88, v2
	v_mov_b32_e32 v89, v2
	v_mov_b32_e32 v114, v2
	v_mov_b32_e32 v115, v2
	v_mov_b32_e32 v116, v2
	v_mov_b32_e32 v117, v2
	v_mov_b32_e32 v66, v2
	v_mov_b32_e32 v67, v2
	v_mov_b32_e32 v68, v2
	v_mov_b32_e32 v69, v2
	v_mov_b32_e32 v106, v2
	v_mov_b32_e32 v107, v2
	v_mov_b32_e32 v108, v2
	v_mov_b32_e32 v109, v2
	s_andn2_b64 vcc, exec, s[4:5]
	s_cbranch_vccnz .LBB0_256
	s_branch .LBB0_257

; #define PG8_STAGE(bufoff, gbase, voff) do { _Pragma("unroll") for (int _i = 0; _i < 2; ++_i) \
;         __builtin_amdgcn_global_load_lds((const unsigned*)((const char*)(gbase) + (voff)[_i]), (PG8_LAS unsigned*)(lds + (bufoff) + ldsw + _i * 8192), 16, 0, 0); } while (0)
; #define PG8_LDA(dst, b, h) do { _Pragma("unroll") for (int m = 0; m < 4; ++m) _Pragma("unroll") for (int k = 0; k < 2; ++k) dst[m][k] = *(const PG8_LAS bf16x8*)(lds + PG8_SA(b, h) + aoff + m * 2048 + k * 1024); } while (0)
; #define PG8_LDB(dst, b, h) do { _Pragma("unroll") for (int n = 0; n < 2; ++n) _Pragma("unroll") for (int k = 0; k < 2; ++k) dst[n][k] = *(const PG8_LAS bf16x8*)(lds + PG8_SB(b, h) + boff + n * 2048 + k * 1024); } while (0)
; #define PG8_MMA(ai, bj, At, Bt) do { __builtin_amdgcn_s_setprio(1); _Pragma("unroll") for (int m = 0; m < 4; ++m) _Pragma("unroll") for (int n = 0; n < 2; ++n) _Pragma("unroll") for (int k = 0; k < 2; ++k) \
;         acc[ai][bj][m][n] = __builtin_amdgcn_mfma_f32_16x16x32_bf16(Bt[n][k], At[m][k], acc[ai][bj][m][n], 0, 0, 0); __builtin_amdgcn_s_setprio(0); } while (0)
; #define PG8_WAIT_V(n) asm volatile("s_waitcnt vmcnt(" #n ")" ::: "memory")
; #define PG8_WAIT_L(n) asm volatile("s_waitcnt lgkmcnt(" #n ")" ::: "memory")
; #define PG8_BAR __builtin_amdgcn_s_barrier()
; #define PG8_SCHED __builtin_amdgcn_sched_barrier(0)
; template <class Epi, class Sched, bool ALIGN_EPI = false, bool SP2 = false>
; __device__ __forceinline__ void gemm_phase(PG8_LAS unsigned char* lds, const Gemm g, const Sched& S, const Epi& E) {
;     ...
;             const bool last = (t == nt - 2);
;             const char* a1 = cA + (size_t)(t + 1) * kstep;
;             const char* a2 = last ? nA : cA + (size_t)(t + 2) * kstep; const char* b2 = last ? nB : cB + (size_t)(t + 2) * kstep;
;             const char* a3 = a2 + kstep; const char* b3 = b2 + kstep;
;             if (last && has_next) S.a_ready(nxt);
;             if constexpr (SP2) {
;             PG8_LDB(B0, 0, 0); PG8_LDB(B1, 0, 1); PG8_SCHED; PG8_LDA(At, 0, 0); PG8_STAGE(PG8_SA(1, 1), a1 + hstep, voffA);
;             PG8_WAIT_V(8); PG8_WAIT_L(0); PG8_BAR; PG8_MMA(0, 0, At, B0); PG8_MMA(0, 1, At, B1); PG8_BAR; PG8_SCHED;
;             PG8_LDA(At, 0, 1); PG8_STAGE(PG8_SB(0, 0), b2, voffB); PG8_STAGE(PG8_SB(0, 1), b2 + hstep, voffB); PG8_STAGE(PG8_SA(0, 0), a2, voffA);
.LBB0_319:
	v_add_u32_e32 v162, s52, v148
	v_add_u32_e32 v178, s53, v148
	s_add_u32 s26, s18, s24
	ds_read_b128 v[150:153], v162
	ds_read_b128 v[154:157], v162 offset:1024
	ds_read_b128 v[158:161], v162 offset:2048
	ds_read_b128 v[162:165], v162 offset:3072
	ds_read_b128 v[166:169], v178
	ds_read_b128 v[170:173], v178 offset:1024
	ds_read_b128 v[174:177], v178 offset:2048
	ds_read_b128 v[178:181], v178 offset:3072
	s_addc_u32 s27, s19, s25
	s_add_u32 s26, s26, 0x100
	s_addc_u32 s27, s27, 0
	s_add_u32 s60, s57, s24
	s_addc_u32 s61, s58, s25
	s_cmpk_eq_i32 s24, 0x1500
	s_cselect_b32 s29, s23, s27
	s_cselect_b32 s28, s22, s26
	s_cselect_b32 s27, s9, s61
	s_cselect_b32 s26, s8, s60
	v_lshl_add_u64 v[216:217], v[142:143], 0, s[24:25]
	s_add_i32 m0, s40, 0xc000
	ds_read_b128 v[182:185], v149
	ds_read_b128 v[188:191], v149 offset:1024
	ds_read_b128 v[192:195], v149 offset:2048
	ds_read_b128 v[196:199], v149 offset:3072
	ds_read_b128 v[200:203], v149 offset:4096
	ds_read_b128 v[204:207], v149 offset:5120
	ds_read_b128 v[208:211], v149 offset:6144
	ds_read_b128 v[212:215], v149 offset:7168
	global_load_lds_dwordx4 v[216:217], off
	v_lshl_add_u64 v[216:217], v[144:145], 0, s[24:25]
	s_add_i32 m0, s40, 0xe000
	s_nop 0
	global_load_lds_dwordx4 v[216:217], off
	s_waitcnt vmcnt(8)
	s_waitcnt lgkmcnt(0)
	s_barrier
	s_setprio 1
	s_waitcnt lgkmcnt(0)
	v_mfma_f32_16x16x32_bf16 v[106:109], v[150:153], v[182:185], v[106:109]
	v_mfma_f32_16x16x32_bf16 v[66:69], v[158:161], v[182:185], v[66:69]
	v_mfma_f32_16x16x32_bf16 v[114:117], v[150:153], v[192:195], v[114:117]
	v_mfma_f32_16x16x32_bf16 v[86:89], v[158:161], v[192:195], v[86:89]
	v_mfma_f32_16x16x32_bf16 v[126:129], v[150:153], v[200:203], v[126:129]
	v_mfma_f32_16x16x32_bf16 v[110:113], v[158:161], v[200:203], v[110:113]
	v_mfma_f32_16x16x32_bf16 v[122:125], v[150:153], v[208:211], v[122:125]
	v_mfma_f32_16x16x32_bf16 v[118:121], v[158:161], v[208:211], v[118:121]
	v_mfma_f32_16x16x32_bf16 v[106:109], v[154:157], v[188:191], v[106:109]
	v_mfma_f32_16x16x32_bf16 v[66:69], v[162:165], v[188:191], v[66:69]
	v_mfma_f32_16x16x32_bf16 v[114:117], v[154:157], v[196:199], v[114:117]
	v_mfma_f32_16x16x32_bf16 v[86:89], v[162:165], v[196:199], v[86:89]
	v_mfma_f32_16x16x32_bf16 v[126:129], v[154:157], v[204:207], v[126:129]
	v_mfma_f32_16x16x32_bf16 v[110:113], v[162:165], v[204:207], v[110:113]
	v_mfma_f32_16x16x32_bf16 v[122:125], v[154:157], v[212:215], v[122:125]
	v_mfma_f32_16x16x32_bf16 v[118:121], v[162:165], v[212:215], v[118:121]
	s_setprio 0
	s_setprio 1
	v_mfma_f32_16x16x32_bf16 v[42:45], v[166:169], v[182:185], v[42:45]
	v_mfma_f32_16x16x32_bf16 v[18:21], v[174:177], v[182:185], v[18:21]
	v_mfma_f32_16x16x32_bf16 v[50:53], v[166:169], v[192:195], v[50:53]
	v_mfma_f32_16x16x32_bf16 v[30:33], v[174:177], v[192:195], v[30:33]
	v_mfma_f32_16x16x32_bf16 v[70:73], v[166:169], v[200:203], v[70:73]
	v_mfma_f32_16x16x32_bf16 v[46:49], v[174:177], v[200:203], v[46:49]
	v_mfma_f32_16x16x32_bf16 v[94:97], v[166:169], v[208:211], v[94:97]
	v_mfma_f32_16x16x32_bf16 v[54:57], v[174:177], v[208:211], v[54:57]
	v_mfma_f32_16x16x32_bf16 v[42:45], v[170:173], v[188:191], v[42:45]
	v_mfma_f32_16x16x32_bf16 v[18:21], v[178:181], v[188:191], v[18:21]
	v_mfma_f32_16x16x32_bf16 v[50:53], v[170:173], v[196:199], v[50:53]
	v_mfma_f32_16x16x32_bf16 v[30:33], v[178:181], v[196:199], v[30:33]
	v_mfma_f32_16x16x32_bf16 v[70:73], v[170:173], v[204:207], v[70:73]
	v_mfma_f32_16x16x32_bf16 v[46:49], v[178:181], v[204:207], v[46:49]
	v_mfma_f32_16x16x32_bf16 v[94:97], v[170:173], v[212:215], v[94:97]
	v_mfma_f32_16x16x32_bf16 v[54:57], v[178:181], v[212:215], v[54:57]
	s_barrier
	s_setprio 0
	s_add_i32 s60, s52, s39
	v_lshl_add_u64 v[216:217], s[26:27], 0, v[130:131]
	s_mov_b32 m0, s60
	ds_read_b128 v[182:185], v149 offset:16384
	ds_read_b128 v[188:191], v149 offset:17408
	ds_read_b128 v[192:195], v149 offset:18432
	ds_read_b128 v[196:199], v149 offset:19456
	ds_read_b128 v[200:203], v149 offset:20480
	ds_read_b128 v[204:207], v149 offset:21504
	ds_read_b128 v[208:211], v149 offset:22528
	ds_read_b128 v[212:215], v149 offset:23552
	global_load_lds_dwordx4 v[216:217], off
	s_add_i32 m0, s60, 0x2000
	s_add_u32 s60, s26, 0xb0000
	v_lshl_add_u64 v[218:219], s[26:27], 0, v[132:133]
	s_addc_u32 s61, s27, 0
	s_add_i32 s62, s53, s39
	global_load_lds_dwordx4 v[218:219], off
	v_lshl_add_u64 v[220:221], s[60:61], 0, v[130:131]
	s_mov_b32 m0, s62
	v_lshl_add_u64 v[222:223], s[28:29], 0, v[132:133]
	global_load_lds_dwordx4 v[220:221], off
	v_lshl_add_u64 v[220:221], s[60:61], 0, v[132:133]
	s_add_i32 m0, s62, 0x2000
	s_nop 0
	global_load_lds_dwordx4 v[220:221], off
	v_lshl_add_u64 v[220:221], s[28:29], 0, v[130:131]
	s_mov_b32 m0, s40
	s_nop 0
	global_load_lds_dwordx4 v[220:221], off
	s_mov_b32 m0, s41
	s_nop 0
	global_load_lds_dwordx4 v[222:223], off
	s_waitcnt vmcnt(8)
	s_waitcnt lgkmcnt(0)
	s_barrier
; #define PG8_STAGE(bufoff, gbase, voff) do { _Pragma("unroll") for (int _i = 0; _i < 2; ++_i) \
;         __builtin_amdgcn_global_load_lds((const unsigned*)((const char*)(gbase) + (voff)[_i]), (PG8_LAS unsigned*)(lds + (bufoff) + ldsw + _i * 8192), 16, 0, 0); } while (0)
; #define PG8_LDA(dst, b, h) do { _Pragma("unroll") for (int m = 0; m < 4; ++m) _Pragma("unroll") for (int k = 0; k < 2; ++k) dst[m][k] = *(const PG8_LAS bf16x8*)(lds + PG8_SA(b, h) + aoff + m * 2048 + k * 1024); } while (0)
; #define PG8_LDB(dst, b, h) do { _Pragma("unroll") for (int n = 0; n < 2; ++n) _Pragma("unroll") for (int k = 0; k < 2; ++k) dst[n][k] = *(const PG8_LAS bf16x8*)(lds + PG8_SB(b, h) + boff + n * 2048 + k * 1024); } while (0)
; #define PG8_MMA(ai, bj, At, Bt) do { __builtin_amdgcn_s_setprio(1); _Pragma("unroll") for (int m = 0; m < 4; ++m) _Pragma("unroll") for (int n = 0; n < 2; ++n) _Pragma("unroll") for (int k = 0; k < 2; ++k) \
;         acc[ai][bj][m][n] = __builtin_amdgcn_mfma_f32_16x16x32_bf16(Bt[n][k], At[m][k], acc[ai][bj][m][n], 0, 0, 0); __builtin_amdgcn_s_setprio(0); } while (0)
; #define PG8_WAIT_V(n) asm volatile("s_waitcnt vmcnt(" #n ")" ::: "memory")
; #define PG8_WAIT_L(n) asm volatile("s_waitcnt lgkmcnt(" #n ")" ::: "memory")
; #define PG8_BAR __builtin_amdgcn_s_barrier()
; #define PG8_SCHED __builtin_amdgcn_sched_barrier(0)
; template <class Epi, class Sched, bool ALIGN_EPI = false, bool SP2 = false>
; __device__ __forceinline__ void gemm_phase(PG8_LAS unsigned char* lds, const Gemm g, const Sched& S, const Epi& E) {
;     ...
;             PG8_WAIT_V(8); PG8_WAIT_L(0); PG8_BAR; PG8_MMA(1, 0, At, B0); PG8_MMA(1, 1, At, B1); PG8_BAR; PG8_SCHED;
;             PG8_LDB(B0, 1, 0); PG8_LDB(B1, 1, 1); PG8_SCHED; PG8_LDA(At, 1, 0); PG8_STAGE(PG8_SA(0, 1), a2 + hstep, voffA);
;             PG8_WAIT_V(8); PG8_WAIT_L(0); PG8_BAR; PG8_MMA(0, 0, At, B0); PG8_MMA(0, 1, At, B1); PG8_BAR; PG8_SCHED;
	s_setprio 1
	s_waitcnt lgkmcnt(0)
	v_mfma_f32_16x16x32_bf16 v[102:105], v[150:153], v[182:185], v[102:105]
	v_mfma_f32_16x16x32_bf16 v[98:101], v[158:161], v[182:185], v[98:101]
	v_mfma_f32_16x16x32_bf16 v[78:81], v[150:153], v[192:195], v[78:81]
	v_mfma_f32_16x16x32_bf16 v[74:77], v[158:161], v[192:195], v[74:77]
	v_mfma_f32_16x16x32_bf16 v[38:41], v[150:153], v[200:203], v[38:41]
	v_mfma_f32_16x16x32_bf16 v[34:37], v[158:161], v[200:203], v[34:37]
	v_mfma_f32_16x16x32_bf16 v[14:17], v[150:153], v[208:211], v[14:17]
	v_mfma_f32_16x16x32_bf16 v[10:13], v[158:161], v[208:211], v[10:13]
	v_mfma_f32_16x16x32_bf16 v[102:105], v[154:157], v[188:191], v[102:105]
	v_mfma_f32_16x16x32_bf16 v[98:101], v[162:165], v[188:191], v[98:101]
	v_mfma_f32_16x16x32_bf16 v[78:81], v[154:157], v[196:199], v[78:81]
	v_mfma_f32_16x16x32_bf16 v[74:77], v[162:165], v[196:199], v[74:77]
	v_mfma_f32_16x16x32_bf16 v[38:41], v[154:157], v[204:207], v[38:41]
	v_mfma_f32_16x16x32_bf16 v[34:37], v[162:165], v[204:207], v[34:37]
	v_mfma_f32_16x16x32_bf16 v[14:17], v[154:157], v[212:215], v[14:17]
	v_mfma_f32_16x16x32_bf16 v[10:13], v[162:165], v[212:215], v[10:13]
	s_setprio 0
	s_setprio 1
	v_mfma_f32_16x16x32_bf16 v[90:93], v[166:169], v[182:185], v[90:93]
	v_mfma_f32_16x16x32_bf16 v[82:85], v[174:177], v[182:185], v[82:85]
	v_mfma_f32_16x16x32_bf16 v[62:65], v[166:169], v[192:195], v[62:65]
	v_mfma_f32_16x16x32_bf16 v[58:61], v[174:177], v[192:195], v[58:61]
	v_mfma_f32_16x16x32_bf16 v[26:29], v[166:169], v[200:203], v[26:29]
	v_mfma_f32_16x16x32_bf16 v[22:25], v[174:177], v[200:203], v[22:25]
	v_mfma_f32_16x16x32_bf16 v[6:9], v[166:169], v[208:211], v[6:9]
	v_mfma_f32_16x16x32_bf16 v[2:5], v[174:177], v[208:211], v[2:5]
	v_mfma_f32_16x16x32_bf16 v[90:93], v[170:173], v[188:191], v[90:93]
	v_mfma_f32_16x16x32_bf16 v[82:85], v[178:181], v[188:191], v[82:85]
	v_mfma_f32_16x16x32_bf16 v[62:65], v[170:173], v[196:199], v[62:65]
	v_mfma_f32_16x16x32_bf16 v[58:61], v[178:181], v[196:199], v[58:61]
	v_mfma_f32_16x16x32_bf16 v[26:29], v[170:173], v[204:207], v[26:29]
	v_mfma_f32_16x16x32_bf16 v[22:25], v[178:181], v[204:207], v[22:25]
	v_mfma_f32_16x16x32_bf16 v[6:9], v[170:173], v[212:215], v[6:9]
	v_mfma_f32_16x16x32_bf16 v[2:5], v[178:181], v[212:215], v[2:5]
	s_barrier
	s_setprio 0
	s_add_i32 s60, 0, 0x18000
	s_add_i32 s61, 0, 0x1c000
	v_add_u32_e32 v162, s60, v148
	v_add_u32_e32 v178, s61, v148
	ds_read_b128 v[150:153], v162
	ds_read_b128 v[154:157], v162 offset:1024
	ds_read_b128 v[158:161], v162 offset:2048
	ds_read_b128 v[162:165], v162 offset:3072
	ds_read_b128 v[166:169], v178
	ds_read_b128 v[170:173], v178 offset:1024
	ds_read_b128 v[174:177], v178 offset:2048
	ds_read_b128 v[178:181], v178 offset:3072
	s_add_u32 s28, s28, 0xb0000
	s_addc_u32 s29, s29, 0
	s_mov_b32 m0, s42
	v_lshl_add_u64 v[224:225], s[28:29], 0, v[130:131]
	ds_read_b128 v[182:185], v149 offset:32768
	ds_read_b128 v[188:191], v149 offset:33792
	ds_read_b128 v[192:195], v149 offset:34816
	ds_read_b128 v[196:199], v149 offset:35840
	ds_read_b128 v[200:203], v149 offset:36864
	ds_read_b128 v[204:207], v149 offset:37888
	ds_read_b128 v[208:211], v149 offset:38912
	ds_read_b128 v[212:215], v149 offset:39936
	global_load_lds_dwordx4 v[224:225], off
	v_lshl_add_u64 v[224:225], s[28:29], 0, v[132:133]
	s_mov_b32 m0, s43
	s_nop 0
	global_load_lds_dwordx4 v[224:225], off
	s_waitcnt vmcnt(8)
	s_waitcnt lgkmcnt(0)
	s_barrier
	s_setprio 1
	s_waitcnt lgkmcnt(0)
	v_mfma_f32_16x16x32_bf16 v[106:109], v[150:153], v[182:185], v[106:109]
	v_mfma_f32_16x16x32_bf16 v[66:69], v[158:161], v[182:185], v[66:69]
	v_mfma_f32_16x16x32_bf16 v[114:117], v[150:153], v[192:195], v[114:117]
	v_mfma_f32_16x16x32_bf16 v[86:89], v[158:161], v[192:195], v[86:89]
	v_mfma_f32_16x16x32_bf16 v[126:129], v[150:153], v[200:203], v[126:129]
	v_mfma_f32_16x16x32_bf16 v[110:113], v[158:161], v[200:203], v[110:113]
	v_mfma_f32_16x16x32_bf16 v[122:125], v[150:153], v[208:211], v[122:125]
	v_mfma_f32_16x16x32_bf16 v[118:121], v[158:161], v[208:211], v[118:121]
	v_mfma_f32_16x16x32_bf16 v[106:109], v[154:157], v[188:191], v[106:109]
	v_mfma_f32_16x16x32_bf16 v[66:69], v[162:165], v[188:191], v[66:69]
	v_mfma_f32_16x16x32_bf16 v[114:117], v[154:157], v[196:199], v[114:117]
	v_mfma_f32_16x16x32_bf16 v[86:89], v[162:165], v[196:199], v[86:89]
	v_mfma_f32_16x16x32_bf16 v[126:129], v[154:157], v[204:207], v[126:129]
	v_mfma_f32_16x16x32_bf16 v[110:113], v[162:165], v[204:207], v[110:113]
	v_mfma_f32_16x16x32_bf16 v[122:125], v[154:157], v[212:215], v[122:125]
	v_mfma_f32_16x16x32_bf16 v[118:121], v[162:165], v[212:215], v[118:121]
	s_setprio 0
	s_setprio 1
	v_mfma_f32_16x16x32_bf16 v[42:45], v[166:169], v[182:185], v[42:45]
	v_mfma_f32_16x16x32_bf16 v[18:21], v[174:177], v[182:185], v[18:21]
	v_mfma_f32_16x16x32_bf16 v[50:53], v[166:169], v[192:195], v[50:53]
	v_mfma_f32_16x16x32_bf16 v[30:33], v[174:177], v[192:195], v[30:33]
	v_mfma_f32_16x16x32_bf16 v[70:73], v[166:169], v[200:203], v[70:73]
	v_mfma_f32_16x16x32_bf16 v[46:49], v[174:177], v[200:203], v[46:49]
	v_mfma_f32_16x16x32_bf16 v[94:97], v[166:169], v[208:211], v[94:97]
	v_mfma_f32_16x16x32_bf16 v[54:57], v[174:177], v[208:211], v[54:57]
	v_mfma_f32_16x16x32_bf16 v[42:45], v[170:173], v[188:191], v[42:45]
	v_mfma_f32_16x16x32_bf16 v[18:21], v[178:181], v[188:191], v[18:21]
	v_mfma_f32_16x16x32_bf16 v[50:53], v[170:173], v[196:199], v[50:53]
	v_mfma_f32_16x16x32_bf16 v[30:33], v[178:181], v[196:199], v[30:33]
	v_mfma_f32_16x16x32_bf16 v[70:73], v[170:173], v[204:207], v[70:73]
	v_mfma_f32_16x16x32_bf16 v[46:49], v[178:181], v[204:207], v[46:49]
	v_mfma_f32_16x16x32_bf16 v[94:97], v[170:173], v[212:215], v[94:97]
	v_mfma_f32_16x16x32_bf16 v[54:57], v[178:181], v[212:215], v[54:57]
	s_barrier
; #define PG8_STAGE(bufoff, gbase, voff) do { _Pragma("unroll") for (int _i = 0; _i < 2; ++_i) \
;         __builtin_amdgcn_global_load_lds((const unsigned*)((const char*)(gbase) + (voff)[_i]), (PG8_LAS unsigned*)(lds + (bufoff) + ldsw + _i * 8192), 16, 0, 0); } while (0)
; #define PG8_LDA(dst, b, h) do { _Pragma("unroll") for (int m = 0; m < 4; ++m) _Pragma("unroll") for (int k = 0; k < 2; ++k) dst[m][k] = *(const PG8_LAS bf16x8*)(lds + PG8_SA(b, h) + aoff + m * 2048 + k * 1024); } while (0)
; #define PG8_MMA(ai, bj, At, Bt) do { __builtin_amdgcn_s_setprio(1); _Pragma("unroll") for (int m = 0; m < 4; ++m) _Pragma("unroll") for (int n = 0; n < 2; ++n) _Pragma("unroll") for (int k = 0; k < 2; ++k) \
;         acc[ai][bj][m][n] = __builtin_amdgcn_mfma_f32_16x16x32_bf16(Bt[n][k], At[m][k], acc[ai][bj][m][n], 0, 0, 0); __builtin_amdgcn_s_setprio(0); } while (0)
; #define PG8_WAIT_V(n) asm volatile("s_waitcnt vmcnt(" #n ")" ::: "memory")
; #define PG8_WAIT_L(n) asm volatile("s_waitcnt lgkmcnt(" #n ")" ::: "memory")
; #define PG8_BAR __builtin_amdgcn_s_barrier()
; #define PG8_SCHED __builtin_amdgcn_sched_barrier(0)
; template <class Epi, class Sched, bool ALIGN_EPI = false, bool SP2 = false>
; __device__ __forceinline__ void gemm_phase(PG8_LAS unsigned char* lds, const Gemm g, const Sched& S, const Epi& E) {
;     ...
;             PG8_LDA(At, 1, 1); PG8_STAGE(PG8_SB(1, 0), b3, voffB); PG8_STAGE(PG8_SB(1, 1), b3 + hstep, voffB); PG8_STAGE(PG8_SA(1, 0), a3, voffA);
;             PG8_WAIT_V(8); PG8_WAIT_L(0); PG8_BAR; PG8_MMA(1, 0, At, B0); PG8_MMA(1, 1, At, B1); PG8_BAR; PG8_SCHED;
;     ...
; #pragma unroll
;         for (int a = 0; a < 2; ++a)
; #pragma unroll
;             for (int b = 0; b < 2; ++b)
; #pragma unroll
;                 for (int m = 0; m < 4; ++m)
; #pragma unroll
;                     for (int n = 0; n < 2; ++n) acc[a][b][m][n] = (f32x4){0.f, 0.f, 0.f, 0.f};
;         cur = nxt; cA = nA; cB = nB; ++ui;
	s_setprio 0
	s_add_i32 s28, s60, s39
	v_lshl_add_u64 v[216:217], v[216:217], 0, s[20:21]
	s_mov_b32 m0, s28
	ds_read_b128 v[182:185], v149 offset:49152
	ds_read_b128 v[188:191], v149 offset:50176
	ds_read_b128 v[192:195], v149 offset:51200
	ds_read_b128 v[196:199], v149 offset:52224
	ds_read_b128 v[200:203], v149 offset:53248
	ds_read_b128 v[204:207], v149 offset:54272
	ds_read_b128 v[208:211], v149 offset:55296
	ds_read_b128 v[212:215], v149 offset:56320
	global_load_lds_dwordx4 v[216:217], off
	s_add_i32 m0, s28, 0x2000
	s_add_u32 s26, s26, 0xb0080
	v_lshl_add_u64 v[216:217], v[218:219], 0, s[20:21]
	s_addc_u32 s27, s27, 0
	s_add_i32 s28, s61, s39
	global_load_lds_dwordx4 v[216:217], off
	v_lshl_add_u64 v[216:217], s[26:27], 0, v[130:131]
	s_mov_b32 m0, s28
	s_nop 0
	global_load_lds_dwordx4 v[216:217], off
	v_lshl_add_u64 v[216:217], s[26:27], 0, v[132:133]
	s_add_i32 m0, s28, 0x2000
	s_nop 0
	global_load_lds_dwordx4 v[216:217], off
	v_lshl_add_u64 v[216:217], v[220:221], 0, s[20:21]
	s_mov_b32 m0, s50
	s_nop 0
	global_load_lds_dwordx4 v[216:217], off
	v_lshl_add_u64 v[216:217], v[222:223], 0, s[20:21]
	s_mov_b32 m0, s51
	s_nop 0
	global_load_lds_dwordx4 v[216:217], off
	s_waitcnt vmcnt(8)
	s_waitcnt lgkmcnt(0)
	s_barrier
	s_setprio 1
	s_waitcnt lgkmcnt(0)
	v_mfma_f32_16x16x32_bf16 v[102:105], v[150:153], v[182:185], v[102:105]
	v_mfma_f32_16x16x32_bf16 v[98:101], v[158:161], v[182:185], v[98:101]
	v_mfma_f32_16x16x32_bf16 v[78:81], v[150:153], v[192:195], v[78:81]
	v_mfma_f32_16x16x32_bf16 v[74:77], v[158:161], v[192:195], v[74:77]
	v_mfma_f32_16x16x32_bf16 v[38:41], v[150:153], v[200:203], v[38:41]
	v_mfma_f32_16x16x32_bf16 v[34:37], v[158:161], v[200:203], v[34:37]
	v_mfma_f32_16x16x32_bf16 v[14:17], v[150:153], v[208:211], v[14:17]
	v_mfma_f32_16x16x32_bf16 v[10:13], v[158:161], v[208:211], v[10:13]
	v_mfma_f32_16x16x32_bf16 v[102:105], v[154:157], v[188:191], v[102:105]
	v_mfma_f32_16x16x32_bf16 v[98:101], v[162:165], v[188:191], v[98:101]
	v_mfma_f32_16x16x32_bf16 v[78:81], v[154:157], v[196:199], v[78:81]
	v_mfma_f32_16x16x32_bf16 v[74:77], v[162:165], v[196:199], v[74:77]
	v_mfma_f32_16x16x32_bf16 v[38:41], v[154:157], v[204:207], v[38:41]
	v_mfma_f32_16x16x32_bf16 v[34:37], v[162:165], v[204:207], v[34:37]
	v_mfma_f32_16x16x32_bf16 v[14:17], v[154:157], v[212:215], v[14:17]
	v_mfma_f32_16x16x32_bf16 v[10:13], v[162:165], v[212:215], v[10:13]
	s_setprio 0
	s_setprio 1
	v_mfma_f32_16x16x32_bf16 v[90:93], v[166:169], v[182:185], v[90:93]
	v_mfma_f32_16x16x32_bf16 v[82:85], v[174:177], v[182:185], v[82:85]
	v_mfma_f32_16x16x32_bf16 v[62:65], v[166:169], v[192:195], v[62:65]
	v_mfma_f32_16x16x32_bf16 v[58:61], v[174:177], v[192:195], v[58:61]
	v_mfma_f32_16x16x32_bf16 v[26:29], v[166:169], v[200:203], v[26:29]
	v_mfma_f32_16x16x32_bf16 v[22:25], v[174:177], v[200:203], v[22:25]
	v_mfma_f32_16x16x32_bf16 v[6:9], v[166:169], v[208:211], v[6:9]
	v_mfma_f32_16x16x32_bf16 v[2:5], v[174:177], v[208:211], v[2:5]
	v_mfma_f32_16x16x32_bf16 v[90:93], v[170:173], v[188:191], v[90:93]
	v_mfma_f32_16x16x32_bf16 v[82:85], v[178:181], v[188:191], v[82:85]
	v_mfma_f32_16x16x32_bf16 v[62:65], v[170:173], v[196:199], v[62:65]
	v_mfma_f32_16x16x32_bf16 v[58:61], v[178:181], v[196:199], v[58:61]
	v_mfma_f32_16x16x32_bf16 v[26:29], v[170:173], v[204:207], v[26:29]
	v_mfma_f32_16x16x32_bf16 v[22:25], v[178:181], v[204:207], v[22:25]
	v_mfma_f32_16x16x32_bf16 v[6:9], v[170:173], v[212:215], v[6:9]
	v_mfma_f32_16x16x32_bf16 v[2:5], v[178:181], v[212:215], v[2:5]
	s_barrier
	s_setprio 0
	s_add_i32 s59, s59, 2
	s_add_u32 s24, s24, 0x100
	s_addc_u32 s25, s25, 0
	s_cmp_gt_u32 s59, 41
	s_cbranch_scc0 .LBB0_319
	s_add_u32 s24, s57, 0xffffff00
	s_addc_u32 s25, s58, -1
	s_and_b64 vcc, exec, s[6:7]
	s_cbranch_vccnz .LBB0_322
	v_mov_b32_e32 v2, 0
	s_mov_b32 s16, s54
	s_mov_b32 s31, s55
	s_mov_b64 s[18:19], s[22:23]
	s_mov_b32 s49, s56
	v_mov_b32_e32 v3, v2
	v_mov_b32_e32 v4, v2
	v_mov_b32_e32 v5, v2
	v_mov_b32_e32 v6, v2
	v_mov_b32_e32 v7, v2
	v_mov_b32_e32 v8, v2
	v_mov_b32_e32 v9, v2
	v_mov_b32_e32 v22, v2
	v_mov_b32_e32 v23, v2
	v_mov_b32_e32 v24, v2
	v_mov_b32_e32 v25, v2
	v_mov_b32_e32 v26, v2
	v_mov_b32_e32 v27, v2
	v_mov_b32_e32 v28, v2
	v_mov_b32_e32 v29, v2
	v_mov_b32_e32 v58, v2
	v_mov_b32_e32 v59, v2
	v_mov_b32_e32 v60, v2
	v_mov_b32_e32 v61, v2
	v_mov_b32_e32 v62, v2
	v_mov_b32_e32 v63, v2
	v_mov_b32_e32 v64, v2
	v_mov_b32_e32 v65, v2
	v_mov_b32_e32 v82, v2
	v_mov_b32_e32 v83, v2
	v_mov_b32_e32 v84, v2
	v_mov_b32_e32 v85, v2
	v_mov_b32_e32 v90, v2
	v_mov_b32_e32 v91, v2
	v_mov_b32_e32 v92, v2
	v_mov_b32_e32 v93, v2
	v_mov_b32_e32 v10, v2
	v_mov_b32_e32 v11, v2
	v_mov_b32_e32 v12, v2
	v_mov_b32_e32 v13, v2
	v_mov_b32_e32 v14, v2
	v_mov_b32_e32 v15, v2
	v_mov_b32_e32 v16, v2
	v_mov_b32_e32 v17, v2
	v_mov_b32_e32 v34, v2
	v_mov_b32_e32 v35, v2
	v_mov_b32_e32 v36, v2
	v_mov_b32_e32 v37, v2
	v_mov_b32_e32 v38, v2
	v_mov_b32_e32 v39, v2
	v_mov_b32_e32 v40, v2
	v_mov_b32_e32 v41, v2
	v_mov_b32_e32 v74, v2
	v_mov_b32_e32 v75, v2
	v_mov_b32_e32 v76, v2
	v_mov_b32_e32 v77, v2
	v_mov_b32_e32 v78, v2
	v_mov_b32_e32 v79, v2
	v_mov_b32_e32 v80, v2
	v_mov_b32_e32 v81, v2
	v_mov_b32_e32 v98, v2
	v_mov_b32_e32 v99, v2
	v_mov_b32_e32 v100, v2
	v_mov_b32_e32 v101, v2
	v_mov_b32_e32 v102, v2
	v_mov_b32_e32 v103, v2
	v_mov_b32_e32 v104, v2
	v_mov_b32_e32 v105, v2
	v_mov_b32_e32 v54, v2
	v_mov_b32_e32 v55, v2
	v_mov_b32_e32 v56, v2
	v_mov_b32_e32 v57, v2
	v_mov_b32_e32 v94, v2
	v_mov_b32_e32 v95, v2
	v_mov_b32_e32 v96, v2
	v_mov_b32_e32 v97, v2
	v_mov_b32_e32 v46, v2
	v_mov_b32_e32 v47, v2
	v_mov_b32_e32 v48, v2
	v_mov_b32_e32 v49, v2
	v_mov_b32_e32 v70, v2
	v_mov_b32_e32 v71, v2
	v_mov_b32_e32 v72, v2
	v_mov_b32_e32 v73, v2
	v_mov_b32_e32 v30, v2
	v_mov_b32_e32 v31, v2
	v_mov_b32_e32 v32, v2
	v_mov_b32_e32 v33, v2
	v_mov_b32_e32 v50, v2
	v_mov_b32_e32 v51, v2
	v_mov_b32_e32 v52, v2
	v_mov_b32_e32 v53, v2
	v_mov_b32_e32 v18, v2
	v_mov_b32_e32 v19, v2
	v_mov_b32_e32 v20, v2
	v_mov_b32_e32 v21, v2
	v_mov_b32_e32 v42, v2
	v_mov_b32_e32 v43, v2
	v_mov_b32_e32 v44, v2
	v_mov_b32_e32 v45, v2
	v_mov_b32_e32 v118, v2
	v_mov_b32_e32 v119, v2
	v_mov_b32_e32 v120, v2
	v_mov_b32_e32 v121, v2
	v_mov_b32_e32 v122, v2
	v_mov_b32_e32 v123, v2
	v_mov_b32_e32 v124, v2
	v_mov_b32_e32 v125, v2
	v_mov_b32_e32 v110, v2
	v_mov_b32_e32 v111, v2
	v_mov_b32_e32 v112, v2
	v_mov_b32_e32 v113, v2
	v_mov_b32_e32 v126, v2
	v_mov_b32_e32 v127, v2
	v_mov_b32_e32 v128, v2
	v_mov_b32_e32 v129, v2
	v_mov_b32_e32 v86, v2
	v_mov_b32_e32 v87, v2
	v_mov_b32_e32 v88, v2
	v_mov_b32_e32 v89, v2
	v_mov_b32_e32 v114, v2
	v_mov_b32_e32 v115, v2
	v_mov_b32_e32 v116, v2
	v_mov_b32_e32 v117, v2
	v_mov_b32_e32 v66, v2
	v_mov_b32_e32 v67, v2
	v_mov_b32_e32 v68, v2
	v_mov_b32_e32 v69, v2
	v_mov_b32_e32 v106, v2
	v_mov_b32_e32 v107, v2
	v_mov_b32_e32 v108, v2
	v_mov_b32_e32 v109, v2
	s_andn2_b64 vcc, exec, s[4:5]
	s_cbranch_vccnz .LBB0_323
	s_branch .LBB0_324

; #define PG8_STAGE(bufoff, gbase, voff) do { _Pragma("unroll") for (int _i = 0; _i < 2; ++_i) \
;         __builtin_amdgcn_global_load_lds((const unsigned*)((const char*)(gbase) + (voff)[_i]), (PG8_LAS unsigned*)(lds + (bufoff) + ldsw + _i * 8192), 16, 0, 0); } while (0)
; #define PG8_LDA(dst, b, h) do { _Pragma("unroll") for (int m = 0; m < 4; ++m) _Pragma("unroll") for (int k = 0; k < 2; ++k) dst[m][k] = *(const PG8_LAS bf16x8*)(lds + PG8_SA(b, h) + aoff + m * 2048 + k * 1024); } while (0)
; #define PG8_LDB(dst, b, h) do { _Pragma("unroll") for (int n = 0; n < 2; ++n) _Pragma("unroll") for (int k = 0; k < 2; ++k) dst[n][k] = *(const PG8_LAS bf16x8*)(lds + PG8_SB(b, h) + boff + n * 2048 + k * 1024); } while (0)
; #define PG8_MMA(ai, bj, At, Bt) do { __builtin_amdgcn_s_setprio(1); _Pragma("unroll") for (int m = 0; m < 4; ++m) _Pragma("unroll") for (int n = 0; n < 2; ++n) _Pragma("unroll") for (int k = 0; k < 2; ++k) \
;         acc[ai][bj][m][n] = __builtin_amdgcn_mfma_f32_16x16x32_bf16(Bt[n][k], At[m][k], acc[ai][bj][m][n], 0, 0, 0); __builtin_amdgcn_s_setprio(0); } while (0)
; #define PG8_WAIT_V(n) asm volatile("s_waitcnt vmcnt(" #n ")" ::: "memory")
; #define PG8_WAIT_L(n) asm volatile("s_waitcnt lgkmcnt(" #n ")" ::: "memory")
; #define PG8_BAR __builtin_amdgcn_s_barrier()
; #define PG8_SCHED __builtin_amdgcn_sched_barrier(0)
; template <class Epi, class Sched, bool ALIGN_EPI = false, bool SP2 = false>
; __device__ __forceinline__ void gemm_phase(PG8_LAS unsigned char* lds, const Gemm g, const Sched& S, const Epi& E) {
;     ...
;             const bool last = (t == nt - 2);
;             const char* a1 = cA + (size_t)(t + 1) * kstep;
;             const char* a2 = last ? nA : cA + (size_t)(t + 2) * kstep; const char* b2 = last ? nB : cB + (size_t)(t + 2) * kstep;
;             const char* a3 = a2 + kstep; const char* b3 = b2 + kstep;
;             if (last && has_next) S.a_ready(nxt);
;             if constexpr (SP2) {
;             PG8_LDB(B0, 0, 0); PG8_LDB(B1, 0, 1); PG8_SCHED; PG8_LDA(At, 0, 0); PG8_STAGE(PG8_SA(1, 1), a1 + hstep, voffA);
;             PG8_WAIT_V(8); PG8_WAIT_L(0); PG8_BAR; PG8_MMA(0, 0, At, B0); PG8_MMA(0, 1, At, B1); PG8_BAR; PG8_SCHED;
;             PG8_LDA(At, 0, 1); PG8_STAGE(PG8_SB(0, 0), b2, voffB); PG8_STAGE(PG8_SB(0, 1), b2 + hstep, voffB); PG8_STAGE(PG8_SA(0, 0), a2, voffA);
.LBB0_457:
	ds_read_b128 v[148:151], v144
	ds_read_b128 v[152:155], v144 offset:1024
	ds_read_b128 v[156:159], v144 offset:2048
	ds_read_b128 v[160:163], v144 offset:3072
	ds_read_b128 v[164:167], v145
	ds_read_b128 v[168:171], v145 offset:1024
	ds_read_b128 v[172:175], v145 offset:2048
	ds_read_b128 v[176:179], v145 offset:3072
	s_add_u32 s24, s22, 0x100
	s_addc_u32 s25, s23, 0
	s_cmp_eq_u32 s53, 12
	s_cselect_b32 s29, s15, s25
	s_cselect_b32 s28, s49, s24
	s_cselect_b32 s27, s13, s52
	s_cselect_b32 s26, s50, s51
	v_lshl_add_u64 v[184:185], s[22:23], 0, v[134:135]
	s_add_i32 m0, s21, 0xc000
	ds_read_b128 v[180:183], v146
	ds_read_b128 v[188:191], v146 offset:1024
	ds_read_b128 v[192:195], v146 offset:2048
	ds_read_b128 v[196:199], v146 offset:3072
	ds_read_b128 v[200:203], v146 offset:4096
	ds_read_b128 v[204:207], v146 offset:5120
	ds_read_b128 v[208:211], v146 offset:6144
	ds_read_b128 v[212:215], v146 offset:7168
	global_load_lds_dwordx4 v[184:185], off
	v_lshl_add_u64 v[184:185], s[22:23], 0, v[136:137]
	s_add_i32 m0, s21, 0xe000
	s_nop 0
	global_load_lds_dwordx4 v[184:185], off
	s_waitcnt vmcnt(8)
	s_waitcnt lgkmcnt(0)
	s_barrier
	s_setprio 1
	s_waitcnt lgkmcnt(0)
	v_mfma_f32_16x16x32_bf16 v[126:129], v[148:151], v[180:183], v[126:129]
	v_mfma_f32_16x16x32_bf16 v[122:125], v[156:159], v[180:183], v[122:125]
	v_mfma_f32_16x16x32_bf16 v[118:121], v[148:151], v[192:195], v[118:121]
	v_mfma_f32_16x16x32_bf16 v[110:113], v[156:159], v[192:195], v[110:113]
	v_mfma_f32_16x16x32_bf16 v[102:105], v[148:151], v[200:203], v[102:105]
	v_mfma_f32_16x16x32_bf16 v[94:97], v[156:159], v[200:203], v[94:97]
	v_mfma_f32_16x16x32_bf16 v[86:89], v[148:151], v[208:211], v[86:89]
	v_mfma_f32_16x16x32_bf16 v[78:81], v[156:159], v[208:211], v[78:81]
	v_mfma_f32_16x16x32_bf16 v[126:129], v[152:155], v[188:191], v[126:129]
	v_mfma_f32_16x16x32_bf16 v[122:125], v[160:163], v[188:191], v[122:125]
	v_mfma_f32_16x16x32_bf16 v[118:121], v[152:155], v[196:199], v[118:121]
	v_mfma_f32_16x16x32_bf16 v[110:113], v[160:163], v[196:199], v[110:113]
	v_mfma_f32_16x16x32_bf16 v[102:105], v[152:155], v[204:207], v[102:105]
	v_mfma_f32_16x16x32_bf16 v[94:97], v[160:163], v[204:207], v[94:97]
	v_mfma_f32_16x16x32_bf16 v[86:89], v[152:155], v[212:215], v[86:89]
	v_mfma_f32_16x16x32_bf16 v[78:81], v[160:163], v[212:215], v[78:81]
	s_setprio 0
	s_setprio 1
	v_mfma_f32_16x16x32_bf16 v[114:117], v[164:167], v[180:183], v[114:117]
	v_mfma_f32_16x16x32_bf16 v[106:109], v[172:175], v[180:183], v[106:109]
	v_mfma_f32_16x16x32_bf16 v[98:101], v[164:167], v[192:195], v[98:101]
	v_mfma_f32_16x16x32_bf16 v[90:93], v[172:175], v[192:195], v[90:93]
	v_mfma_f32_16x16x32_bf16 v[82:85], v[164:167], v[200:203], v[82:85]
	v_mfma_f32_16x16x32_bf16 v[74:77], v[172:175], v[200:203], v[74:77]
	v_mfma_f32_16x16x32_bf16 v[70:73], v[164:167], v[208:211], v[70:73]
	v_mfma_f32_16x16x32_bf16 v[66:69], v[172:175], v[208:211], v[66:69]
	v_mfma_f32_16x16x32_bf16 v[114:117], v[168:171], v[188:191], v[114:117]
	v_mfma_f32_16x16x32_bf16 v[106:109], v[176:179], v[188:191], v[106:109]
	v_mfma_f32_16x16x32_bf16 v[98:101], v[168:171], v[196:199], v[98:101]
	v_mfma_f32_16x16x32_bf16 v[90:93], v[176:179], v[196:199], v[90:93]
	v_mfma_f32_16x16x32_bf16 v[82:85], v[168:171], v[204:207], v[82:85]
	v_mfma_f32_16x16x32_bf16 v[74:77], v[176:179], v[204:207], v[74:77]
	v_mfma_f32_16x16x32_bf16 v[70:73], v[168:171], v[212:215], v[70:73]
	v_mfma_f32_16x16x32_bf16 v[66:69], v[176:179], v[212:215], v[66:69]
	s_barrier
	s_setprio 0
	s_add_i32 s22, s41, s31
	v_lshl_add_u64 v[184:185], s[26:27], 0, v[130:131]
	s_mov_b32 m0, s22
	ds_read_b128 v[180:183], v146 offset:16384
	ds_read_b128 v[188:191], v146 offset:17408
	ds_read_b128 v[192:195], v146 offset:18432
	ds_read_b128 v[196:199], v146 offset:19456
	ds_read_b128 v[200:203], v146 offset:20480
	ds_read_b128 v[204:207], v146 offset:21504
	ds_read_b128 v[208:211], v146 offset:22528
	ds_read_b128 v[212:215], v146 offset:23552
	global_load_lds_dwordx4 v[184:185], off
	s_add_i32 m0, s22, 0x2000
	s_add_u32 s22, s26, 0x40000
	v_lshl_add_u64 v[216:217], s[26:27], 0, v[132:133]
	s_addc_u32 s23, s27, 0
	s_add_i32 s54, s42, s31
	global_load_lds_dwordx4 v[216:217], off
	v_lshl_add_u64 v[218:219], s[22:23], 0, v[130:131]
	s_mov_b32 m0, s54
	v_lshl_add_u64 v[220:221], s[28:29], 0, v[132:133]
	global_load_lds_dwordx4 v[218:219], off
	v_lshl_add_u64 v[218:219], s[22:23], 0, v[132:133]
	s_add_i32 m0, s54, 0x2000
	s_nop 0
	global_load_lds_dwordx4 v[218:219], off
	v_lshl_add_u64 v[218:219], s[28:29], 0, v[130:131]
	s_mov_b32 m0, s21
	s_nop 0
	global_load_lds_dwordx4 v[218:219], off
	s_mov_b32 m0, s34
	s_nop 0
	global_load_lds_dwordx4 v[220:221], off
	s_waitcnt vmcnt(8)
	s_waitcnt lgkmcnt(0)
	s_barrier
; #define PG8_STAGE(bufoff, gbase, voff) do { _Pragma("unroll") for (int _i = 0; _i < 2; ++_i) \
;         __builtin_amdgcn_global_load_lds((const unsigned*)((const char*)(gbase) + (voff)[_i]), (PG8_LAS unsigned*)(lds + (bufoff) + ldsw + _i * 8192), 16, 0, 0); } while (0)
; #define PG8_LDA(dst, b, h) do { _Pragma("unroll") for (int m = 0; m < 4; ++m) _Pragma("unroll") for (int k = 0; k < 2; ++k) dst[m][k] = *(const PG8_LAS bf16x8*)(lds + PG8_SA(b, h) + aoff + m * 2048 + k * 1024); } while (0)
; #define PG8_LDB(dst, b, h) do { _Pragma("unroll") for (int n = 0; n < 2; ++n) _Pragma("unroll") for (int k = 0; k < 2; ++k) dst[n][k] = *(const PG8_LAS bf16x8*)(lds + PG8_SB(b, h) + boff + n * 2048 + k * 1024); } while (0)
; #define PG8_MMA(ai, bj, At, Bt) do { __builtin_amdgcn_s_setprio(1); _Pragma("unroll") for (int m = 0; m < 4; ++m) _Pragma("unroll") for (int n = 0; n < 2; ++n) _Pragma("unroll") for (int k = 0; k < 2; ++k) \
;         acc[ai][bj][m][n] = __builtin_amdgcn_mfma_f32_16x16x32_bf16(Bt[n][k], At[m][k], acc[ai][bj][m][n], 0, 0, 0); __builtin_amdgcn_s_setprio(0); } while (0)
; #define PG8_WAIT_V(n) asm volatile("s_waitcnt vmcnt(" #n ")" ::: "memory")
; #define PG8_WAIT_L(n) asm volatile("s_waitcnt lgkmcnt(" #n ")" ::: "memory")
; #define PG8_BAR __builtin_amdgcn_s_barrier()
; #define PG8_SCHED __builtin_amdgcn_sched_barrier(0)
; template <class Epi, class Sched, bool ALIGN_EPI = false, bool SP2 = false>
; __device__ __forceinline__ void gemm_phase(PG8_LAS unsigned char* lds, const Gemm g, const Sched& S, const Epi& E) {
;     ...
;             PG8_WAIT_V(8); PG8_WAIT_L(0); PG8_BAR; PG8_MMA(1, 0, At, B0); PG8_MMA(1, 1, At, B1); PG8_BAR; PG8_SCHED;
;             PG8_LDB(B0, 1, 0); PG8_LDB(B1, 1, 1); PG8_SCHED; PG8_LDA(At, 1, 0); PG8_STAGE(PG8_SA(0, 1), a2 + hstep, voffA);
;             PG8_WAIT_V(8); PG8_WAIT_L(0); PG8_BAR; PG8_MMA(0, 0, At, B0); PG8_MMA(0, 1, At, B1); PG8_BAR; PG8_SCHED;
	s_setprio 1
	s_waitcnt lgkmcnt(0)
	v_mfma_f32_16x16x32_bf16 v[62:65], v[148:151], v[180:183], v[62:65]
	v_mfma_f32_16x16x32_bf16 v[58:61], v[156:159], v[180:183], v[58:61]
	v_mfma_f32_16x16x32_bf16 v[54:57], v[148:151], v[192:195], v[54:57]
	v_mfma_f32_16x16x32_bf16 v[46:49], v[156:159], v[192:195], v[46:49]
	v_mfma_f32_16x16x32_bf16 v[38:41], v[148:151], v[200:203], v[38:41]
	v_mfma_f32_16x16x32_bf16 v[30:33], v[156:159], v[200:203], v[30:33]
	v_mfma_f32_16x16x32_bf16 v[22:25], v[148:151], v[208:211], v[22:25]
	v_mfma_f32_16x16x32_bf16 v[14:17], v[156:159], v[208:211], v[14:17]
	v_mfma_f32_16x16x32_bf16 v[62:65], v[152:155], v[188:191], v[62:65]
	v_mfma_f32_16x16x32_bf16 v[58:61], v[160:163], v[188:191], v[58:61]
	v_mfma_f32_16x16x32_bf16 v[54:57], v[152:155], v[196:199], v[54:57]
	v_mfma_f32_16x16x32_bf16 v[46:49], v[160:163], v[196:199], v[46:49]
	v_mfma_f32_16x16x32_bf16 v[38:41], v[152:155], v[204:207], v[38:41]
	v_mfma_f32_16x16x32_bf16 v[30:33], v[160:163], v[204:207], v[30:33]
	v_mfma_f32_16x16x32_bf16 v[22:25], v[152:155], v[212:215], v[22:25]
	v_mfma_f32_16x16x32_bf16 v[14:17], v[160:163], v[212:215], v[14:17]
	s_setprio 0
	s_setprio 1
	v_mfma_f32_16x16x32_bf16 v[50:53], v[164:167], v[180:183], v[50:53]
	v_mfma_f32_16x16x32_bf16 v[42:45], v[172:175], v[180:183], v[42:45]
	v_mfma_f32_16x16x32_bf16 v[34:37], v[164:167], v[192:195], v[34:37]
	v_mfma_f32_16x16x32_bf16 v[26:29], v[172:175], v[192:195], v[26:29]
	v_mfma_f32_16x16x32_bf16 v[18:21], v[164:167], v[200:203], v[18:21]
	v_mfma_f32_16x16x32_bf16 v[10:13], v[172:175], v[200:203], v[10:13]
	v_mfma_f32_16x16x32_bf16 v[6:9], v[164:167], v[208:211], v[6:9]
	v_mfma_f32_16x16x32_bf16 v[2:5], v[172:175], v[208:211], v[2:5]
	v_mfma_f32_16x16x32_bf16 v[50:53], v[168:171], v[188:191], v[50:53]
	v_mfma_f32_16x16x32_bf16 v[42:45], v[176:179], v[188:191], v[42:45]
	v_mfma_f32_16x16x32_bf16 v[34:37], v[168:171], v[196:199], v[34:37]
	v_mfma_f32_16x16x32_bf16 v[26:29], v[176:179], v[196:199], v[26:29]
	v_mfma_f32_16x16x32_bf16 v[18:21], v[168:171], v[204:207], v[18:21]
	v_mfma_f32_16x16x32_bf16 v[10:13], v[176:179], v[204:207], v[10:13]
	v_mfma_f32_16x16x32_bf16 v[6:9], v[168:171], v[212:215], v[6:9]
	v_mfma_f32_16x16x32_bf16 v[2:5], v[176:179], v[212:215], v[2:5]
	s_barrier
	s_setprio 0
	s_add_i32 s54, 0, 0x18000
	v_add_u32_e32 v147, s54, v142
	s_add_i32 s55, 0, 0x1c000
	ds_read_b128 v[148:151], v147
	ds_read_b128 v[152:155], v147 offset:1024
	ds_read_b128 v[156:159], v147 offset:2048
	ds_read_b128 v[160:163], v147 offset:3072
	v_add_u32_e32 v147, s55, v142
	ds_read_b128 v[164:167], v147
	ds_read_b128 v[168:171], v147 offset:1024
	ds_read_b128 v[172:175], v147 offset:2048
	ds_read_b128 v[176:179], v147 offset:3072
	s_add_u32 s22, s28, 0x40000
	s_addc_u32 s23, s29, 0
	s_mov_b32 m0, s35
	v_lshl_add_u64 v[222:223], s[22:23], 0, v[130:131]
	ds_read_b128 v[180:183], v146 offset:32768
	ds_read_b128 v[188:191], v146 offset:33792
	ds_read_b128 v[192:195], v146 offset:34816
	ds_read_b128 v[196:199], v146 offset:35840
	ds_read_b128 v[200:203], v146 offset:36864
	ds_read_b128 v[204:207], v146 offset:37888
	ds_read_b128 v[208:211], v146 offset:38912
	ds_read_b128 v[212:215], v146 offset:39936
	global_load_lds_dwordx4 v[222:223], off
	v_lshl_add_u64 v[222:223], s[22:23], 0, v[132:133]
	s_mov_b32 m0, s36
	s_nop 0
	global_load_lds_dwordx4 v[222:223], off
	s_waitcnt vmcnt(8)
	s_waitcnt lgkmcnt(0)
	s_barrier
	s_setprio 1
	s_waitcnt lgkmcnt(0)
	v_mfma_f32_16x16x32_bf16 v[126:129], v[148:151], v[180:183], v[126:129]
	v_mfma_f32_16x16x32_bf16 v[122:125], v[156:159], v[180:183], v[122:125]
	v_mfma_f32_16x16x32_bf16 v[118:121], v[148:151], v[192:195], v[118:121]
	v_mfma_f32_16x16x32_bf16 v[110:113], v[156:159], v[192:195], v[110:113]
	v_mfma_f32_16x16x32_bf16 v[102:105], v[148:151], v[200:203], v[102:105]
	v_mfma_f32_16x16x32_bf16 v[94:97], v[156:159], v[200:203], v[94:97]
	v_mfma_f32_16x16x32_bf16 v[86:89], v[148:151], v[208:211], v[86:89]
	v_mfma_f32_16x16x32_bf16 v[78:81], v[156:159], v[208:211], v[78:81]
	v_mfma_f32_16x16x32_bf16 v[126:129], v[152:155], v[188:191], v[126:129]
	v_mfma_f32_16x16x32_bf16 v[122:125], v[160:163], v[188:191], v[122:125]
	v_mfma_f32_16x16x32_bf16 v[118:121], v[152:155], v[196:199], v[118:121]
	v_mfma_f32_16x16x32_bf16 v[110:113], v[160:163], v[196:199], v[110:113]
	v_mfma_f32_16x16x32_bf16 v[102:105], v[152:155], v[204:207], v[102:105]
	v_mfma_f32_16x16x32_bf16 v[94:97], v[160:163], v[204:207], v[94:97]
	v_mfma_f32_16x16x32_bf16 v[86:89], v[152:155], v[212:215], v[86:89]
	v_mfma_f32_16x16x32_bf16 v[78:81], v[160:163], v[212:215], v[78:81]
	s_setprio 0
	s_setprio 1
	v_mfma_f32_16x16x32_bf16 v[114:117], v[164:167], v[180:183], v[114:117]
	v_mfma_f32_16x16x32_bf16 v[106:109], v[172:175], v[180:183], v[106:109]
	v_mfma_f32_16x16x32_bf16 v[98:101], v[164:167], v[192:195], v[98:101]
	v_mfma_f32_16x16x32_bf16 v[90:93], v[172:175], v[192:195], v[90:93]
	v_mfma_f32_16x16x32_bf16 v[82:85], v[164:167], v[200:203], v[82:85]
	v_mfma_f32_16x16x32_bf16 v[74:77], v[172:175], v[200:203], v[74:77]
	v_mfma_f32_16x16x32_bf16 v[70:73], v[164:167], v[208:211], v[70:73]
	v_mfma_f32_16x16x32_bf16 v[66:69], v[172:175], v[208:211], v[66:69]
	v_mfma_f32_16x16x32_bf16 v[114:117], v[168:171], v[188:191], v[114:117]
	v_mfma_f32_16x16x32_bf16 v[106:109], v[176:179], v[188:191], v[106:109]
	v_mfma_f32_16x16x32_bf16 v[98:101], v[168:171], v[196:199], v[98:101]
	v_mfma_f32_16x16x32_bf16 v[90:93], v[176:179], v[196:199], v[90:93]
	v_mfma_f32_16x16x32_bf16 v[82:85], v[168:171], v[204:207], v[82:85]
	v_mfma_f32_16x16x32_bf16 v[74:77], v[176:179], v[204:207], v[74:77]
	v_mfma_f32_16x16x32_bf16 v[70:73], v[168:171], v[212:215], v[70:73]
	v_mfma_f32_16x16x32_bf16 v[66:69], v[176:179], v[212:215], v[66:69]
	s_barrier
; #define PG8_STAGE(bufoff, gbase, voff) do { _Pragma("unroll") for (int _i = 0; _i < 2; ++_i) \
;         __builtin_amdgcn_global_load_lds((const unsigned*)((const char*)(gbase) + (voff)[_i]), (PG8_LAS unsigned*)(lds + (bufoff) + ldsw + _i * 8192), 16, 0, 0); } while (0)
; #define PG8_LDA(dst, b, h) do { _Pragma("unroll") for (int m = 0; m < 4; ++m) _Pragma("unroll") for (int k = 0; k < 2; ++k) dst[m][k] = *(const PG8_LAS bf16x8*)(lds + PG8_SA(b, h) + aoff + m * 2048 + k * 1024); } while (0)
; #define PG8_MMA(ai, bj, At, Bt) do { __builtin_amdgcn_s_setprio(1); _Pragma("unroll") for (int m = 0; m < 4; ++m) _Pragma("unroll") for (int n = 0; n < 2; ++n) _Pragma("unroll") for (int k = 0; k < 2; ++k) \
;         acc[ai][bj][m][n] = __builtin_amdgcn_mfma_f32_16x16x32_bf16(Bt[n][k], At[m][k], acc[ai][bj][m][n], 0, 0, 0); __builtin_amdgcn_s_setprio(0); } while (0)
; #define PG8_WAIT_V(n) asm volatile("s_waitcnt vmcnt(" #n ")" ::: "memory")
; #define PG8_WAIT_L(n) asm volatile("s_waitcnt lgkmcnt(" #n ")" ::: "memory")
; #define PG8_BAR __builtin_amdgcn_s_barrier()
; #define PG8_SCHED __builtin_amdgcn_sched_barrier(0)
; template <class Epi, class Sched, bool ALIGN_EPI = false, bool SP2 = false>
; __device__ __forceinline__ void gemm_phase(PG8_LAS unsigned char* lds, const Gemm g, const Sched& S, const Epi& E) {
;     ...
;             PG8_LDA(At, 1, 1); PG8_STAGE(PG8_SB(1, 0), b3, voffB); PG8_STAGE(PG8_SB(1, 1), b3 + hstep, voffB); PG8_STAGE(PG8_SA(1, 0), a3, voffA);
;             PG8_WAIT_V(8); PG8_WAIT_L(0); PG8_BAR; PG8_MMA(1, 0, At, B0); PG8_MMA(1, 1, At, B1); PG8_BAR; PG8_SCHED;
;     ...
;         if constexpr (ALIGN_EPI) { if (wr == 0) PG8_BAR; }
	s_setprio 0
	s_add_i32 s22, s54, s31
	v_lshl_add_u64 v[184:185], v[184:185], 0, s[8:9]
	s_mov_b32 m0, s22
	ds_read_b128 v[180:183], v146 offset:49152
	ds_read_b128 v[188:191], v146 offset:50176
	ds_read_b128 v[192:195], v146 offset:51200
	ds_read_b128 v[196:199], v146 offset:52224
	ds_read_b128 v[200:203], v146 offset:53248
	ds_read_b128 v[204:207], v146 offset:54272
	ds_read_b128 v[208:211], v146 offset:55296
	ds_read_b128 v[212:215], v146 offset:56320
	global_load_lds_dwordx4 v[184:185], off
	s_add_i32 m0, s22, 0x2000
	s_add_u32 s22, s26, 0x40080
	v_lshl_add_u64 v[184:185], v[216:217], 0, s[8:9]
	s_addc_u32 s23, s27, 0
	s_add_i32 s26, s55, s31
	global_load_lds_dwordx4 v[184:185], off
	v_lshl_add_u64 v[184:185], s[22:23], 0, v[130:131]
	s_mov_b32 m0, s26
	s_nop 0
	global_load_lds_dwordx4 v[184:185], off
	v_lshl_add_u64 v[184:185], s[22:23], 0, v[132:133]
	s_add_i32 m0, s26, 0x2000
	s_nop 0
	global_load_lds_dwordx4 v[184:185], off
	v_lshl_add_u64 v[184:185], v[218:219], 0, s[8:9]
	s_mov_b32 m0, s38
	s_nop 0
	global_load_lds_dwordx4 v[184:185], off
	v_lshl_add_u64 v[184:185], v[220:221], 0, s[8:9]
	s_mov_b32 m0, s39
	s_nop 0
	global_load_lds_dwordx4 v[184:185], off
	s_waitcnt vmcnt(8)
	s_waitcnt lgkmcnt(0)
	s_barrier
	s_setprio 1
	s_waitcnt lgkmcnt(0)
	v_mfma_f32_16x16x32_bf16 v[62:65], v[148:151], v[180:183], v[62:65]
	v_mfma_f32_16x16x32_bf16 v[58:61], v[156:159], v[180:183], v[58:61]
	v_mfma_f32_16x16x32_bf16 v[54:57], v[148:151], v[192:195], v[54:57]
	v_mfma_f32_16x16x32_bf16 v[46:49], v[156:159], v[192:195], v[46:49]
	v_mfma_f32_16x16x32_bf16 v[38:41], v[148:151], v[200:203], v[38:41]
	v_mfma_f32_16x16x32_bf16 v[30:33], v[156:159], v[200:203], v[30:33]
	v_mfma_f32_16x16x32_bf16 v[22:25], v[148:151], v[208:211], v[22:25]
	v_mfma_f32_16x16x32_bf16 v[14:17], v[156:159], v[208:211], v[14:17]
	v_mfma_f32_16x16x32_bf16 v[62:65], v[152:155], v[188:191], v[62:65]
	v_mfma_f32_16x16x32_bf16 v[58:61], v[160:163], v[188:191], v[58:61]
	v_mfma_f32_16x16x32_bf16 v[54:57], v[152:155], v[196:199], v[54:57]
	v_mfma_f32_16x16x32_bf16 v[46:49], v[160:163], v[196:199], v[46:49]
	v_mfma_f32_16x16x32_bf16 v[38:41], v[152:155], v[204:207], v[38:41]
	v_mfma_f32_16x16x32_bf16 v[30:33], v[160:163], v[204:207], v[30:33]
	v_mfma_f32_16x16x32_bf16 v[22:25], v[152:155], v[212:215], v[22:25]
	v_mfma_f32_16x16x32_bf16 v[14:17], v[160:163], v[212:215], v[14:17]
	s_setprio 0
	s_setprio 1
	v_mfma_f32_16x16x32_bf16 v[50:53], v[164:167], v[180:183], v[50:53]
	v_mfma_f32_16x16x32_bf16 v[42:45], v[172:175], v[180:183], v[42:45]
	v_mfma_f32_16x16x32_bf16 v[34:37], v[164:167], v[192:195], v[34:37]
	v_mfma_f32_16x16x32_bf16 v[26:29], v[172:175], v[192:195], v[26:29]
	v_mfma_f32_16x16x32_bf16 v[18:21], v[164:167], v[200:203], v[18:21]
	v_mfma_f32_16x16x32_bf16 v[10:13], v[172:175], v[200:203], v[10:13]
	v_mfma_f32_16x16x32_bf16 v[6:9], v[164:167], v[208:211], v[6:9]
	v_mfma_f32_16x16x32_bf16 v[2:5], v[172:175], v[208:211], v[2:5]
	v_mfma_f32_16x16x32_bf16 v[50:53], v[168:171], v[188:191], v[50:53]
	v_mfma_f32_16x16x32_bf16 v[42:45], v[176:179], v[188:191], v[42:45]
	v_mfma_f32_16x16x32_bf16 v[34:37], v[168:171], v[196:199], v[34:37]
	v_mfma_f32_16x16x32_bf16 v[26:29], v[176:179], v[196:199], v[26:29]
	v_mfma_f32_16x16x32_bf16 v[18:21], v[168:171], v[204:207], v[18:21]
	v_mfma_f32_16x16x32_bf16 v[10:13], v[176:179], v[204:207], v[10:13]
	v_mfma_f32_16x16x32_bf16 v[6:9], v[168:171], v[212:215], v[6:9]
	v_mfma_f32_16x16x32_bf16 v[2:5], v[176:179], v[212:215], v[2:5]
	s_barrier
	s_setprio 0
	s_add_i32 s53, s53, 2
	s_add_u32 s51, s51, 0x100
	s_addc_u32 s52, s52, 0
	s_cmp_gt_u32 s53, 13
	s_mov_b64 s[22:23], s[24:25]
	s_cbranch_scc0 .LBB0_457
	s_and_b64 vcc, exec, s[10:11]
	s_cbranch_vccz .LBB0_460
	s_barrier

; #define PG8_STAGE(bufoff, gbase, voff) do { _Pragma("unroll") for (int _i = 0; _i < 2; ++_i) \
;         __builtin_amdgcn_global_load_lds((const unsigned*)((const char*)(gbase) + (voff)[_i]), (PG8_LAS unsigned*)(lds + (bufoff) + ldsw + _i * 8192), 16, 0, 0); } while (0)
; #define PG8_LDA(dst, b, h) do { _Pragma("unroll") for (int m = 0; m < 4; ++m) _Pragma("unroll") for (int k = 0; k < 2; ++k) dst[m][k] = *(const PG8_LAS bf16x8*)(lds + PG8_SA(b, h) + aoff + m * 2048 + k * 1024); } while (0)
; #define PG8_LDB(dst, b, h) do { _Pragma("unroll") for (int n = 0; n < 2; ++n) _Pragma("unroll") for (int k = 0; k < 2; ++k) dst[n][k] = *(const PG8_LAS bf16x8*)(lds + PG8_SB(b, h) + boff + n * 2048 + k * 1024); } while (0)
; #define PG8_MMA(ai, bj, At, Bt) do { __builtin_amdgcn_s_setprio(1); _Pragma("unroll") for (int m = 0; m < 4; ++m) _Pragma("unroll") for (int n = 0; n < 2; ++n) _Pragma("unroll") for (int k = 0; k < 2; ++k) \
;         acc[ai][bj][m][n] = __builtin_amdgcn_mfma_f32_16x16x32_bf16(Bt[n][k], At[m][k], acc[ai][bj][m][n], 0, 0, 0); __builtin_amdgcn_s_setprio(0); } while (0)
; #define PG8_WAIT_V(n) asm volatile("s_waitcnt vmcnt(" #n ")" ::: "memory")
; #define PG8_WAIT_L(n) asm volatile("s_waitcnt lgkmcnt(" #n ")" ::: "memory")
; #define PG8_BAR __builtin_amdgcn_s_barrier()
; #define PG8_SCHED __builtin_amdgcn_sched_barrier(0)
; template <class Epi, class Sched, bool ALIGN_EPI = false, bool SP2 = false>
; __device__ __forceinline__ void gemm_phase(PG8_LAS unsigned char* lds, const Gemm g, const Sched& S, const Epi& E) {
;     ...
;             const bool last = (t == nt - 2);
;             const char* a1 = cA + (size_t)(t + 1) * kstep;
;             const char* a2 = last ? nA : cA + (size_t)(t + 2) * kstep; const char* b2 = last ? nB : cB + (size_t)(t + 2) * kstep;
;             const char* a3 = a2 + kstep; const char* b3 = b2 + kstep;
;             if (last && has_next) S.a_ready(nxt);
;             if constexpr (SP2) {
;             PG8_LDB(B0, 0, 0); PG8_LDB(B1, 0, 1); PG8_SCHED; PG8_LDA(At, 0, 0); PG8_STAGE(PG8_SA(1, 1), a1 + hstep, voffA);
;             PG8_WAIT_V(8); PG8_WAIT_L(0); PG8_BAR; PG8_MMA(0, 0, At, B0); PG8_MMA(0, 1, At, B1); PG8_BAR; PG8_SCHED;
;             PG8_LDA(At, 0, 1); PG8_STAGE(PG8_SB(0, 0), b2, voffB); PG8_STAGE(PG8_SB(0, 1), b2 + hstep, voffB); PG8_STAGE(PG8_SA(0, 0), a2, voffA);
.LBB0_713:
	ds_read_b128 v[162:165], v159
	ds_read_b128 v[166:169], v159 offset:1024
	ds_read_b128 v[170:173], v159 offset:2048
	ds_read_b128 v[174:177], v159 offset:3072
	ds_read_b128 v[178:181], v160
	ds_read_b128 v[182:185], v160 offset:1024
	ds_read_b128 v[188:191], v160 offset:2048
	ds_read_b128 v[192:195], v160 offset:3072
	s_add_i32 s66, s36, 2
	s_add_u32 s67, s34, 0x80
	s_addc_u32 s37, s35, 0
	s_cmp_eq_u32 s52, s36
	s_cselect_b32 s36, s4, s67
	s_cselect_b32 s37, s5, s37
	s_cselect_b32 s69, s31, s65
	s_cselect_b32 s68, s30, s63
	v_lshl_add_u64 v[156:157], s[34:35], 0, v[146:147]
	s_add_i32 m0, s42, 0xc000
	ds_read_b128 v[196:199], v161
	ds_read_b128 v[200:203], v161 offset:1024
	ds_read_b128 v[204:207], v161 offset:2048
	ds_read_b128 v[208:211], v161 offset:3072
	ds_read_b128 v[212:215], v161 offset:4096
	ds_read_b128 v[216:219], v161 offset:5120
	ds_read_b128 v[220:223], v161 offset:6144
	ds_read_b128 v[224:227], v161 offset:7168
	global_load_lds_dwordx4 v[156:157], off
	v_lshl_add_u64 v[156:157], s[34:35], 0, v[148:149]
	s_add_i32 m0, s42, 0xe000
	s_nop 0
	global_load_lds_dwordx4 v[156:157], off
	s_waitcnt vmcnt(8)
	s_waitcnt lgkmcnt(0)
	s_barrier
	s_setprio 1
	s_waitcnt lgkmcnt(0)
	v_mfma_f32_16x16x32_bf16 v[126:129], v[162:165], v[196:199], v[126:129]
	v_mfma_f32_16x16x32_bf16 v[122:125], v[170:173], v[196:199], v[122:125]
	v_mfma_f32_16x16x32_bf16 v[110:113], v[162:165], v[204:207], v[110:113]
	v_mfma_f32_16x16x32_bf16 v[106:109], v[170:173], v[204:207], v[106:109]
	v_mfma_f32_16x16x32_bf16 v[94:97], v[162:165], v[212:215], v[94:97]
	v_mfma_f32_16x16x32_bf16 v[90:93], v[170:173], v[212:215], v[90:93]
	v_mfma_f32_16x16x32_bf16 v[78:81], v[162:165], v[220:223], v[78:81]
	v_mfma_f32_16x16x32_bf16 v[74:77], v[170:173], v[220:223], v[74:77]
	v_mfma_f32_16x16x32_bf16 v[126:129], v[166:169], v[200:203], v[126:129]
	v_mfma_f32_16x16x32_bf16 v[122:125], v[174:177], v[200:203], v[122:125]
	v_mfma_f32_16x16x32_bf16 v[110:113], v[166:169], v[208:211], v[110:113]
	v_mfma_f32_16x16x32_bf16 v[106:109], v[174:177], v[208:211], v[106:109]
	v_mfma_f32_16x16x32_bf16 v[94:97], v[166:169], v[216:219], v[94:97]
	v_mfma_f32_16x16x32_bf16 v[90:93], v[174:177], v[216:219], v[90:93]
	v_mfma_f32_16x16x32_bf16 v[78:81], v[166:169], v[224:227], v[78:81]
	v_mfma_f32_16x16x32_bf16 v[74:77], v[174:177], v[224:227], v[74:77]
	s_setprio 0
	s_setprio 1
	v_mfma_f32_16x16x32_bf16 v[118:121], v[178:181], v[196:199], v[118:121]
	v_mfma_f32_16x16x32_bf16 v[114:117], v[188:191], v[196:199], v[114:117]
	v_mfma_f32_16x16x32_bf16 v[102:105], v[178:181], v[204:207], v[102:105]
	v_mfma_f32_16x16x32_bf16 v[98:101], v[188:191], v[204:207], v[98:101]
	v_mfma_f32_16x16x32_bf16 v[86:89], v[178:181], v[212:215], v[86:89]
	v_mfma_f32_16x16x32_bf16 v[82:85], v[188:191], v[212:215], v[82:85]
	v_mfma_f32_16x16x32_bf16 v[70:73], v[178:181], v[220:223], v[70:73]
	v_mfma_f32_16x16x32_bf16 v[66:69], v[188:191], v[220:223], v[66:69]
	v_mfma_f32_16x16x32_bf16 v[118:121], v[182:185], v[200:203], v[118:121]
	v_mfma_f32_16x16x32_bf16 v[114:117], v[192:195], v[200:203], v[114:117]
	v_mfma_f32_16x16x32_bf16 v[102:105], v[182:185], v[208:211], v[102:105]
	v_mfma_f32_16x16x32_bf16 v[98:101], v[192:195], v[208:211], v[98:101]
	v_mfma_f32_16x16x32_bf16 v[86:89], v[182:185], v[216:219], v[86:89]
	v_mfma_f32_16x16x32_bf16 v[82:85], v[192:195], v[216:219], v[82:85]
	v_mfma_f32_16x16x32_bf16 v[70:73], v[182:185], v[224:227], v[70:73]
	v_mfma_f32_16x16x32_bf16 v[66:69], v[192:195], v[224:227], v[66:69]
	s_barrier
	s_setprio 0
	s_add_i32 s67, s55, s40
	v_lshl_add_u64 v[156:157], s[68:69], 0, v[134:135]
	s_mov_b32 m0, s67
	ds_read_b128 v[196:199], v161 offset:16384
	ds_read_b128 v[200:203], v161 offset:17408
	ds_read_b128 v[204:207], v161 offset:18432
	ds_read_b128 v[208:211], v161 offset:19456
	ds_read_b128 v[212:215], v161 offset:20480
	ds_read_b128 v[216:219], v161 offset:21504
	ds_read_b128 v[220:223], v161 offset:22528
	ds_read_b128 v[224:227], v161 offset:23552
	global_load_lds_dwordx4 v[156:157], off
	s_add_i32 m0, s67, 0x2000
	v_lshl_add_u64 v[228:229], s[68:69], 0, v[130:131]
	s_add_u32 s68, s68, s6
	s_addc_u32 s69, s69, s7
	s_add_i32 s67, s56, s40
	global_load_lds_dwordx4 v[228:229], off
	v_lshl_add_u64 v[230:231], s[68:69], 0, v[134:135]
	s_mov_b32 m0, s67
	v_lshl_add_u64 v[232:233], s[68:69], 0, v[130:131]
	global_load_lds_dwordx4 v[230:231], off
	s_add_i32 m0, s67, 0x2000
	v_lshl_add_u64 v[234:235], s[36:37], 0, v[136:137]
	global_load_lds_dwordx4 v[232:233], off
	s_mov_b32 m0, s42
	v_lshl_add_u64 v[236:237], s[36:37], 0, v[132:133]
	global_load_lds_dwordx4 v[234:235], off
	s_mov_b32 m0, s43
	s_nop 0
	global_load_lds_dwordx4 v[236:237], off
	s_waitcnt vmcnt(8)
	s_waitcnt lgkmcnt(0)
	s_barrier
; #define PG8_STAGE(bufoff, gbase, voff) do { _Pragma("unroll") for (int _i = 0; _i < 2; ++_i) \
;         __builtin_amdgcn_global_load_lds((const unsigned*)((const char*)(gbase) + (voff)[_i]), (PG8_LAS unsigned*)(lds + (bufoff) + ldsw + _i * 8192), 16, 0, 0); } while (0)
; #define PG8_LDA(dst, b, h) do { _Pragma("unroll") for (int m = 0; m < 4; ++m) _Pragma("unroll") for (int k = 0; k < 2; ++k) dst[m][k] = *(const PG8_LAS bf16x8*)(lds + PG8_SA(b, h) + aoff + m * 2048 + k * 1024); } while (0)
; #define PG8_LDB(dst, b, h) do { _Pragma("unroll") for (int n = 0; n < 2; ++n) _Pragma("unroll") for (int k = 0; k < 2; ++k) dst[n][k] = *(const PG8_LAS bf16x8*)(lds + PG8_SB(b, h) + boff + n * 2048 + k * 1024); } while (0)
; #define PG8_MMA(ai, bj, At, Bt) do { __builtin_amdgcn_s_setprio(1); _Pragma("unroll") for (int m = 0; m < 4; ++m) _Pragma("unroll") for (int n = 0; n < 2; ++n) _Pragma("unroll") for (int k = 0; k < 2; ++k) \
;         acc[ai][bj][m][n] = __builtin_amdgcn_mfma_f32_16x16x32_bf16(Bt[n][k], At[m][k], acc[ai][bj][m][n], 0, 0, 0); __builtin_amdgcn_s_setprio(0); } while (0)
; #define PG8_WAIT_V(n) asm volatile("s_waitcnt vmcnt(" #n ")" ::: "memory")
; #define PG8_WAIT_L(n) asm volatile("s_waitcnt lgkmcnt(" #n ")" ::: "memory")
; #define PG8_BAR __builtin_amdgcn_s_barrier()
; #define PG8_SCHED __builtin_amdgcn_sched_barrier(0)
; template <class Epi, class Sched, bool ALIGN_EPI = false, bool SP2 = false>
; __device__ __forceinline__ void gemm_phase(PG8_LAS unsigned char* lds, const Gemm g, const Sched& S, const Epi& E) {
;     ...
;             PG8_WAIT_V(8); PG8_WAIT_L(0); PG8_BAR; PG8_MMA(1, 0, At, B0); PG8_MMA(1, 1, At, B1); PG8_BAR; PG8_SCHED;
;             PG8_LDB(B0, 1, 0); PG8_LDB(B1, 1, 1); PG8_SCHED; PG8_LDA(At, 1, 0); PG8_STAGE(PG8_SA(0, 1), a2 + hstep, voffA);
;             PG8_WAIT_V(8); PG8_WAIT_L(0); PG8_BAR; PG8_MMA(0, 0, At, B0); PG8_MMA(0, 1, At, B1); PG8_BAR; PG8_SCHED;
	s_setprio 1
	s_waitcnt lgkmcnt(0)
	v_mfma_f32_16x16x32_bf16 v[62:65], v[162:165], v[196:199], v[62:65]
	v_mfma_f32_16x16x32_bf16 v[58:61], v[170:173], v[196:199], v[58:61]
	v_mfma_f32_16x16x32_bf16 v[46:49], v[162:165], v[204:207], v[46:49]
	v_mfma_f32_16x16x32_bf16 v[42:45], v[170:173], v[204:207], v[42:45]
	v_mfma_f32_16x16x32_bf16 v[30:33], v[162:165], v[212:215], v[30:33]
	v_mfma_f32_16x16x32_bf16 v[26:29], v[170:173], v[212:215], v[26:29]
	v_mfma_f32_16x16x32_bf16 v[14:17], v[162:165], v[220:223], v[14:17]
	v_mfma_f32_16x16x32_bf16 v[10:13], v[170:173], v[220:223], v[10:13]
	v_mfma_f32_16x16x32_bf16 v[62:65], v[166:169], v[200:203], v[62:65]
	v_mfma_f32_16x16x32_bf16 v[58:61], v[174:177], v[200:203], v[58:61]
	v_mfma_f32_16x16x32_bf16 v[46:49], v[166:169], v[208:211], v[46:49]
	v_mfma_f32_16x16x32_bf16 v[42:45], v[174:177], v[208:211], v[42:45]
	v_mfma_f32_16x16x32_bf16 v[30:33], v[166:169], v[216:219], v[30:33]
	v_mfma_f32_16x16x32_bf16 v[26:29], v[174:177], v[216:219], v[26:29]
	v_mfma_f32_16x16x32_bf16 v[14:17], v[166:169], v[224:227], v[14:17]
	v_mfma_f32_16x16x32_bf16 v[10:13], v[174:177], v[224:227], v[10:13]
	s_setprio 0
	s_setprio 1
	v_mfma_f32_16x16x32_bf16 v[54:57], v[178:181], v[196:199], v[54:57]
	v_mfma_f32_16x16x32_bf16 v[50:53], v[188:191], v[196:199], v[50:53]
	v_mfma_f32_16x16x32_bf16 v[38:41], v[178:181], v[204:207], v[38:41]
	v_mfma_f32_16x16x32_bf16 v[34:37], v[188:191], v[204:207], v[34:37]
	v_mfma_f32_16x16x32_bf16 v[22:25], v[178:181], v[212:215], v[22:25]
	v_mfma_f32_16x16x32_bf16 v[18:21], v[188:191], v[212:215], v[18:21]
	v_mfma_f32_16x16x32_bf16 v[6:9], v[178:181], v[220:223], v[6:9]
	v_mfma_f32_16x16x32_bf16 v[2:5], v[188:191], v[220:223], v[2:5]
	v_mfma_f32_16x16x32_bf16 v[54:57], v[182:185], v[200:203], v[54:57]
	v_mfma_f32_16x16x32_bf16 v[50:53], v[192:195], v[200:203], v[50:53]
	v_mfma_f32_16x16x32_bf16 v[38:41], v[182:185], v[208:211], v[38:41]
	v_mfma_f32_16x16x32_bf16 v[34:37], v[192:195], v[208:211], v[34:37]
	v_mfma_f32_16x16x32_bf16 v[22:25], v[182:185], v[216:219], v[22:25]
	v_mfma_f32_16x16x32_bf16 v[18:21], v[192:195], v[216:219], v[18:21]
	v_mfma_f32_16x16x32_bf16 v[6:9], v[182:185], v[224:227], v[6:9]
	v_mfma_f32_16x16x32_bf16 v[2:5], v[192:195], v[224:227], v[2:5]
	s_barrier
	s_setprio 0
	s_add_i32 s67, 0, 0x18000
	v_add_u32_e32 v138, s67, v158
	s_add_i32 s68, 0, 0x1c000
	ds_read_b128 v[162:165], v138
	ds_read_b128 v[166:169], v138 offset:1024
	ds_read_b128 v[170:173], v138 offset:2048
	ds_read_b128 v[174:177], v138 offset:3072
	v_add_u32_e32 v138, s68, v158
	ds_read_b128 v[178:181], v138
	ds_read_b128 v[182:185], v138 offset:1024
	ds_read_b128 v[188:191], v138 offset:2048
	ds_read_b128 v[192:195], v138 offset:3072
	s_add_u32 s36, s36, s6
	s_addc_u32 s37, s37, s7
	s_mov_b32 m0, s48
	v_lshl_add_u64 v[238:239], s[36:37], 0, v[136:137]
	ds_read_b128 v[196:199], v161 offset:32768
	ds_read_b128 v[200:203], v161 offset:33792
	ds_read_b128 v[204:207], v161 offset:34816
	ds_read_b128 v[208:211], v161 offset:35840
	ds_read_b128 v[212:215], v161 offset:36864
	ds_read_b128 v[216:219], v161 offset:37888
	ds_read_b128 v[220:223], v161 offset:38912
	ds_read_b128 v[224:227], v161 offset:39936
	global_load_lds_dwordx4 v[238:239], off
	v_lshl_add_u64 v[238:239], s[36:37], 0, v[132:133]
	s_mov_b32 m0, s49
	s_nop 0
	global_load_lds_dwordx4 v[238:239], off
	s_waitcnt vmcnt(8)
	s_waitcnt lgkmcnt(0)
	s_barrier
	s_setprio 1
	s_waitcnt lgkmcnt(0)
	v_mfma_f32_16x16x32_bf16 v[126:129], v[162:165], v[196:199], v[126:129]
	v_mfma_f32_16x16x32_bf16 v[122:125], v[170:173], v[196:199], v[122:125]
	v_mfma_f32_16x16x32_bf16 v[110:113], v[162:165], v[204:207], v[110:113]
	v_mfma_f32_16x16x32_bf16 v[106:109], v[170:173], v[204:207], v[106:109]
	v_mfma_f32_16x16x32_bf16 v[94:97], v[162:165], v[212:215], v[94:97]
	v_mfma_f32_16x16x32_bf16 v[90:93], v[170:173], v[212:215], v[90:93]
	v_mfma_f32_16x16x32_bf16 v[78:81], v[162:165], v[220:223], v[78:81]
	v_mfma_f32_16x16x32_bf16 v[74:77], v[170:173], v[220:223], v[74:77]
	v_mfma_f32_16x16x32_bf16 v[126:129], v[166:169], v[200:203], v[126:129]
	v_mfma_f32_16x16x32_bf16 v[122:125], v[174:177], v[200:203], v[122:125]
	v_mfma_f32_16x16x32_bf16 v[110:113], v[166:169], v[208:211], v[110:113]
	v_mfma_f32_16x16x32_bf16 v[106:109], v[174:177], v[208:211], v[106:109]
	v_mfma_f32_16x16x32_bf16 v[94:97], v[166:169], v[216:219], v[94:97]
	v_mfma_f32_16x16x32_bf16 v[90:93], v[174:177], v[216:219], v[90:93]
	v_mfma_f32_16x16x32_bf16 v[78:81], v[166:169], v[224:227], v[78:81]
	v_mfma_f32_16x16x32_bf16 v[74:77], v[174:177], v[224:227], v[74:77]
	s_setprio 0
	s_setprio 1
	v_mfma_f32_16x16x32_bf16 v[118:121], v[178:181], v[196:199], v[118:121]
	v_mfma_f32_16x16x32_bf16 v[114:117], v[188:191], v[196:199], v[114:117]
	v_mfma_f32_16x16x32_bf16 v[102:105], v[178:181], v[204:207], v[102:105]
	v_mfma_f32_16x16x32_bf16 v[98:101], v[188:191], v[204:207], v[98:101]
	v_mfma_f32_16x16x32_bf16 v[86:89], v[178:181], v[212:215], v[86:89]
	v_mfma_f32_16x16x32_bf16 v[82:85], v[188:191], v[212:215], v[82:85]
	v_mfma_f32_16x16x32_bf16 v[70:73], v[178:181], v[220:223], v[70:73]
	v_mfma_f32_16x16x32_bf16 v[66:69], v[188:191], v[220:223], v[66:69]
	v_mfma_f32_16x16x32_bf16 v[118:121], v[182:185], v[200:203], v[118:121]
	v_mfma_f32_16x16x32_bf16 v[114:117], v[192:195], v[200:203], v[114:117]
	v_mfma_f32_16x16x32_bf16 v[102:105], v[182:185], v[208:211], v[102:105]
	v_mfma_f32_16x16x32_bf16 v[98:101], v[192:195], v[208:211], v[98:101]
	v_mfma_f32_16x16x32_bf16 v[86:89], v[182:185], v[216:219], v[86:89]
	v_mfma_f32_16x16x32_bf16 v[82:85], v[192:195], v[216:219], v[82:85]
	v_mfma_f32_16x16x32_bf16 v[70:73], v[182:185], v[224:227], v[70:73]
	v_mfma_f32_16x16x32_bf16 v[66:69], v[192:195], v[224:227], v[66:69]
	s_barrier
; #define PG8_STAGE(bufoff, gbase, voff) do { _Pragma("unroll") for (int _i = 0; _i < 2; ++_i) \
;         __builtin_amdgcn_global_load_lds((const unsigned*)((const char*)(gbase) + (voff)[_i]), (PG8_LAS unsigned*)(lds + (bufoff) + ldsw + _i * 8192), 16, 0, 0); } while (0)
; #define PG8_LDA(dst, b, h) do { _Pragma("unroll") for (int m = 0; m < 4; ++m) _Pragma("unroll") for (int k = 0; k < 2; ++k) dst[m][k] = *(const PG8_LAS bf16x8*)(lds + PG8_SA(b, h) + aoff + m * 2048 + k * 1024); } while (0)
; #define PG8_MMA(ai, bj, At, Bt) do { __builtin_amdgcn_s_setprio(1); _Pragma("unroll") for (int m = 0; m < 4; ++m) _Pragma("unroll") for (int n = 0; n < 2; ++n) _Pragma("unroll") for (int k = 0; k < 2; ++k) \
;         acc[ai][bj][m][n] = __builtin_amdgcn_mfma_f32_16x16x32_bf16(Bt[n][k], At[m][k], acc[ai][bj][m][n], 0, 0, 0); __builtin_amdgcn_s_setprio(0); } while (0)
; #define PG8_WAIT_V(n) asm volatile("s_waitcnt vmcnt(" #n ")" ::: "memory")
; #define PG8_WAIT_L(n) asm volatile("s_waitcnt lgkmcnt(" #n ")" ::: "memory")
; #define PG8_BAR __builtin_amdgcn_s_barrier()
; #define PG8_SCHED __builtin_amdgcn_sched_barrier(0)
; template <class Epi, class Sched, bool ALIGN_EPI = false, bool SP2 = false>
; __device__ __forceinline__ void gemm_phase(PG8_LAS unsigned char* lds, const Gemm g, const Sched& S, const Epi& E) {
;     ...
;             PG8_LDA(At, 1, 1); PG8_STAGE(PG8_SB(1, 0), b3, voffB); PG8_STAGE(PG8_SB(1, 1), b3 + hstep, voffB); PG8_STAGE(PG8_SA(1, 0), a3, voffA);
;             PG8_WAIT_V(8); PG8_WAIT_L(0); PG8_BAR; PG8_MMA(1, 0, At, B0); PG8_MMA(1, 1, At, B1); PG8_BAR; PG8_SCHED;
	s_setprio 0
	s_add_i32 s36, s67, s40
	v_lshl_add_u64 v[156:157], v[156:157], 0, s[22:23]
	s_mov_b32 m0, s36
	ds_read_b128 v[196:199], v161 offset:49152
	ds_read_b128 v[200:203], v161 offset:50176
	ds_read_b128 v[204:207], v161 offset:51200
	ds_read_b128 v[208:211], v161 offset:52224
	ds_read_b128 v[212:215], v161 offset:53248
	ds_read_b128 v[216:219], v161 offset:54272
	ds_read_b128 v[220:223], v161 offset:55296
	ds_read_b128 v[224:227], v161 offset:56320
	global_load_lds_dwordx4 v[156:157], off
	v_lshl_add_u64 v[156:157], v[228:229], 0, s[22:23]
	s_add_i32 m0, s36, 0x2000
	s_add_i32 s36, s68, s40
	global_load_lds_dwordx4 v[156:157], off
	v_lshl_add_u64 v[156:157], v[230:231], 0, s[22:23]
	s_mov_b32 m0, s36
	s_nop 0
	global_load_lds_dwordx4 v[156:157], off
	v_lshl_add_u64 v[156:157], v[232:233], 0, s[22:23]
	s_add_i32 m0, s36, 0x2000
	s_nop 0
	global_load_lds_dwordx4 v[156:157], off
	v_lshl_add_u64 v[156:157], v[234:235], 0, s[22:23]
	s_mov_b32 m0, s50
	s_nop 0
	global_load_lds_dwordx4 v[156:157], off
	v_lshl_add_u64 v[156:157], v[236:237], 0, s[22:23]
	s_mov_b32 m0, s51
	s_nop 0
	global_load_lds_dwordx4 v[156:157], off
	s_waitcnt vmcnt(8)
	s_waitcnt lgkmcnt(0)
	s_barrier
	s_setprio 1
	s_waitcnt lgkmcnt(0)
	v_mfma_f32_16x16x32_bf16 v[62:65], v[162:165], v[196:199], v[62:65]
	v_mfma_f32_16x16x32_bf16 v[58:61], v[170:173], v[196:199], v[58:61]
	v_mfma_f32_16x16x32_bf16 v[46:49], v[162:165], v[204:207], v[46:49]
	v_mfma_f32_16x16x32_bf16 v[42:45], v[170:173], v[204:207], v[42:45]
	v_mfma_f32_16x16x32_bf16 v[30:33], v[162:165], v[212:215], v[30:33]
	v_mfma_f32_16x16x32_bf16 v[26:29], v[170:173], v[212:215], v[26:29]
	v_mfma_f32_16x16x32_bf16 v[14:17], v[162:165], v[220:223], v[14:17]
	v_mfma_f32_16x16x32_bf16 v[10:13], v[170:173], v[220:223], v[10:13]
	v_mfma_f32_16x16x32_bf16 v[62:65], v[166:169], v[200:203], v[62:65]
	v_mfma_f32_16x16x32_bf16 v[58:61], v[174:177], v[200:203], v[58:61]
	v_mfma_f32_16x16x32_bf16 v[46:49], v[166:169], v[208:211], v[46:49]
	v_mfma_f32_16x16x32_bf16 v[42:45], v[174:177], v[208:211], v[42:45]
	v_mfma_f32_16x16x32_bf16 v[30:33], v[166:169], v[216:219], v[30:33]
	v_mfma_f32_16x16x32_bf16 v[26:29], v[174:177], v[216:219], v[26:29]
	v_mfma_f32_16x16x32_bf16 v[14:17], v[166:169], v[224:227], v[14:17]
	v_mfma_f32_16x16x32_bf16 v[10:13], v[174:177], v[224:227], v[10:13]
	s_setprio 0
	s_setprio 1
	v_mfma_f32_16x16x32_bf16 v[54:57], v[178:181], v[196:199], v[54:57]
	v_mfma_f32_16x16x32_bf16 v[50:53], v[188:191], v[196:199], v[50:53]
	v_mfma_f32_16x16x32_bf16 v[38:41], v[178:181], v[204:207], v[38:41]
	v_mfma_f32_16x16x32_bf16 v[34:37], v[188:191], v[204:207], v[34:37]
	v_mfma_f32_16x16x32_bf16 v[22:25], v[178:181], v[212:215], v[22:25]
	v_mfma_f32_16x16x32_bf16 v[18:21], v[188:191], v[212:215], v[18:21]
	v_mfma_f32_16x16x32_bf16 v[6:9], v[178:181], v[220:223], v[6:9]
	v_mfma_f32_16x16x32_bf16 v[2:5], v[188:191], v[220:223], v[2:5]
	v_mfma_f32_16x16x32_bf16 v[54:57], v[182:185], v[200:203], v[54:57]
	v_mfma_f32_16x16x32_bf16 v[50:53], v[192:195], v[200:203], v[50:53]
	v_mfma_f32_16x16x32_bf16 v[38:41], v[182:185], v[208:211], v[38:41]
	v_mfma_f32_16x16x32_bf16 v[34:37], v[192:195], v[208:211], v[34:37]
	v_mfma_f32_16x16x32_bf16 v[22:25], v[182:185], v[216:219], v[22:25]
	v_mfma_f32_16x16x32_bf16 v[18:21], v[192:195], v[216:219], v[18:21]
	v_mfma_f32_16x16x32_bf16 v[6:9], v[182:185], v[224:227], v[6:9]
	v_mfma_f32_16x16x32_bf16 v[2:5], v[192:195], v[224:227], v[2:5]
	s_barrier
	s_setprio 0
	s_add_u32 s34, s34, 0x100
	s_addc_u32 s35, s35, 0
	s_add_u32 s63, s63, 0x100
	s_addc_u32 s65, s65, 0
	s_cmp_ge_i32 s66, s0
	s_mov_b32 s36, s66
	s_cbranch_scc0 .LBB0_713

; #define PG8_STAGE(bufoff, gbase, voff) do { _Pragma("unroll") for (int _i = 0; _i < 2; ++_i) \
;         __builtin_amdgcn_global_load_lds((const unsigned*)((const char*)(gbase) + (voff)[_i]), (PG8_LAS unsigned*)(lds + (bufoff) + ldsw + _i * 8192), 16, 0, 0); } while (0)
; #define PG8_LDA(dst, b, h) do { _Pragma("unroll") for (int m = 0; m < 4; ++m) _Pragma("unroll") for (int k = 0; k < 2; ++k) dst[m][k] = *(const PG8_LAS bf16x8*)(lds + PG8_SA(b, h) + aoff + m * 2048 + k * 1024); } while (0)
; #define PG8_LDB(dst, b, h) do { _Pragma("unroll") for (int n = 0; n < 2; ++n) _Pragma("unroll") for (int k = 0; k < 2; ++k) dst[n][k] = *(const PG8_LAS bf16x8*)(lds + PG8_SB(b, h) + boff + n * 2048 + k * 1024); } while (0)
; #define PG8_MMA(ai, bj, At, Bt) do { __builtin_amdgcn_s_setprio(1); _Pragma("unroll") for (int m = 0; m < 4; ++m) _Pragma("unroll") for (int n = 0; n < 2; ++n) _Pragma("unroll") for (int k = 0; k < 2; ++k) \
;         acc[ai][bj][m][n] = __builtin_amdgcn_mfma_f32_16x16x32_bf16(Bt[n][k], At[m][k], acc[ai][bj][m][n], 0, 0, 0); __builtin_amdgcn_s_setprio(0); } while (0)
; #define PG8_WAIT_V(n) asm volatile("s_waitcnt vmcnt(" #n ")" ::: "memory")
; #define PG8_WAIT_L(n) asm volatile("s_waitcnt lgkmcnt(" #n ")" ::: "memory")
; #define PG8_BAR __builtin_amdgcn_s_barrier()
; #define PG8_SCHED __builtin_amdgcn_sched_barrier(0)
; template <class Epi, class Sched, bool ALIGN_EPI = false, bool SP2 = false>
; __device__ __forceinline__ void gemm_phase(PG8_LAS unsigned char* lds, const Gemm g, const Sched& S, const Epi& E) {
;     ...
;             const bool last = (t == nt - 2);
;             const char* a1 = cA + (size_t)(t + 1) * kstep;
;             const char* a2 = last ? nA : cA + (size_t)(t + 2) * kstep; const char* b2 = last ? nB : cB + (size_t)(t + 2) * kstep;
;             const char* a3 = a2 + kstep; const char* b3 = b2 + kstep;
;             if (last && has_next) S.a_ready(nxt);
;             if constexpr (SP2) {
;             PG8_LDB(B0, 0, 0); PG8_LDB(B1, 0, 1); PG8_SCHED; PG8_LDA(At, 0, 0); PG8_STAGE(PG8_SA(1, 1), a1 + hstep, voffA);
;             PG8_WAIT_V(8); PG8_WAIT_L(0); PG8_BAR; PG8_MMA(0, 0, At, B0); PG8_MMA(0, 1, At, B1); PG8_BAR; PG8_SCHED;
;             PG8_LDA(At, 0, 1); PG8_STAGE(PG8_SB(0, 0), b2, voffB); PG8_STAGE(PG8_SB(0, 1), b2 + hstep, voffB); PG8_STAGE(PG8_SA(0, 0), a2, voffA);
.LBB0_738:
	ds_read_b128 v[160:163], v156
	ds_read_b128 v[164:167], v156 offset:1024
	ds_read_b128 v[168:171], v156 offset:2048
	ds_read_b128 v[172:175], v156 offset:3072
	ds_read_b128 v[176:179], v157
	ds_read_b128 v[180:183], v157 offset:1024
	ds_read_b128 v[188:191], v157 offset:2048
	ds_read_b128 v[192:195], v157 offset:3072
	s_add_i32 s71, s36, 2
	s_add_u32 s72, s34, 0x80
	s_addc_u32 s37, s35, 0
	s_cmp_eq_u32 s52, s36
	s_cselect_b32 s36, s14, s72
	s_cselect_b32 s37, s15, s37
	s_cselect_b32 s73, s31, s70
	s_cselect_b32 s72, s30, s69
	v_lshl_add_u64 v[152:153], s[34:35], 0, v[146:147]
	s_add_i32 m0, s42, 0xc000
	ds_read_b128 v[196:199], v158
	ds_read_b128 v[200:203], v158 offset:1024
	ds_read_b128 v[204:207], v158 offset:2048
	ds_read_b128 v[208:211], v158 offset:3072
	ds_read_b128 v[212:215], v158 offset:4096
	ds_read_b128 v[216:219], v158 offset:5120
	ds_read_b128 v[220:223], v158 offset:6144
	ds_read_b128 v[224:227], v158 offset:7168
	global_load_lds_dwordx4 v[152:153], off
	v_lshl_add_u64 v[152:153], s[34:35], 0, v[148:149]
	s_add_i32 m0, s42, 0xe000
	s_nop 0
	global_load_lds_dwordx4 v[152:153], off
	s_waitcnt vmcnt(8)
	s_waitcnt lgkmcnt(0)
	s_barrier
	s_setprio 1
	s_waitcnt lgkmcnt(0)
	v_mfma_f32_16x16x32_bf16 v[126:129], v[160:163], v[196:199], v[126:129]
	v_mfma_f32_16x16x32_bf16 v[122:125], v[168:171], v[196:199], v[122:125]
	v_mfma_f32_16x16x32_bf16 v[110:113], v[160:163], v[204:207], v[110:113]
	v_mfma_f32_16x16x32_bf16 v[106:109], v[168:171], v[204:207], v[106:109]
	v_mfma_f32_16x16x32_bf16 v[94:97], v[160:163], v[212:215], v[94:97]
	v_mfma_f32_16x16x32_bf16 v[90:93], v[168:171], v[212:215], v[90:93]
	v_mfma_f32_16x16x32_bf16 v[78:81], v[160:163], v[220:223], v[78:81]
	v_mfma_f32_16x16x32_bf16 v[74:77], v[168:171], v[220:223], v[74:77]
	v_mfma_f32_16x16x32_bf16 v[126:129], v[164:167], v[200:203], v[126:129]
	v_mfma_f32_16x16x32_bf16 v[122:125], v[172:175], v[200:203], v[122:125]
	v_mfma_f32_16x16x32_bf16 v[110:113], v[164:167], v[208:211], v[110:113]
	v_mfma_f32_16x16x32_bf16 v[106:109], v[172:175], v[208:211], v[106:109]
	v_mfma_f32_16x16x32_bf16 v[94:97], v[164:167], v[216:219], v[94:97]
	v_mfma_f32_16x16x32_bf16 v[90:93], v[172:175], v[216:219], v[90:93]
	v_mfma_f32_16x16x32_bf16 v[78:81], v[164:167], v[224:227], v[78:81]
	v_mfma_f32_16x16x32_bf16 v[74:77], v[172:175], v[224:227], v[74:77]
	s_setprio 0
	s_setprio 1
	v_mfma_f32_16x16x32_bf16 v[118:121], v[176:179], v[196:199], v[118:121]
	v_mfma_f32_16x16x32_bf16 v[114:117], v[188:191], v[196:199], v[114:117]
	v_mfma_f32_16x16x32_bf16 v[102:105], v[176:179], v[204:207], v[102:105]
	v_mfma_f32_16x16x32_bf16 v[98:101], v[188:191], v[204:207], v[98:101]
	v_mfma_f32_16x16x32_bf16 v[86:89], v[176:179], v[212:215], v[86:89]
	v_mfma_f32_16x16x32_bf16 v[82:85], v[188:191], v[212:215], v[82:85]
	v_mfma_f32_16x16x32_bf16 v[70:73], v[176:179], v[220:223], v[70:73]
	v_mfma_f32_16x16x32_bf16 v[66:69], v[188:191], v[220:223], v[66:69]
	v_mfma_f32_16x16x32_bf16 v[118:121], v[180:183], v[200:203], v[118:121]
	v_mfma_f32_16x16x32_bf16 v[114:117], v[192:195], v[200:203], v[114:117]
	v_mfma_f32_16x16x32_bf16 v[102:105], v[180:183], v[208:211], v[102:105]
	v_mfma_f32_16x16x32_bf16 v[98:101], v[192:195], v[208:211], v[98:101]
	v_mfma_f32_16x16x32_bf16 v[86:89], v[180:183], v[216:219], v[86:89]
	v_mfma_f32_16x16x32_bf16 v[82:85], v[192:195], v[216:219], v[82:85]
	v_mfma_f32_16x16x32_bf16 v[70:73], v[180:183], v[224:227], v[70:73]
	v_mfma_f32_16x16x32_bf16 v[66:69], v[192:195], v[224:227], v[66:69]
	s_barrier
	s_setprio 0
	s_add_i32 s74, s13, s41
	v_lshl_add_u64 v[152:153], s[72:73], 0, v[134:135]
	s_mov_b32 m0, s74
	ds_read_b128 v[196:199], v158 offset:16384
	ds_read_b128 v[200:203], v158 offset:17408
	ds_read_b128 v[204:207], v158 offset:18432
	ds_read_b128 v[208:211], v158 offset:19456
	ds_read_b128 v[212:215], v158 offset:20480
	ds_read_b128 v[216:219], v158 offset:21504
	ds_read_b128 v[220:223], v158 offset:22528
	ds_read_b128 v[224:227], v158 offset:23552
	global_load_lds_dwordx4 v[152:153], off
	s_add_i32 m0, s74, 0x2000
	v_lshl_add_u64 v[184:185], s[72:73], 0, v[130:131]
	s_add_u32 s72, s72, s6
	s_addc_u32 s73, s73, s7
	s_add_i32 s74, s53, s41
	global_load_lds_dwordx4 v[184:185], off
	v_lshl_add_u64 v[228:229], s[72:73], 0, v[134:135]
	s_mov_b32 m0, s74
	v_lshl_add_u64 v[230:231], s[72:73], 0, v[130:131]
	global_load_lds_dwordx4 v[228:229], off
	s_add_i32 m0, s74, 0x2000
	v_lshl_add_u64 v[232:233], s[36:37], 0, v[136:137]
	global_load_lds_dwordx4 v[230:231], off
	s_mov_b32 m0, s42
	v_lshl_add_u64 v[234:235], s[36:37], 0, v[132:133]
	global_load_lds_dwordx4 v[232:233], off
	s_mov_b32 m0, s43
	s_nop 0
	global_load_lds_dwordx4 v[234:235], off
	s_waitcnt vmcnt(8)
	s_waitcnt lgkmcnt(0)
	s_barrier
; #define PG8_STAGE(bufoff, gbase, voff) do { _Pragma("unroll") for (int _i = 0; _i < 2; ++_i) \
;         __builtin_amdgcn_global_load_lds((const unsigned*)((const char*)(gbase) + (voff)[_i]), (PG8_LAS unsigned*)(lds + (bufoff) + ldsw + _i * 8192), 16, 0, 0); } while (0)
; #define PG8_LDA(dst, b, h) do { _Pragma("unroll") for (int m = 0; m < 4; ++m) _Pragma("unroll") for (int k = 0; k < 2; ++k) dst[m][k] = *(const PG8_LAS bf16x8*)(lds + PG8_SA(b, h) + aoff + m * 2048 + k * 1024); } while (0)
; #define PG8_LDB(dst, b, h) do { _Pragma("unroll") for (int n = 0; n < 2; ++n) _Pragma("unroll") for (int k = 0; k < 2; ++k) dst[n][k] = *(const PG8_LAS bf16x8*)(lds + PG8_SB(b, h) + boff + n * 2048 + k * 1024); } while (0)
; #define PG8_MMA(ai, bj, At, Bt) do { __builtin_amdgcn_s_setprio(1); _Pragma("unroll") for (int m = 0; m < 4; ++m) _Pragma("unroll") for (int n = 0; n < 2; ++n) _Pragma("unroll") for (int k = 0; k < 2; ++k) \
;         acc[ai][bj][m][n] = __builtin_amdgcn_mfma_f32_16x16x32_bf16(Bt[n][k], At[m][k], acc[ai][bj][m][n], 0, 0, 0); __builtin_amdgcn_s_setprio(0); } while (0)
; #define PG8_WAIT_V(n) asm volatile("s_waitcnt vmcnt(" #n ")" ::: "memory")
; #define PG8_WAIT_L(n) asm volatile("s_waitcnt lgkmcnt(" #n ")" ::: "memory")
; #define PG8_BAR __builtin_amdgcn_s_barrier()
; #define PG8_SCHED __builtin_amdgcn_sched_barrier(0)
; template <class Epi, class Sched, bool ALIGN_EPI = false, bool SP2 = false>
; __device__ __forceinline__ void gemm_phase(PG8_LAS unsigned char* lds, const Gemm g, const Sched& S, const Epi& E) {
;     ...
;             PG8_WAIT_V(8); PG8_WAIT_L(0); PG8_BAR; PG8_MMA(1, 0, At, B0); PG8_MMA(1, 1, At, B1); PG8_BAR; PG8_SCHED;
;             PG8_LDB(B0, 1, 0); PG8_LDB(B1, 1, 1); PG8_SCHED; PG8_LDA(At, 1, 0); PG8_STAGE(PG8_SA(0, 1), a2 + hstep, voffA);
;             PG8_WAIT_V(8); PG8_WAIT_L(0); PG8_BAR; PG8_MMA(0, 0, At, B0); PG8_MMA(0, 1, At, B1); PG8_BAR; PG8_SCHED;
;             PG8_LDA(At, 1, 1); PG8_STAGE(PG8_SB(1, 0), b3, voffB); PG8_STAGE(PG8_SB(1, 1), b3 + hstep, voffB); PG8_STAGE(PG8_SA(1, 0), a3, voffA);
;             PG8_WAIT_V(8); PG8_WAIT_L(0); PG8_BAR; PG8_MMA(1, 0, At, B0); PG8_MMA(1, 1, At, B1); PG8_BAR; PG8_SCHED;
	s_setprio 1
	s_waitcnt lgkmcnt(0)
	v_mfma_f32_16x16x32_bf16 v[62:65], v[160:163], v[196:199], v[62:65]
	v_mfma_f32_16x16x32_bf16 v[58:61], v[168:171], v[196:199], v[58:61]
	v_mfma_f32_16x16x32_bf16 v[46:49], v[160:163], v[204:207], v[46:49]
	v_mfma_f32_16x16x32_bf16 v[42:45], v[168:171], v[204:207], v[42:45]
	v_mfma_f32_16x16x32_bf16 v[30:33], v[160:163], v[212:215], v[30:33]
	v_mfma_f32_16x16x32_bf16 v[26:29], v[168:171], v[212:215], v[26:29]
	v_mfma_f32_16x16x32_bf16 v[14:17], v[160:163], v[220:223], v[14:17]
	v_mfma_f32_16x16x32_bf16 v[10:13], v[168:171], v[220:223], v[10:13]
	v_mfma_f32_16x16x32_bf16 v[62:65], v[164:167], v[200:203], v[62:65]
	v_mfma_f32_16x16x32_bf16 v[58:61], v[172:175], v[200:203], v[58:61]
	v_mfma_f32_16x16x32_bf16 v[46:49], v[164:167], v[208:211], v[46:49]
	v_mfma_f32_16x16x32_bf16 v[42:45], v[172:175], v[208:211], v[42:45]
	v_mfma_f32_16x16x32_bf16 v[30:33], v[164:167], v[216:219], v[30:33]
	v_mfma_f32_16x16x32_bf16 v[26:29], v[172:175], v[216:219], v[26:29]
	v_mfma_f32_16x16x32_bf16 v[14:17], v[164:167], v[224:227], v[14:17]
	v_mfma_f32_16x16x32_bf16 v[10:13], v[172:175], v[224:227], v[10:13]
	s_setprio 0
	s_setprio 1
	v_mfma_f32_16x16x32_bf16 v[54:57], v[176:179], v[196:199], v[54:57]
	v_mfma_f32_16x16x32_bf16 v[50:53], v[188:191], v[196:199], v[50:53]
	v_mfma_f32_16x16x32_bf16 v[38:41], v[176:179], v[204:207], v[38:41]
	v_mfma_f32_16x16x32_bf16 v[34:37], v[188:191], v[204:207], v[34:37]
	v_mfma_f32_16x16x32_bf16 v[22:25], v[176:179], v[212:215], v[22:25]
	v_mfma_f32_16x16x32_bf16 v[18:21], v[188:191], v[212:215], v[18:21]
	v_mfma_f32_16x16x32_bf16 v[6:9], v[176:179], v[220:223], v[6:9]
	v_mfma_f32_16x16x32_bf16 v[2:5], v[188:191], v[220:223], v[2:5]
	v_mfma_f32_16x16x32_bf16 v[54:57], v[180:183], v[200:203], v[54:57]
	v_mfma_f32_16x16x32_bf16 v[50:53], v[192:195], v[200:203], v[50:53]
	v_mfma_f32_16x16x32_bf16 v[38:41], v[180:183], v[208:211], v[38:41]
	v_mfma_f32_16x16x32_bf16 v[34:37], v[192:195], v[208:211], v[34:37]
	v_mfma_f32_16x16x32_bf16 v[22:25], v[180:183], v[216:219], v[22:25]
	v_mfma_f32_16x16x32_bf16 v[18:21], v[192:195], v[216:219], v[18:21]
	v_mfma_f32_16x16x32_bf16 v[6:9], v[180:183], v[224:227], v[6:9]
	v_mfma_f32_16x16x32_bf16 v[2:5], v[192:195], v[224:227], v[2:5]
	s_barrier
	s_setprio 0
	s_add_i32 s72, 0, 0x18000
	v_add_u32_e32 v138, s72, v154
	s_add_i32 s73, 0, 0x1c000
	ds_read_b128 v[160:163], v138
	ds_read_b128 v[164:167], v138 offset:1024
	ds_read_b128 v[168:171], v138 offset:2048
	ds_read_b128 v[172:175], v138 offset:3072
	v_add_u32_e32 v138, s73, v154
	ds_read_b128 v[176:179], v138
	ds_read_b128 v[180:183], v138 offset:1024
	ds_read_b128 v[188:191], v138 offset:2048
	ds_read_b128 v[192:195], v138 offset:3072
	s_add_u32 s36, s36, s6
	s_addc_u32 s37, s37, s7
	s_mov_b32 m0, s48
	v_lshl_add_u64 v[236:237], s[36:37], 0, v[136:137]
	ds_read_b128 v[196:199], v158 offset:32768
	ds_read_b128 v[200:203], v158 offset:33792
	ds_read_b128 v[204:207], v158 offset:34816
	ds_read_b128 v[208:211], v158 offset:35840
	ds_read_b128 v[212:215], v158 offset:36864
	ds_read_b128 v[216:219], v158 offset:37888
	ds_read_b128 v[220:223], v158 offset:38912
	ds_read_b128 v[224:227], v158 offset:39936
	global_load_lds_dwordx4 v[236:237], off
	v_lshl_add_u64 v[236:237], s[36:37], 0, v[132:133]
	s_mov_b32 m0, s49
	s_nop 0
	global_load_lds_dwordx4 v[236:237], off
	s_waitcnt vmcnt(8)
	s_waitcnt lgkmcnt(0)
	s_barrier
	s_setprio 1
	s_waitcnt lgkmcnt(0)
	v_mfma_f32_16x16x32_bf16 v[126:129], v[160:163], v[196:199], v[126:129]
	v_mfma_f32_16x16x32_bf16 v[122:125], v[168:171], v[196:199], v[122:125]
	v_mfma_f32_16x16x32_bf16 v[110:113], v[160:163], v[204:207], v[110:113]
	v_mfma_f32_16x16x32_bf16 v[106:109], v[168:171], v[204:207], v[106:109]
	v_mfma_f32_16x16x32_bf16 v[94:97], v[160:163], v[212:215], v[94:97]
	v_mfma_f32_16x16x32_bf16 v[90:93], v[168:171], v[212:215], v[90:93]
	v_mfma_f32_16x16x32_bf16 v[78:81], v[160:163], v[220:223], v[78:81]
	v_mfma_f32_16x16x32_bf16 v[74:77], v[168:171], v[220:223], v[74:77]
	v_mfma_f32_16x16x32_bf16 v[126:129], v[164:167], v[200:203], v[126:129]
	v_mfma_f32_16x16x32_bf16 v[122:125], v[172:175], v[200:203], v[122:125]
	v_mfma_f32_16x16x32_bf16 v[110:113], v[164:167], v[208:211], v[110:113]
	v_mfma_f32_16x16x32_bf16 v[106:109], v[172:175], v[208:211], v[106:109]
	v_mfma_f32_16x16x32_bf16 v[94:97], v[164:167], v[216:219], v[94:97]
	v_mfma_f32_16x16x32_bf16 v[90:93], v[172:175], v[216:219], v[90:93]
	v_mfma_f32_16x16x32_bf16 v[78:81], v[164:167], v[224:227], v[78:81]
	v_mfma_f32_16x16x32_bf16 v[74:77], v[172:175], v[224:227], v[74:77]
	s_setprio 0
	s_setprio 1
	v_mfma_f32_16x16x32_bf16 v[118:121], v[176:179], v[196:199], v[118:121]
	v_mfma_f32_16x16x32_bf16 v[114:117], v[188:191], v[196:199], v[114:117]
	v_mfma_f32_16x16x32_bf16 v[102:105], v[176:179], v[204:207], v[102:105]
	v_mfma_f32_16x16x32_bf16 v[98:101], v[188:191], v[204:207], v[98:101]
	v_mfma_f32_16x16x32_bf16 v[86:89], v[176:179], v[212:215], v[86:89]
	v_mfma_f32_16x16x32_bf16 v[82:85], v[188:191], v[212:215], v[82:85]
	v_mfma_f32_16x16x32_bf16 v[70:73], v[176:179], v[220:223], v[70:73]
	v_mfma_f32_16x16x32_bf16 v[66:69], v[188:191], v[220:223], v[66:69]
	v_mfma_f32_16x16x32_bf16 v[118:121], v[180:183], v[200:203], v[118:121]
	v_mfma_f32_16x16x32_bf16 v[114:117], v[192:195], v[200:203], v[114:117]
	v_mfma_f32_16x16x32_bf16 v[102:105], v[180:183], v[208:211], v[102:105]
	v_mfma_f32_16x16x32_bf16 v[98:101], v[192:195], v[208:211], v[98:101]
	v_mfma_f32_16x16x32_bf16 v[86:89], v[180:183], v[216:219], v[86:89]
	v_mfma_f32_16x16x32_bf16 v[82:85], v[192:195], v[216:219], v[82:85]
	v_mfma_f32_16x16x32_bf16 v[70:73], v[180:183], v[224:227], v[70:73]
	v_mfma_f32_16x16x32_bf16 v[66:69], v[192:195], v[224:227], v[66:69]
	s_barrier
; #define PG8_STAGE(bufoff, gbase, voff) do { _Pragma("unroll") for (int _i = 0; _i < 2; ++_i) \
;         __builtin_amdgcn_global_load_lds((const unsigned*)((const char*)(gbase) + (voff)[_i]), (PG8_LAS unsigned*)(lds + (bufoff) + ldsw + _i * 8192), 16, 0, 0); } while (0)
; #define PG8_LDA(dst, b, h) do { _Pragma("unroll") for (int m = 0; m < 4; ++m) _Pragma("unroll") for (int k = 0; k < 2; ++k) dst[m][k] = *(const PG8_LAS bf16x8*)(lds + PG8_SA(b, h) + aoff + m * 2048 + k * 1024); } while (0)
; #define PG8_MMA(ai, bj, At, Bt) do { __builtin_amdgcn_s_setprio(1); _Pragma("unroll") for (int m = 0; m < 4; ++m) _Pragma("unroll") for (int n = 0; n < 2; ++n) _Pragma("unroll") for (int k = 0; k < 2; ++k) \
;         acc[ai][bj][m][n] = __builtin_amdgcn_mfma_f32_16x16x32_bf16(Bt[n][k], At[m][k], acc[ai][bj][m][n], 0, 0, 0); __builtin_amdgcn_s_setprio(0); } while (0)
; #define PG8_WAIT_V(n) asm volatile("s_waitcnt vmcnt(" #n ")" ::: "memory")
; #define PG8_WAIT_L(n) asm volatile("s_waitcnt lgkmcnt(" #n ")" ::: "memory")
; #define PG8_BAR __builtin_amdgcn_s_barrier()
; #define PG8_SCHED __builtin_amdgcn_sched_barrier(0)
; template <class Epi, class Sched, bool ALIGN_EPI = false, bool SP2 = false>
; __device__ __forceinline__ void gemm_phase(PG8_LAS unsigned char* lds, const Gemm g, const Sched& S, const Epi& E) {
;     ...
;             PG8_WAIT_V(8); PG8_WAIT_L(0); PG8_BAR; PG8_MMA(0, 0, At, B0); PG8_MMA(0, 1, At, B1); PG8_BAR; PG8_SCHED;
;             PG8_LDA(At, 1, 1); PG8_STAGE(PG8_SB(1, 0), b3, voffB); PG8_STAGE(PG8_SB(1, 1), b3 + hstep, voffB); PG8_STAGE(PG8_SA(1, 0), a3, voffA);
;             PG8_WAIT_V(8); PG8_WAIT_L(0); PG8_BAR; PG8_MMA(1, 0, At, B0); PG8_MMA(1, 1, At, B1); PG8_BAR; PG8_SCHED;
	s_setprio 0
	s_add_i32 s36, s72, s41
	v_lshl_add_u64 v[152:153], v[152:153], 0, s[24:25]
	s_mov_b32 m0, s36
	ds_read_b128 v[196:199], v158 offset:49152
	ds_read_b128 v[200:203], v158 offset:50176
	ds_read_b128 v[204:207], v158 offset:51200
	ds_read_b128 v[208:211], v158 offset:52224
	ds_read_b128 v[212:215], v158 offset:53248
	ds_read_b128 v[216:219], v158 offset:54272
	ds_read_b128 v[220:223], v158 offset:55296
	ds_read_b128 v[224:227], v158 offset:56320
	global_load_lds_dwordx4 v[152:153], off
	v_lshl_add_u64 v[152:153], v[184:185], 0, s[24:25]
	s_add_i32 m0, s36, 0x2000
	s_add_i32 s36, s73, s41
	global_load_lds_dwordx4 v[152:153], off
	v_lshl_add_u64 v[152:153], v[228:229], 0, s[24:25]
	s_mov_b32 m0, s36
	s_nop 0
	global_load_lds_dwordx4 v[152:153], off
	v_lshl_add_u64 v[152:153], v[230:231], 0, s[24:25]
	s_add_i32 m0, s36, 0x2000
	s_nop 0
	global_load_lds_dwordx4 v[152:153], off
	v_lshl_add_u64 v[152:153], v[232:233], 0, s[24:25]
	s_mov_b32 m0, s11
	s_nop 0
	global_load_lds_dwordx4 v[152:153], off
	v_lshl_add_u64 v[152:153], v[234:235], 0, s[24:25]
	s_mov_b32 m0, s50
	s_nop 0
	global_load_lds_dwordx4 v[152:153], off
	s_waitcnt vmcnt(8)
	s_waitcnt lgkmcnt(0)
	s_barrier
	s_setprio 1
	s_waitcnt lgkmcnt(0)
	v_mfma_f32_16x16x32_bf16 v[62:65], v[160:163], v[196:199], v[62:65]
	v_mfma_f32_16x16x32_bf16 v[58:61], v[168:171], v[196:199], v[58:61]
	v_mfma_f32_16x16x32_bf16 v[46:49], v[160:163], v[204:207], v[46:49]
	v_mfma_f32_16x16x32_bf16 v[42:45], v[168:171], v[204:207], v[42:45]
	v_mfma_f32_16x16x32_bf16 v[30:33], v[160:163], v[212:215], v[30:33]
	v_mfma_f32_16x16x32_bf16 v[26:29], v[168:171], v[212:215], v[26:29]
	v_mfma_f32_16x16x32_bf16 v[14:17], v[160:163], v[220:223], v[14:17]
	v_mfma_f32_16x16x32_bf16 v[10:13], v[168:171], v[220:223], v[10:13]
	v_mfma_f32_16x16x32_bf16 v[62:65], v[164:167], v[200:203], v[62:65]
	v_mfma_f32_16x16x32_bf16 v[58:61], v[172:175], v[200:203], v[58:61]
	v_mfma_f32_16x16x32_bf16 v[46:49], v[164:167], v[208:211], v[46:49]
	v_mfma_f32_16x16x32_bf16 v[42:45], v[172:175], v[208:211], v[42:45]
	v_mfma_f32_16x16x32_bf16 v[30:33], v[164:167], v[216:219], v[30:33]
	v_mfma_f32_16x16x32_bf16 v[26:29], v[172:175], v[216:219], v[26:29]
	v_mfma_f32_16x16x32_bf16 v[14:17], v[164:167], v[224:227], v[14:17]
	v_mfma_f32_16x16x32_bf16 v[10:13], v[172:175], v[224:227], v[10:13]
	s_setprio 0
	s_setprio 1
	v_mfma_f32_16x16x32_bf16 v[54:57], v[176:179], v[196:199], v[54:57]
	v_mfma_f32_16x16x32_bf16 v[50:53], v[188:191], v[196:199], v[50:53]
	v_mfma_f32_16x16x32_bf16 v[38:41], v[176:179], v[204:207], v[38:41]
	v_mfma_f32_16x16x32_bf16 v[34:37], v[188:191], v[204:207], v[34:37]
	v_mfma_f32_16x16x32_bf16 v[22:25], v[176:179], v[212:215], v[22:25]
	v_mfma_f32_16x16x32_bf16 v[18:21], v[188:191], v[212:215], v[18:21]
	v_mfma_f32_16x16x32_bf16 v[6:9], v[176:179], v[220:223], v[6:9]
	v_mfma_f32_16x16x32_bf16 v[2:5], v[188:191], v[220:223], v[2:5]
	v_mfma_f32_16x16x32_bf16 v[54:57], v[180:183], v[200:203], v[54:57]
	v_mfma_f32_16x16x32_bf16 v[50:53], v[192:195], v[200:203], v[50:53]
	v_mfma_f32_16x16x32_bf16 v[38:41], v[180:183], v[208:211], v[38:41]
	v_mfma_f32_16x16x32_bf16 v[34:37], v[192:195], v[208:211], v[34:37]
	v_mfma_f32_16x16x32_bf16 v[22:25], v[180:183], v[216:219], v[22:25]
	v_mfma_f32_16x16x32_bf16 v[18:21], v[192:195], v[216:219], v[18:21]
	v_mfma_f32_16x16x32_bf16 v[6:9], v[180:183], v[224:227], v[6:9]
	v_mfma_f32_16x16x32_bf16 v[2:5], v[192:195], v[224:227], v[2:5]
	s_barrier
	s_setprio 0
	s_add_u32 s34, s34, 0x100
	s_addc_u32 s35, s35, 0
	s_add_u32 s69, s69, 0x100
	s_addc_u32 s70, s70, 0
	s_cmp_ge_i32 s71, s0
	s_mov_b32 s36, s71
	s_cbranch_scc0 .LBB0_738

; #define PG8_STAGE(bufoff, gbase, voff) do { _Pragma("unroll") for (int _i = 0; _i < 2; ++_i) \
;         __builtin_amdgcn_global_load_lds((const unsigned*)((const char*)(gbase) + (voff)[_i]), (PG8_LAS unsigned*)(lds + (bufoff) + ldsw + _i * 8192), 16, 0, 0); } while (0)
; #define PG8_LDA(dst, b, h) do { _Pragma("unroll") for (int m = 0; m < 4; ++m) _Pragma("unroll") for (int k = 0; k < 2; ++k) dst[m][k] = *(const PG8_LAS bf16x8*)(lds + PG8_SA(b, h) + aoff + m * 2048 + k * 1024); } while (0)
; #define PG8_LDB(dst, b, h) do { _Pragma("unroll") for (int n = 0; n < 2; ++n) _Pragma("unroll") for (int k = 0; k < 2; ++k) dst[n][k] = *(const PG8_LAS bf16x8*)(lds + PG8_SB(b, h) + boff + n * 2048 + k * 1024); } while (0)
; #define PG8_MMA(ai, bj, At, Bt) do { __builtin_amdgcn_s_setprio(1); _Pragma("unroll") for (int m = 0; m < 4; ++m) _Pragma("unroll") for (int n = 0; n < 2; ++n) _Pragma("unroll") for (int k = 0; k < 2; ++k) \
;         acc[ai][bj][m][n] = __builtin_amdgcn_mfma_f32_16x16x32_bf16(Bt[n][k], At[m][k], acc[ai][bj][m][n], 0, 0, 0); __builtin_amdgcn_s_setprio(0); } while (0)
; #define PG8_WAIT_V(n) asm volatile("s_waitcnt vmcnt(" #n ")" ::: "memory")
; #define PG8_BAR __builtin_amdgcn_s_barrier()
; template <class Epi, class Sched, bool ALIGN_EPI = false, bool SP2 = false>
; __device__ __forceinline__ void gemm_phase(PG8_LAS unsigned char* lds, const Gemm g, const Sched& S, const Epi& E) {
;     ...
;         for (int t = 0; t < nt; t += 2) {
;             const bool last = (t == nt - 2);
;             const char* a1 = cA + (size_t)(t + 1) * kstep;
;             const char* a2 = last ? nA : cA + (size_t)(t + 2) * kstep; const char* b2 = last ? nB : cB + (size_t)(t + 2) * kstep;
;             const char* a3 = a2 + kstep; const char* b3 = b2 + kstep;
;             if (last && has_next) S.a_ready(nxt);
;             if constexpr (SP2) {
;             PG8_LDB(B0, 0, 0); PG8_LDB(B1, 0, 1); PG8_SCHED; PG8_LDA(At, 0, 0); PG8_STAGE(PG8_SA(1, 1), a1 + hstep, voffA);
;             PG8_WAIT_V(8); PG8_WAIT_L(0); PG8_BAR; PG8_MMA(0, 0, At, B0); PG8_MMA(0, 1, At, B1); PG8_BAR; PG8_SCHED;
;             PG8_LDA(At, 0, 1); PG8_STAGE(PG8_SB(0, 0), b2, voffB); PG8_STAGE(PG8_SB(0, 1), b2 + hstep, voffB); PG8_STAGE(PG8_SA(0, 0), a2, voffA);
;             PG8_WAIT_V(8); PG8_WAIT_L(0); PG8_BAR; PG8_MMA(1, 0, At, B0); PG8_MMA(1, 1, At, B1); PG8_BAR; PG8_SCHED;
.LBB0_771:
	ds_read_b128 v[156:159], v152
	ds_read_b128 v[160:163], v152 offset:1024
	ds_read_b128 v[164:167], v152 offset:2048
	ds_read_b128 v[168:171], v152 offset:3072
	ds_read_b128 v[172:175], v153
	ds_read_b128 v[176:179], v153 offset:1024
	ds_read_b128 v[180:183], v153 offset:2048
	ds_read_b128 v[188:191], v153 offset:3072
	s_add_i32 s65, s34, 2
	s_add_u32 s66, s30, 0x80
	s_addc_u32 s35, s31, 0
	s_cmp_eq_u32 s52, s34
	s_cselect_b32 s34, s4, s66
	s_cselect_b32 s35, s5, s35
	s_cselect_b32 s67, s29, s63
	s_cselect_b32 s66, s28, s62
	v_lshl_add_u64 v[184:185], s[30:31], 0, v[142:143]
	s_add_i32 m0, s40, 0xc000
	ds_read_b128 v[192:195], v154
	ds_read_b128 v[196:199], v154 offset:1024
	ds_read_b128 v[200:203], v154 offset:2048
	ds_read_b128 v[204:207], v154 offset:3072
	ds_read_b128 v[208:211], v154 offset:4096
	ds_read_b128 v[212:215], v154 offset:5120
	ds_read_b128 v[216:219], v154 offset:6144
	ds_read_b128 v[220:223], v154 offset:7168
	global_load_lds_dwordx4 v[184:185], off
	v_lshl_add_u64 v[184:185], s[30:31], 0, v[144:145]
	s_add_i32 m0, s40, 0xe000
	s_nop 0
	global_load_lds_dwordx4 v[184:185], off
	s_waitcnt vmcnt(8)
	s_waitcnt lgkmcnt(0)
	s_barrier
	s_setprio 1
	s_waitcnt lgkmcnt(0)
	v_mfma_f32_16x16x32_bf16 v[122:125], v[156:159], v[192:195], v[122:125]
	v_mfma_f32_16x16x32_bf16 v[126:129], v[164:167], v[192:195], v[126:129]
	v_mfma_f32_16x16x32_bf16 v[110:113], v[156:159], v[200:203], v[110:113]
	v_mfma_f32_16x16x32_bf16 v[106:109], v[164:167], v[200:203], v[106:109]
	v_mfma_f32_16x16x32_bf16 v[94:97], v[156:159], v[208:211], v[94:97]
	v_mfma_f32_16x16x32_bf16 v[90:93], v[164:167], v[208:211], v[90:93]
	v_mfma_f32_16x16x32_bf16 v[78:81], v[156:159], v[216:219], v[78:81]
	v_mfma_f32_16x16x32_bf16 v[74:77], v[164:167], v[216:219], v[74:77]
	v_mfma_f32_16x16x32_bf16 v[122:125], v[160:163], v[196:199], v[122:125]
	v_mfma_f32_16x16x32_bf16 v[126:129], v[168:171], v[196:199], v[126:129]
	v_mfma_f32_16x16x32_bf16 v[110:113], v[160:163], v[204:207], v[110:113]
	v_mfma_f32_16x16x32_bf16 v[106:109], v[168:171], v[204:207], v[106:109]
	v_mfma_f32_16x16x32_bf16 v[94:97], v[160:163], v[212:215], v[94:97]
	v_mfma_f32_16x16x32_bf16 v[90:93], v[168:171], v[212:215], v[90:93]
	v_mfma_f32_16x16x32_bf16 v[78:81], v[160:163], v[220:223], v[78:81]
	v_mfma_f32_16x16x32_bf16 v[74:77], v[168:171], v[220:223], v[74:77]
	s_setprio 0
	s_setprio 1
	v_mfma_f32_16x16x32_bf16 v[118:121], v[172:175], v[192:195], v[118:121]
	v_mfma_f32_16x16x32_bf16 v[114:117], v[180:183], v[192:195], v[114:117]
	v_mfma_f32_16x16x32_bf16 v[102:105], v[172:175], v[200:203], v[102:105]
	v_mfma_f32_16x16x32_bf16 v[98:101], v[180:183], v[200:203], v[98:101]
	v_mfma_f32_16x16x32_bf16 v[86:89], v[172:175], v[208:211], v[86:89]
	v_mfma_f32_16x16x32_bf16 v[82:85], v[180:183], v[208:211], v[82:85]
	v_mfma_f32_16x16x32_bf16 v[70:73], v[172:175], v[216:219], v[70:73]
	v_mfma_f32_16x16x32_bf16 v[66:69], v[180:183], v[216:219], v[66:69]
	v_mfma_f32_16x16x32_bf16 v[118:121], v[176:179], v[196:199], v[118:121]
	v_mfma_f32_16x16x32_bf16 v[114:117], v[188:191], v[196:199], v[114:117]
	v_mfma_f32_16x16x32_bf16 v[102:105], v[176:179], v[204:207], v[102:105]
	v_mfma_f32_16x16x32_bf16 v[98:101], v[188:191], v[204:207], v[98:101]
	v_mfma_f32_16x16x32_bf16 v[86:89], v[176:179], v[212:215], v[86:89]
	v_mfma_f32_16x16x32_bf16 v[82:85], v[188:191], v[212:215], v[82:85]
	v_mfma_f32_16x16x32_bf16 v[70:73], v[176:179], v[220:223], v[70:73]
	v_mfma_f32_16x16x32_bf16 v[66:69], v[188:191], v[220:223], v[66:69]
	s_barrier
	s_setprio 0
	s_add_i32 s68, s55, s39
	v_lshl_add_u64 v[184:185], s[66:67], 0, v[132:133]
	s_mov_b32 m0, s68
	ds_read_b128 v[192:195], v154 offset:16384
	ds_read_b128 v[196:199], v154 offset:17408
	ds_read_b128 v[200:203], v154 offset:18432
	ds_read_b128 v[204:207], v154 offset:19456
	ds_read_b128 v[208:211], v154 offset:20480
	ds_read_b128 v[212:215], v154 offset:21504
	ds_read_b128 v[216:219], v154 offset:22528
	ds_read_b128 v[220:223], v154 offset:23552
	global_load_lds_dwordx4 v[184:185], off
	s_add_i32 m0, s68, 0x2000
	v_lshl_add_u64 v[224:225], s[66:67], 0, v[136:137]
	s_add_u32 s66, s66, s12
	s_addc_u32 s67, s67, s13
	s_add_i32 s68, s56, s39
	global_load_lds_dwordx4 v[224:225], off
	v_lshl_add_u64 v[226:227], s[66:67], 0, v[132:133]
	s_mov_b32 m0, s68
	v_lshl_add_u64 v[228:229], s[66:67], 0, v[136:137]
	global_load_lds_dwordx4 v[226:227], off
	s_add_i32 m0, s68, 0x2000
	v_lshl_add_u64 v[230:231], s[34:35], 0, v[130:131]
	global_load_lds_dwordx4 v[228:229], off
	s_mov_b32 m0, s40
	v_lshl_add_u64 v[232:233], s[34:35], 0, v[134:135]
	global_load_lds_dwordx4 v[230:231], off
	s_mov_b32 m0, s41
	s_nop 0
	global_load_lds_dwordx4 v[232:233], off
	s_waitcnt vmcnt(8)
	s_waitcnt lgkmcnt(0)
	s_barrier
; #define PG8_STAGE(bufoff, gbase, voff) do { _Pragma("unroll") for (int _i = 0; _i < 2; ++_i) \
;         __builtin_amdgcn_global_load_lds((const unsigned*)((const char*)(gbase) + (voff)[_i]), (PG8_LAS unsigned*)(lds + (bufoff) + ldsw + _i * 8192), 16, 0, 0); } while (0)
; #define PG8_LDA(dst, b, h) do { _Pragma("unroll") for (int m = 0; m < 4; ++m) _Pragma("unroll") for (int k = 0; k < 2; ++k) dst[m][k] = *(const PG8_LAS bf16x8*)(lds + PG8_SA(b, h) + aoff + m * 2048 + k * 1024); } while (0)
; #define PG8_LDB(dst, b, h) do { _Pragma("unroll") for (int n = 0; n < 2; ++n) _Pragma("unroll") for (int k = 0; k < 2; ++k) dst[n][k] = *(const PG8_LAS bf16x8*)(lds + PG8_SB(b, h) + boff + n * 2048 + k * 1024); } while (0)
; #define PG8_MMA(ai, bj, At, Bt) do { __builtin_amdgcn_s_setprio(1); _Pragma("unroll") for (int m = 0; m < 4; ++m) _Pragma("unroll") for (int n = 0; n < 2; ++n) _Pragma("unroll") for (int k = 0; k < 2; ++k) \
;         acc[ai][bj][m][n] = __builtin_amdgcn_mfma_f32_16x16x32_bf16(Bt[n][k], At[m][k], acc[ai][bj][m][n], 0, 0, 0); __builtin_amdgcn_s_setprio(0); } while (0)
; #define PG8_WAIT_V(n) asm volatile("s_waitcnt vmcnt(" #n ")" ::: "memory")
; #define PG8_WAIT_L(n) asm volatile("s_waitcnt lgkmcnt(" #n ")" ::: "memory")
; #define PG8_BAR __builtin_amdgcn_s_barrier()
; #define PG8_SCHED __builtin_amdgcn_sched_barrier(0)
; template <class Epi, class Sched, bool ALIGN_EPI = false, bool SP2 = false>
; __device__ __forceinline__ void gemm_phase(PG8_LAS unsigned char* lds, const Gemm g, const Sched& S, const Epi& E) {
;     ...
;             PG8_WAIT_V(8); PG8_WAIT_L(0); PG8_BAR; PG8_MMA(1, 0, At, B0); PG8_MMA(1, 1, At, B1); PG8_BAR; PG8_SCHED;
;             PG8_LDB(B0, 1, 0); PG8_LDB(B1, 1, 1); PG8_SCHED; PG8_LDA(At, 1, 0); PG8_STAGE(PG8_SA(0, 1), a2 + hstep, voffA);
;             PG8_WAIT_V(8); PG8_WAIT_L(0); PG8_BAR; PG8_MMA(0, 0, At, B0); PG8_MMA(0, 1, At, B1); PG8_BAR; PG8_SCHED;
	s_setprio 1
	s_waitcnt lgkmcnt(0)
	v_mfma_f32_16x16x32_bf16 v[62:65], v[156:159], v[192:195], v[62:65]
	v_mfma_f32_16x16x32_bf16 v[58:61], v[164:167], v[192:195], v[58:61]
	v_mfma_f32_16x16x32_bf16 v[46:49], v[156:159], v[200:203], v[46:49]
	v_mfma_f32_16x16x32_bf16 v[42:45], v[164:167], v[200:203], v[42:45]
	v_mfma_f32_16x16x32_bf16 v[30:33], v[156:159], v[208:211], v[30:33]
	v_mfma_f32_16x16x32_bf16 v[26:29], v[164:167], v[208:211], v[26:29]
	v_mfma_f32_16x16x32_bf16 v[14:17], v[156:159], v[216:219], v[14:17]
	v_mfma_f32_16x16x32_bf16 v[10:13], v[164:167], v[216:219], v[10:13]
	v_mfma_f32_16x16x32_bf16 v[62:65], v[160:163], v[196:199], v[62:65]
	v_mfma_f32_16x16x32_bf16 v[58:61], v[168:171], v[196:199], v[58:61]
	v_mfma_f32_16x16x32_bf16 v[46:49], v[160:163], v[204:207], v[46:49]
	v_mfma_f32_16x16x32_bf16 v[42:45], v[168:171], v[204:207], v[42:45]
	v_mfma_f32_16x16x32_bf16 v[30:33], v[160:163], v[212:215], v[30:33]
	v_mfma_f32_16x16x32_bf16 v[26:29], v[168:171], v[212:215], v[26:29]
	v_mfma_f32_16x16x32_bf16 v[14:17], v[160:163], v[220:223], v[14:17]
	v_mfma_f32_16x16x32_bf16 v[10:13], v[168:171], v[220:223], v[10:13]
	s_setprio 0
	s_setprio 1
	v_mfma_f32_16x16x32_bf16 v[54:57], v[172:175], v[192:195], v[54:57]
	v_mfma_f32_16x16x32_bf16 v[50:53], v[180:183], v[192:195], v[50:53]
	v_mfma_f32_16x16x32_bf16 v[38:41], v[172:175], v[200:203], v[38:41]
	v_mfma_f32_16x16x32_bf16 v[34:37], v[180:183], v[200:203], v[34:37]
	v_mfma_f32_16x16x32_bf16 v[22:25], v[172:175], v[208:211], v[22:25]
	v_mfma_f32_16x16x32_bf16 v[18:21], v[180:183], v[208:211], v[18:21]
	v_mfma_f32_16x16x32_bf16 v[6:9], v[172:175], v[216:219], v[6:9]
	v_mfma_f32_16x16x32_bf16 v[2:5], v[180:183], v[216:219], v[2:5]
	v_mfma_f32_16x16x32_bf16 v[54:57], v[176:179], v[196:199], v[54:57]
	v_mfma_f32_16x16x32_bf16 v[50:53], v[188:191], v[196:199], v[50:53]
	v_mfma_f32_16x16x32_bf16 v[38:41], v[176:179], v[204:207], v[38:41]
	v_mfma_f32_16x16x32_bf16 v[34:37], v[188:191], v[204:207], v[34:37]
	v_mfma_f32_16x16x32_bf16 v[22:25], v[176:179], v[212:215], v[22:25]
	v_mfma_f32_16x16x32_bf16 v[18:21], v[188:191], v[212:215], v[18:21]
	v_mfma_f32_16x16x32_bf16 v[6:9], v[176:179], v[220:223], v[6:9]
	v_mfma_f32_16x16x32_bf16 v[2:5], v[188:191], v[220:223], v[2:5]
	s_barrier
	s_setprio 0
	s_add_i32 s66, 0, 0x18000
	v_add_u32_e32 v138, s66, v150
	s_add_i32 s67, 0, 0x1c000
	ds_read_b128 v[156:159], v138
	ds_read_b128 v[160:163], v138 offset:1024
	ds_read_b128 v[164:167], v138 offset:2048
	ds_read_b128 v[168:171], v138 offset:3072
	v_add_u32_e32 v138, s67, v150
	ds_read_b128 v[172:175], v138
	ds_read_b128 v[176:179], v138 offset:1024
	ds_read_b128 v[180:183], v138 offset:2048
	ds_read_b128 v[188:191], v138 offset:3072
	s_add_u32 s34, s34, s12
	s_addc_u32 s35, s35, s13
	s_mov_b32 m0, s42
	v_lshl_add_u64 v[234:235], s[34:35], 0, v[130:131]
	ds_read_b128 v[192:195], v154 offset:32768
	ds_read_b128 v[196:199], v154 offset:33792
	ds_read_b128 v[200:203], v154 offset:34816
	ds_read_b128 v[204:207], v154 offset:35840
	ds_read_b128 v[208:211], v154 offset:36864
	ds_read_b128 v[212:215], v154 offset:37888
	ds_read_b128 v[216:219], v154 offset:38912
	ds_read_b128 v[220:223], v154 offset:39936
	global_load_lds_dwordx4 v[234:235], off
	v_lshl_add_u64 v[234:235], s[34:35], 0, v[134:135]
	s_mov_b32 m0, s43
	s_nop 0
	global_load_lds_dwordx4 v[234:235], off
	s_waitcnt vmcnt(8)
	s_waitcnt lgkmcnt(0)
	s_barrier
	s_setprio 1
	s_waitcnt lgkmcnt(0)
	v_mfma_f32_16x16x32_bf16 v[122:125], v[156:159], v[192:195], v[122:125]
	v_mfma_f32_16x16x32_bf16 v[126:129], v[164:167], v[192:195], v[126:129]
	v_mfma_f32_16x16x32_bf16 v[110:113], v[156:159], v[200:203], v[110:113]
	v_mfma_f32_16x16x32_bf16 v[106:109], v[164:167], v[200:203], v[106:109]
	v_mfma_f32_16x16x32_bf16 v[94:97], v[156:159], v[208:211], v[94:97]
	v_mfma_f32_16x16x32_bf16 v[90:93], v[164:167], v[208:211], v[90:93]
	v_mfma_f32_16x16x32_bf16 v[78:81], v[156:159], v[216:219], v[78:81]
	v_mfma_f32_16x16x32_bf16 v[74:77], v[164:167], v[216:219], v[74:77]
	v_mfma_f32_16x16x32_bf16 v[122:125], v[160:163], v[196:199], v[122:125]
	v_mfma_f32_16x16x32_bf16 v[126:129], v[168:171], v[196:199], v[126:129]
	v_mfma_f32_16x16x32_bf16 v[110:113], v[160:163], v[204:207], v[110:113]
	v_mfma_f32_16x16x32_bf16 v[106:109], v[168:171], v[204:207], v[106:109]
	v_mfma_f32_16x16x32_bf16 v[94:97], v[160:163], v[212:215], v[94:97]
	v_mfma_f32_16x16x32_bf16 v[90:93], v[168:171], v[212:215], v[90:93]
	v_mfma_f32_16x16x32_bf16 v[78:81], v[160:163], v[220:223], v[78:81]
	v_mfma_f32_16x16x32_bf16 v[74:77], v[168:171], v[220:223], v[74:77]
	s_setprio 0
	s_setprio 1
	v_mfma_f32_16x16x32_bf16 v[118:121], v[172:175], v[192:195], v[118:121]
	v_mfma_f32_16x16x32_bf16 v[114:117], v[180:183], v[192:195], v[114:117]
	v_mfma_f32_16x16x32_bf16 v[102:105], v[172:175], v[200:203], v[102:105]
	v_mfma_f32_16x16x32_bf16 v[98:101], v[180:183], v[200:203], v[98:101]
	v_mfma_f32_16x16x32_bf16 v[86:89], v[172:175], v[208:211], v[86:89]
	v_mfma_f32_16x16x32_bf16 v[82:85], v[180:183], v[208:211], v[82:85]
	v_mfma_f32_16x16x32_bf16 v[70:73], v[172:175], v[216:219], v[70:73]
	v_mfma_f32_16x16x32_bf16 v[66:69], v[180:183], v[216:219], v[66:69]
	v_mfma_f32_16x16x32_bf16 v[118:121], v[176:179], v[196:199], v[118:121]
	v_mfma_f32_16x16x32_bf16 v[114:117], v[188:191], v[196:199], v[114:117]
	v_mfma_f32_16x16x32_bf16 v[102:105], v[176:179], v[204:207], v[102:105]
	v_mfma_f32_16x16x32_bf16 v[98:101], v[188:191], v[204:207], v[98:101]
	v_mfma_f32_16x16x32_bf16 v[86:89], v[176:179], v[212:215], v[86:89]
	v_mfma_f32_16x16x32_bf16 v[82:85], v[188:191], v[212:215], v[82:85]
	v_mfma_f32_16x16x32_bf16 v[70:73], v[176:179], v[220:223], v[70:73]
	v_mfma_f32_16x16x32_bf16 v[66:69], v[188:191], v[220:223], v[66:69]
	s_barrier
; #define PG8_STAGE(bufoff, gbase, voff) do { _Pragma("unroll") for (int _i = 0; _i < 2; ++_i) \
;         __builtin_amdgcn_global_load_lds((const unsigned*)((const char*)(gbase) + (voff)[_i]), (PG8_LAS unsigned*)(lds + (bufoff) + ldsw + _i * 8192), 16, 0, 0); } while (0)
; #define PG8_LDA(dst, b, h) do { _Pragma("unroll") for (int m = 0; m < 4; ++m) _Pragma("unroll") for (int k = 0; k < 2; ++k) dst[m][k] = *(const PG8_LAS bf16x8*)(lds + PG8_SA(b, h) + aoff + m * 2048 + k * 1024); } while (0)
; #define PG8_MMA(ai, bj, At, Bt) do { __builtin_amdgcn_s_setprio(1); _Pragma("unroll") for (int m = 0; m < 4; ++m) _Pragma("unroll") for (int n = 0; n < 2; ++n) _Pragma("unroll") for (int k = 0; k < 2; ++k) \
;         acc[ai][bj][m][n] = __builtin_amdgcn_mfma_f32_16x16x32_bf16(Bt[n][k], At[m][k], acc[ai][bj][m][n], 0, 0, 0); __builtin_amdgcn_s_setprio(0); } while (0)
; #define PG8_WAIT_V(n) asm volatile("s_waitcnt vmcnt(" #n ")" ::: "memory")
; #define PG8_WAIT_L(n) asm volatile("s_waitcnt lgkmcnt(" #n ")" ::: "memory")
; #define PG8_BAR __builtin_amdgcn_s_barrier()
; #define PG8_SCHED __builtin_amdgcn_sched_barrier(0)
; template <class Epi, class Sched, bool ALIGN_EPI = false, bool SP2 = false>
; __device__ __forceinline__ void gemm_phase(PG8_LAS unsigned char* lds, const Gemm g, const Sched& S, const Epi& E) {
;     ...
;         for (int t = 0; t < nt; t += 2) {
;             const bool last = (t == nt - 2);
;             const char* a1 = cA + (size_t)(t + 1) * kstep;
;             const char* a2 = last ? nA : cA + (size_t)(t + 2) * kstep; const char* b2 = last ? nB : cB + (size_t)(t + 2) * kstep;
;             const char* a3 = a2 + kstep; const char* b3 = b2 + kstep;
;     ...
;             PG8_LDA(At, 1, 1); PG8_STAGE(PG8_SB(1, 0), b3, voffB); PG8_STAGE(PG8_SB(1, 1), b3 + hstep, voffB); PG8_STAGE(PG8_SA(1, 0), a3, voffA);
;             PG8_WAIT_V(8); PG8_WAIT_L(0); PG8_BAR; PG8_MMA(1, 0, At, B0); PG8_MMA(1, 1, At, B1); PG8_BAR; PG8_SCHED;
	s_setprio 0
	s_add_i32 s34, s66, s39
	v_lshl_add_u64 v[184:185], v[184:185], 0, s[22:23]
	s_mov_b32 m0, s34
	ds_read_b128 v[192:195], v154 offset:49152
	ds_read_b128 v[196:199], v154 offset:50176
	ds_read_b128 v[200:203], v154 offset:51200
	ds_read_b128 v[204:207], v154 offset:52224
	ds_read_b128 v[208:211], v154 offset:53248
	ds_read_b128 v[212:215], v154 offset:54272
	ds_read_b128 v[216:219], v154 offset:55296
	ds_read_b128 v[220:223], v154 offset:56320
	global_load_lds_dwordx4 v[184:185], off
	v_lshl_add_u64 v[184:185], v[224:225], 0, s[22:23]
	s_add_i32 m0, s34, 0x2000
	s_add_i32 s34, s67, s39
	global_load_lds_dwordx4 v[184:185], off
	v_lshl_add_u64 v[184:185], v[226:227], 0, s[22:23]
	s_mov_b32 m0, s34
	s_nop 0
	global_load_lds_dwordx4 v[184:185], off
	v_lshl_add_u64 v[184:185], v[228:229], 0, s[22:23]
	s_add_i32 m0, s34, 0x2000
	s_nop 0
	global_load_lds_dwordx4 v[184:185], off
	v_lshl_add_u64 v[184:185], v[230:231], 0, s[22:23]
	s_mov_b32 m0, s48
	s_nop 0
	global_load_lds_dwordx4 v[184:185], off
	v_lshl_add_u64 v[184:185], v[232:233], 0, s[22:23]
	s_mov_b32 m0, s49
	s_nop 0
	global_load_lds_dwordx4 v[184:185], off
	s_waitcnt vmcnt(8)
	s_waitcnt lgkmcnt(0)
	s_barrier
	s_setprio 1
	s_waitcnt lgkmcnt(0)
	v_mfma_f32_16x16x32_bf16 v[62:65], v[156:159], v[192:195], v[62:65]
	v_mfma_f32_16x16x32_bf16 v[58:61], v[164:167], v[192:195], v[58:61]
	v_mfma_f32_16x16x32_bf16 v[46:49], v[156:159], v[200:203], v[46:49]
	v_mfma_f32_16x16x32_bf16 v[42:45], v[164:167], v[200:203], v[42:45]
	v_mfma_f32_16x16x32_bf16 v[30:33], v[156:159], v[208:211], v[30:33]
	v_mfma_f32_16x16x32_bf16 v[26:29], v[164:167], v[208:211], v[26:29]
	v_mfma_f32_16x16x32_bf16 v[14:17], v[156:159], v[216:219], v[14:17]
	v_mfma_f32_16x16x32_bf16 v[10:13], v[164:167], v[216:219], v[10:13]
	v_mfma_f32_16x16x32_bf16 v[62:65], v[160:163], v[196:199], v[62:65]
	v_mfma_f32_16x16x32_bf16 v[58:61], v[168:171], v[196:199], v[58:61]
	v_mfma_f32_16x16x32_bf16 v[46:49], v[160:163], v[204:207], v[46:49]
	v_mfma_f32_16x16x32_bf16 v[42:45], v[168:171], v[204:207], v[42:45]
	v_mfma_f32_16x16x32_bf16 v[30:33], v[160:163], v[212:215], v[30:33]
	v_mfma_f32_16x16x32_bf16 v[26:29], v[168:171], v[212:215], v[26:29]
	v_mfma_f32_16x16x32_bf16 v[14:17], v[160:163], v[220:223], v[14:17]
	v_mfma_f32_16x16x32_bf16 v[10:13], v[168:171], v[220:223], v[10:13]
	s_setprio 0
	s_setprio 1
	v_mfma_f32_16x16x32_bf16 v[54:57], v[172:175], v[192:195], v[54:57]
	v_mfma_f32_16x16x32_bf16 v[50:53], v[180:183], v[192:195], v[50:53]
	v_mfma_f32_16x16x32_bf16 v[38:41], v[172:175], v[200:203], v[38:41]
	v_mfma_f32_16x16x32_bf16 v[34:37], v[180:183], v[200:203], v[34:37]
	v_mfma_f32_16x16x32_bf16 v[22:25], v[172:175], v[208:211], v[22:25]
	v_mfma_f32_16x16x32_bf16 v[18:21], v[180:183], v[208:211], v[18:21]
	v_mfma_f32_16x16x32_bf16 v[6:9], v[172:175], v[216:219], v[6:9]
	v_mfma_f32_16x16x32_bf16 v[2:5], v[180:183], v[216:219], v[2:5]
	v_mfma_f32_16x16x32_bf16 v[54:57], v[176:179], v[196:199], v[54:57]
	v_mfma_f32_16x16x32_bf16 v[50:53], v[188:191], v[196:199], v[50:53]
	v_mfma_f32_16x16x32_bf16 v[38:41], v[176:179], v[204:207], v[38:41]
	v_mfma_f32_16x16x32_bf16 v[34:37], v[188:191], v[204:207], v[34:37]
	v_mfma_f32_16x16x32_bf16 v[22:25], v[176:179], v[212:215], v[22:25]
	v_mfma_f32_16x16x32_bf16 v[18:21], v[188:191], v[212:215], v[18:21]
	v_mfma_f32_16x16x32_bf16 v[6:9], v[176:179], v[220:223], v[6:9]
	v_mfma_f32_16x16x32_bf16 v[2:5], v[188:191], v[220:223], v[2:5]
	s_barrier
	s_setprio 0
	s_add_u32 s30, s30, 0x100
	s_addc_u32 s31, s31, 0
	s_add_u32 s62, s62, 0x100
	s_addc_u32 s63, s63, 0
	s_cmp_ge_i32 s65, s50
	s_mov_b32 s34, s65
	s_cbranch_scc0 .LBB0_771

; #define PG8_STAGE(bufoff, gbase, voff) do { _Pragma("unroll") for (int _i = 0; _i < 2; ++_i) \
;         __builtin_amdgcn_global_load_lds((const unsigned*)((const char*)(gbase) + (voff)[_i]), (PG8_LAS unsigned*)(lds + (bufoff) + ldsw + _i * 8192), 16, 0, 0); } while (0)
; #define PG8_LDA(dst, b, h) do { _Pragma("unroll") for (int m = 0; m < 4; ++m) _Pragma("unroll") for (int k = 0; k < 2; ++k) dst[m][k] = *(const PG8_LAS bf16x8*)(lds + PG8_SA(b, h) + aoff + m * 2048 + k * 1024); } while (0)
; #define PG8_LDB(dst, b, h) do { _Pragma("unroll") for (int n = 0; n < 2; ++n) _Pragma("unroll") for (int k = 0; k < 2; ++k) dst[n][k] = *(const PG8_LAS bf16x8*)(lds + PG8_SB(b, h) + boff + n * 2048 + k * 1024); } while (0)
; #define PG8_MMA(ai, bj, At, Bt) do { __builtin_amdgcn_s_setprio(1); _Pragma("unroll") for (int m = 0; m < 4; ++m) _Pragma("unroll") for (int n = 0; n < 2; ++n) _Pragma("unroll") for (int k = 0; k < 2; ++k) \
;         acc[ai][bj][m][n] = __builtin_amdgcn_mfma_f32_16x16x32_bf16(Bt[n][k], At[m][k], acc[ai][bj][m][n], 0, 0, 0); __builtin_amdgcn_s_setprio(0); } while (0)
; #define PG8_WAIT_V(n) asm volatile("s_waitcnt vmcnt(" #n ")" ::: "memory")
; #define PG8_BAR __builtin_amdgcn_s_barrier()
; template <class Epi, class Sched, bool ALIGN_EPI = false, bool SP2 = false>
; __device__ __forceinline__ void gemm_phase(PG8_LAS unsigned char* lds, const Gemm g, const Sched& S, const Epi& E) {
;     ...
;         for (int t = 0; t < nt; t += 2) {
;             const bool last = (t == nt - 2);
;             const char* a1 = cA + (size_t)(t + 1) * kstep;
;             const char* a2 = last ? nA : cA + (size_t)(t + 2) * kstep; const char* b2 = last ? nB : cB + (size_t)(t + 2) * kstep;
;             const char* a3 = a2 + kstep; const char* b3 = b2 + kstep;
;             if (last && has_next) S.a_ready(nxt);
;             if constexpr (SP2) {
;             PG8_LDB(B0, 0, 0); PG8_LDB(B1, 0, 1); PG8_SCHED; PG8_LDA(At, 0, 0); PG8_STAGE(PG8_SA(1, 1), a1 + hstep, voffA);
;             PG8_WAIT_V(8); PG8_WAIT_L(0); PG8_BAR; PG8_MMA(0, 0, At, B0); PG8_MMA(0, 1, At, B1); PG8_BAR; PG8_SCHED;
;             PG8_LDA(At, 0, 1); PG8_STAGE(PG8_SB(0, 0), b2, voffB); PG8_STAGE(PG8_SB(0, 1), b2 + hstep, voffB); PG8_STAGE(PG8_SA(0, 0), a2, voffA);
;             PG8_WAIT_V(8); PG8_WAIT_L(0); PG8_BAR; PG8_MMA(1, 0, At, B0); PG8_MMA(1, 1, At, B1); PG8_BAR; PG8_SCHED;
.LBB0_791:
	ds_read_b128 v[148:151], v144
	ds_read_b128 v[152:155], v144 offset:1024
	ds_read_b128 v[156:159], v144 offset:2048
	ds_read_b128 v[160:163], v144 offset:3072
	ds_read_b128 v[164:167], v145
	ds_read_b128 v[168:171], v145 offset:1024
	ds_read_b128 v[172:175], v145 offset:2048
	ds_read_b128 v[176:179], v145 offset:3072
	s_add_i32 s56, s24, 2
	s_add_u32 s57, s22, 0x80
	s_addc_u32 s25, s23, 0
	s_cmp_eq_u32 s40, s24
	s_cselect_b32 s24, s4, s57
	s_cselect_b32 s25, s5, s25
	s_cselect_b32 s59, s21, s55
	s_cselect_b32 s58, s20, s54
	v_lshl_add_u64 v[184:185], s[22:23], 0, v[134:135]
	s_add_i32 m0, s30, 0xc000
	ds_read_b128 v[180:183], v146
	ds_read_b128 v[188:191], v146 offset:1024
	ds_read_b128 v[192:195], v146 offset:2048
	ds_read_b128 v[196:199], v146 offset:3072
	ds_read_b128 v[200:203], v146 offset:4096
	ds_read_b128 v[204:207], v146 offset:5120
	ds_read_b128 v[208:211], v146 offset:6144
	ds_read_b128 v[212:215], v146 offset:7168
	global_load_lds_dwordx4 v[184:185], off
	v_lshl_add_u64 v[184:185], s[22:23], 0, v[136:137]
	s_add_i32 m0, s30, 0xe000
	s_nop 0
	global_load_lds_dwordx4 v[184:185], off
	s_waitcnt vmcnt(8)
	s_waitcnt lgkmcnt(0)
	s_barrier
	s_setprio 1
	s_waitcnt lgkmcnt(0)
	v_mfma_f32_16x16x32_bf16 v[126:129], v[148:151], v[180:183], v[126:129]
	v_mfma_f32_16x16x32_bf16 v[122:125], v[156:159], v[180:183], v[122:125]
	v_mfma_f32_16x16x32_bf16 v[110:113], v[148:151], v[192:195], v[110:113]
	v_mfma_f32_16x16x32_bf16 v[106:109], v[156:159], v[192:195], v[106:109]
	v_mfma_f32_16x16x32_bf16 v[94:97], v[148:151], v[200:203], v[94:97]
	v_mfma_f32_16x16x32_bf16 v[90:93], v[156:159], v[200:203], v[90:93]
	v_mfma_f32_16x16x32_bf16 v[78:81], v[148:151], v[208:211], v[78:81]
	v_mfma_f32_16x16x32_bf16 v[74:77], v[156:159], v[208:211], v[74:77]
	v_mfma_f32_16x16x32_bf16 v[126:129], v[152:155], v[188:191], v[126:129]
	v_mfma_f32_16x16x32_bf16 v[122:125], v[160:163], v[188:191], v[122:125]
	v_mfma_f32_16x16x32_bf16 v[110:113], v[152:155], v[196:199], v[110:113]
	v_mfma_f32_16x16x32_bf16 v[106:109], v[160:163], v[196:199], v[106:109]
	v_mfma_f32_16x16x32_bf16 v[94:97], v[152:155], v[204:207], v[94:97]
	v_mfma_f32_16x16x32_bf16 v[90:93], v[160:163], v[204:207], v[90:93]
	v_mfma_f32_16x16x32_bf16 v[78:81], v[152:155], v[212:215], v[78:81]
	v_mfma_f32_16x16x32_bf16 v[74:77], v[160:163], v[212:215], v[74:77]
	s_setprio 0
	s_setprio 1
	v_mfma_f32_16x16x32_bf16 v[118:121], v[164:167], v[180:183], v[118:121]
	v_mfma_f32_16x16x32_bf16 v[114:117], v[172:175], v[180:183], v[114:117]
	v_mfma_f32_16x16x32_bf16 v[102:105], v[164:167], v[192:195], v[102:105]
	v_mfma_f32_16x16x32_bf16 v[98:101], v[172:175], v[192:195], v[98:101]
	v_mfma_f32_16x16x32_bf16 v[86:89], v[164:167], v[200:203], v[86:89]
	v_mfma_f32_16x16x32_bf16 v[82:85], v[172:175], v[200:203], v[82:85]
	v_mfma_f32_16x16x32_bf16 v[70:73], v[164:167], v[208:211], v[70:73]
	v_mfma_f32_16x16x32_bf16 v[66:69], v[172:175], v[208:211], v[66:69]
	v_mfma_f32_16x16x32_bf16 v[118:121], v[168:171], v[188:191], v[118:121]
	v_mfma_f32_16x16x32_bf16 v[114:117], v[176:179], v[188:191], v[114:117]
	v_mfma_f32_16x16x32_bf16 v[102:105], v[168:171], v[196:199], v[102:105]
	v_mfma_f32_16x16x32_bf16 v[98:101], v[176:179], v[196:199], v[98:101]
	v_mfma_f32_16x16x32_bf16 v[86:89], v[168:171], v[204:207], v[86:89]
	v_mfma_f32_16x16x32_bf16 v[82:85], v[176:179], v[204:207], v[82:85]
	v_mfma_f32_16x16x32_bf16 v[70:73], v[168:171], v[212:215], v[70:73]
	v_mfma_f32_16x16x32_bf16 v[66:69], v[176:179], v[212:215], v[66:69]
	s_barrier
	s_setprio 0
	s_add_i32 s57, s43, s29
	v_lshl_add_u64 v[184:185], s[58:59], 0, v[130:131]
	s_mov_b32 m0, s57
	ds_read_b128 v[180:183], v146 offset:16384
	ds_read_b128 v[188:191], v146 offset:17408
	ds_read_b128 v[192:195], v146 offset:18432
	ds_read_b128 v[196:199], v146 offset:19456
	ds_read_b128 v[200:203], v146 offset:20480
	ds_read_b128 v[204:207], v146 offset:21504
	ds_read_b128 v[208:211], v146 offset:22528
	ds_read_b128 v[212:215], v146 offset:23552
	global_load_lds_dwordx4 v[184:185], off
	s_add_i32 m0, s57, 0x2000
	v_lshl_add_u64 v[216:217], s[58:59], 0, v[132:133]
	s_add_u32 s58, s58, s6
	s_addc_u32 s59, s59, s7
	s_add_i32 s57, s48, s29
	global_load_lds_dwordx4 v[216:217], off
	v_lshl_add_u64 v[218:219], s[58:59], 0, v[130:131]
	s_mov_b32 m0, s57
	v_lshl_add_u64 v[220:221], s[58:59], 0, v[132:133]
	global_load_lds_dwordx4 v[218:219], off
	s_add_i32 m0, s57, 0x2000
	v_lshl_add_u64 v[222:223], s[24:25], 0, v[130:131]
	global_load_lds_dwordx4 v[220:221], off
	s_mov_b32 m0, s30
	v_lshl_add_u64 v[224:225], s[24:25], 0, v[132:133]
	global_load_lds_dwordx4 v[222:223], off
	s_mov_b32 m0, s31
	s_nop 0
	global_load_lds_dwordx4 v[224:225], off
	s_waitcnt vmcnt(8)
	s_waitcnt lgkmcnt(0)
	s_barrier
; #define PG8_STAGE(bufoff, gbase, voff) do { _Pragma("unroll") for (int _i = 0; _i < 2; ++_i) \
;         __builtin_amdgcn_global_load_lds((const unsigned*)((const char*)(gbase) + (voff)[_i]), (PG8_LAS unsigned*)(lds + (bufoff) + ldsw + _i * 8192), 16, 0, 0); } while (0)
; #define PG8_LDA(dst, b, h) do { _Pragma("unroll") for (int m = 0; m < 4; ++m) _Pragma("unroll") for (int k = 0; k < 2; ++k) dst[m][k] = *(const PG8_LAS bf16x8*)(lds + PG8_SA(b, h) + aoff + m * 2048 + k * 1024); } while (0)
; #define PG8_LDB(dst, b, h) do { _Pragma("unroll") for (int n = 0; n < 2; ++n) _Pragma("unroll") for (int k = 0; k < 2; ++k) dst[n][k] = *(const PG8_LAS bf16x8*)(lds + PG8_SB(b, h) + boff + n * 2048 + k * 1024); } while (0)
; #define PG8_MMA(ai, bj, At, Bt) do { __builtin_amdgcn_s_setprio(1); _Pragma("unroll") for (int m = 0; m < 4; ++m) _Pragma("unroll") for (int n = 0; n < 2; ++n) _Pragma("unroll") for (int k = 0; k < 2; ++k) \
;         acc[ai][bj][m][n] = __builtin_amdgcn_mfma_f32_16x16x32_bf16(Bt[n][k], At[m][k], acc[ai][bj][m][n], 0, 0, 0); __builtin_amdgcn_s_setprio(0); } while (0)
; #define PG8_WAIT_V(n) asm volatile("s_waitcnt vmcnt(" #n ")" ::: "memory")
; #define PG8_WAIT_L(n) asm volatile("s_waitcnt lgkmcnt(" #n ")" ::: "memory")
; #define PG8_BAR __builtin_amdgcn_s_barrier()
; #define PG8_SCHED __builtin_amdgcn_sched_barrier(0)
; template <class Epi, class Sched, bool ALIGN_EPI = false, bool SP2 = false>
; __device__ __forceinline__ void gemm_phase(PG8_LAS unsigned char* lds, const Gemm g, const Sched& S, const Epi& E) {
;     ...
;             PG8_WAIT_V(8); PG8_WAIT_L(0); PG8_BAR; PG8_MMA(1, 0, At, B0); PG8_MMA(1, 1, At, B1); PG8_BAR; PG8_SCHED;
;             PG8_LDB(B0, 1, 0); PG8_LDB(B1, 1, 1); PG8_SCHED; PG8_LDA(At, 1, 0); PG8_STAGE(PG8_SA(0, 1), a2 + hstep, voffA);
;             PG8_WAIT_V(8); PG8_WAIT_L(0); PG8_BAR; PG8_MMA(0, 0, At, B0); PG8_MMA(0, 1, At, B1); PG8_BAR; PG8_SCHED;
	s_setprio 1
	s_waitcnt lgkmcnt(0)
	v_mfma_f32_16x16x32_bf16 v[62:65], v[148:151], v[180:183], v[62:65]
	v_mfma_f32_16x16x32_bf16 v[58:61], v[156:159], v[180:183], v[58:61]
	v_mfma_f32_16x16x32_bf16 v[46:49], v[148:151], v[192:195], v[46:49]
	v_mfma_f32_16x16x32_bf16 v[42:45], v[156:159], v[192:195], v[42:45]
	v_mfma_f32_16x16x32_bf16 v[30:33], v[148:151], v[200:203], v[30:33]
	v_mfma_f32_16x16x32_bf16 v[26:29], v[156:159], v[200:203], v[26:29]
	v_mfma_f32_16x16x32_bf16 v[14:17], v[148:151], v[208:211], v[14:17]
	v_mfma_f32_16x16x32_bf16 v[10:13], v[156:159], v[208:211], v[10:13]
	v_mfma_f32_16x16x32_bf16 v[62:65], v[152:155], v[188:191], v[62:65]
	v_mfma_f32_16x16x32_bf16 v[58:61], v[160:163], v[188:191], v[58:61]
	v_mfma_f32_16x16x32_bf16 v[46:49], v[152:155], v[196:199], v[46:49]
	v_mfma_f32_16x16x32_bf16 v[42:45], v[160:163], v[196:199], v[42:45]
	v_mfma_f32_16x16x32_bf16 v[30:33], v[152:155], v[204:207], v[30:33]
	v_mfma_f32_16x16x32_bf16 v[26:29], v[160:163], v[204:207], v[26:29]
	v_mfma_f32_16x16x32_bf16 v[14:17], v[152:155], v[212:215], v[14:17]
	v_mfma_f32_16x16x32_bf16 v[10:13], v[160:163], v[212:215], v[10:13]
	s_setprio 0
	s_setprio 1
	v_mfma_f32_16x16x32_bf16 v[54:57], v[164:167], v[180:183], v[54:57]
	v_mfma_f32_16x16x32_bf16 v[50:53], v[172:175], v[180:183], v[50:53]
	v_mfma_f32_16x16x32_bf16 v[38:41], v[164:167], v[192:195], v[38:41]
	v_mfma_f32_16x16x32_bf16 v[34:37], v[172:175], v[192:195], v[34:37]
	v_mfma_f32_16x16x32_bf16 v[22:25], v[164:167], v[200:203], v[22:25]
	v_mfma_f32_16x16x32_bf16 v[18:21], v[172:175], v[200:203], v[18:21]
	v_mfma_f32_16x16x32_bf16 v[6:9], v[164:167], v[208:211], v[6:9]
	v_mfma_f32_16x16x32_bf16 v[2:5], v[172:175], v[208:211], v[2:5]
	v_mfma_f32_16x16x32_bf16 v[54:57], v[168:171], v[188:191], v[54:57]
	v_mfma_f32_16x16x32_bf16 v[50:53], v[176:179], v[188:191], v[50:53]
	v_mfma_f32_16x16x32_bf16 v[38:41], v[168:171], v[196:199], v[38:41]
	v_mfma_f32_16x16x32_bf16 v[34:37], v[176:179], v[196:199], v[34:37]
	v_mfma_f32_16x16x32_bf16 v[22:25], v[168:171], v[204:207], v[22:25]
	v_mfma_f32_16x16x32_bf16 v[18:21], v[176:179], v[204:207], v[18:21]
	v_mfma_f32_16x16x32_bf16 v[6:9], v[168:171], v[212:215], v[6:9]
	v_mfma_f32_16x16x32_bf16 v[2:5], v[176:179], v[212:215], v[2:5]
	s_barrier
	s_setprio 0
	s_add_i32 s57, 0, 0x18000
	v_add_u32_e32 v147, s57, v142
	s_add_i32 s58, 0, 0x1c000
	ds_read_b128 v[148:151], v147
	ds_read_b128 v[152:155], v147 offset:1024
	ds_read_b128 v[156:159], v147 offset:2048
	ds_read_b128 v[160:163], v147 offset:3072
	v_add_u32_e32 v147, s58, v142
	ds_read_b128 v[164:167], v147
	ds_read_b128 v[168:171], v147 offset:1024
	ds_read_b128 v[172:175], v147 offset:2048
	ds_read_b128 v[176:179], v147 offset:3072
	s_add_u32 s24, s24, s6
	s_addc_u32 s25, s25, s7
	s_mov_b32 m0, s34
	v_lshl_add_u64 v[226:227], s[24:25], 0, v[130:131]
	ds_read_b128 v[180:183], v146 offset:32768
	ds_read_b128 v[188:191], v146 offset:33792
	ds_read_b128 v[192:195], v146 offset:34816
	ds_read_b128 v[196:199], v146 offset:35840
	ds_read_b128 v[200:203], v146 offset:36864
	ds_read_b128 v[204:207], v146 offset:37888
	ds_read_b128 v[208:211], v146 offset:38912
	ds_read_b128 v[212:215], v146 offset:39936
	global_load_lds_dwordx4 v[226:227], off
	v_lshl_add_u64 v[226:227], s[24:25], 0, v[132:133]
	s_mov_b32 m0, s35
	s_nop 0
	global_load_lds_dwordx4 v[226:227], off
	s_waitcnt vmcnt(8)
	s_waitcnt lgkmcnt(0)
	s_barrier
	s_setprio 1
	s_waitcnt lgkmcnt(0)
	v_mfma_f32_16x16x32_bf16 v[126:129], v[148:151], v[180:183], v[126:129]
	v_mfma_f32_16x16x32_bf16 v[122:125], v[156:159], v[180:183], v[122:125]
	v_mfma_f32_16x16x32_bf16 v[110:113], v[148:151], v[192:195], v[110:113]
	v_mfma_f32_16x16x32_bf16 v[106:109], v[156:159], v[192:195], v[106:109]
	v_mfma_f32_16x16x32_bf16 v[94:97], v[148:151], v[200:203], v[94:97]
	v_mfma_f32_16x16x32_bf16 v[90:93], v[156:159], v[200:203], v[90:93]
	v_mfma_f32_16x16x32_bf16 v[78:81], v[148:151], v[208:211], v[78:81]
	v_mfma_f32_16x16x32_bf16 v[74:77], v[156:159], v[208:211], v[74:77]
	v_mfma_f32_16x16x32_bf16 v[126:129], v[152:155], v[188:191], v[126:129]
	v_mfma_f32_16x16x32_bf16 v[122:125], v[160:163], v[188:191], v[122:125]
	v_mfma_f32_16x16x32_bf16 v[110:113], v[152:155], v[196:199], v[110:113]
	v_mfma_f32_16x16x32_bf16 v[106:109], v[160:163], v[196:199], v[106:109]
	v_mfma_f32_16x16x32_bf16 v[94:97], v[152:155], v[204:207], v[94:97]
	v_mfma_f32_16x16x32_bf16 v[90:93], v[160:163], v[204:207], v[90:93]
	v_mfma_f32_16x16x32_bf16 v[78:81], v[152:155], v[212:215], v[78:81]
	v_mfma_f32_16x16x32_bf16 v[74:77], v[160:163], v[212:215], v[74:77]
	s_setprio 0
	s_setprio 1
	v_mfma_f32_16x16x32_bf16 v[118:121], v[164:167], v[180:183], v[118:121]
	v_mfma_f32_16x16x32_bf16 v[114:117], v[172:175], v[180:183], v[114:117]
	v_mfma_f32_16x16x32_bf16 v[102:105], v[164:167], v[192:195], v[102:105]
	v_mfma_f32_16x16x32_bf16 v[98:101], v[172:175], v[192:195], v[98:101]
	v_mfma_f32_16x16x32_bf16 v[86:89], v[164:167], v[200:203], v[86:89]
	v_mfma_f32_16x16x32_bf16 v[82:85], v[172:175], v[200:203], v[82:85]
	v_mfma_f32_16x16x32_bf16 v[70:73], v[164:167], v[208:211], v[70:73]
	v_mfma_f32_16x16x32_bf16 v[66:69], v[172:175], v[208:211], v[66:69]
	v_mfma_f32_16x16x32_bf16 v[118:121], v[168:171], v[188:191], v[118:121]
	v_mfma_f32_16x16x32_bf16 v[114:117], v[176:179], v[188:191], v[114:117]
	v_mfma_f32_16x16x32_bf16 v[102:105], v[168:171], v[196:199], v[102:105]
	v_mfma_f32_16x16x32_bf16 v[98:101], v[176:179], v[196:199], v[98:101]
	v_mfma_f32_16x16x32_bf16 v[86:89], v[168:171], v[204:207], v[86:89]
	v_mfma_f32_16x16x32_bf16 v[82:85], v[176:179], v[204:207], v[82:85]
	v_mfma_f32_16x16x32_bf16 v[70:73], v[168:171], v[212:215], v[70:73]
	v_mfma_f32_16x16x32_bf16 v[66:69], v[176:179], v[212:215], v[66:69]
	s_barrier
; #define PG8_STAGE(bufoff, gbase, voff) do { _Pragma("unroll") for (int _i = 0; _i < 2; ++_i) \
;         __builtin_amdgcn_global_load_lds((const unsigned*)((const char*)(gbase) + (voff)[_i]), (PG8_LAS unsigned*)(lds + (bufoff) + ldsw + _i * 8192), 16, 0, 0); } while (0)
; #define PG8_LDA(dst, b, h) do { _Pragma("unroll") for (int m = 0; m < 4; ++m) _Pragma("unroll") for (int k = 0; k < 2; ++k) dst[m][k] = *(const PG8_LAS bf16x8*)(lds + PG8_SA(b, h) + aoff + m * 2048 + k * 1024); } while (0)
; #define PG8_MMA(ai, bj, At, Bt) do { __builtin_amdgcn_s_setprio(1); _Pragma("unroll") for (int m = 0; m < 4; ++m) _Pragma("unroll") for (int n = 0; n < 2; ++n) _Pragma("unroll") for (int k = 0; k < 2; ++k) \
;         acc[ai][bj][m][n] = __builtin_amdgcn_mfma_f32_16x16x32_bf16(Bt[n][k], At[m][k], acc[ai][bj][m][n], 0, 0, 0); __builtin_amdgcn_s_setprio(0); } while (0)
; #define PG8_WAIT_V(n) asm volatile("s_waitcnt vmcnt(" #n ")" ::: "memory")
; #define PG8_WAIT_L(n) asm volatile("s_waitcnt lgkmcnt(" #n ")" ::: "memory")
; #define PG8_BAR __builtin_amdgcn_s_barrier()
; #define PG8_SCHED __builtin_amdgcn_sched_barrier(0)
; template <class Epi, class Sched, bool ALIGN_EPI = false, bool SP2 = false>
; __device__ __forceinline__ void gemm_phase(PG8_LAS unsigned char* lds, const Gemm g, const Sched& S, const Epi& E) {
;     ...
;         for (int t = 0; t < nt; t += 2) {
;             const bool last = (t == nt - 2);
;             const char* a1 = cA + (size_t)(t + 1) * kstep;
;             const char* a2 = last ? nA : cA + (size_t)(t + 2) * kstep; const char* b2 = last ? nB : cB + (size_t)(t + 2) * kstep;
;             const char* a3 = a2 + kstep; const char* b3 = b2 + kstep;
;     ...
;             PG8_LDA(At, 1, 1); PG8_STAGE(PG8_SB(1, 0), b3, voffB); PG8_STAGE(PG8_SB(1, 1), b3 + hstep, voffB); PG8_STAGE(PG8_SA(1, 0), a3, voffA);
;             PG8_WAIT_V(8); PG8_WAIT_L(0); PG8_BAR; PG8_MMA(1, 0, At, B0); PG8_MMA(1, 1, At, B1); PG8_BAR; PG8_SCHED;
	s_setprio 0
	s_add_i32 s24, s57, s29
	v_lshl_add_u64 v[184:185], v[184:185], 0, s[16:17]
	s_mov_b32 m0, s24
	ds_read_b128 v[180:183], v146 offset:49152
	ds_read_b128 v[188:191], v146 offset:50176
	ds_read_b128 v[192:195], v146 offset:51200
	ds_read_b128 v[196:199], v146 offset:52224
	ds_read_b128 v[200:203], v146 offset:53248
	ds_read_b128 v[204:207], v146 offset:54272
	ds_read_b128 v[208:211], v146 offset:55296
	ds_read_b128 v[212:215], v146 offset:56320
	global_load_lds_dwordx4 v[184:185], off
	v_lshl_add_u64 v[184:185], v[216:217], 0, s[16:17]
	s_add_i32 m0, s24, 0x2000
	s_add_i32 s24, s58, s29
	global_load_lds_dwordx4 v[184:185], off
	v_lshl_add_u64 v[184:185], v[218:219], 0, s[16:17]
	s_mov_b32 m0, s24
	s_nop 0
	global_load_lds_dwordx4 v[184:185], off
	v_lshl_add_u64 v[184:185], v[220:221], 0, s[16:17]
	s_add_i32 m0, s24, 0x2000
	s_nop 0
	global_load_lds_dwordx4 v[184:185], off
	v_lshl_add_u64 v[184:185], v[222:223], 0, s[16:17]
	s_mov_b32 m0, s38
	s_nop 0
	global_load_lds_dwordx4 v[184:185], off
	v_lshl_add_u64 v[184:185], v[224:225], 0, s[16:17]
	s_mov_b32 m0, s39
	s_nop 0
	global_load_lds_dwordx4 v[184:185], off
	s_waitcnt vmcnt(8)
	s_waitcnt lgkmcnt(0)
	s_barrier
	s_setprio 1
	s_waitcnt lgkmcnt(0)
	v_mfma_f32_16x16x32_bf16 v[62:65], v[148:151], v[180:183], v[62:65]
	v_mfma_f32_16x16x32_bf16 v[58:61], v[156:159], v[180:183], v[58:61]
	v_mfma_f32_16x16x32_bf16 v[46:49], v[148:151], v[192:195], v[46:49]
	v_mfma_f32_16x16x32_bf16 v[42:45], v[156:159], v[192:195], v[42:45]
	v_mfma_f32_16x16x32_bf16 v[30:33], v[148:151], v[200:203], v[30:33]
	v_mfma_f32_16x16x32_bf16 v[26:29], v[156:159], v[200:203], v[26:29]
	v_mfma_f32_16x16x32_bf16 v[14:17], v[148:151], v[208:211], v[14:17]
	v_mfma_f32_16x16x32_bf16 v[10:13], v[156:159], v[208:211], v[10:13]
	v_mfma_f32_16x16x32_bf16 v[62:65], v[152:155], v[188:191], v[62:65]
	v_mfma_f32_16x16x32_bf16 v[58:61], v[160:163], v[188:191], v[58:61]
	v_mfma_f32_16x16x32_bf16 v[46:49], v[152:155], v[196:199], v[46:49]
	v_mfma_f32_16x16x32_bf16 v[42:45], v[160:163], v[196:199], v[42:45]
	v_mfma_f32_16x16x32_bf16 v[30:33], v[152:155], v[204:207], v[30:33]
	v_mfma_f32_16x16x32_bf16 v[26:29], v[160:163], v[204:207], v[26:29]
	v_mfma_f32_16x16x32_bf16 v[14:17], v[152:155], v[212:215], v[14:17]
	v_mfma_f32_16x16x32_bf16 v[10:13], v[160:163], v[212:215], v[10:13]
	s_setprio 0
	s_setprio 1
	v_mfma_f32_16x16x32_bf16 v[54:57], v[164:167], v[180:183], v[54:57]
	v_mfma_f32_16x16x32_bf16 v[50:53], v[172:175], v[180:183], v[50:53]
	v_mfma_f32_16x16x32_bf16 v[38:41], v[164:167], v[192:195], v[38:41]
	v_mfma_f32_16x16x32_bf16 v[34:37], v[172:175], v[192:195], v[34:37]
	v_mfma_f32_16x16x32_bf16 v[22:25], v[164:167], v[200:203], v[22:25]
	v_mfma_f32_16x16x32_bf16 v[18:21], v[172:175], v[200:203], v[18:21]
	v_mfma_f32_16x16x32_bf16 v[6:9], v[164:167], v[208:211], v[6:9]
	v_mfma_f32_16x16x32_bf16 v[2:5], v[172:175], v[208:211], v[2:5]
	v_mfma_f32_16x16x32_bf16 v[54:57], v[168:171], v[188:191], v[54:57]
	v_mfma_f32_16x16x32_bf16 v[50:53], v[176:179], v[188:191], v[50:53]
	v_mfma_f32_16x16x32_bf16 v[38:41], v[168:171], v[196:199], v[38:41]
	v_mfma_f32_16x16x32_bf16 v[34:37], v[176:179], v[196:199], v[34:37]
	v_mfma_f32_16x16x32_bf16 v[22:25], v[168:171], v[204:207], v[22:25]
	v_mfma_f32_16x16x32_bf16 v[18:21], v[176:179], v[204:207], v[18:21]
	v_mfma_f32_16x16x32_bf16 v[6:9], v[168:171], v[212:215], v[6:9]
	v_mfma_f32_16x16x32_bf16 v[2:5], v[176:179], v[212:215], v[2:5]
	s_barrier
	s_setprio 0
	s_add_u32 s22, s22, 0x100
	s_addc_u32 s23, s23, 0
	s_add_u32 s54, s54, 0x100
	s_addc_u32 s55, s55, 0
	s_cmp_ge_i32 s56, 2
	s_mov_b32 s24, s56
	s_cbranch_scc0 .LBB0_791

; #define PG8_STAGE(bufoff, gbase, voff) do { _Pragma("unroll") for (int _i = 0; _i < 2; ++_i) \
;         __builtin_amdgcn_global_load_lds((const unsigned*)((const char*)(gbase) + (voff)[_i]), (PG8_LAS unsigned*)(lds + (bufoff) + ldsw + _i * 8192), 16, 0, 0); } while (0)
; #define PG8_LDA(dst, b, h) do { _Pragma("unroll") for (int m = 0; m < 4; ++m) _Pragma("unroll") for (int k = 0; k < 2; ++k) dst[m][k] = *(const PG8_LAS bf16x8*)(lds + PG8_SA(b, h) + aoff + m * 2048 + k * 1024); } while (0)
; #define PG8_LDB(dst, b, h) do { _Pragma("unroll") for (int n = 0; n < 2; ++n) _Pragma("unroll") for (int k = 0; k < 2; ++k) dst[n][k] = *(const PG8_LAS bf16x8*)(lds + PG8_SB(b, h) + boff + n * 2048 + k * 1024); } while (0)
; #define PG8_MMA(ai, bj, At, Bt) do { __builtin_amdgcn_s_setprio(1); _Pragma("unroll") for (int m = 0; m < 4; ++m) _Pragma("unroll") for (int n = 0; n < 2; ++n) _Pragma("unroll") for (int k = 0; k < 2; ++k) \
;         acc[ai][bj][m][n] = __builtin_amdgcn_mfma_f32_16x16x32_bf16(Bt[n][k], At[m][k], acc[ai][bj][m][n], 0, 0, 0); __builtin_amdgcn_s_setprio(0); } while (0)
; #define PG8_WAIT_V(n) asm volatile("s_waitcnt vmcnt(" #n ")" ::: "memory")
; #define PG8_BAR __builtin_amdgcn_s_barrier()
; template <class Epi, class Sched, bool ALIGN_EPI = false, bool SP2 = false>
; __device__ __forceinline__ void gemm_phase(PG8_LAS unsigned char* lds, const Gemm g, const Sched& S, const Epi& E) {
;     ...
;         for (int t = 0; t < nt; t += 2) {
;             const bool last = (t == nt - 2);
;             const char* a1 = cA + (size_t)(t + 1) * kstep;
;             const char* a2 = last ? nA : cA + (size_t)(t + 2) * kstep; const char* b2 = last ? nB : cB + (size_t)(t + 2) * kstep;
;             const char* a3 = a2 + kstep; const char* b3 = b2 + kstep;
;             if (last && has_next) S.a_ready(nxt);
;             if constexpr (SP2) {
;             PG8_LDB(B0, 0, 0); PG8_LDB(B1, 0, 1); PG8_SCHED; PG8_LDA(At, 0, 0); PG8_STAGE(PG8_SA(1, 1), a1 + hstep, voffA);
;             PG8_WAIT_V(8); PG8_WAIT_L(0); PG8_BAR; PG8_MMA(0, 0, At, B0); PG8_MMA(0, 1, At, B1); PG8_BAR; PG8_SCHED;
;             PG8_LDA(At, 0, 1); PG8_STAGE(PG8_SB(0, 0), b2, voffB); PG8_STAGE(PG8_SB(0, 1), b2 + hstep, voffB); PG8_STAGE(PG8_SA(0, 0), a2, voffA);
;             PG8_WAIT_V(8); PG8_WAIT_L(0); PG8_BAR; PG8_MMA(1, 0, At, B0); PG8_MMA(1, 1, At, B1); PG8_BAR; PG8_SCHED;
.LBB0_1405:
	v_add_u32_e32 v162, s56, v148
	v_add_u32_e32 v178, s57, v148
	s_add_u32 s34, s18, s30
	ds_read_b128 v[150:153], v162
	ds_read_b128 v[154:157], v162 offset:1024
	ds_read_b128 v[158:161], v162 offset:2048
	ds_read_b128 v[162:165], v162 offset:3072
	ds_read_b128 v[166:169], v178
	ds_read_b128 v[170:173], v178 offset:1024
	ds_read_b128 v[174:177], v178 offset:2048
	ds_read_b128 v[178:181], v178 offset:3072
	s_addc_u32 s35, s19, s31
	s_add_u32 s34, s34, 0x100
	s_addc_u32 s35, s35, 0
	s_add_u32 s65, s59, s30
	s_addc_u32 s66, s60, s31
	s_cmpk_eq_i32 s30, 0x700
	s_cselect_b32 s37, s25, s35
	s_cselect_b32 s36, s61, s34
	s_cselect_b32 s35, s23, s66
	s_cselect_b32 s34, s62, s65
	v_lshl_add_u64 v[216:217], v[142:143], 0, s[30:31]
	s_add_i32 m0, s42, 0xc000
	ds_read_b128 v[182:185], v149
	ds_read_b128 v[188:191], v149 offset:1024
	ds_read_b128 v[192:195], v149 offset:2048
	ds_read_b128 v[196:199], v149 offset:3072
	ds_read_b128 v[200:203], v149 offset:4096
	ds_read_b128 v[204:207], v149 offset:5120
	ds_read_b128 v[208:211], v149 offset:6144
	ds_read_b128 v[212:215], v149 offset:7168
	global_load_lds_dwordx4 v[216:217], off
	v_lshl_add_u64 v[216:217], v[144:145], 0, s[30:31]
	s_add_i32 m0, s42, 0xe000
	s_nop 0
	global_load_lds_dwordx4 v[216:217], off
	s_waitcnt vmcnt(8)
	s_waitcnt lgkmcnt(0)
	s_barrier
	s_setprio 1
	s_waitcnt lgkmcnt(0)
	v_mfma_f32_16x16x32_bf16 v[110:113], v[150:153], v[182:185], v[110:113]
	v_mfma_f32_16x16x32_bf16 v[74:77], v[158:161], v[182:185], v[74:77]
	v_mfma_f32_16x16x32_bf16 v[118:121], v[150:153], v[192:195], v[118:121]
	v_mfma_f32_16x16x32_bf16 v[94:97], v[158:161], v[192:195], v[94:97]
	v_mfma_f32_16x16x32_bf16 v[126:129], v[150:153], v[200:203], v[126:129]
	v_mfma_f32_16x16x32_bf16 v[106:109], v[158:161], v[200:203], v[106:109]
	v_mfma_f32_16x16x32_bf16 v[122:125], v[150:153], v[208:211], v[122:125]
	v_mfma_f32_16x16x32_bf16 v[114:117], v[158:161], v[208:211], v[114:117]
	v_mfma_f32_16x16x32_bf16 v[110:113], v[154:157], v[188:191], v[110:113]
	v_mfma_f32_16x16x32_bf16 v[74:77], v[162:165], v[188:191], v[74:77]
	v_mfma_f32_16x16x32_bf16 v[118:121], v[154:157], v[196:199], v[118:121]
	v_mfma_f32_16x16x32_bf16 v[94:97], v[162:165], v[196:199], v[94:97]
	v_mfma_f32_16x16x32_bf16 v[126:129], v[154:157], v[204:207], v[126:129]
	v_mfma_f32_16x16x32_bf16 v[106:109], v[162:165], v[204:207], v[106:109]
	v_mfma_f32_16x16x32_bf16 v[122:125], v[154:157], v[212:215], v[122:125]
	v_mfma_f32_16x16x32_bf16 v[114:117], v[162:165], v[212:215], v[114:117]
	s_setprio 0
	s_setprio 1
	v_mfma_f32_16x16x32_bf16 v[46:49], v[166:169], v[182:185], v[46:49]
	v_mfma_f32_16x16x32_bf16 v[14:17], v[174:177], v[182:185], v[14:17]
	v_mfma_f32_16x16x32_bf16 v[54:57], v[166:169], v[192:195], v[54:57]
	v_mfma_f32_16x16x32_bf16 v[30:33], v[174:177], v[192:195], v[30:33]
	v_mfma_f32_16x16x32_bf16 v[70:73], v[166:169], v[200:203], v[70:73]
	v_mfma_f32_16x16x32_bf16 v[42:45], v[174:177], v[200:203], v[42:45]
	v_mfma_f32_16x16x32_bf16 v[86:89], v[166:169], v[208:211], v[86:89]
	v_mfma_f32_16x16x32_bf16 v[50:53], v[174:177], v[208:211], v[50:53]
	v_mfma_f32_16x16x32_bf16 v[46:49], v[170:173], v[188:191], v[46:49]
	v_mfma_f32_16x16x32_bf16 v[14:17], v[178:181], v[188:191], v[14:17]
	v_mfma_f32_16x16x32_bf16 v[54:57], v[170:173], v[196:199], v[54:57]
	v_mfma_f32_16x16x32_bf16 v[30:33], v[178:181], v[196:199], v[30:33]
	v_mfma_f32_16x16x32_bf16 v[70:73], v[170:173], v[204:207], v[70:73]
	v_mfma_f32_16x16x32_bf16 v[42:45], v[178:181], v[204:207], v[42:45]
	v_mfma_f32_16x16x32_bf16 v[86:89], v[170:173], v[212:215], v[86:89]
	v_mfma_f32_16x16x32_bf16 v[50:53], v[178:181], v[212:215], v[50:53]
	s_barrier
	s_setprio 0
	s_add_i32 s65, s56, s41
	v_lshl_add_u64 v[216:217], s[34:35], 0, v[130:131]
	s_mov_b32 m0, s65
	ds_read_b128 v[182:185], v149 offset:16384
	ds_read_b128 v[188:191], v149 offset:17408
	ds_read_b128 v[192:195], v149 offset:18432
	ds_read_b128 v[196:199], v149 offset:19456
	ds_read_b128 v[200:203], v149 offset:20480
	ds_read_b128 v[204:207], v149 offset:21504
	ds_read_b128 v[208:211], v149 offset:22528
	ds_read_b128 v[212:215], v149 offset:23552
	global_load_lds_dwordx4 v[216:217], off
	s_add_i32 m0, s65, 0x2000
	s_add_u32 s66, s34, 0x40000
	v_lshl_add_u64 v[218:219], s[34:35], 0, v[132:133]
	s_addc_u32 s67, s35, 0
	s_add_i32 s65, s57, s41
	global_load_lds_dwordx4 v[218:219], off
	v_lshl_add_u64 v[220:221], s[66:67], 0, v[130:131]
	s_mov_b32 m0, s65
	v_lshl_add_u64 v[222:223], s[36:37], 0, v[132:133]
	global_load_lds_dwordx4 v[220:221], off
	v_lshl_add_u64 v[220:221], s[66:67], 0, v[132:133]
	s_add_i32 m0, s65, 0x2000
	s_nop 0
	global_load_lds_dwordx4 v[220:221], off
	v_lshl_add_u64 v[220:221], s[36:37], 0, v[130:131]
	s_mov_b32 m0, s42
	s_nop 0
	global_load_lds_dwordx4 v[220:221], off
	s_mov_b32 m0, s48
	s_nop 0
	global_load_lds_dwordx4 v[222:223], off
	s_waitcnt vmcnt(8)
	s_waitcnt lgkmcnt(0)
	s_barrier
; #define PG8_STAGE(bufoff, gbase, voff) do { _Pragma("unroll") for (int _i = 0; _i < 2; ++_i) \
;         __builtin_amdgcn_global_load_lds((const unsigned*)((const char*)(gbase) + (voff)[_i]), (PG8_LAS unsigned*)(lds + (bufoff) + ldsw + _i * 8192), 16, 0, 0); } while (0)
; #define PG8_LDA(dst, b, h) do { _Pragma("unroll") for (int m = 0; m < 4; ++m) _Pragma("unroll") for (int k = 0; k < 2; ++k) dst[m][k] = *(const PG8_LAS bf16x8*)(lds + PG8_SA(b, h) + aoff + m * 2048 + k * 1024); } while (0)
; #define PG8_LDB(dst, b, h) do { _Pragma("unroll") for (int n = 0; n < 2; ++n) _Pragma("unroll") for (int k = 0; k < 2; ++k) dst[n][k] = *(const PG8_LAS bf16x8*)(lds + PG8_SB(b, h) + boff + n * 2048 + k * 1024); } while (0)
; #define PG8_MMA(ai, bj, At, Bt) do { __builtin_amdgcn_s_setprio(1); _Pragma("unroll") for (int m = 0; m < 4; ++m) _Pragma("unroll") for (int n = 0; n < 2; ++n) _Pragma("unroll") for (int k = 0; k < 2; ++k) \
;         acc[ai][bj][m][n] = __builtin_amdgcn_mfma_f32_16x16x32_bf16(Bt[n][k], At[m][k], acc[ai][bj][m][n], 0, 0, 0); __builtin_amdgcn_s_setprio(0); } while (0)
; #define PG8_WAIT_V(n) asm volatile("s_waitcnt vmcnt(" #n ")" ::: "memory")
; #define PG8_WAIT_L(n) asm volatile("s_waitcnt lgkmcnt(" #n ")" ::: "memory")
; #define PG8_BAR __builtin_amdgcn_s_barrier()
; #define PG8_SCHED __builtin_amdgcn_sched_barrier(0)
; template <class Epi, class Sched, bool ALIGN_EPI = false, bool SP2 = false>
; __device__ __forceinline__ void gemm_phase(PG8_LAS unsigned char* lds, const Gemm g, const Sched& S, const Epi& E) {
;     ...
;             PG8_WAIT_V(8); PG8_WAIT_L(0); PG8_BAR; PG8_MMA(1, 0, At, B0); PG8_MMA(1, 1, At, B1); PG8_BAR; PG8_SCHED;
;             PG8_LDB(B0, 1, 0); PG8_LDB(B1, 1, 1); PG8_SCHED; PG8_LDA(At, 1, 0); PG8_STAGE(PG8_SA(0, 1), a2 + hstep, voffA);
;             PG8_WAIT_V(8); PG8_WAIT_L(0); PG8_BAR; PG8_MMA(0, 0, At, B0); PG8_MMA(0, 1, At, B1); PG8_BAR; PG8_SCHED;
	s_setprio 1
	s_waitcnt lgkmcnt(0)
	v_mfma_f32_16x16x32_bf16 v[102:105], v[150:153], v[182:185], v[102:105]
	v_mfma_f32_16x16x32_bf16 v[98:101], v[158:161], v[182:185], v[98:101]
	v_mfma_f32_16x16x32_bf16 v[82:85], v[150:153], v[192:195], v[82:85]
	v_mfma_f32_16x16x32_bf16 v[78:81], v[158:161], v[192:195], v[78:81]
	v_mfma_f32_16x16x32_bf16 v[38:41], v[150:153], v[200:203], v[38:41]
	v_mfma_f32_16x16x32_bf16 v[34:37], v[158:161], v[200:203], v[34:37]
	v_mfma_f32_16x16x32_bf16 v[18:21], v[150:153], v[208:211], v[18:21]
	v_mfma_f32_16x16x32_bf16 v[10:13], v[158:161], v[208:211], v[10:13]
	v_mfma_f32_16x16x32_bf16 v[102:105], v[154:157], v[188:191], v[102:105]
	v_mfma_f32_16x16x32_bf16 v[98:101], v[162:165], v[188:191], v[98:101]
	v_mfma_f32_16x16x32_bf16 v[82:85], v[154:157], v[196:199], v[82:85]
	v_mfma_f32_16x16x32_bf16 v[78:81], v[162:165], v[196:199], v[78:81]
	v_mfma_f32_16x16x32_bf16 v[38:41], v[154:157], v[204:207], v[38:41]
	v_mfma_f32_16x16x32_bf16 v[34:37], v[162:165], v[204:207], v[34:37]
	v_mfma_f32_16x16x32_bf16 v[18:21], v[154:157], v[212:215], v[18:21]
	v_mfma_f32_16x16x32_bf16 v[10:13], v[162:165], v[212:215], v[10:13]
	s_setprio 0
	s_setprio 1
	v_mfma_f32_16x16x32_bf16 v[90:93], v[166:169], v[182:185], v[90:93]
	v_mfma_f32_16x16x32_bf16 v[66:69], v[174:177], v[182:185], v[66:69]
	v_mfma_f32_16x16x32_bf16 v[62:65], v[166:169], v[192:195], v[62:65]
	v_mfma_f32_16x16x32_bf16 v[58:61], v[174:177], v[192:195], v[58:61]
	v_mfma_f32_16x16x32_bf16 v[26:29], v[166:169], v[200:203], v[26:29]
	v_mfma_f32_16x16x32_bf16 v[22:25], v[174:177], v[200:203], v[22:25]
	v_mfma_f32_16x16x32_bf16 v[6:9], v[166:169], v[208:211], v[6:9]
	v_mfma_f32_16x16x32_bf16 v[2:5], v[174:177], v[208:211], v[2:5]
	v_mfma_f32_16x16x32_bf16 v[90:93], v[170:173], v[188:191], v[90:93]
	v_mfma_f32_16x16x32_bf16 v[66:69], v[178:181], v[188:191], v[66:69]
	v_mfma_f32_16x16x32_bf16 v[62:65], v[170:173], v[196:199], v[62:65]
	v_mfma_f32_16x16x32_bf16 v[58:61], v[178:181], v[196:199], v[58:61]
	v_mfma_f32_16x16x32_bf16 v[26:29], v[170:173], v[204:207], v[26:29]
	v_mfma_f32_16x16x32_bf16 v[22:25], v[178:181], v[204:207], v[22:25]
	v_mfma_f32_16x16x32_bf16 v[6:9], v[170:173], v[212:215], v[6:9]
	v_mfma_f32_16x16x32_bf16 v[2:5], v[178:181], v[212:215], v[2:5]
	s_barrier
	s_setprio 0
	s_add_i32 s65, 0, 0x18000
	s_add_i32 s66, 0, 0x1c000
	v_add_u32_e32 v162, s65, v148
	v_add_u32_e32 v178, s66, v148
	ds_read_b128 v[150:153], v162
	ds_read_b128 v[154:157], v162 offset:1024
	ds_read_b128 v[158:161], v162 offset:2048
	ds_read_b128 v[162:165], v162 offset:3072
	ds_read_b128 v[166:169], v178
	ds_read_b128 v[170:173], v178 offset:1024
	ds_read_b128 v[174:177], v178 offset:2048
	ds_read_b128 v[178:181], v178 offset:3072
	s_add_u32 s36, s36, 0x40000
	s_addc_u32 s37, s37, 0
	s_mov_b32 m0, s49
	v_lshl_add_u64 v[224:225], s[36:37], 0, v[130:131]
	ds_read_b128 v[182:185], v149 offset:32768
	ds_read_b128 v[188:191], v149 offset:33792
	ds_read_b128 v[192:195], v149 offset:34816
	ds_read_b128 v[196:199], v149 offset:35840
	ds_read_b128 v[200:203], v149 offset:36864
	ds_read_b128 v[204:207], v149 offset:37888
	ds_read_b128 v[208:211], v149 offset:38912
	ds_read_b128 v[212:215], v149 offset:39936
	global_load_lds_dwordx4 v[224:225], off
	v_lshl_add_u64 v[224:225], s[36:37], 0, v[132:133]
	s_mov_b32 m0, s51
	s_nop 0
	global_load_lds_dwordx4 v[224:225], off
	s_waitcnt vmcnt(8)
	s_waitcnt lgkmcnt(0)
	s_barrier
	s_setprio 1
	s_waitcnt lgkmcnt(0)
	v_mfma_f32_16x16x32_bf16 v[110:113], v[150:153], v[182:185], v[110:113]
	v_mfma_f32_16x16x32_bf16 v[74:77], v[158:161], v[182:185], v[74:77]
	v_mfma_f32_16x16x32_bf16 v[118:121], v[150:153], v[192:195], v[118:121]
	v_mfma_f32_16x16x32_bf16 v[94:97], v[158:161], v[192:195], v[94:97]
	v_mfma_f32_16x16x32_bf16 v[126:129], v[150:153], v[200:203], v[126:129]
	v_mfma_f32_16x16x32_bf16 v[106:109], v[158:161], v[200:203], v[106:109]
	v_mfma_f32_16x16x32_bf16 v[122:125], v[150:153], v[208:211], v[122:125]
	v_mfma_f32_16x16x32_bf16 v[114:117], v[158:161], v[208:211], v[114:117]
	v_mfma_f32_16x16x32_bf16 v[110:113], v[154:157], v[188:191], v[110:113]
	v_mfma_f32_16x16x32_bf16 v[74:77], v[162:165], v[188:191], v[74:77]
	v_mfma_f32_16x16x32_bf16 v[118:121], v[154:157], v[196:199], v[118:121]
	v_mfma_f32_16x16x32_bf16 v[94:97], v[162:165], v[196:199], v[94:97]
	v_mfma_f32_16x16x32_bf16 v[126:129], v[154:157], v[204:207], v[126:129]
	v_mfma_f32_16x16x32_bf16 v[106:109], v[162:165], v[204:207], v[106:109]
	v_mfma_f32_16x16x32_bf16 v[122:125], v[154:157], v[212:215], v[122:125]
	v_mfma_f32_16x16x32_bf16 v[114:117], v[162:165], v[212:215], v[114:117]
	s_setprio 0
	s_setprio 1
	v_mfma_f32_16x16x32_bf16 v[46:49], v[166:169], v[182:185], v[46:49]
	v_mfma_f32_16x16x32_bf16 v[14:17], v[174:177], v[182:185], v[14:17]
	v_mfma_f32_16x16x32_bf16 v[54:57], v[166:169], v[192:195], v[54:57]
	v_mfma_f32_16x16x32_bf16 v[30:33], v[174:177], v[192:195], v[30:33]
	v_mfma_f32_16x16x32_bf16 v[70:73], v[166:169], v[200:203], v[70:73]
	v_mfma_f32_16x16x32_bf16 v[42:45], v[174:177], v[200:203], v[42:45]
	v_mfma_f32_16x16x32_bf16 v[86:89], v[166:169], v[208:211], v[86:89]
	v_mfma_f32_16x16x32_bf16 v[50:53], v[174:177], v[208:211], v[50:53]
	v_mfma_f32_16x16x32_bf16 v[46:49], v[170:173], v[188:191], v[46:49]
	v_mfma_f32_16x16x32_bf16 v[14:17], v[178:181], v[188:191], v[14:17]
	v_mfma_f32_16x16x32_bf16 v[54:57], v[170:173], v[196:199], v[54:57]
	v_mfma_f32_16x16x32_bf16 v[30:33], v[178:181], v[196:199], v[30:33]
	v_mfma_f32_16x16x32_bf16 v[70:73], v[170:173], v[204:207], v[70:73]
	v_mfma_f32_16x16x32_bf16 v[42:45], v[178:181], v[204:207], v[42:45]
	v_mfma_f32_16x16x32_bf16 v[86:89], v[170:173], v[212:215], v[86:89]
	v_mfma_f32_16x16x32_bf16 v[50:53], v[178:181], v[212:215], v[50:53]
	s_barrier
; #define PG8_STAGE(bufoff, gbase, voff) do { _Pragma("unroll") for (int _i = 0; _i < 2; ++_i) \
;         __builtin_amdgcn_global_load_lds((const unsigned*)((const char*)(gbase) + (voff)[_i]), (PG8_LAS unsigned*)(lds + (bufoff) + ldsw + _i * 8192), 16, 0, 0); } while (0)
; #define PG8_LDA(dst, b, h) do { _Pragma("unroll") for (int m = 0; m < 4; ++m) _Pragma("unroll") for (int k = 0; k < 2; ++k) dst[m][k] = *(const PG8_LAS bf16x8*)(lds + PG8_SA(b, h) + aoff + m * 2048 + k * 1024); } while (0)
; #define PG8_MMA(ai, bj, At, Bt) do { __builtin_amdgcn_s_setprio(1); _Pragma("unroll") for (int m = 0; m < 4; ++m) _Pragma("unroll") for (int n = 0; n < 2; ++n) _Pragma("unroll") for (int k = 0; k < 2; ++k) \
;         acc[ai][bj][m][n] = __builtin_amdgcn_mfma_f32_16x16x32_bf16(Bt[n][k], At[m][k], acc[ai][bj][m][n], 0, 0, 0); __builtin_amdgcn_s_setprio(0); } while (0)
; #define PG8_WAIT_V(n) asm volatile("s_waitcnt vmcnt(" #n ")" ::: "memory")
; #define PG8_WAIT_L(n) asm volatile("s_waitcnt lgkmcnt(" #n ")" ::: "memory")
; #define PG8_BAR __builtin_amdgcn_s_barrier()
; #define PG8_SCHED __builtin_amdgcn_sched_barrier(0)
; template <class Epi, class Sched, bool ALIGN_EPI = false, bool SP2 = false>
; __device__ __forceinline__ void gemm_phase(PG8_LAS unsigned char* lds, const Gemm g, const Sched& S, const Epi& E) {
;     ...
;             PG8_LDA(At, 1, 1); PG8_STAGE(PG8_SB(1, 0), b3, voffB); PG8_STAGE(PG8_SB(1, 1), b3 + hstep, voffB); PG8_STAGE(PG8_SA(1, 0), a3, voffA);
;             PG8_WAIT_V(8); PG8_WAIT_L(0); PG8_BAR; PG8_MMA(1, 0, At, B0); PG8_MMA(1, 1, At, B1); PG8_BAR; PG8_SCHED;
;     ...
;         if (!has_next) break;
; #pragma unroll
;         for (int a = 0; a < 2; ++a)
; #pragma unroll
;             for (int b = 0; b < 2; ++b)
; #pragma unroll
;                 for (int m = 0; m < 4; ++m)
; #pragma unroll
;                     for (int n = 0; n < 2; ++n) acc[a][b][m][n] = (f32x4){0.f, 0.f, 0.f, 0.f};
;         cur = nxt; cA = nA; cB = nB; ++ui;
	s_setprio 0
	s_add_i32 s36, s65, s41
	v_lshl_add_u64 v[216:217], v[216:217], 0, s[20:21]
	s_mov_b32 m0, s36
	ds_read_b128 v[182:185], v149 offset:49152
	ds_read_b128 v[188:191], v149 offset:50176
	ds_read_b128 v[192:195], v149 offset:51200
	ds_read_b128 v[196:199], v149 offset:52224
	ds_read_b128 v[200:203], v149 offset:53248
	ds_read_b128 v[204:207], v149 offset:54272
	ds_read_b128 v[208:211], v149 offset:55296
	ds_read_b128 v[212:215], v149 offset:56320
	global_load_lds_dwordx4 v[216:217], off
	s_add_i32 m0, s36, 0x2000
	s_add_u32 s34, s34, 0x40080
	v_lshl_add_u64 v[216:217], v[218:219], 0, s[20:21]
	s_addc_u32 s35, s35, 0
	s_add_i32 s36, s66, s41
	global_load_lds_dwordx4 v[216:217], off
	v_lshl_add_u64 v[216:217], s[34:35], 0, v[130:131]
	s_mov_b32 m0, s36
	s_nop 0
	global_load_lds_dwordx4 v[216:217], off
	v_lshl_add_u64 v[216:217], s[34:35], 0, v[132:133]
	s_add_i32 m0, s36, 0x2000
	s_nop 0
	global_load_lds_dwordx4 v[216:217], off
	v_lshl_add_u64 v[216:217], v[220:221], 0, s[20:21]
	s_mov_b32 m0, s54
	s_nop 0
	global_load_lds_dwordx4 v[216:217], off
	v_lshl_add_u64 v[216:217], v[222:223], 0, s[20:21]
	s_mov_b32 m0, s55
	s_nop 0
	global_load_lds_dwordx4 v[216:217], off
	s_waitcnt vmcnt(8)
	s_waitcnt lgkmcnt(0)
	s_barrier
	s_setprio 1
	s_waitcnt lgkmcnt(0)
	v_mfma_f32_16x16x32_bf16 v[102:105], v[150:153], v[182:185], v[102:105]
	v_mfma_f32_16x16x32_bf16 v[98:101], v[158:161], v[182:185], v[98:101]
	v_mfma_f32_16x16x32_bf16 v[82:85], v[150:153], v[192:195], v[82:85]
	v_mfma_f32_16x16x32_bf16 v[78:81], v[158:161], v[192:195], v[78:81]
	v_mfma_f32_16x16x32_bf16 v[38:41], v[150:153], v[200:203], v[38:41]
	v_mfma_f32_16x16x32_bf16 v[34:37], v[158:161], v[200:203], v[34:37]
	v_mfma_f32_16x16x32_bf16 v[18:21], v[150:153], v[208:211], v[18:21]
	v_mfma_f32_16x16x32_bf16 v[10:13], v[158:161], v[208:211], v[10:13]
	v_mfma_f32_16x16x32_bf16 v[102:105], v[154:157], v[188:191], v[102:105]
	v_mfma_f32_16x16x32_bf16 v[98:101], v[162:165], v[188:191], v[98:101]
	v_mfma_f32_16x16x32_bf16 v[82:85], v[154:157], v[196:199], v[82:85]
	v_mfma_f32_16x16x32_bf16 v[78:81], v[162:165], v[196:199], v[78:81]
	v_mfma_f32_16x16x32_bf16 v[38:41], v[154:157], v[204:207], v[38:41]
	v_mfma_f32_16x16x32_bf16 v[34:37], v[162:165], v[204:207], v[34:37]
	v_mfma_f32_16x16x32_bf16 v[18:21], v[154:157], v[212:215], v[18:21]
	v_mfma_f32_16x16x32_bf16 v[10:13], v[162:165], v[212:215], v[10:13]
	s_setprio 0
	s_setprio 1
	v_mfma_f32_16x16x32_bf16 v[90:93], v[166:169], v[182:185], v[90:93]
	v_mfma_f32_16x16x32_bf16 v[66:69], v[174:177], v[182:185], v[66:69]
	v_mfma_f32_16x16x32_bf16 v[62:65], v[166:169], v[192:195], v[62:65]
	v_mfma_f32_16x16x32_bf16 v[58:61], v[174:177], v[192:195], v[58:61]
	v_mfma_f32_16x16x32_bf16 v[26:29], v[166:169], v[200:203], v[26:29]
	v_mfma_f32_16x16x32_bf16 v[22:25], v[174:177], v[200:203], v[22:25]
	v_mfma_f32_16x16x32_bf16 v[6:9], v[166:169], v[208:211], v[6:9]
	v_mfma_f32_16x16x32_bf16 v[2:5], v[174:177], v[208:211], v[2:5]
	v_mfma_f32_16x16x32_bf16 v[90:93], v[170:173], v[188:191], v[90:93]
	v_mfma_f32_16x16x32_bf16 v[66:69], v[178:181], v[188:191], v[66:69]
	v_mfma_f32_16x16x32_bf16 v[62:65], v[170:173], v[196:199], v[62:65]
	v_mfma_f32_16x16x32_bf16 v[58:61], v[178:181], v[196:199], v[58:61]
	v_mfma_f32_16x16x32_bf16 v[26:29], v[170:173], v[204:207], v[26:29]
	v_mfma_f32_16x16x32_bf16 v[22:25], v[178:181], v[204:207], v[22:25]
	v_mfma_f32_16x16x32_bf16 v[6:9], v[170:173], v[212:215], v[6:9]
	v_mfma_f32_16x16x32_bf16 v[2:5], v[178:181], v[212:215], v[2:5]
	s_barrier
	s_setprio 0
	s_add_i32 s63, s63, 2
	s_add_u32 s30, s30, 0x100
	s_addc_u32 s31, s31, 0
	s_cmp_gt_u32 s63, 13
	s_cbranch_scc0 .LBB0_1405
	s_add_u32 s30, s59, 0xffffff00
	s_addc_u32 s31, s60, -1
	s_andn2_b64 vcc, exec, s[6:7]
	s_cbranch_vccnz .LBB0_1408
	v_mov_b32_e32 v2, 0
	s_mov_b32 s8, s22
	s_mov_b32 s16, s24
	s_mov_b64 s[18:19], s[28:29]
	s_mov_b32 s53, s58
	v_mov_b32_e32 v3, v2
	v_mov_b32_e32 v4, v2
	v_mov_b32_e32 v5, v2
	v_mov_b32_e32 v6, v2
	v_mov_b32_e32 v7, v2
	v_mov_b32_e32 v8, v2
	v_mov_b32_e32 v9, v2
	v_mov_b32_e32 v22, v2
	v_mov_b32_e32 v23, v2
	v_mov_b32_e32 v24, v2
	v_mov_b32_e32 v25, v2
	v_mov_b32_e32 v26, v2
	v_mov_b32_e32 v27, v2
	v_mov_b32_e32 v28, v2
	v_mov_b32_e32 v29, v2
	v_mov_b32_e32 v58, v2
	v_mov_b32_e32 v59, v2
	v_mov_b32_e32 v60, v2
	v_mov_b32_e32 v61, v2
	v_mov_b32_e32 v62, v2
	v_mov_b32_e32 v63, v2
	v_mov_b32_e32 v64, v2
	v_mov_b32_e32 v65, v2
	v_mov_b32_e32 v66, v2
	v_mov_b32_e32 v67, v2
	v_mov_b32_e32 v68, v2
	v_mov_b32_e32 v69, v2
	v_mov_b32_e32 v90, v2
	v_mov_b32_e32 v91, v2
	v_mov_b32_e32 v92, v2
	v_mov_b32_e32 v93, v2
	v_mov_b32_e32 v10, v2
	v_mov_b32_e32 v11, v2
	v_mov_b32_e32 v12, v2
	v_mov_b32_e32 v13, v2
	v_mov_b32_e32 v18, v2
	v_mov_b32_e32 v19, v2
	v_mov_b32_e32 v20, v2
	v_mov_b32_e32 v21, v2
	v_mov_b32_e32 v34, v2
	v_mov_b32_e32 v35, v2
	v_mov_b32_e32 v36, v2
	v_mov_b32_e32 v37, v2
	v_mov_b32_e32 v38, v2
	v_mov_b32_e32 v39, v2
	v_mov_b32_e32 v40, v2
	v_mov_b32_e32 v41, v2
	v_mov_b32_e32 v78, v2
	v_mov_b32_e32 v79, v2
	v_mov_b32_e32 v80, v2
	v_mov_b32_e32 v81, v2
	v_mov_b32_e32 v82, v2
	v_mov_b32_e32 v83, v2
	v_mov_b32_e32 v84, v2
	v_mov_b32_e32 v85, v2
	v_mov_b32_e32 v98, v2
	v_mov_b32_e32 v99, v2
	v_mov_b32_e32 v100, v2
	v_mov_b32_e32 v101, v2
	v_mov_b32_e32 v102, v2
	v_mov_b32_e32 v103, v2
	v_mov_b32_e32 v104, v2
	v_mov_b32_e32 v105, v2
	v_mov_b32_e32 v50, v2
	v_mov_b32_e32 v51, v2
	v_mov_b32_e32 v52, v2
	v_mov_b32_e32 v53, v2
	v_mov_b32_e32 v86, v2
	v_mov_b32_e32 v87, v2
	v_mov_b32_e32 v88, v2
	v_mov_b32_e32 v89, v2
	v_mov_b32_e32 v42, v2
	v_mov_b32_e32 v43, v2
	v_mov_b32_e32 v44, v2
	v_mov_b32_e32 v45, v2
	v_mov_b32_e32 v70, v2
	v_mov_b32_e32 v71, v2
	v_mov_b32_e32 v72, v2
	v_mov_b32_e32 v73, v2
	v_mov_b32_e32 v30, v2
	v_mov_b32_e32 v31, v2
	v_mov_b32_e32 v32, v2
	v_mov_b32_e32 v33, v2
	v_mov_b32_e32 v54, v2
	v_mov_b32_e32 v55, v2
	v_mov_b32_e32 v56, v2
	v_mov_b32_e32 v57, v2
	v_mov_b32_e32 v14, v2
	v_mov_b32_e32 v15, v2
	v_mov_b32_e32 v16, v2
	v_mov_b32_e32 v17, v2
	v_mov_b32_e32 v46, v2
	v_mov_b32_e32 v47, v2
	v_mov_b32_e32 v48, v2
	v_mov_b32_e32 v49, v2
	v_mov_b32_e32 v114, v2
	v_mov_b32_e32 v115, v2
	v_mov_b32_e32 v116, v2
	v_mov_b32_e32 v117, v2
	v_mov_b32_e32 v122, v2
	v_mov_b32_e32 v123, v2
	v_mov_b32_e32 v124, v2
	v_mov_b32_e32 v125, v2
	v_mov_b32_e32 v106, v2
	v_mov_b32_e32 v107, v2
	v_mov_b32_e32 v108, v2
	v_mov_b32_e32 v109, v2
	v_mov_b32_e32 v126, v2
	v_mov_b32_e32 v127, v2
	v_mov_b32_e32 v128, v2
	v_mov_b32_e32 v129, v2
	v_mov_b32_e32 v94, v2
	v_mov_b32_e32 v95, v2
	v_mov_b32_e32 v96, v2
	v_mov_b32_e32 v97, v2
	v_mov_b32_e32 v118, v2
	v_mov_b32_e32 v119, v2
	v_mov_b32_e32 v120, v2
	v_mov_b32_e32 v121, v2
	v_mov_b32_e32 v74, v2
	v_mov_b32_e32 v75, v2
	v_mov_b32_e32 v76, v2
	v_mov_b32_e32 v77, v2
	v_mov_b32_e32 v110, v2
	v_mov_b32_e32 v111, v2
	v_mov_b32_e32 v112, v2
	v_mov_b32_e32 v113, v2
	s_andn2_b64 vcc, exec, s[4:5]
	s_cbranch_vccnz .LBB0_1409
	s_branch .LBB0_1410

; #define PG8_STAGE(bufoff, gbase, voff) do { _Pragma("unroll") for (int _i = 0; _i < 2; ++_i) \
;         __builtin_amdgcn_global_load_lds((const unsigned*)((const char*)(gbase) + (voff)[_i]), (PG8_LAS unsigned*)(lds + (bufoff) + ldsw + _i * 8192), 16, 0, 0); } while (0)
; #define PG8_LDA(dst, b, h) do { _Pragma("unroll") for (int m = 0; m < 4; ++m) _Pragma("unroll") for (int k = 0; k < 2; ++k) dst[m][k] = *(const PG8_LAS bf16x8*)(lds + PG8_SA(b, h) + aoff + m * 2048 + k * 1024); } while (0)
; #define PG8_LDB(dst, b, h) do { _Pragma("unroll") for (int n = 0; n < 2; ++n) _Pragma("unroll") for (int k = 0; k < 2; ++k) dst[n][k] = *(const PG8_LAS bf16x8*)(lds + PG8_SB(b, h) + boff + n * 2048 + k * 1024); } while (0)
; #define PG8_MMA(ai, bj, At, Bt) do { __builtin_amdgcn_s_setprio(1); _Pragma("unroll") for (int m = 0; m < 4; ++m) _Pragma("unroll") for (int n = 0; n < 2; ++n) _Pragma("unroll") for (int k = 0; k < 2; ++k) \
;         acc[ai][bj][m][n] = __builtin_amdgcn_mfma_f32_16x16x32_bf16(Bt[n][k], At[m][k], acc[ai][bj][m][n], 0, 0, 0); __builtin_amdgcn_s_setprio(0); } while (0)
; #define PG8_WAIT_V(n) asm volatile("s_waitcnt vmcnt(" #n ")" ::: "memory")
; #define PG8_BAR __builtin_amdgcn_s_barrier()
; template <class Epi, class Sched, bool ALIGN_EPI = false, bool SP2 = false>
; __device__ __forceinline__ void gemm_phase(PG8_LAS unsigned char* lds, const Gemm g, const Sched& S, const Epi& E) {
;     ...
;         for (int t = 0; t < nt; t += 2) {
;             const bool last = (t == nt - 2);
;             const char* a1 = cA + (size_t)(t + 1) * kstep;
;             const char* a2 = last ? nA : cA + (size_t)(t + 2) * kstep; const char* b2 = last ? nB : cB + (size_t)(t + 2) * kstep;
;             const char* a3 = a2 + kstep; const char* b3 = b2 + kstep;
;             if (last && has_next) S.a_ready(nxt);
;             if constexpr (SP2) {
;             PG8_LDB(B0, 0, 0); PG8_LDB(B1, 0, 1); PG8_SCHED; PG8_LDA(At, 0, 0); PG8_STAGE(PG8_SA(1, 1), a1 + hstep, voffA);
;             PG8_WAIT_V(8); PG8_WAIT_L(0); PG8_BAR; PG8_MMA(0, 0, At, B0); PG8_MMA(0, 1, At, B1); PG8_BAR; PG8_SCHED;
;             PG8_LDA(At, 0, 1); PG8_STAGE(PG8_SB(0, 0), b2, voffB); PG8_STAGE(PG8_SB(0, 1), b2 + hstep, voffB); PG8_STAGE(PG8_SA(0, 0), a2, voffA);
;             PG8_WAIT_V(8); PG8_WAIT_L(0); PG8_BAR; PG8_MMA(1, 0, At, B0); PG8_MMA(1, 1, At, B1); PG8_BAR; PG8_SCHED;
.LBB0_1482:
	ds_read_b128 v[144:147], v140
	ds_read_b128 v[148:151], v140 offset:1024
	ds_read_b128 v[152:155], v140 offset:2048
	ds_read_b128 v[156:159], v140 offset:3072
	ds_read_b128 v[160:163], v141
	ds_read_b128 v[164:167], v141 offset:1024
	ds_read_b128 v[168:171], v141 offset:2048
	ds_read_b128 v[172:175], v141 offset:3072
	s_add_i32 s75, s40, 2
	s_add_u32 s38, s36, 0x100
	s_addc_u32 s39, s37, 0
	s_cmp_eq_u32 s61, s40
	s_cselect_b32 s40, s34, s73
	s_cselect_b32 s49, s31, s39
	s_cselect_b32 s48, s30, s38
	s_cselect_b32 s41, s35, s74
	v_lshl_add_u64 v[184:185], s[36:37], 0, v[134:135]
	s_add_i32 m0, s53, 0xc000
	ds_read_b128 v[176:179], v142
	ds_read_b128 v[180:183], v142 offset:1024
	ds_read_b128 v[188:191], v142 offset:2048
	ds_read_b128 v[192:195], v142 offset:3072
	ds_read_b128 v[196:199], v142 offset:4096
	ds_read_b128 v[200:203], v142 offset:5120
	ds_read_b128 v[204:207], v142 offset:6144
	ds_read_b128 v[208:211], v142 offset:7168
	global_load_lds_dwordx4 v[184:185], off
	v_lshl_add_u64 v[184:185], s[36:37], 0, v[136:137]
	s_add_i32 m0, s53, 0xe000
	s_nop 0
	global_load_lds_dwordx4 v[184:185], off
	s_waitcnt vmcnt(8)
	s_waitcnt lgkmcnt(0)
	s_barrier
	s_setprio 1
	s_waitcnt lgkmcnt(0)
	v_mfma_f32_16x16x32_bf16 v[126:129], v[144:147], v[176:179], v[126:129]
	v_mfma_f32_16x16x32_bf16 v[122:125], v[152:155], v[176:179], v[122:125]
	v_mfma_f32_16x16x32_bf16 v[110:113], v[144:147], v[188:191], v[110:113]
	v_mfma_f32_16x16x32_bf16 v[106:109], v[152:155], v[188:191], v[106:109]
	v_mfma_f32_16x16x32_bf16 v[94:97], v[144:147], v[196:199], v[94:97]
	v_mfma_f32_16x16x32_bf16 v[90:93], v[152:155], v[196:199], v[90:93]
	v_mfma_f32_16x16x32_bf16 v[78:81], v[144:147], v[204:207], v[78:81]
	v_mfma_f32_16x16x32_bf16 v[74:77], v[152:155], v[204:207], v[74:77]
	v_mfma_f32_16x16x32_bf16 v[126:129], v[148:151], v[180:183], v[126:129]
	v_mfma_f32_16x16x32_bf16 v[122:125], v[156:159], v[180:183], v[122:125]
	v_mfma_f32_16x16x32_bf16 v[110:113], v[148:151], v[192:195], v[110:113]
	v_mfma_f32_16x16x32_bf16 v[106:109], v[156:159], v[192:195], v[106:109]
	v_mfma_f32_16x16x32_bf16 v[94:97], v[148:151], v[200:203], v[94:97]
	v_mfma_f32_16x16x32_bf16 v[90:93], v[156:159], v[200:203], v[90:93]
	v_mfma_f32_16x16x32_bf16 v[78:81], v[148:151], v[208:211], v[78:81]
	v_mfma_f32_16x16x32_bf16 v[74:77], v[156:159], v[208:211], v[74:77]
	s_setprio 0
	s_setprio 1
	v_mfma_f32_16x16x32_bf16 v[118:121], v[160:163], v[176:179], v[118:121]
	v_mfma_f32_16x16x32_bf16 v[114:117], v[168:171], v[176:179], v[114:117]
	v_mfma_f32_16x16x32_bf16 v[102:105], v[160:163], v[188:191], v[102:105]
	v_mfma_f32_16x16x32_bf16 v[98:101], v[168:171], v[188:191], v[98:101]
	v_mfma_f32_16x16x32_bf16 v[86:89], v[160:163], v[196:199], v[86:89]
	v_mfma_f32_16x16x32_bf16 v[82:85], v[168:171], v[196:199], v[82:85]
	v_mfma_f32_16x16x32_bf16 v[70:73], v[160:163], v[204:207], v[70:73]
	v_mfma_f32_16x16x32_bf16 v[66:69], v[168:171], v[204:207], v[66:69]
	v_mfma_f32_16x16x32_bf16 v[118:121], v[164:167], v[180:183], v[118:121]
	v_mfma_f32_16x16x32_bf16 v[114:117], v[172:175], v[180:183], v[114:117]
	v_mfma_f32_16x16x32_bf16 v[102:105], v[164:167], v[192:195], v[102:105]
	v_mfma_f32_16x16x32_bf16 v[98:101], v[172:175], v[192:195], v[98:101]
	v_mfma_f32_16x16x32_bf16 v[86:89], v[164:167], v[200:203], v[86:89]
	v_mfma_f32_16x16x32_bf16 v[82:85], v[172:175], v[200:203], v[82:85]
	v_mfma_f32_16x16x32_bf16 v[70:73], v[164:167], v[208:211], v[70:73]
	v_mfma_f32_16x16x32_bf16 v[66:69], v[172:175], v[208:211], v[66:69]
	s_barrier
	s_setprio 0
	s_add_i32 s36, s62, s52
	v_lshl_add_u64 v[184:185], s[40:41], 0, v[132:133]
	s_mov_b32 m0, s36
	ds_read_b128 v[176:179], v142 offset:16384
	ds_read_b128 v[180:183], v142 offset:17408
	ds_read_b128 v[188:191], v142 offset:18432
	ds_read_b128 v[192:195], v142 offset:19456
	ds_read_b128 v[196:199], v142 offset:20480
	ds_read_b128 v[200:203], v142 offset:21504
	ds_read_b128 v[204:207], v142 offset:22528
	ds_read_b128 v[208:211], v142 offset:23552
	global_load_lds_dwordx4 v[184:185], off
	s_add_i32 m0, s36, 0x2000
	s_add_u32 s36, s40, 0x60000
	v_lshl_add_u64 v[212:213], s[40:41], 0, v[130:131]
	s_addc_u32 s37, s41, 0
	s_add_i32 s76, s63, s52
	global_load_lds_dwordx4 v[212:213], off
	v_lshl_add_u64 v[214:215], s[36:37], 0, v[132:133]
	s_mov_b32 m0, s76
	v_lshl_add_u64 v[216:217], s[48:49], 0, v[130:131]
	global_load_lds_dwordx4 v[214:215], off
	v_lshl_add_u64 v[214:215], s[36:37], 0, v[130:131]
	s_add_i32 m0, s76, 0x2000
	s_nop 0
	global_load_lds_dwordx4 v[214:215], off
	v_lshl_add_u64 v[214:215], s[48:49], 0, v[132:133]
	s_mov_b32 m0, s53
	s_nop 0
	global_load_lds_dwordx4 v[214:215], off
	s_mov_b32 m0, s54
	s_nop 0
	global_load_lds_dwordx4 v[216:217], off
	s_waitcnt vmcnt(8)
	s_waitcnt lgkmcnt(0)
	s_barrier
; #define PG8_STAGE(bufoff, gbase, voff) do { _Pragma("unroll") for (int _i = 0; _i < 2; ++_i) \
;         __builtin_amdgcn_global_load_lds((const unsigned*)((const char*)(gbase) + (voff)[_i]), (PG8_LAS unsigned*)(lds + (bufoff) + ldsw + _i * 8192), 16, 0, 0); } while (0)
; #define PG8_LDA(dst, b, h) do { _Pragma("unroll") for (int m = 0; m < 4; ++m) _Pragma("unroll") for (int k = 0; k < 2; ++k) dst[m][k] = *(const PG8_LAS bf16x8*)(lds + PG8_SA(b, h) + aoff + m * 2048 + k * 1024); } while (0)
; #define PG8_LDB(dst, b, h) do { _Pragma("unroll") for (int n = 0; n < 2; ++n) _Pragma("unroll") for (int k = 0; k < 2; ++k) dst[n][k] = *(const PG8_LAS bf16x8*)(lds + PG8_SB(b, h) + boff + n * 2048 + k * 1024); } while (0)
; #define PG8_MMA(ai, bj, At, Bt) do { __builtin_amdgcn_s_setprio(1); _Pragma("unroll") for (int m = 0; m < 4; ++m) _Pragma("unroll") for (int n = 0; n < 2; ++n) _Pragma("unroll") for (int k = 0; k < 2; ++k) \
;         acc[ai][bj][m][n] = __builtin_amdgcn_mfma_f32_16x16x32_bf16(Bt[n][k], At[m][k], acc[ai][bj][m][n], 0, 0, 0); __builtin_amdgcn_s_setprio(0); } while (0)
; #define PG8_WAIT_V(n) asm volatile("s_waitcnt vmcnt(" #n ")" ::: "memory")
; #define PG8_WAIT_L(n) asm volatile("s_waitcnt lgkmcnt(" #n ")" ::: "memory")
; #define PG8_BAR __builtin_amdgcn_s_barrier()
; #define PG8_SCHED __builtin_amdgcn_sched_barrier(0)
; template <class Epi, class Sched, bool ALIGN_EPI = false, bool SP2 = false>
; __device__ __forceinline__ void gemm_phase(PG8_LAS unsigned char* lds, const Gemm g, const Sched& S, const Epi& E) {
;     ...
;             PG8_WAIT_V(8); PG8_WAIT_L(0); PG8_BAR; PG8_MMA(1, 0, At, B0); PG8_MMA(1, 1, At, B1); PG8_BAR; PG8_SCHED;
;             PG8_LDB(B0, 1, 0); PG8_LDB(B1, 1, 1); PG8_SCHED; PG8_LDA(At, 1, 0); PG8_STAGE(PG8_SA(0, 1), a2 + hstep, voffA);
;             PG8_WAIT_V(8); PG8_WAIT_L(0); PG8_BAR; PG8_MMA(0, 0, At, B0); PG8_MMA(0, 1, At, B1); PG8_BAR; PG8_SCHED;
	s_setprio 1
	s_waitcnt lgkmcnt(0)
	v_mfma_f32_16x16x32_bf16 v[62:65], v[144:147], v[176:179], v[62:65]
	v_mfma_f32_16x16x32_bf16 v[58:61], v[152:155], v[176:179], v[58:61]
	v_mfma_f32_16x16x32_bf16 v[46:49], v[144:147], v[188:191], v[46:49]
	v_mfma_f32_16x16x32_bf16 v[42:45], v[152:155], v[188:191], v[42:45]
	v_mfma_f32_16x16x32_bf16 v[30:33], v[144:147], v[196:199], v[30:33]
	v_mfma_f32_16x16x32_bf16 v[26:29], v[152:155], v[196:199], v[26:29]
	v_mfma_f32_16x16x32_bf16 v[14:17], v[144:147], v[204:207], v[14:17]
	v_mfma_f32_16x16x32_bf16 v[10:13], v[152:155], v[204:207], v[10:13]
	v_mfma_f32_16x16x32_bf16 v[62:65], v[148:151], v[180:183], v[62:65]
	v_mfma_f32_16x16x32_bf16 v[58:61], v[156:159], v[180:183], v[58:61]
	v_mfma_f32_16x16x32_bf16 v[46:49], v[148:151], v[192:195], v[46:49]
	v_mfma_f32_16x16x32_bf16 v[42:45], v[156:159], v[192:195], v[42:45]
	v_mfma_f32_16x16x32_bf16 v[30:33], v[148:151], v[200:203], v[30:33]
	v_mfma_f32_16x16x32_bf16 v[26:29], v[156:159], v[200:203], v[26:29]
	v_mfma_f32_16x16x32_bf16 v[14:17], v[148:151], v[208:211], v[14:17]
	v_mfma_f32_16x16x32_bf16 v[10:13], v[156:159], v[208:211], v[10:13]
	s_setprio 0
	s_setprio 1
	v_mfma_f32_16x16x32_bf16 v[54:57], v[160:163], v[176:179], v[54:57]
	v_mfma_f32_16x16x32_bf16 v[50:53], v[168:171], v[176:179], v[50:53]
	v_mfma_f32_16x16x32_bf16 v[38:41], v[160:163], v[188:191], v[38:41]
	v_mfma_f32_16x16x32_bf16 v[34:37], v[168:171], v[188:191], v[34:37]
	v_mfma_f32_16x16x32_bf16 v[22:25], v[160:163], v[196:199], v[22:25]
	v_mfma_f32_16x16x32_bf16 v[18:21], v[168:171], v[196:199], v[18:21]
	v_mfma_f32_16x16x32_bf16 v[6:9], v[160:163], v[204:207], v[6:9]
	v_mfma_f32_16x16x32_bf16 v[2:5], v[168:171], v[204:207], v[2:5]
	v_mfma_f32_16x16x32_bf16 v[54:57], v[164:167], v[180:183], v[54:57]
	v_mfma_f32_16x16x32_bf16 v[50:53], v[172:175], v[180:183], v[50:53]
	v_mfma_f32_16x16x32_bf16 v[38:41], v[164:167], v[192:195], v[38:41]
	v_mfma_f32_16x16x32_bf16 v[34:37], v[172:175], v[192:195], v[34:37]
	v_mfma_f32_16x16x32_bf16 v[22:25], v[164:167], v[200:203], v[22:25]
	v_mfma_f32_16x16x32_bf16 v[18:21], v[172:175], v[200:203], v[18:21]
	v_mfma_f32_16x16x32_bf16 v[6:9], v[164:167], v[208:211], v[6:9]
	v_mfma_f32_16x16x32_bf16 v[2:5], v[172:175], v[208:211], v[2:5]
	s_barrier
	s_setprio 0
	s_add_i32 s76, 0, 0x18000
	v_add_u32_e32 v143, s76, v1
	s_add_i32 s77, 0, 0x1c000
	ds_read_b128 v[144:147], v143
	ds_read_b128 v[148:151], v143 offset:1024
	ds_read_b128 v[152:155], v143 offset:2048
	ds_read_b128 v[156:159], v143 offset:3072
	v_add_u32_e32 v143, s77, v1
	ds_read_b128 v[160:163], v143
	ds_read_b128 v[164:167], v143 offset:1024
	ds_read_b128 v[168:171], v143 offset:2048
	ds_read_b128 v[172:175], v143 offset:3072
	s_add_u32 s36, s48, 0x60000
	s_addc_u32 s37, s49, 0
	s_mov_b32 m0, s55
	v_lshl_add_u64 v[218:219], s[36:37], 0, v[132:133]
	ds_read_b128 v[176:179], v142 offset:32768
	ds_read_b128 v[180:183], v142 offset:33792
	ds_read_b128 v[188:191], v142 offset:34816
	ds_read_b128 v[192:195], v142 offset:35840
	ds_read_b128 v[196:199], v142 offset:36864
	ds_read_b128 v[200:203], v142 offset:37888
	ds_read_b128 v[204:207], v142 offset:38912
	ds_read_b128 v[208:211], v142 offset:39936
	global_load_lds_dwordx4 v[218:219], off
	v_lshl_add_u64 v[218:219], s[36:37], 0, v[130:131]
	s_mov_b32 m0, s56
	s_nop 0
	global_load_lds_dwordx4 v[218:219], off
	s_waitcnt vmcnt(8)
	s_waitcnt lgkmcnt(0)
	s_barrier
	s_setprio 1
	s_waitcnt lgkmcnt(0)
	v_mfma_f32_16x16x32_bf16 v[126:129], v[144:147], v[176:179], v[126:129]
	v_mfma_f32_16x16x32_bf16 v[122:125], v[152:155], v[176:179], v[122:125]
	v_mfma_f32_16x16x32_bf16 v[110:113], v[144:147], v[188:191], v[110:113]
	v_mfma_f32_16x16x32_bf16 v[106:109], v[152:155], v[188:191], v[106:109]
	v_mfma_f32_16x16x32_bf16 v[94:97], v[144:147], v[196:199], v[94:97]
	v_mfma_f32_16x16x32_bf16 v[90:93], v[152:155], v[196:199], v[90:93]
	v_mfma_f32_16x16x32_bf16 v[78:81], v[144:147], v[204:207], v[78:81]
	v_mfma_f32_16x16x32_bf16 v[74:77], v[152:155], v[204:207], v[74:77]
	v_mfma_f32_16x16x32_bf16 v[126:129], v[148:151], v[180:183], v[126:129]
	v_mfma_f32_16x16x32_bf16 v[122:125], v[156:159], v[180:183], v[122:125]
	v_mfma_f32_16x16x32_bf16 v[110:113], v[148:151], v[192:195], v[110:113]
	v_mfma_f32_16x16x32_bf16 v[106:109], v[156:159], v[192:195], v[106:109]
	v_mfma_f32_16x16x32_bf16 v[94:97], v[148:151], v[200:203], v[94:97]
	v_mfma_f32_16x16x32_bf16 v[90:93], v[156:159], v[200:203], v[90:93]
	v_mfma_f32_16x16x32_bf16 v[78:81], v[148:151], v[208:211], v[78:81]
	v_mfma_f32_16x16x32_bf16 v[74:77], v[156:159], v[208:211], v[74:77]
	s_setprio 0
	s_setprio 1
	v_mfma_f32_16x16x32_bf16 v[118:121], v[160:163], v[176:179], v[118:121]
	v_mfma_f32_16x16x32_bf16 v[114:117], v[168:171], v[176:179], v[114:117]
	v_mfma_f32_16x16x32_bf16 v[102:105], v[160:163], v[188:191], v[102:105]
	v_mfma_f32_16x16x32_bf16 v[98:101], v[168:171], v[188:191], v[98:101]
	v_mfma_f32_16x16x32_bf16 v[86:89], v[160:163], v[196:199], v[86:89]
	v_mfma_f32_16x16x32_bf16 v[82:85], v[168:171], v[196:199], v[82:85]
	v_mfma_f32_16x16x32_bf16 v[70:73], v[160:163], v[204:207], v[70:73]
	v_mfma_f32_16x16x32_bf16 v[66:69], v[168:171], v[204:207], v[66:69]
	v_mfma_f32_16x16x32_bf16 v[118:121], v[164:167], v[180:183], v[118:121]
	v_mfma_f32_16x16x32_bf16 v[114:117], v[172:175], v[180:183], v[114:117]
	v_mfma_f32_16x16x32_bf16 v[102:105], v[164:167], v[192:195], v[102:105]
	v_mfma_f32_16x16x32_bf16 v[98:101], v[172:175], v[192:195], v[98:101]
	v_mfma_f32_16x16x32_bf16 v[86:89], v[164:167], v[200:203], v[86:89]
	v_mfma_f32_16x16x32_bf16 v[82:85], v[172:175], v[200:203], v[82:85]
	v_mfma_f32_16x16x32_bf16 v[70:73], v[164:167], v[208:211], v[70:73]
	v_mfma_f32_16x16x32_bf16 v[66:69], v[172:175], v[208:211], v[66:69]
	s_barrier
; #define PG8_STAGE(bufoff, gbase, voff) do { _Pragma("unroll") for (int _i = 0; _i < 2; ++_i) \
;         __builtin_amdgcn_global_load_lds((const unsigned*)((const char*)(gbase) + (voff)[_i]), (PG8_LAS unsigned*)(lds + (bufoff) + ldsw + _i * 8192), 16, 0, 0); } while (0)
; #define PG8_LDA(dst, b, h) do { _Pragma("unroll") for (int m = 0; m < 4; ++m) _Pragma("unroll") for (int k = 0; k < 2; ++k) dst[m][k] = *(const PG8_LAS bf16x8*)(lds + PG8_SA(b, h) + aoff + m * 2048 + k * 1024); } while (0)
; #define PG8_MMA(ai, bj, At, Bt) do { __builtin_amdgcn_s_setprio(1); _Pragma("unroll") for (int m = 0; m < 4; ++m) _Pragma("unroll") for (int n = 0; n < 2; ++n) _Pragma("unroll") for (int k = 0; k < 2; ++k) \
;         acc[ai][bj][m][n] = __builtin_amdgcn_mfma_f32_16x16x32_bf16(Bt[n][k], At[m][k], acc[ai][bj][m][n], 0, 0, 0); __builtin_amdgcn_s_setprio(0); } while (0)
; #define PG8_WAIT_V(n) asm volatile("s_waitcnt vmcnt(" #n ")" ::: "memory")
; #define PG8_WAIT_L(n) asm volatile("s_waitcnt lgkmcnt(" #n ")" ::: "memory")
; #define PG8_BAR __builtin_amdgcn_s_barrier()
; #define PG8_SCHED __builtin_amdgcn_sched_barrier(0)
; template <class Epi, class Sched, bool ALIGN_EPI = false, bool SP2 = false>
; __device__ __forceinline__ void gemm_phase(PG8_LAS unsigned char* lds, const Gemm g, const Sched& S, const Epi& E) {
;     ...
;         for (int t = 0; t < nt; t += 2) {
;             const bool last = (t == nt - 2);
;             const char* a1 = cA + (size_t)(t + 1) * kstep;
;             const char* a2 = last ? nA : cA + (size_t)(t + 2) * kstep; const char* b2 = last ? nB : cB + (size_t)(t + 2) * kstep;
;             const char* a3 = a2 + kstep; const char* b3 = b2 + kstep;
;     ...
;             PG8_LDA(At, 1, 1); PG8_STAGE(PG8_SB(1, 0), b3, voffB); PG8_STAGE(PG8_SB(1, 1), b3 + hstep, voffB); PG8_STAGE(PG8_SA(1, 0), a3, voffA);
;             PG8_WAIT_V(8); PG8_WAIT_L(0); PG8_BAR; PG8_MMA(1, 0, At, B0); PG8_MMA(1, 1, At, B1); PG8_BAR; PG8_SCHED;
	s_setprio 0
	s_add_i32 s36, s76, s52
	v_lshl_add_u64 v[184:185], v[184:185], 0, s[16:17]
	s_mov_b32 m0, s36
	ds_read_b128 v[176:179], v142 offset:49152
	ds_read_b128 v[180:183], v142 offset:50176
	ds_read_b128 v[188:191], v142 offset:51200
	ds_read_b128 v[192:195], v142 offset:52224
	ds_read_b128 v[196:199], v142 offset:53248
	ds_read_b128 v[200:203], v142 offset:54272
	ds_read_b128 v[204:207], v142 offset:55296
	ds_read_b128 v[208:211], v142 offset:56320
	global_load_lds_dwordx4 v[184:185], off
	s_add_i32 m0, s36, 0x2000
	s_add_u32 s36, s40, 0x60080
	v_lshl_add_u64 v[184:185], v[212:213], 0, s[16:17]
	s_addc_u32 s37, s41, 0
	s_add_i32 s40, s77, s52
	global_load_lds_dwordx4 v[184:185], off
	v_lshl_add_u64 v[184:185], s[36:37], 0, v[132:133]
	s_mov_b32 m0, s40
	s_nop 0
	global_load_lds_dwordx4 v[184:185], off
	v_lshl_add_u64 v[184:185], s[36:37], 0, v[130:131]
	s_add_i32 m0, s40, 0x2000
	s_nop 0
	global_load_lds_dwordx4 v[184:185], off
	v_lshl_add_u64 v[184:185], v[214:215], 0, s[16:17]
	s_mov_b32 m0, s59
	s_nop 0
	global_load_lds_dwordx4 v[184:185], off
	v_lshl_add_u64 v[184:185], v[216:217], 0, s[16:17]
	s_mov_b32 m0, s60
	s_nop 0
	global_load_lds_dwordx4 v[184:185], off
	s_waitcnt vmcnt(8)
	s_waitcnt lgkmcnt(0)
	s_barrier
	s_setprio 1
	s_waitcnt lgkmcnt(0)
	v_mfma_f32_16x16x32_bf16 v[62:65], v[144:147], v[176:179], v[62:65]
	v_mfma_f32_16x16x32_bf16 v[58:61], v[152:155], v[176:179], v[58:61]
	v_mfma_f32_16x16x32_bf16 v[46:49], v[144:147], v[188:191], v[46:49]
	v_mfma_f32_16x16x32_bf16 v[42:45], v[152:155], v[188:191], v[42:45]
	v_mfma_f32_16x16x32_bf16 v[30:33], v[144:147], v[196:199], v[30:33]
	v_mfma_f32_16x16x32_bf16 v[26:29], v[152:155], v[196:199], v[26:29]
	v_mfma_f32_16x16x32_bf16 v[14:17], v[144:147], v[204:207], v[14:17]
	v_mfma_f32_16x16x32_bf16 v[10:13], v[152:155], v[204:207], v[10:13]
	v_mfma_f32_16x16x32_bf16 v[62:65], v[148:151], v[180:183], v[62:65]
	v_mfma_f32_16x16x32_bf16 v[58:61], v[156:159], v[180:183], v[58:61]
	v_mfma_f32_16x16x32_bf16 v[46:49], v[148:151], v[192:195], v[46:49]
	v_mfma_f32_16x16x32_bf16 v[42:45], v[156:159], v[192:195], v[42:45]
	v_mfma_f32_16x16x32_bf16 v[30:33], v[148:151], v[200:203], v[30:33]
	v_mfma_f32_16x16x32_bf16 v[26:29], v[156:159], v[200:203], v[26:29]
	v_mfma_f32_16x16x32_bf16 v[14:17], v[148:151], v[208:211], v[14:17]
	v_mfma_f32_16x16x32_bf16 v[10:13], v[156:159], v[208:211], v[10:13]
	s_setprio 0
	s_setprio 1
	v_mfma_f32_16x16x32_bf16 v[54:57], v[160:163], v[176:179], v[54:57]
	v_mfma_f32_16x16x32_bf16 v[50:53], v[168:171], v[176:179], v[50:53]
	v_mfma_f32_16x16x32_bf16 v[38:41], v[160:163], v[188:191], v[38:41]
	v_mfma_f32_16x16x32_bf16 v[34:37], v[168:171], v[188:191], v[34:37]
	v_mfma_f32_16x16x32_bf16 v[22:25], v[160:163], v[196:199], v[22:25]
	v_mfma_f32_16x16x32_bf16 v[18:21], v[168:171], v[196:199], v[18:21]
	v_mfma_f32_16x16x32_bf16 v[6:9], v[160:163], v[204:207], v[6:9]
	v_mfma_f32_16x16x32_bf16 v[2:5], v[168:171], v[204:207], v[2:5]
	v_mfma_f32_16x16x32_bf16 v[54:57], v[164:167], v[180:183], v[54:57]
	v_mfma_f32_16x16x32_bf16 v[50:53], v[172:175], v[180:183], v[50:53]
	v_mfma_f32_16x16x32_bf16 v[38:41], v[164:167], v[192:195], v[38:41]
	v_mfma_f32_16x16x32_bf16 v[34:37], v[172:175], v[192:195], v[34:37]
	v_mfma_f32_16x16x32_bf16 v[22:25], v[164:167], v[200:203], v[22:25]
	v_mfma_f32_16x16x32_bf16 v[18:21], v[172:175], v[200:203], v[18:21]
	v_mfma_f32_16x16x32_bf16 v[6:9], v[164:167], v[208:211], v[6:9]
	v_mfma_f32_16x16x32_bf16 v[2:5], v[172:175], v[208:211], v[2:5]
	s_barrier
	s_setprio 0
	s_add_u32 s73, s73, 0x100
	s_addc_u32 s74, s74, 0
	s_cmp_ge_i32 s75, s58
	s_mov_b64 s[36:37], s[38:39]
	s_mov_b32 s40, s75
	s_cbranch_scc0 .LBB0_1482

; #define PG8_STAGE(bufoff, gbase, voff) do { _Pragma("unroll") for (int _i = 0; _i < 2; ++_i) \
;         __builtin_amdgcn_global_load_lds((const unsigned*)((const char*)(gbase) + (voff)[_i]), (PG8_LAS unsigned*)(lds + (bufoff) + ldsw + _i * 8192), 16, 0, 0); } while (0)
; #define PG8_LDA(dst, b, h) do { _Pragma("unroll") for (int m = 0; m < 4; ++m) _Pragma("unroll") for (int k = 0; k < 2; ++k) dst[m][k] = *(const PG8_LAS bf16x8*)(lds + PG8_SA(b, h) + aoff + m * 2048 + k * 1024); } while (0)
; #define PG8_LDB(dst, b, h) do { _Pragma("unroll") for (int n = 0; n < 2; ++n) _Pragma("unroll") for (int k = 0; k < 2; ++k) dst[n][k] = *(const PG8_LAS bf16x8*)(lds + PG8_SB(b, h) + boff + n * 2048 + k * 1024); } while (0)
; #define PG8_MMA(ai, bj, At, Bt) do { __builtin_amdgcn_s_setprio(1); _Pragma("unroll") for (int m = 0; m < 4; ++m) _Pragma("unroll") for (int n = 0; n < 2; ++n) _Pragma("unroll") for (int k = 0; k < 2; ++k) \
;         acc[ai][bj][m][n] = __builtin_amdgcn_mfma_f32_16x16x32_bf16(Bt[n][k], At[m][k], acc[ai][bj][m][n], 0, 0, 0); __builtin_amdgcn_s_setprio(0); } while (0)
; #define PG8_WAIT_V(n) asm volatile("s_waitcnt vmcnt(" #n ")" ::: "memory")
; #define PG8_BAR __builtin_amdgcn_s_barrier()
; template <class Epi, class Sched, bool ALIGN_EPI = false, bool SP2 = false>
; __device__ __forceinline__ void gemm_phase(PG8_LAS unsigned char* lds, const Gemm g, const Sched& S, const Epi& E) {
;     ...
;         for (int t = 0; t < nt; t += 2) {
;             const bool last = (t == nt - 2);
;             const char* a1 = cA + (size_t)(t + 1) * kstep;
;             const char* a2 = last ? nA : cA + (size_t)(t + 2) * kstep; const char* b2 = last ? nB : cB + (size_t)(t + 2) * kstep;
;             const char* a3 = a2 + kstep; const char* b3 = b2 + kstep;
;             if (last && has_next) S.a_ready(nxt);
;             if constexpr (SP2) {
;             PG8_LDB(B0, 0, 0); PG8_LDB(B1, 0, 1); PG8_SCHED; PG8_LDA(At, 0, 0); PG8_STAGE(PG8_SA(1, 1), a1 + hstep, voffA);
;             PG8_WAIT_V(8); PG8_WAIT_L(0); PG8_BAR; PG8_MMA(0, 0, At, B0); PG8_MMA(0, 1, At, B1); PG8_BAR; PG8_SCHED;
;             PG8_LDA(At, 0, 1); PG8_STAGE(PG8_SB(0, 0), b2, voffB); PG8_STAGE(PG8_SB(0, 1), b2 + hstep, voffB); PG8_STAGE(PG8_SA(0, 0), a2, voffA);
;             PG8_WAIT_V(8); PG8_WAIT_L(0); PG8_BAR; PG8_MMA(1, 0, At, B0); PG8_MMA(1, 1, At, B1); PG8_BAR; PG8_SCHED;
.LBB0_1523:
	v_add_u32_e32 v162, s56, v148
	v_add_u32_e32 v178, s57, v148
	s_add_u32 s34, s18, s30
	ds_read_b128 v[150:153], v162
	ds_read_b128 v[154:157], v162 offset:1024
	ds_read_b128 v[158:161], v162 offset:2048
	ds_read_b128 v[162:165], v162 offset:3072
	ds_read_b128 v[166:169], v178
	ds_read_b128 v[170:173], v178 offset:1024
	ds_read_b128 v[174:177], v178 offset:2048
	ds_read_b128 v[178:181], v178 offset:3072
	s_addc_u32 s35, s19, s31
	s_add_u32 s34, s34, 0x100
	s_addc_u32 s35, s35, 0
	s_add_u32 s65, s59, s30
	s_addc_u32 s66, s60, s31
	s_cmpk_eq_i32 s30, 0x700
	s_cselect_b32 s37, s25, s35
	s_cselect_b32 s36, s61, s34
	s_cselect_b32 s35, s23, s66
	s_cselect_b32 s34, s62, s65
	v_lshl_add_u64 v[216:217], v[142:143], 0, s[30:31]
	s_add_i32 m0, s48, 0xc000
	ds_read_b128 v[182:185], v149
	ds_read_b128 v[188:191], v149 offset:1024
	ds_read_b128 v[192:195], v149 offset:2048
	ds_read_b128 v[196:199], v149 offset:3072
	ds_read_b128 v[200:203], v149 offset:4096
	ds_read_b128 v[204:207], v149 offset:5120
	ds_read_b128 v[208:211], v149 offset:6144
	ds_read_b128 v[212:215], v149 offset:7168
	global_load_lds_dwordx4 v[216:217], off
	v_lshl_add_u64 v[216:217], v[144:145], 0, s[30:31]
	s_add_i32 m0, s48, 0xe000
	s_nop 0
	global_load_lds_dwordx4 v[216:217], off
	s_waitcnt vmcnt(8)
	s_waitcnt lgkmcnt(0)
	s_barrier
	s_setprio 1
	s_waitcnt lgkmcnt(0)
	v_mfma_f32_16x16x32_bf16 v[110:113], v[150:153], v[182:185], v[110:113]
	v_mfma_f32_16x16x32_bf16 v[74:77], v[158:161], v[182:185], v[74:77]
	v_mfma_f32_16x16x32_bf16 v[118:121], v[150:153], v[192:195], v[118:121]
	v_mfma_f32_16x16x32_bf16 v[94:97], v[158:161], v[192:195], v[94:97]
	v_mfma_f32_16x16x32_bf16 v[126:129], v[150:153], v[200:203], v[126:129]
	v_mfma_f32_16x16x32_bf16 v[106:109], v[158:161], v[200:203], v[106:109]
	v_mfma_f32_16x16x32_bf16 v[122:125], v[150:153], v[208:211], v[122:125]
	v_mfma_f32_16x16x32_bf16 v[114:117], v[158:161], v[208:211], v[114:117]
	v_mfma_f32_16x16x32_bf16 v[110:113], v[154:157], v[188:191], v[110:113]
	v_mfma_f32_16x16x32_bf16 v[74:77], v[162:165], v[188:191], v[74:77]
	v_mfma_f32_16x16x32_bf16 v[118:121], v[154:157], v[196:199], v[118:121]
	v_mfma_f32_16x16x32_bf16 v[94:97], v[162:165], v[196:199], v[94:97]
	v_mfma_f32_16x16x32_bf16 v[126:129], v[154:157], v[204:207], v[126:129]
	v_mfma_f32_16x16x32_bf16 v[106:109], v[162:165], v[204:207], v[106:109]
	v_mfma_f32_16x16x32_bf16 v[122:125], v[154:157], v[212:215], v[122:125]
	v_mfma_f32_16x16x32_bf16 v[114:117], v[162:165], v[212:215], v[114:117]
	s_setprio 0
	s_setprio 1
	v_mfma_f32_16x16x32_bf16 v[46:49], v[166:169], v[182:185], v[46:49]
	v_mfma_f32_16x16x32_bf16 v[14:17], v[174:177], v[182:185], v[14:17]
	v_mfma_f32_16x16x32_bf16 v[54:57], v[166:169], v[192:195], v[54:57]
	v_mfma_f32_16x16x32_bf16 v[30:33], v[174:177], v[192:195], v[30:33]
	v_mfma_f32_16x16x32_bf16 v[70:73], v[166:169], v[200:203], v[70:73]
	v_mfma_f32_16x16x32_bf16 v[42:45], v[174:177], v[200:203], v[42:45]
	v_mfma_f32_16x16x32_bf16 v[86:89], v[166:169], v[208:211], v[86:89]
	v_mfma_f32_16x16x32_bf16 v[50:53], v[174:177], v[208:211], v[50:53]
	v_mfma_f32_16x16x32_bf16 v[46:49], v[170:173], v[188:191], v[46:49]
	v_mfma_f32_16x16x32_bf16 v[14:17], v[178:181], v[188:191], v[14:17]
	v_mfma_f32_16x16x32_bf16 v[54:57], v[170:173], v[196:199], v[54:57]
	v_mfma_f32_16x16x32_bf16 v[30:33], v[178:181], v[196:199], v[30:33]
	v_mfma_f32_16x16x32_bf16 v[70:73], v[170:173], v[204:207], v[70:73]
	v_mfma_f32_16x16x32_bf16 v[42:45], v[178:181], v[204:207], v[42:45]
	v_mfma_f32_16x16x32_bf16 v[86:89], v[170:173], v[212:215], v[86:89]
	v_mfma_f32_16x16x32_bf16 v[50:53], v[178:181], v[212:215], v[50:53]
	s_barrier
	s_setprio 0
	s_add_i32 s65, s56, s43
	v_lshl_add_u64 v[216:217], s[34:35], 0, v[130:131]
	s_mov_b32 m0, s65
	ds_read_b128 v[182:185], v149 offset:16384
	ds_read_b128 v[188:191], v149 offset:17408
	ds_read_b128 v[192:195], v149 offset:18432
	ds_read_b128 v[196:199], v149 offset:19456
	ds_read_b128 v[200:203], v149 offset:20480
	ds_read_b128 v[204:207], v149 offset:21504
	ds_read_b128 v[208:211], v149 offset:22528
	ds_read_b128 v[212:215], v149 offset:23552
	global_load_lds_dwordx4 v[216:217], off
	s_add_i32 m0, s65, 0x2000
	s_add_u32 s66, s34, 0x40000
	v_lshl_add_u64 v[218:219], s[34:35], 0, v[132:133]
	s_addc_u32 s67, s35, 0
	s_add_i32 s65, s57, s43
	global_load_lds_dwordx4 v[218:219], off
	v_lshl_add_u64 v[220:221], s[66:67], 0, v[130:131]
	s_mov_b32 m0, s65
	v_lshl_add_u64 v[222:223], s[36:37], 0, v[132:133]
	global_load_lds_dwordx4 v[220:221], off
	v_lshl_add_u64 v[220:221], s[66:67], 0, v[132:133]
	s_add_i32 m0, s65, 0x2000
	s_nop 0
	global_load_lds_dwordx4 v[220:221], off
	v_lshl_add_u64 v[220:221], s[36:37], 0, v[130:131]
	s_mov_b32 m0, s48
	s_nop 0
	global_load_lds_dwordx4 v[220:221], off
	s_mov_b32 m0, s49
	s_nop 0
	global_load_lds_dwordx4 v[222:223], off
	s_waitcnt vmcnt(8)
	s_waitcnt lgkmcnt(0)
	s_barrier
; #define PG8_STAGE(bufoff, gbase, voff) do { _Pragma("unroll") for (int _i = 0; _i < 2; ++_i) \
;         __builtin_amdgcn_global_load_lds((const unsigned*)((const char*)(gbase) + (voff)[_i]), (PG8_LAS unsigned*)(lds + (bufoff) + ldsw + _i * 8192), 16, 0, 0); } while (0)
; #define PG8_LDA(dst, b, h) do { _Pragma("unroll") for (int m = 0; m < 4; ++m) _Pragma("unroll") for (int k = 0; k < 2; ++k) dst[m][k] = *(const PG8_LAS bf16x8*)(lds + PG8_SA(b, h) + aoff + m * 2048 + k * 1024); } while (0)
; #define PG8_LDB(dst, b, h) do { _Pragma("unroll") for (int n = 0; n < 2; ++n) _Pragma("unroll") for (int k = 0; k < 2; ++k) dst[n][k] = *(const PG8_LAS bf16x8*)(lds + PG8_SB(b, h) + boff + n * 2048 + k * 1024); } while (0)
; #define PG8_MMA(ai, bj, At, Bt) do { __builtin_amdgcn_s_setprio(1); _Pragma("unroll") for (int m = 0; m < 4; ++m) _Pragma("unroll") for (int n = 0; n < 2; ++n) _Pragma("unroll") for (int k = 0; k < 2; ++k) \
;         acc[ai][bj][m][n] = __builtin_amdgcn_mfma_f32_16x16x32_bf16(Bt[n][k], At[m][k], acc[ai][bj][m][n], 0, 0, 0); __builtin_amdgcn_s_setprio(0); } while (0)
; #define PG8_WAIT_V(n) asm volatile("s_waitcnt vmcnt(" #n ")" ::: "memory")
; #define PG8_WAIT_L(n) asm volatile("s_waitcnt lgkmcnt(" #n ")" ::: "memory")
; #define PG8_BAR __builtin_amdgcn_s_barrier()
; #define PG8_SCHED __builtin_amdgcn_sched_barrier(0)
; template <class Epi, class Sched, bool ALIGN_EPI = false, bool SP2 = false>
; __device__ __forceinline__ void gemm_phase(PG8_LAS unsigned char* lds, const Gemm g, const Sched& S, const Epi& E) {
;     ...
;             PG8_WAIT_V(8); PG8_WAIT_L(0); PG8_BAR; PG8_MMA(1, 0, At, B0); PG8_MMA(1, 1, At, B1); PG8_BAR; PG8_SCHED;
;             PG8_LDB(B0, 1, 0); PG8_LDB(B1, 1, 1); PG8_SCHED; PG8_LDA(At, 1, 0); PG8_STAGE(PG8_SA(0, 1), a2 + hstep, voffA);
;             PG8_WAIT_V(8); PG8_WAIT_L(0); PG8_BAR; PG8_MMA(0, 0, At, B0); PG8_MMA(0, 1, At, B1); PG8_BAR; PG8_SCHED;
	s_setprio 1
	s_waitcnt lgkmcnt(0)
	v_mfma_f32_16x16x32_bf16 v[102:105], v[150:153], v[182:185], v[102:105]
	v_mfma_f32_16x16x32_bf16 v[98:101], v[158:161], v[182:185], v[98:101]
	v_mfma_f32_16x16x32_bf16 v[82:85], v[150:153], v[192:195], v[82:85]
	v_mfma_f32_16x16x32_bf16 v[78:81], v[158:161], v[192:195], v[78:81]
	v_mfma_f32_16x16x32_bf16 v[38:41], v[150:153], v[200:203], v[38:41]
	v_mfma_f32_16x16x32_bf16 v[34:37], v[158:161], v[200:203], v[34:37]
	v_mfma_f32_16x16x32_bf16 v[18:21], v[150:153], v[208:211], v[18:21]
	v_mfma_f32_16x16x32_bf16 v[10:13], v[158:161], v[208:211], v[10:13]
	v_mfma_f32_16x16x32_bf16 v[102:105], v[154:157], v[188:191], v[102:105]
	v_mfma_f32_16x16x32_bf16 v[98:101], v[162:165], v[188:191], v[98:101]
	v_mfma_f32_16x16x32_bf16 v[82:85], v[154:157], v[196:199], v[82:85]
	v_mfma_f32_16x16x32_bf16 v[78:81], v[162:165], v[196:199], v[78:81]
	v_mfma_f32_16x16x32_bf16 v[38:41], v[154:157], v[204:207], v[38:41]
	v_mfma_f32_16x16x32_bf16 v[34:37], v[162:165], v[204:207], v[34:37]
	v_mfma_f32_16x16x32_bf16 v[18:21], v[154:157], v[212:215], v[18:21]
	v_mfma_f32_16x16x32_bf16 v[10:13], v[162:165], v[212:215], v[10:13]
	s_setprio 0
	s_setprio 1
	v_mfma_f32_16x16x32_bf16 v[90:93], v[166:169], v[182:185], v[90:93]
	v_mfma_f32_16x16x32_bf16 v[66:69], v[174:177], v[182:185], v[66:69]
	v_mfma_f32_16x16x32_bf16 v[62:65], v[166:169], v[192:195], v[62:65]
	v_mfma_f32_16x16x32_bf16 v[58:61], v[174:177], v[192:195], v[58:61]
	v_mfma_f32_16x16x32_bf16 v[26:29], v[166:169], v[200:203], v[26:29]
	v_mfma_f32_16x16x32_bf16 v[22:25], v[174:177], v[200:203], v[22:25]
	v_mfma_f32_16x16x32_bf16 v[6:9], v[166:169], v[208:211], v[6:9]
	v_mfma_f32_16x16x32_bf16 v[2:5], v[174:177], v[208:211], v[2:5]
	v_mfma_f32_16x16x32_bf16 v[90:93], v[170:173], v[188:191], v[90:93]
	v_mfma_f32_16x16x32_bf16 v[66:69], v[178:181], v[188:191], v[66:69]
	v_mfma_f32_16x16x32_bf16 v[62:65], v[170:173], v[196:199], v[62:65]
	v_mfma_f32_16x16x32_bf16 v[58:61], v[178:181], v[196:199], v[58:61]
	v_mfma_f32_16x16x32_bf16 v[26:29], v[170:173], v[204:207], v[26:29]
	v_mfma_f32_16x16x32_bf16 v[22:25], v[178:181], v[204:207], v[22:25]
	v_mfma_f32_16x16x32_bf16 v[6:9], v[170:173], v[212:215], v[6:9]
	v_mfma_f32_16x16x32_bf16 v[2:5], v[178:181], v[212:215], v[2:5]
	s_barrier
	s_setprio 0
	s_add_i32 s65, 0, 0x18000
	s_add_i32 s66, 0, 0x1c000
	v_add_u32_e32 v162, s65, v148
	v_add_u32_e32 v178, s66, v148
	ds_read_b128 v[150:153], v162
	ds_read_b128 v[154:157], v162 offset:1024
	ds_read_b128 v[158:161], v162 offset:2048
	ds_read_b128 v[162:165], v162 offset:3072
	ds_read_b128 v[166:169], v178
	ds_read_b128 v[170:173], v178 offset:1024
	ds_read_b128 v[174:177], v178 offset:2048
	ds_read_b128 v[178:181], v178 offset:3072
	s_add_u32 s36, s36, 0x40000
	s_addc_u32 s37, s37, 0
	s_mov_b32 m0, s50
	v_lshl_add_u64 v[224:225], s[36:37], 0, v[130:131]
	ds_read_b128 v[182:185], v149 offset:32768
	ds_read_b128 v[188:191], v149 offset:33792
	ds_read_b128 v[192:195], v149 offset:34816
	ds_read_b128 v[196:199], v149 offset:35840
	ds_read_b128 v[200:203], v149 offset:36864
	ds_read_b128 v[204:207], v149 offset:37888
	ds_read_b128 v[208:211], v149 offset:38912
	ds_read_b128 v[212:215], v149 offset:39936
	global_load_lds_dwordx4 v[224:225], off
	v_lshl_add_u64 v[224:225], s[36:37], 0, v[132:133]
	s_mov_b32 m0, s51
	s_nop 0
	global_load_lds_dwordx4 v[224:225], off
	s_waitcnt vmcnt(8)
	s_waitcnt lgkmcnt(0)
	s_barrier
	s_setprio 1
	s_waitcnt lgkmcnt(0)
	v_mfma_f32_16x16x32_bf16 v[110:113], v[150:153], v[182:185], v[110:113]
	v_mfma_f32_16x16x32_bf16 v[74:77], v[158:161], v[182:185], v[74:77]
	v_mfma_f32_16x16x32_bf16 v[118:121], v[150:153], v[192:195], v[118:121]
	v_mfma_f32_16x16x32_bf16 v[94:97], v[158:161], v[192:195], v[94:97]
	v_mfma_f32_16x16x32_bf16 v[126:129], v[150:153], v[200:203], v[126:129]
	v_mfma_f32_16x16x32_bf16 v[106:109], v[158:161], v[200:203], v[106:109]
	v_mfma_f32_16x16x32_bf16 v[122:125], v[150:153], v[208:211], v[122:125]
	v_mfma_f32_16x16x32_bf16 v[114:117], v[158:161], v[208:211], v[114:117]
	v_mfma_f32_16x16x32_bf16 v[110:113], v[154:157], v[188:191], v[110:113]
	v_mfma_f32_16x16x32_bf16 v[74:77], v[162:165], v[188:191], v[74:77]
	v_mfma_f32_16x16x32_bf16 v[118:121], v[154:157], v[196:199], v[118:121]
	v_mfma_f32_16x16x32_bf16 v[94:97], v[162:165], v[196:199], v[94:97]
	v_mfma_f32_16x16x32_bf16 v[126:129], v[154:157], v[204:207], v[126:129]
	v_mfma_f32_16x16x32_bf16 v[106:109], v[162:165], v[204:207], v[106:109]
	v_mfma_f32_16x16x32_bf16 v[122:125], v[154:157], v[212:215], v[122:125]
	v_mfma_f32_16x16x32_bf16 v[114:117], v[162:165], v[212:215], v[114:117]
	s_setprio 0
	s_setprio 1
	v_mfma_f32_16x16x32_bf16 v[46:49], v[166:169], v[182:185], v[46:49]
	v_mfma_f32_16x16x32_bf16 v[14:17], v[174:177], v[182:185], v[14:17]
	v_mfma_f32_16x16x32_bf16 v[54:57], v[166:169], v[192:195], v[54:57]
	v_mfma_f32_16x16x32_bf16 v[30:33], v[174:177], v[192:195], v[30:33]
	v_mfma_f32_16x16x32_bf16 v[70:73], v[166:169], v[200:203], v[70:73]
	v_mfma_f32_16x16x32_bf16 v[42:45], v[174:177], v[200:203], v[42:45]
	v_mfma_f32_16x16x32_bf16 v[86:89], v[166:169], v[208:211], v[86:89]
	v_mfma_f32_16x16x32_bf16 v[50:53], v[174:177], v[208:211], v[50:53]
	v_mfma_f32_16x16x32_bf16 v[46:49], v[170:173], v[188:191], v[46:49]
	v_mfma_f32_16x16x32_bf16 v[14:17], v[178:181], v[188:191], v[14:17]
	v_mfma_f32_16x16x32_bf16 v[54:57], v[170:173], v[196:199], v[54:57]
	v_mfma_f32_16x16x32_bf16 v[30:33], v[178:181], v[196:199], v[30:33]
	v_mfma_f32_16x16x32_bf16 v[70:73], v[170:173], v[204:207], v[70:73]
	v_mfma_f32_16x16x32_bf16 v[42:45], v[178:181], v[204:207], v[42:45]
	v_mfma_f32_16x16x32_bf16 v[86:89], v[170:173], v[212:215], v[86:89]
	v_mfma_f32_16x16x32_bf16 v[50:53], v[178:181], v[212:215], v[50:53]
	s_barrier
; #define PG8_STAGE(bufoff, gbase, voff) do { _Pragma("unroll") for (int _i = 0; _i < 2; ++_i) \
;         __builtin_amdgcn_global_load_lds((const unsigned*)((const char*)(gbase) + (voff)[_i]), (PG8_LAS unsigned*)(lds + (bufoff) + ldsw + _i * 8192), 16, 0, 0); } while (0)
; #define PG8_LDA(dst, b, h) do { _Pragma("unroll") for (int m = 0; m < 4; ++m) _Pragma("unroll") for (int k = 0; k < 2; ++k) dst[m][k] = *(const PG8_LAS bf16x8*)(lds + PG8_SA(b, h) + aoff + m * 2048 + k * 1024); } while (0)
; #define PG8_MMA(ai, bj, At, Bt) do { __builtin_amdgcn_s_setprio(1); _Pragma("unroll") for (int m = 0; m < 4; ++m) _Pragma("unroll") for (int n = 0; n < 2; ++n) _Pragma("unroll") for (int k = 0; k < 2; ++k) \
;         acc[ai][bj][m][n] = __builtin_amdgcn_mfma_f32_16x16x32_bf16(Bt[n][k], At[m][k], acc[ai][bj][m][n], 0, 0, 0); __builtin_amdgcn_s_setprio(0); } while (0)
; #define PG8_WAIT_V(n) asm volatile("s_waitcnt vmcnt(" #n ")" ::: "memory")
; #define PG8_WAIT_L(n) asm volatile("s_waitcnt lgkmcnt(" #n ")" ::: "memory")
; #define PG8_BAR __builtin_amdgcn_s_barrier()
; #define PG8_SCHED __builtin_amdgcn_sched_barrier(0)
; template <class Epi, class Sched, bool ALIGN_EPI = false, bool SP2 = false>
; __device__ __forceinline__ void gemm_phase(PG8_LAS unsigned char* lds, const Gemm g, const Sched& S, const Epi& E) {
;     ...
;             PG8_LDA(At, 1, 1); PG8_STAGE(PG8_SB(1, 0), b3, voffB); PG8_STAGE(PG8_SB(1, 1), b3 + hstep, voffB); PG8_STAGE(PG8_SA(1, 0), a3, voffA);
;             PG8_WAIT_V(8); PG8_WAIT_L(0); PG8_BAR; PG8_MMA(1, 0, At, B0); PG8_MMA(1, 1, At, B1); PG8_BAR; PG8_SCHED;
;     ...
;         if (!has_next) break;
; #pragma unroll
;         for (int a = 0; a < 2; ++a)
; #pragma unroll
;             for (int b = 0; b < 2; ++b)
; #pragma unroll
;                 for (int m = 0; m < 4; ++m)
; #pragma unroll
;                     for (int n = 0; n < 2; ++n) acc[a][b][m][n] = (f32x4){0.f, 0.f, 0.f, 0.f};
;         cur = nxt; cA = nA; cB = nB; ++ui;
	s_setprio 0
	s_add_i32 s36, s65, s43
	v_lshl_add_u64 v[216:217], v[216:217], 0, s[20:21]
	s_mov_b32 m0, s36
	ds_read_b128 v[182:185], v149 offset:49152
	ds_read_b128 v[188:191], v149 offset:50176
	ds_read_b128 v[192:195], v149 offset:51200
	ds_read_b128 v[196:199], v149 offset:52224
	ds_read_b128 v[200:203], v149 offset:53248
	ds_read_b128 v[204:207], v149 offset:54272
	ds_read_b128 v[208:211], v149 offset:55296
	ds_read_b128 v[212:215], v149 offset:56320
	global_load_lds_dwordx4 v[216:217], off
	s_add_i32 m0, s36, 0x2000
	s_add_u32 s34, s34, 0x40080
	v_lshl_add_u64 v[216:217], v[218:219], 0, s[20:21]
	s_addc_u32 s35, s35, 0
	s_add_i32 s36, s66, s43
	global_load_lds_dwordx4 v[216:217], off
	v_lshl_add_u64 v[216:217], s[34:35], 0, v[130:131]
	s_mov_b32 m0, s36
	s_nop 0
	global_load_lds_dwordx4 v[216:217], off
	v_lshl_add_u64 v[216:217], s[34:35], 0, v[132:133]
	s_add_i32 m0, s36, 0x2000
	s_nop 0
	global_load_lds_dwordx4 v[216:217], off
	v_lshl_add_u64 v[216:217], v[220:221], 0, s[20:21]
	s_mov_b32 m0, s54
	s_nop 0
	global_load_lds_dwordx4 v[216:217], off
	v_lshl_add_u64 v[216:217], v[222:223], 0, s[20:21]
	s_mov_b32 m0, s55
	s_nop 0
	global_load_lds_dwordx4 v[216:217], off
	s_waitcnt vmcnt(8)
	s_waitcnt lgkmcnt(0)
	s_barrier
	s_setprio 1
	s_waitcnt lgkmcnt(0)
	v_mfma_f32_16x16x32_bf16 v[102:105], v[150:153], v[182:185], v[102:105]
	v_mfma_f32_16x16x32_bf16 v[98:101], v[158:161], v[182:185], v[98:101]
	v_mfma_f32_16x16x32_bf16 v[82:85], v[150:153], v[192:195], v[82:85]
	v_mfma_f32_16x16x32_bf16 v[78:81], v[158:161], v[192:195], v[78:81]
	v_mfma_f32_16x16x32_bf16 v[38:41], v[150:153], v[200:203], v[38:41]
	v_mfma_f32_16x16x32_bf16 v[34:37], v[158:161], v[200:203], v[34:37]
	v_mfma_f32_16x16x32_bf16 v[18:21], v[150:153], v[208:211], v[18:21]
	v_mfma_f32_16x16x32_bf16 v[10:13], v[158:161], v[208:211], v[10:13]
	v_mfma_f32_16x16x32_bf16 v[102:105], v[154:157], v[188:191], v[102:105]
	v_mfma_f32_16x16x32_bf16 v[98:101], v[162:165], v[188:191], v[98:101]
	v_mfma_f32_16x16x32_bf16 v[82:85], v[154:157], v[196:199], v[82:85]
	v_mfma_f32_16x16x32_bf16 v[78:81], v[162:165], v[196:199], v[78:81]
	v_mfma_f32_16x16x32_bf16 v[38:41], v[154:157], v[204:207], v[38:41]
	v_mfma_f32_16x16x32_bf16 v[34:37], v[162:165], v[204:207], v[34:37]
	v_mfma_f32_16x16x32_bf16 v[18:21], v[154:157], v[212:215], v[18:21]
	v_mfma_f32_16x16x32_bf16 v[10:13], v[162:165], v[212:215], v[10:13]
	s_setprio 0
	s_setprio 1
	v_mfma_f32_16x16x32_bf16 v[90:93], v[166:169], v[182:185], v[90:93]
	v_mfma_f32_16x16x32_bf16 v[66:69], v[174:177], v[182:185], v[66:69]
	v_mfma_f32_16x16x32_bf16 v[62:65], v[166:169], v[192:195], v[62:65]
	v_mfma_f32_16x16x32_bf16 v[58:61], v[174:177], v[192:195], v[58:61]
	v_mfma_f32_16x16x32_bf16 v[26:29], v[166:169], v[200:203], v[26:29]
	v_mfma_f32_16x16x32_bf16 v[22:25], v[174:177], v[200:203], v[22:25]
	v_mfma_f32_16x16x32_bf16 v[6:9], v[166:169], v[208:211], v[6:9]
	v_mfma_f32_16x16x32_bf16 v[2:5], v[174:177], v[208:211], v[2:5]
	v_mfma_f32_16x16x32_bf16 v[90:93], v[170:173], v[188:191], v[90:93]
	v_mfma_f32_16x16x32_bf16 v[66:69], v[178:181], v[188:191], v[66:69]
	v_mfma_f32_16x16x32_bf16 v[62:65], v[170:173], v[196:199], v[62:65]
	v_mfma_f32_16x16x32_bf16 v[58:61], v[178:181], v[196:199], v[58:61]
	v_mfma_f32_16x16x32_bf16 v[26:29], v[170:173], v[204:207], v[26:29]
	v_mfma_f32_16x16x32_bf16 v[22:25], v[178:181], v[204:207], v[22:25]
	v_mfma_f32_16x16x32_bf16 v[6:9], v[170:173], v[212:215], v[6:9]
	v_mfma_f32_16x16x32_bf16 v[2:5], v[178:181], v[212:215], v[2:5]
	s_barrier
	s_setprio 0
	s_add_i32 s63, s63, 2
	s_add_u32 s30, s30, 0x100
	s_addc_u32 s31, s31, 0
	s_cmp_gt_u32 s63, 13
	s_cbranch_scc0 .LBB0_1523
	s_add_u32 s30, s59, 0xffffff00
	s_addc_u32 s31, s60, -1
	s_andn2_b64 vcc, exec, s[6:7]
	s_cbranch_vccnz .LBB0_1526
	v_mov_b32_e32 v2, 0
	s_mov_b32 s8, s22
	s_mov_b32 s16, s24
	s_mov_b64 s[18:19], s[28:29]
	s_mov_b32 s53, s58
	v_mov_b32_e32 v3, v2
	v_mov_b32_e32 v4, v2
	v_mov_b32_e32 v5, v2
	v_mov_b32_e32 v6, v2
	v_mov_b32_e32 v7, v2
	v_mov_b32_e32 v8, v2
	v_mov_b32_e32 v9, v2
	v_mov_b32_e32 v22, v2
	v_mov_b32_e32 v23, v2
	v_mov_b32_e32 v24, v2
	v_mov_b32_e32 v25, v2
	v_mov_b32_e32 v26, v2
	v_mov_b32_e32 v27, v2
	v_mov_b32_e32 v28, v2
	v_mov_b32_e32 v29, v2
	v_mov_b32_e32 v58, v2
	v_mov_b32_e32 v59, v2
	v_mov_b32_e32 v60, v2
	v_mov_b32_e32 v61, v2
	v_mov_b32_e32 v62, v2
	v_mov_b32_e32 v63, v2
	v_mov_b32_e32 v64, v2
	v_mov_b32_e32 v65, v2
	v_mov_b32_e32 v66, v2
	v_mov_b32_e32 v67, v2
	v_mov_b32_e32 v68, v2
	v_mov_b32_e32 v69, v2
	v_mov_b32_e32 v90, v2
	v_mov_b32_e32 v91, v2
	v_mov_b32_e32 v92, v2
	v_mov_b32_e32 v93, v2
	v_mov_b32_e32 v10, v2
	v_mov_b32_e32 v11, v2
	v_mov_b32_e32 v12, v2
	v_mov_b32_e32 v13, v2
	v_mov_b32_e32 v18, v2
	v_mov_b32_e32 v19, v2
	v_mov_b32_e32 v20, v2
	v_mov_b32_e32 v21, v2
	v_mov_b32_e32 v34, v2
	v_mov_b32_e32 v35, v2
	v_mov_b32_e32 v36, v2
	v_mov_b32_e32 v37, v2
	v_mov_b32_e32 v38, v2
	v_mov_b32_e32 v39, v2
	v_mov_b32_e32 v40, v2
	v_mov_b32_e32 v41, v2
	v_mov_b32_e32 v78, v2
	v_mov_b32_e32 v79, v2
	v_mov_b32_e32 v80, v2
	v_mov_b32_e32 v81, v2
	v_mov_b32_e32 v82, v2
	v_mov_b32_e32 v83, v2
	v_mov_b32_e32 v84, v2
	v_mov_b32_e32 v85, v2
	v_mov_b32_e32 v98, v2
	v_mov_b32_e32 v99, v2
	v_mov_b32_e32 v100, v2
	v_mov_b32_e32 v101, v2
	v_mov_b32_e32 v102, v2
	v_mov_b32_e32 v103, v2
	v_mov_b32_e32 v104, v2
	v_mov_b32_e32 v105, v2
	v_mov_b32_e32 v50, v2
	v_mov_b32_e32 v51, v2
	v_mov_b32_e32 v52, v2
	v_mov_b32_e32 v53, v2
	v_mov_b32_e32 v86, v2
	v_mov_b32_e32 v87, v2
	v_mov_b32_e32 v88, v2
	v_mov_b32_e32 v89, v2
	v_mov_b32_e32 v42, v2
	v_mov_b32_e32 v43, v2
	v_mov_b32_e32 v44, v2
	v_mov_b32_e32 v45, v2
	v_mov_b32_e32 v70, v2
	v_mov_b32_e32 v71, v2
	v_mov_b32_e32 v72, v2
	v_mov_b32_e32 v73, v2
	v_mov_b32_e32 v30, v2
	v_mov_b32_e32 v31, v2
	v_mov_b32_e32 v32, v2
	v_mov_b32_e32 v33, v2
	v_mov_b32_e32 v54, v2
	v_mov_b32_e32 v55, v2
	v_mov_b32_e32 v56, v2
	v_mov_b32_e32 v57, v2
	v_mov_b32_e32 v14, v2
	v_mov_b32_e32 v15, v2
	v_mov_b32_e32 v16, v2
	v_mov_b32_e32 v17, v2
	v_mov_b32_e32 v46, v2
	v_mov_b32_e32 v47, v2
	v_mov_b32_e32 v48, v2
	v_mov_b32_e32 v49, v2
	v_mov_b32_e32 v114, v2
	v_mov_b32_e32 v115, v2
	v_mov_b32_e32 v116, v2
	v_mov_b32_e32 v117, v2
	v_mov_b32_e32 v122, v2
	v_mov_b32_e32 v123, v2
	v_mov_b32_e32 v124, v2
	v_mov_b32_e32 v125, v2
	v_mov_b32_e32 v106, v2
	v_mov_b32_e32 v107, v2
	v_mov_b32_e32 v108, v2
	v_mov_b32_e32 v109, v2
	v_mov_b32_e32 v126, v2
	v_mov_b32_e32 v127, v2
	v_mov_b32_e32 v128, v2
	v_mov_b32_e32 v129, v2
	v_mov_b32_e32 v94, v2
	v_mov_b32_e32 v95, v2
	v_mov_b32_e32 v96, v2
	v_mov_b32_e32 v97, v2
	v_mov_b32_e32 v118, v2
	v_mov_b32_e32 v119, v2
	v_mov_b32_e32 v120, v2
	v_mov_b32_e32 v121, v2
	v_mov_b32_e32 v74, v2
	v_mov_b32_e32 v75, v2
	v_mov_b32_e32 v76, v2
	v_mov_b32_e32 v77, v2
	v_mov_b32_e32 v110, v2
	v_mov_b32_e32 v111, v2
	v_mov_b32_e32 v112, v2
	v_mov_b32_e32 v113, v2
	s_andn2_b64 vcc, exec, s[4:5]
	s_cbranch_vccnz .LBB0_1527
	s_branch .LBB0_1528

; #define PG8_STAGE(bufoff, gbase, voff) do { _Pragma("unroll") for (int _i = 0; _i < 2; ++_i) \
;         __builtin_amdgcn_global_load_lds((const unsigned*)((const char*)(gbase) + (voff)[_i]), (PG8_LAS unsigned*)(lds + (bufoff) + ldsw + _i * 8192), 16, 0, 0); } while (0)
; #define PG8_LDA(dst, b, h) do { _Pragma("unroll") for (int m = 0; m < 4; ++m) _Pragma("unroll") for (int k = 0; k < 2; ++k) dst[m][k] = *(const PG8_LAS bf16x8*)(lds + PG8_SA(b, h) + aoff + m * 2048 + k * 1024); } while (0)
; #define PG8_LDB(dst, b, h) do { _Pragma("unroll") for (int n = 0; n < 2; ++n) _Pragma("unroll") for (int k = 0; k < 2; ++k) dst[n][k] = *(const PG8_LAS bf16x8*)(lds + PG8_SB(b, h) + boff + n * 2048 + k * 1024); } while (0)
; #define PG8_MMA(ai, bj, At, Bt) do { __builtin_amdgcn_s_setprio(1); _Pragma("unroll") for (int m = 0; m < 4; ++m) _Pragma("unroll") for (int n = 0; n < 2; ++n) _Pragma("unroll") for (int k = 0; k < 2; ++k) \
;         acc[ai][bj][m][n] = __builtin_amdgcn_mfma_f32_16x16x32_bf16(Bt[n][k], At[m][k], acc[ai][bj][m][n], 0, 0, 0); __builtin_amdgcn_s_setprio(0); } while (0)
; #define PG8_WAIT_V(n) asm volatile("s_waitcnt vmcnt(" #n ")" ::: "memory")
; #define PG8_BAR __builtin_amdgcn_s_barrier()
; template <class Epi, class Sched, bool ALIGN_EPI = false, bool SP2 = false>
; __device__ __forceinline__ void gemm_phase(PG8_LAS unsigned char* lds, const Gemm g, const Sched& S, const Epi& E) {
;     ...
;         for (int t = 0; t < nt; t += 2) {
;             const bool last = (t == nt - 2);
;             const char* a1 = cA + (size_t)(t + 1) * kstep;
;             const char* a2 = last ? nA : cA + (size_t)(t + 2) * kstep; const char* b2 = last ? nB : cB + (size_t)(t + 2) * kstep;
;             const char* a3 = a2 + kstep; const char* b3 = b2 + kstep;
;             if (last && has_next) S.a_ready(nxt);
;             if constexpr (SP2) {
;             PG8_LDB(B0, 0, 0); PG8_LDB(B1, 0, 1); PG8_SCHED; PG8_LDA(At, 0, 0); PG8_STAGE(PG8_SA(1, 1), a1 + hstep, voffA);
;             PG8_WAIT_V(8); PG8_WAIT_L(0); PG8_BAR; PG8_MMA(0, 0, At, B0); PG8_MMA(0, 1, At, B1); PG8_BAR; PG8_SCHED;
;             PG8_LDA(At, 0, 1); PG8_STAGE(PG8_SB(0, 0), b2, voffB); PG8_STAGE(PG8_SB(0, 1), b2 + hstep, voffB); PG8_STAGE(PG8_SA(0, 0), a2, voffA);
;             PG8_WAIT_V(8); PG8_WAIT_L(0); PG8_BAR; PG8_MMA(1, 0, At, B0); PG8_MMA(1, 1, At, B1); PG8_BAR; PG8_SCHED;
.LBB0_1733:
	ds_read_b128 v[144:147], v140
	ds_read_b128 v[148:151], v140 offset:1024
	ds_read_b128 v[152:155], v140 offset:2048
	ds_read_b128 v[156:159], v140 offset:3072
	ds_read_b128 v[160:163], v141
	ds_read_b128 v[164:167], v141 offset:1024
	ds_read_b128 v[168:171], v141 offset:2048
	ds_read_b128 v[172:175], v141 offset:3072
	s_add_i32 s66, s36, 2
	s_add_u32 s34, s30, 0x100
	s_addc_u32 s35, s31, 0
	s_cmp_eq_u32 s50, s36
	s_cselect_b32 s36, s28, s63
	s_cselect_b32 s39, s27, s35
	s_cselect_b32 s38, s26, s34
	s_cselect_b32 s37, s29, s65
	s_mov_b32 m0, s58
	v_lshl_add_u64 v[184:185], s[30:31], 0, v[134:135]
	ds_read_b128 v[176:179], v142
	ds_read_b128 v[180:183], v142 offset:1024
	ds_read_b128 v[188:191], v142 offset:2048
	ds_read_b128 v[192:195], v142 offset:3072
	ds_read_b128 v[196:199], v142 offset:4096
	ds_read_b128 v[200:203], v142 offset:5120
	ds_read_b128 v[204:207], v142 offset:6144
	ds_read_b128 v[208:211], v142 offset:7168
	global_load_lds_dwordx4 v[184:185], off
	v_lshl_add_u64 v[184:185], s[30:31], 0, v[136:137]
	s_add_i32 m0, s1, 0xe000
	s_nop 0
	global_load_lds_dwordx4 v[184:185], off
	s_waitcnt vmcnt(8)
	s_waitcnt lgkmcnt(0)
	s_barrier
	s_setprio 1
	s_waitcnt lgkmcnt(0)
	v_mfma_f32_16x16x32_bf16 v[126:129], v[144:147], v[176:179], v[126:129]
	v_mfma_f32_16x16x32_bf16 v[122:125], v[152:155], v[176:179], v[122:125]
	v_mfma_f32_16x16x32_bf16 v[110:113], v[144:147], v[188:191], v[110:113]
	v_mfma_f32_16x16x32_bf16 v[106:109], v[152:155], v[188:191], v[106:109]
	v_mfma_f32_16x16x32_bf16 v[94:97], v[144:147], v[196:199], v[94:97]
	v_mfma_f32_16x16x32_bf16 v[90:93], v[152:155], v[196:199], v[90:93]
	v_mfma_f32_16x16x32_bf16 v[78:81], v[144:147], v[204:207], v[78:81]
	v_mfma_f32_16x16x32_bf16 v[74:77], v[152:155], v[204:207], v[74:77]
	v_mfma_f32_16x16x32_bf16 v[126:129], v[148:151], v[180:183], v[126:129]
	v_mfma_f32_16x16x32_bf16 v[122:125], v[156:159], v[180:183], v[122:125]
	v_mfma_f32_16x16x32_bf16 v[110:113], v[148:151], v[192:195], v[110:113]
	v_mfma_f32_16x16x32_bf16 v[106:109], v[156:159], v[192:195], v[106:109]
	v_mfma_f32_16x16x32_bf16 v[94:97], v[148:151], v[200:203], v[94:97]
	v_mfma_f32_16x16x32_bf16 v[90:93], v[156:159], v[200:203], v[90:93]
	v_mfma_f32_16x16x32_bf16 v[78:81], v[148:151], v[208:211], v[78:81]
	v_mfma_f32_16x16x32_bf16 v[74:77], v[156:159], v[208:211], v[74:77]
	s_setprio 0
	s_setprio 1
	v_mfma_f32_16x16x32_bf16 v[118:121], v[160:163], v[176:179], v[118:121]
	v_mfma_f32_16x16x32_bf16 v[114:117], v[168:171], v[176:179], v[114:117]
	v_mfma_f32_16x16x32_bf16 v[102:105], v[160:163], v[188:191], v[102:105]
	v_mfma_f32_16x16x32_bf16 v[98:101], v[168:171], v[188:191], v[98:101]
	v_mfma_f32_16x16x32_bf16 v[86:89], v[160:163], v[196:199], v[86:89]
	v_mfma_f32_16x16x32_bf16 v[82:85], v[168:171], v[196:199], v[82:85]
	v_mfma_f32_16x16x32_bf16 v[70:73], v[160:163], v[204:207], v[70:73]
	v_mfma_f32_16x16x32_bf16 v[66:69], v[168:171], v[204:207], v[66:69]
	v_mfma_f32_16x16x32_bf16 v[118:121], v[164:167], v[180:183], v[118:121]
	v_mfma_f32_16x16x32_bf16 v[114:117], v[172:175], v[180:183], v[114:117]
	v_mfma_f32_16x16x32_bf16 v[102:105], v[164:167], v[192:195], v[102:105]
	v_mfma_f32_16x16x32_bf16 v[98:101], v[172:175], v[192:195], v[98:101]
	v_mfma_f32_16x16x32_bf16 v[86:89], v[164:167], v[200:203], v[86:89]
	v_mfma_f32_16x16x32_bf16 v[82:85], v[172:175], v[200:203], v[82:85]
	v_mfma_f32_16x16x32_bf16 v[70:73], v[164:167], v[208:211], v[70:73]
	v_mfma_f32_16x16x32_bf16 v[66:69], v[172:175], v[208:211], v[66:69]
	s_barrier
	s_setprio 0
	s_add_i32 s30, s51, s0
	v_lshl_add_u64 v[184:185], s[36:37], 0, v[132:133]
	s_mov_b32 m0, s30
	ds_read_b128 v[176:179], v142 offset:16384
	ds_read_b128 v[180:183], v142 offset:17408
	ds_read_b128 v[188:191], v142 offset:18432
	ds_read_b128 v[192:195], v142 offset:19456
	ds_read_b128 v[196:199], v142 offset:20480
	ds_read_b128 v[200:203], v142 offset:21504
	ds_read_b128 v[204:207], v142 offset:22528
	ds_read_b128 v[208:211], v142 offset:23552
	global_load_lds_dwordx4 v[184:185], off
	s_add_i32 m0, s30, 0x2000
	s_add_u32 s30, s36, 0xb0000
	v_lshl_add_u64 v[212:213], s[36:37], 0, v[130:131]
	s_addc_u32 s31, s37, 0
	s_add_i32 s67, s52, s0
	global_load_lds_dwordx4 v[212:213], off
	v_lshl_add_u64 v[214:215], s[30:31], 0, v[132:133]
	s_mov_b32 m0, s67
	v_lshl_add_u64 v[216:217], s[38:39], 0, v[130:131]
	global_load_lds_dwordx4 v[214:215], off
	v_lshl_add_u64 v[214:215], s[30:31], 0, v[130:131]
	s_add_i32 m0, s67, 0x2000
	s_nop 0
	global_load_lds_dwordx4 v[214:215], off
	v_lshl_add_u64 v[214:215], s[38:39], 0, v[132:133]
	s_mov_b32 m0, s1
	s_nop 0
	global_load_lds_dwordx4 v[214:215], off
	s_mov_b32 m0, s40
	s_nop 0
	global_load_lds_dwordx4 v[216:217], off
	s_waitcnt vmcnt(8)
	s_waitcnt lgkmcnt(0)
	s_barrier
; #define PG8_STAGE(bufoff, gbase, voff) do { _Pragma("unroll") for (int _i = 0; _i < 2; ++_i) \
;         __builtin_amdgcn_global_load_lds((const unsigned*)((const char*)(gbase) + (voff)[_i]), (PG8_LAS unsigned*)(lds + (bufoff) + ldsw + _i * 8192), 16, 0, 0); } while (0)
; #define PG8_LDA(dst, b, h) do { _Pragma("unroll") for (int m = 0; m < 4; ++m) _Pragma("unroll") for (int k = 0; k < 2; ++k) dst[m][k] = *(const PG8_LAS bf16x8*)(lds + PG8_SA(b, h) + aoff + m * 2048 + k * 1024); } while (0)
; #define PG8_LDB(dst, b, h) do { _Pragma("unroll") for (int n = 0; n < 2; ++n) _Pragma("unroll") for (int k = 0; k < 2; ++k) dst[n][k] = *(const PG8_LAS bf16x8*)(lds + PG8_SB(b, h) + boff + n * 2048 + k * 1024); } while (0)
; #define PG8_MMA(ai, bj, At, Bt) do { __builtin_amdgcn_s_setprio(1); _Pragma("unroll") for (int m = 0; m < 4; ++m) _Pragma("unroll") for (int n = 0; n < 2; ++n) _Pragma("unroll") for (int k = 0; k < 2; ++k) \
;         acc[ai][bj][m][n] = __builtin_amdgcn_mfma_f32_16x16x32_bf16(Bt[n][k], At[m][k], acc[ai][bj][m][n], 0, 0, 0); __builtin_amdgcn_s_setprio(0); } while (0)
; #define PG8_WAIT_V(n) asm volatile("s_waitcnt vmcnt(" #n ")" ::: "memory")
; #define PG8_WAIT_L(n) asm volatile("s_waitcnt lgkmcnt(" #n ")" ::: "memory")
; #define PG8_BAR __builtin_amdgcn_s_barrier()
; #define PG8_SCHED __builtin_amdgcn_sched_barrier(0)
; template <class Epi, class Sched, bool ALIGN_EPI = false, bool SP2 = false>
; __device__ __forceinline__ void gemm_phase(PG8_LAS unsigned char* lds, const Gemm g, const Sched& S, const Epi& E) {
;     ...
;             PG8_WAIT_V(8); PG8_WAIT_L(0); PG8_BAR; PG8_MMA(1, 0, At, B0); PG8_MMA(1, 1, At, B1); PG8_BAR; PG8_SCHED;
;             PG8_LDB(B0, 1, 0); PG8_LDB(B1, 1, 1); PG8_SCHED; PG8_LDA(At, 1, 0); PG8_STAGE(PG8_SA(0, 1), a2 + hstep, voffA);
;             PG8_WAIT_V(8); PG8_WAIT_L(0); PG8_BAR; PG8_MMA(0, 0, At, B0); PG8_MMA(0, 1, At, B1); PG8_BAR; PG8_SCHED;
	s_setprio 1
	s_waitcnt lgkmcnt(0)
	v_mfma_f32_16x16x32_bf16 v[62:65], v[144:147], v[176:179], v[62:65]
	v_mfma_f32_16x16x32_bf16 v[58:61], v[152:155], v[176:179], v[58:61]
	v_mfma_f32_16x16x32_bf16 v[46:49], v[144:147], v[188:191], v[46:49]
	v_mfma_f32_16x16x32_bf16 v[42:45], v[152:155], v[188:191], v[42:45]
	v_mfma_f32_16x16x32_bf16 v[30:33], v[144:147], v[196:199], v[30:33]
	v_mfma_f32_16x16x32_bf16 v[26:29], v[152:155], v[196:199], v[26:29]
	v_mfma_f32_16x16x32_bf16 v[14:17], v[144:147], v[204:207], v[14:17]
	v_mfma_f32_16x16x32_bf16 v[10:13], v[152:155], v[204:207], v[10:13]
	v_mfma_f32_16x16x32_bf16 v[62:65], v[148:151], v[180:183], v[62:65]
	v_mfma_f32_16x16x32_bf16 v[58:61], v[156:159], v[180:183], v[58:61]
	v_mfma_f32_16x16x32_bf16 v[46:49], v[148:151], v[192:195], v[46:49]
	v_mfma_f32_16x16x32_bf16 v[42:45], v[156:159], v[192:195], v[42:45]
	v_mfma_f32_16x16x32_bf16 v[30:33], v[148:151], v[200:203], v[30:33]
	v_mfma_f32_16x16x32_bf16 v[26:29], v[156:159], v[200:203], v[26:29]
	v_mfma_f32_16x16x32_bf16 v[14:17], v[148:151], v[208:211], v[14:17]
	v_mfma_f32_16x16x32_bf16 v[10:13], v[156:159], v[208:211], v[10:13]
	s_setprio 0
	s_setprio 1
	v_mfma_f32_16x16x32_bf16 v[54:57], v[160:163], v[176:179], v[54:57]
	v_mfma_f32_16x16x32_bf16 v[50:53], v[168:171], v[176:179], v[50:53]
	v_mfma_f32_16x16x32_bf16 v[38:41], v[160:163], v[188:191], v[38:41]
	v_mfma_f32_16x16x32_bf16 v[34:37], v[168:171], v[188:191], v[34:37]
	v_mfma_f32_16x16x32_bf16 v[22:25], v[160:163], v[196:199], v[22:25]
	v_mfma_f32_16x16x32_bf16 v[18:21], v[168:171], v[196:199], v[18:21]
	v_mfma_f32_16x16x32_bf16 v[6:9], v[160:163], v[204:207], v[6:9]
	v_mfma_f32_16x16x32_bf16 v[2:5], v[168:171], v[204:207], v[2:5]
	v_mfma_f32_16x16x32_bf16 v[54:57], v[164:167], v[180:183], v[54:57]
	v_mfma_f32_16x16x32_bf16 v[50:53], v[172:175], v[180:183], v[50:53]
	v_mfma_f32_16x16x32_bf16 v[38:41], v[164:167], v[192:195], v[38:41]
	v_mfma_f32_16x16x32_bf16 v[34:37], v[172:175], v[192:195], v[34:37]
	v_mfma_f32_16x16x32_bf16 v[22:25], v[164:167], v[200:203], v[22:25]
	v_mfma_f32_16x16x32_bf16 v[18:21], v[172:175], v[200:203], v[18:21]
	v_mfma_f32_16x16x32_bf16 v[6:9], v[164:167], v[208:211], v[6:9]
	v_mfma_f32_16x16x32_bf16 v[2:5], v[172:175], v[208:211], v[2:5]
	s_barrier
	s_setprio 0
	s_add_i32 s67, 0, 0x18000
	v_add_u32_e32 v143, s67, v1
	s_add_i32 s68, 0, 0x1c000
	ds_read_b128 v[144:147], v143
	ds_read_b128 v[148:151], v143 offset:1024
	ds_read_b128 v[152:155], v143 offset:2048
	ds_read_b128 v[156:159], v143 offset:3072
	v_add_u32_e32 v143, s68, v1
	ds_read_b128 v[160:163], v143
	ds_read_b128 v[164:167], v143 offset:1024
	ds_read_b128 v[168:171], v143 offset:2048
	ds_read_b128 v[172:175], v143 offset:3072
	s_add_u32 s30, s38, 0xb0000
	s_addc_u32 s31, s39, 0
	s_mov_b32 m0, s41
	v_lshl_add_u64 v[218:219], s[30:31], 0, v[132:133]
	ds_read_b128 v[176:179], v142 offset:32768
	ds_read_b128 v[180:183], v142 offset:33792
	ds_read_b128 v[188:191], v142 offset:34816
	ds_read_b128 v[192:195], v142 offset:35840
	ds_read_b128 v[196:199], v142 offset:36864
	ds_read_b128 v[200:203], v142 offset:37888
	ds_read_b128 v[204:207], v142 offset:38912
	ds_read_b128 v[208:211], v142 offset:39936
	global_load_lds_dwordx4 v[218:219], off
	v_lshl_add_u64 v[218:219], s[30:31], 0, v[130:131]
	s_mov_b32 m0, s42
	s_nop 0
	global_load_lds_dwordx4 v[218:219], off
	s_waitcnt vmcnt(8)
	s_waitcnt lgkmcnt(0)
	s_barrier
	s_setprio 1
	s_waitcnt lgkmcnt(0)
	v_mfma_f32_16x16x32_bf16 v[126:129], v[144:147], v[176:179], v[126:129]
	v_mfma_f32_16x16x32_bf16 v[122:125], v[152:155], v[176:179], v[122:125]
	v_mfma_f32_16x16x32_bf16 v[110:113], v[144:147], v[188:191], v[110:113]
	v_mfma_f32_16x16x32_bf16 v[106:109], v[152:155], v[188:191], v[106:109]
	v_mfma_f32_16x16x32_bf16 v[94:97], v[144:147], v[196:199], v[94:97]
	v_mfma_f32_16x16x32_bf16 v[90:93], v[152:155], v[196:199], v[90:93]
	v_mfma_f32_16x16x32_bf16 v[78:81], v[144:147], v[204:207], v[78:81]
	v_mfma_f32_16x16x32_bf16 v[74:77], v[152:155], v[204:207], v[74:77]
	v_mfma_f32_16x16x32_bf16 v[126:129], v[148:151], v[180:183], v[126:129]
	v_mfma_f32_16x16x32_bf16 v[122:125], v[156:159], v[180:183], v[122:125]
	v_mfma_f32_16x16x32_bf16 v[110:113], v[148:151], v[192:195], v[110:113]
	v_mfma_f32_16x16x32_bf16 v[106:109], v[156:159], v[192:195], v[106:109]
	v_mfma_f32_16x16x32_bf16 v[94:97], v[148:151], v[200:203], v[94:97]
	v_mfma_f32_16x16x32_bf16 v[90:93], v[156:159], v[200:203], v[90:93]
	v_mfma_f32_16x16x32_bf16 v[78:81], v[148:151], v[208:211], v[78:81]
	v_mfma_f32_16x16x32_bf16 v[74:77], v[156:159], v[208:211], v[74:77]
	s_setprio 0
	s_setprio 1
	v_mfma_f32_16x16x32_bf16 v[118:121], v[160:163], v[176:179], v[118:121]
	v_mfma_f32_16x16x32_bf16 v[114:117], v[168:171], v[176:179], v[114:117]
	v_mfma_f32_16x16x32_bf16 v[102:105], v[160:163], v[188:191], v[102:105]
	v_mfma_f32_16x16x32_bf16 v[98:101], v[168:171], v[188:191], v[98:101]
	v_mfma_f32_16x16x32_bf16 v[86:89], v[160:163], v[196:199], v[86:89]
	v_mfma_f32_16x16x32_bf16 v[82:85], v[168:171], v[196:199], v[82:85]
	v_mfma_f32_16x16x32_bf16 v[70:73], v[160:163], v[204:207], v[70:73]
	v_mfma_f32_16x16x32_bf16 v[66:69], v[168:171], v[204:207], v[66:69]
	v_mfma_f32_16x16x32_bf16 v[118:121], v[164:167], v[180:183], v[118:121]
	v_mfma_f32_16x16x32_bf16 v[114:117], v[172:175], v[180:183], v[114:117]
	v_mfma_f32_16x16x32_bf16 v[102:105], v[164:167], v[192:195], v[102:105]
	v_mfma_f32_16x16x32_bf16 v[98:101], v[172:175], v[192:195], v[98:101]
	v_mfma_f32_16x16x32_bf16 v[86:89], v[164:167], v[200:203], v[86:89]
	v_mfma_f32_16x16x32_bf16 v[82:85], v[172:175], v[200:203], v[82:85]
	v_mfma_f32_16x16x32_bf16 v[70:73], v[164:167], v[208:211], v[70:73]
	v_mfma_f32_16x16x32_bf16 v[66:69], v[172:175], v[208:211], v[66:69]
	s_barrier
; #define PG8_STAGE(bufoff, gbase, voff) do { _Pragma("unroll") for (int _i = 0; _i < 2; ++_i) \
;         __builtin_amdgcn_global_load_lds((const unsigned*)((const char*)(gbase) + (voff)[_i]), (PG8_LAS unsigned*)(lds + (bufoff) + ldsw + _i * 8192), 16, 0, 0); } while (0)
; #define PG8_LDA(dst, b, h) do { _Pragma("unroll") for (int m = 0; m < 4; ++m) _Pragma("unroll") for (int k = 0; k < 2; ++k) dst[m][k] = *(const PG8_LAS bf16x8*)(lds + PG8_SA(b, h) + aoff + m * 2048 + k * 1024); } while (0)
; #define PG8_MMA(ai, bj, At, Bt) do { __builtin_amdgcn_s_setprio(1); _Pragma("unroll") for (int m = 0; m < 4; ++m) _Pragma("unroll") for (int n = 0; n < 2; ++n) _Pragma("unroll") for (int k = 0; k < 2; ++k) \
;         acc[ai][bj][m][n] = __builtin_amdgcn_mfma_f32_16x16x32_bf16(Bt[n][k], At[m][k], acc[ai][bj][m][n], 0, 0, 0); __builtin_amdgcn_s_setprio(0); } while (0)
; #define PG8_WAIT_V(n) asm volatile("s_waitcnt vmcnt(" #n ")" ::: "memory")
; #define PG8_WAIT_L(n) asm volatile("s_waitcnt lgkmcnt(" #n ")" ::: "memory")
; #define PG8_BAR __builtin_amdgcn_s_barrier()
; #define PG8_SCHED __builtin_amdgcn_sched_barrier(0)
; template <class Epi, class Sched, bool ALIGN_EPI = false, bool SP2 = false>
; __device__ __forceinline__ void gemm_phase(PG8_LAS unsigned char* lds, const Gemm g, const Sched& S, const Epi& E) {
;     ...
;         for (int t = 0; t < nt; t += 2) {
;             const bool last = (t == nt - 2);
;             const char* a1 = cA + (size_t)(t + 1) * kstep;
;             const char* a2 = last ? nA : cA + (size_t)(t + 2) * kstep; const char* b2 = last ? nB : cB + (size_t)(t + 2) * kstep;
;             const char* a3 = a2 + kstep; const char* b3 = b2 + kstep;
;     ...
;             PG8_LDA(At, 1, 1); PG8_STAGE(PG8_SB(1, 0), b3, voffB); PG8_STAGE(PG8_SB(1, 1), b3 + hstep, voffB); PG8_STAGE(PG8_SA(1, 0), a3, voffA);
;             PG8_WAIT_V(8); PG8_WAIT_L(0); PG8_BAR; PG8_MMA(1, 0, At, B0); PG8_MMA(1, 1, At, B1); PG8_BAR; PG8_SCHED;
	s_setprio 0
	s_add_i32 s30, s67, s0
	v_lshl_add_u64 v[184:185], v[184:185], 0, s[14:15]
	s_mov_b32 m0, s30
	ds_read_b128 v[176:179], v142 offset:49152
	ds_read_b128 v[180:183], v142 offset:50176
	ds_read_b128 v[188:191], v142 offset:51200
	ds_read_b128 v[192:195], v142 offset:52224
	ds_read_b128 v[196:199], v142 offset:53248
	ds_read_b128 v[200:203], v142 offset:54272
	ds_read_b128 v[204:207], v142 offset:55296
	ds_read_b128 v[208:211], v142 offset:56320
	global_load_lds_dwordx4 v[184:185], off
	s_add_i32 m0, s30, 0x2000
	s_add_u32 s30, s36, 0xb0080
	v_lshl_add_u64 v[184:185], v[212:213], 0, s[14:15]
	s_addc_u32 s31, s37, 0
	s_add_i32 s36, s68, s0
	global_load_lds_dwordx4 v[184:185], off
	v_lshl_add_u64 v[184:185], s[30:31], 0, v[132:133]
	s_mov_b32 m0, s36
	s_nop 0
	global_load_lds_dwordx4 v[184:185], off
	v_lshl_add_u64 v[184:185], s[30:31], 0, v[130:131]
	s_add_i32 m0, s36, 0x2000
	s_nop 0
	global_load_lds_dwordx4 v[184:185], off
	v_lshl_add_u64 v[184:185], v[214:215], 0, s[14:15]
	s_mov_b32 m0, s48
	s_nop 0
	global_load_lds_dwordx4 v[184:185], off
	v_lshl_add_u64 v[184:185], v[216:217], 0, s[14:15]
	s_mov_b32 m0, s49
	s_nop 0
	global_load_lds_dwordx4 v[184:185], off
	s_waitcnt vmcnt(8)
	s_waitcnt lgkmcnt(0)
	s_barrier
	s_setprio 1
	s_waitcnt lgkmcnt(0)
	v_mfma_f32_16x16x32_bf16 v[62:65], v[144:147], v[176:179], v[62:65]
	v_mfma_f32_16x16x32_bf16 v[58:61], v[152:155], v[176:179], v[58:61]
	v_mfma_f32_16x16x32_bf16 v[46:49], v[144:147], v[188:191], v[46:49]
	v_mfma_f32_16x16x32_bf16 v[42:45], v[152:155], v[188:191], v[42:45]
	v_mfma_f32_16x16x32_bf16 v[30:33], v[144:147], v[196:199], v[30:33]
	v_mfma_f32_16x16x32_bf16 v[26:29], v[152:155], v[196:199], v[26:29]
	v_mfma_f32_16x16x32_bf16 v[14:17], v[144:147], v[204:207], v[14:17]
	v_mfma_f32_16x16x32_bf16 v[10:13], v[152:155], v[204:207], v[10:13]
	v_mfma_f32_16x16x32_bf16 v[62:65], v[148:151], v[180:183], v[62:65]
	v_mfma_f32_16x16x32_bf16 v[58:61], v[156:159], v[180:183], v[58:61]
	v_mfma_f32_16x16x32_bf16 v[46:49], v[148:151], v[192:195], v[46:49]
	v_mfma_f32_16x16x32_bf16 v[42:45], v[156:159], v[192:195], v[42:45]
	v_mfma_f32_16x16x32_bf16 v[30:33], v[148:151], v[200:203], v[30:33]
	v_mfma_f32_16x16x32_bf16 v[26:29], v[156:159], v[200:203], v[26:29]
	v_mfma_f32_16x16x32_bf16 v[14:17], v[148:151], v[208:211], v[14:17]
	v_mfma_f32_16x16x32_bf16 v[10:13], v[156:159], v[208:211], v[10:13]
	s_setprio 0
	s_setprio 1
	v_mfma_f32_16x16x32_bf16 v[54:57], v[160:163], v[176:179], v[54:57]
	v_mfma_f32_16x16x32_bf16 v[50:53], v[168:171], v[176:179], v[50:53]
	v_mfma_f32_16x16x32_bf16 v[38:41], v[160:163], v[188:191], v[38:41]
	v_mfma_f32_16x16x32_bf16 v[34:37], v[168:171], v[188:191], v[34:37]
	v_mfma_f32_16x16x32_bf16 v[22:25], v[160:163], v[196:199], v[22:25]
	v_mfma_f32_16x16x32_bf16 v[18:21], v[168:171], v[196:199], v[18:21]
	v_mfma_f32_16x16x32_bf16 v[6:9], v[160:163], v[204:207], v[6:9]
	v_mfma_f32_16x16x32_bf16 v[2:5], v[168:171], v[204:207], v[2:5]
	v_mfma_f32_16x16x32_bf16 v[54:57], v[164:167], v[180:183], v[54:57]
	v_mfma_f32_16x16x32_bf16 v[50:53], v[172:175], v[180:183], v[50:53]
	v_mfma_f32_16x16x32_bf16 v[38:41], v[164:167], v[192:195], v[38:41]
	v_mfma_f32_16x16x32_bf16 v[34:37], v[172:175], v[192:195], v[34:37]
	v_mfma_f32_16x16x32_bf16 v[22:25], v[164:167], v[200:203], v[22:25]
	v_mfma_f32_16x16x32_bf16 v[18:21], v[172:175], v[200:203], v[18:21]
	v_mfma_f32_16x16x32_bf16 v[6:9], v[164:167], v[208:211], v[6:9]
	v_mfma_f32_16x16x32_bf16 v[2:5], v[172:175], v[208:211], v[2:5]
	s_barrier
	s_setprio 0
	s_add_u32 s63, s63, 0x100
	s_addc_u32 s65, s65, 0
	s_cmp_ge_i32 s66, s47
	s_mov_b64 s[30:31], s[34:35]
	s_mov_b32 s36, s66
	s_cbranch_scc0 .LBB0_1733

; #define PG8_STAGE(bufoff, gbase, voff) do { _Pragma("unroll") for (int _i = 0; _i < 2; ++_i) \
;         __builtin_amdgcn_global_load_lds((const unsigned*)((const char*)(gbase) + (voff)[_i]), (PG8_LAS unsigned*)(lds + (bufoff) + ldsw + _i * 8192), 16, 0, 0); } while (0)
; #define PG8_LDA(dst, b, h) do { _Pragma("unroll") for (int m = 0; m < 4; ++m) _Pragma("unroll") for (int k = 0; k < 2; ++k) dst[m][k] = *(const PG8_LAS bf16x8*)(lds + PG8_SA(b, h) + aoff + m * 2048 + k * 1024); } while (0)
; #define PG8_LDB(dst, b, h) do { _Pragma("unroll") for (int n = 0; n < 2; ++n) _Pragma("unroll") for (int k = 0; k < 2; ++k) dst[n][k] = *(const PG8_LAS bf16x8*)(lds + PG8_SB(b, h) + boff + n * 2048 + k * 1024); } while (0)
; #define PG8_MMA(ai, bj, At, Bt) do { __builtin_amdgcn_s_setprio(1); _Pragma("unroll") for (int m = 0; m < 4; ++m) _Pragma("unroll") for (int n = 0; n < 2; ++n) _Pragma("unroll") for (int k = 0; k < 2; ++k) \
;         acc[ai][bj][m][n] = __builtin_amdgcn_mfma_f32_16x16x32_bf16(Bt[n][k], At[m][k], acc[ai][bj][m][n], 0, 0, 0); __builtin_amdgcn_s_setprio(0); } while (0)
; #define PG8_WAIT_V(n) asm volatile("s_waitcnt vmcnt(" #n ")" ::: "memory")
; #define PG8_BAR __builtin_amdgcn_s_barrier()
; template <class Epi, class Sched, bool ALIGN_EPI = false, bool SP2 = false>
; __device__ __forceinline__ void gemm_phase(PG8_LAS unsigned char* lds, const Gemm g, const Sched& S, const Epi& E) {
;     ...
;         for (int t = 0; t < nt; t += 2) {
;             const bool last = (t == nt - 2);
;             const char* a1 = cA + (size_t)(t + 1) * kstep;
;             const char* a2 = last ? nA : cA + (size_t)(t + 2) * kstep; const char* b2 = last ? nB : cB + (size_t)(t + 2) * kstep;
;             const char* a3 = a2 + kstep; const char* b3 = b2 + kstep;
;             if (last && has_next) S.a_ready(nxt);
;             if constexpr (SP2) {
;             PG8_LDB(B0, 0, 0); PG8_LDB(B1, 0, 1); PG8_SCHED; PG8_LDA(At, 0, 0); PG8_STAGE(PG8_SA(1, 1), a1 + hstep, voffA);
;             PG8_WAIT_V(8); PG8_WAIT_L(0); PG8_BAR; PG8_MMA(0, 0, At, B0); PG8_MMA(0, 1, At, B1); PG8_BAR; PG8_SCHED;
;             PG8_LDA(At, 0, 1); PG8_STAGE(PG8_SB(0, 0), b2, voffB); PG8_STAGE(PG8_SB(0, 1), b2 + hstep, voffB); PG8_STAGE(PG8_SA(0, 0), a2, voffA);
;             PG8_WAIT_V(8); PG8_WAIT_L(0); PG8_BAR; PG8_MMA(1, 0, At, B0); PG8_MMA(1, 1, At, B1); PG8_BAR; PG8_SCHED;
.LBB0_1778:
	v_add_u32_e32 v162, s51, v148
	v_add_u32_e32 v178, s52, v148
	s_add_u32 s30, s22, s28
	ds_read_b128 v[150:153], v162
	ds_read_b128 v[154:157], v162 offset:1024
	ds_read_b128 v[158:161], v162 offset:2048
	ds_read_b128 v[162:165], v162 offset:3072
	ds_read_b128 v[166:169], v178
	ds_read_b128 v[170:173], v178 offset:1024
	ds_read_b128 v[174:177], v178 offset:2048
	ds_read_b128 v[178:181], v178 offset:3072
	s_addc_u32 s31, s23, s29
	s_add_u32 s30, s30, 0x100
	s_addc_u32 s31, s31, 0
	s_add_u32 s60, s57, s28
	s_addc_u32 s61, s58, s29
	s_cmpk_eq_i32 s28, 0x1500
	s_cselect_b32 s35, s27, s31
	s_cselect_b32 s34, s26, s30
	s_cselect_b32 s31, s9, s61
	s_cselect_b32 s30, s8, s60
	v_lshl_add_u64 v[216:217], v[142:143], 0, s[28:29]
	s_add_i32 m0, s40, 0xc000
	ds_read_b128 v[182:185], v149
	ds_read_b128 v[188:191], v149 offset:1024
	ds_read_b128 v[192:195], v149 offset:2048
	ds_read_b128 v[196:199], v149 offset:3072
	ds_read_b128 v[200:203], v149 offset:4096
	ds_read_b128 v[204:207], v149 offset:5120
	ds_read_b128 v[208:211], v149 offset:6144
	ds_read_b128 v[212:215], v149 offset:7168
	global_load_lds_dwordx4 v[216:217], off
	v_lshl_add_u64 v[216:217], v[144:145], 0, s[28:29]
	s_add_i32 m0, s40, 0xe000
	s_nop 0
	global_load_lds_dwordx4 v[216:217], off
	s_waitcnt vmcnt(8)
	s_waitcnt lgkmcnt(0)
	s_barrier
	s_setprio 1
	s_waitcnt lgkmcnt(0)
	v_mfma_f32_16x16x32_bf16 v[114:117], v[150:153], v[182:185], v[114:117]
	v_mfma_f32_16x16x32_bf16 v[82:85], v[158:161], v[182:185], v[82:85]
	v_mfma_f32_16x16x32_bf16 v[122:125], v[150:153], v[192:195], v[122:125]
	v_mfma_f32_16x16x32_bf16 v[86:89], v[158:161], v[192:195], v[86:89]
	v_mfma_f32_16x16x32_bf16 v[126:129], v[150:153], v[200:203], v[126:129]
	v_mfma_f32_16x16x32_bf16 v[90:93], v[158:161], v[200:203], v[90:93]
	v_mfma_f32_16x16x32_bf16 v[118:121], v[150:153], v[208:211], v[118:121]
	v_mfma_f32_16x16x32_bf16 v[102:105], v[158:161], v[208:211], v[102:105]
	v_mfma_f32_16x16x32_bf16 v[114:117], v[154:157], v[188:191], v[114:117]
	v_mfma_f32_16x16x32_bf16 v[82:85], v[162:165], v[188:191], v[82:85]
	v_mfma_f32_16x16x32_bf16 v[122:125], v[154:157], v[196:199], v[122:125]
	v_mfma_f32_16x16x32_bf16 v[86:89], v[162:165], v[196:199], v[86:89]
	v_mfma_f32_16x16x32_bf16 v[126:129], v[154:157], v[204:207], v[126:129]
	v_mfma_f32_16x16x32_bf16 v[90:93], v[162:165], v[204:207], v[90:93]
	v_mfma_f32_16x16x32_bf16 v[118:121], v[154:157], v[212:215], v[118:121]
	v_mfma_f32_16x16x32_bf16 v[102:105], v[162:165], v[212:215], v[102:105]
	s_setprio 0
	s_setprio 1
	v_mfma_f32_16x16x32_bf16 v[26:29], v[166:169], v[182:185], v[26:29]
	v_mfma_f32_16x16x32_bf16 v[2:5], v[174:177], v[182:185], v[2:5]
	v_mfma_f32_16x16x32_bf16 v[30:33], v[166:169], v[192:195], v[30:33]
	v_mfma_f32_16x16x32_bf16 v[6:9], v[174:177], v[192:195], v[6:9]
	v_mfma_f32_16x16x32_bf16 v[42:45], v[166:169], v[200:203], v[42:45]
	v_mfma_f32_16x16x32_bf16 v[10:13], v[174:177], v[200:203], v[10:13]
	v_mfma_f32_16x16x32_bf16 v[58:61], v[166:169], v[208:211], v[58:61]
	v_mfma_f32_16x16x32_bf16 v[14:17], v[174:177], v[208:211], v[14:17]
	v_mfma_f32_16x16x32_bf16 v[26:29], v[170:173], v[188:191], v[26:29]
	v_mfma_f32_16x16x32_bf16 v[2:5], v[178:181], v[188:191], v[2:5]
	v_mfma_f32_16x16x32_bf16 v[30:33], v[170:173], v[196:199], v[30:33]
	v_mfma_f32_16x16x32_bf16 v[6:9], v[178:181], v[196:199], v[6:9]
	v_mfma_f32_16x16x32_bf16 v[42:45], v[170:173], v[204:207], v[42:45]
	v_mfma_f32_16x16x32_bf16 v[10:13], v[178:181], v[204:207], v[10:13]
	v_mfma_f32_16x16x32_bf16 v[58:61], v[170:173], v[212:215], v[58:61]
	v_mfma_f32_16x16x32_bf16 v[14:17], v[178:181], v[212:215], v[14:17]
	s_barrier
	s_setprio 0
	s_add_i32 s60, s51, s39
	v_lshl_add_u64 v[216:217], s[30:31], 0, v[130:131]
	s_mov_b32 m0, s60
	ds_read_b128 v[182:185], v149 offset:16384
	ds_read_b128 v[188:191], v149 offset:17408
	ds_read_b128 v[192:195], v149 offset:18432
	ds_read_b128 v[196:199], v149 offset:19456
	ds_read_b128 v[200:203], v149 offset:20480
	ds_read_b128 v[204:207], v149 offset:21504
	ds_read_b128 v[208:211], v149 offset:22528
	ds_read_b128 v[212:215], v149 offset:23552
	global_load_lds_dwordx4 v[216:217], off
	s_add_i32 m0, s60, 0x2000
	s_add_u32 s60, s30, 0xb0000
	v_lshl_add_u64 v[218:219], s[30:31], 0, v[132:133]
	s_addc_u32 s61, s31, 0
	s_add_i32 s62, s52, s39
	global_load_lds_dwordx4 v[218:219], off
	v_lshl_add_u64 v[220:221], s[60:61], 0, v[130:131]
	s_mov_b32 m0, s62
	v_lshl_add_u64 v[222:223], s[34:35], 0, v[132:133]
	global_load_lds_dwordx4 v[220:221], off
	v_lshl_add_u64 v[220:221], s[60:61], 0, v[132:133]
	s_add_i32 m0, s62, 0x2000
	s_nop 0
	global_load_lds_dwordx4 v[220:221], off
	v_lshl_add_u64 v[220:221], s[34:35], 0, v[130:131]
	s_mov_b32 m0, s40
	s_nop 0
	global_load_lds_dwordx4 v[220:221], off
	s_mov_b32 m0, s41
	s_nop 0
	global_load_lds_dwordx4 v[222:223], off
	s_waitcnt vmcnt(8)
	s_waitcnt lgkmcnt(0)
	s_barrier
; #define PG8_STAGE(bufoff, gbase, voff) do { _Pragma("unroll") for (int _i = 0; _i < 2; ++_i) \
;         __builtin_amdgcn_global_load_lds((const unsigned*)((const char*)(gbase) + (voff)[_i]), (PG8_LAS unsigned*)(lds + (bufoff) + ldsw + _i * 8192), 16, 0, 0); } while (0)
; #define PG8_LDA(dst, b, h) do { _Pragma("unroll") for (int m = 0; m < 4; ++m) _Pragma("unroll") for (int k = 0; k < 2; ++k) dst[m][k] = *(const PG8_LAS bf16x8*)(lds + PG8_SA(b, h) + aoff + m * 2048 + k * 1024); } while (0)
; #define PG8_LDB(dst, b, h) do { _Pragma("unroll") for (int n = 0; n < 2; ++n) _Pragma("unroll") for (int k = 0; k < 2; ++k) dst[n][k] = *(const PG8_LAS bf16x8*)(lds + PG8_SB(b, h) + boff + n * 2048 + k * 1024); } while (0)
; #define PG8_MMA(ai, bj, At, Bt) do { __builtin_amdgcn_s_setprio(1); _Pragma("unroll") for (int m = 0; m < 4; ++m) _Pragma("unroll") for (int n = 0; n < 2; ++n) _Pragma("unroll") for (int k = 0; k < 2; ++k) \
;         acc[ai][bj][m][n] = __builtin_amdgcn_mfma_f32_16x16x32_bf16(Bt[n][k], At[m][k], acc[ai][bj][m][n], 0, 0, 0); __builtin_amdgcn_s_setprio(0); } while (0)
; #define PG8_WAIT_V(n) asm volatile("s_waitcnt vmcnt(" #n ")" ::: "memory")
; #define PG8_WAIT_L(n) asm volatile("s_waitcnt lgkmcnt(" #n ")" ::: "memory")
; #define PG8_BAR __builtin_amdgcn_s_barrier()
; #define PG8_SCHED __builtin_amdgcn_sched_barrier(0)
; template <class Epi, class Sched, bool ALIGN_EPI = false, bool SP2 = false>
; __device__ __forceinline__ void gemm_phase(PG8_LAS unsigned char* lds, const Gemm g, const Sched& S, const Epi& E) {
;     ...
;             PG8_WAIT_V(8); PG8_WAIT_L(0); PG8_BAR; PG8_MMA(1, 0, At, B0); PG8_MMA(1, 1, At, B1); PG8_BAR; PG8_SCHED;
;             PG8_LDB(B0, 1, 0); PG8_LDB(B1, 1, 1); PG8_SCHED; PG8_LDA(At, 1, 0); PG8_STAGE(PG8_SA(0, 1), a2 + hstep, voffA);
;             PG8_WAIT_V(8); PG8_WAIT_L(0); PG8_BAR; PG8_MMA(0, 0, At, B0); PG8_MMA(0, 1, At, B1); PG8_BAR; PG8_SCHED;
	s_setprio 1
	s_waitcnt lgkmcnt(0)
	v_mfma_f32_16x16x32_bf16 v[110:113], v[150:153], v[182:185], v[110:113]
	v_mfma_f32_16x16x32_bf16 v[106:109], v[158:161], v[182:185], v[106:109]
	v_mfma_f32_16x16x32_bf16 v[98:101], v[150:153], v[192:195], v[98:101]
	v_mfma_f32_16x16x32_bf16 v[94:97], v[158:161], v[192:195], v[94:97]
	v_mfma_f32_16x16x32_bf16 v[74:77], v[150:153], v[200:203], v[74:77]
	v_mfma_f32_16x16x32_bf16 v[70:73], v[158:161], v[200:203], v[70:73]
	v_mfma_f32_16x16x32_bf16 v[54:57], v[150:153], v[208:211], v[54:57]
	v_mfma_f32_16x16x32_bf16 v[50:53], v[158:161], v[208:211], v[50:53]
	v_mfma_f32_16x16x32_bf16 v[110:113], v[154:157], v[188:191], v[110:113]
	v_mfma_f32_16x16x32_bf16 v[106:109], v[162:165], v[188:191], v[106:109]
	v_mfma_f32_16x16x32_bf16 v[98:101], v[154:157], v[196:199], v[98:101]
	v_mfma_f32_16x16x32_bf16 v[94:97], v[162:165], v[196:199], v[94:97]
	v_mfma_f32_16x16x32_bf16 v[74:77], v[154:157], v[204:207], v[74:77]
	v_mfma_f32_16x16x32_bf16 v[70:73], v[162:165], v[204:207], v[70:73]
	v_mfma_f32_16x16x32_bf16 v[54:57], v[154:157], v[212:215], v[54:57]
	v_mfma_f32_16x16x32_bf16 v[50:53], v[162:165], v[212:215], v[50:53]
	s_setprio 0
	s_setprio 1
	v_mfma_f32_16x16x32_bf16 v[66:69], v[166:169], v[182:185], v[66:69]
	v_mfma_f32_16x16x32_bf16 v[18:21], v[174:177], v[182:185], v[18:21]
	v_mfma_f32_16x16x32_bf16 v[78:81], v[166:169], v[192:195], v[78:81]
	v_mfma_f32_16x16x32_bf16 v[22:25], v[174:177], v[192:195], v[22:25]
	v_mfma_f32_16x16x32_bf16 v[62:65], v[166:169], v[200:203], v[62:65]
	v_mfma_f32_16x16x32_bf16 v[46:49], v[174:177], v[200:203], v[46:49]
	v_mfma_f32_16x16x32_bf16 v[38:41], v[166:169], v[208:211], v[38:41]
	v_mfma_f32_16x16x32_bf16 v[34:37], v[174:177], v[208:211], v[34:37]
	v_mfma_f32_16x16x32_bf16 v[66:69], v[170:173], v[188:191], v[66:69]
	v_mfma_f32_16x16x32_bf16 v[18:21], v[178:181], v[188:191], v[18:21]
	v_mfma_f32_16x16x32_bf16 v[78:81], v[170:173], v[196:199], v[78:81]
	v_mfma_f32_16x16x32_bf16 v[22:25], v[178:181], v[196:199], v[22:25]
	v_mfma_f32_16x16x32_bf16 v[62:65], v[170:173], v[204:207], v[62:65]
	v_mfma_f32_16x16x32_bf16 v[46:49], v[178:181], v[204:207], v[46:49]
	v_mfma_f32_16x16x32_bf16 v[38:41], v[170:173], v[212:215], v[38:41]
	v_mfma_f32_16x16x32_bf16 v[34:37], v[178:181], v[212:215], v[34:37]
	s_barrier
	s_setprio 0
	s_add_i32 s60, 0, 0x18000
	s_add_i32 s61, 0, 0x1c000
	v_add_u32_e32 v162, s60, v148
	v_add_u32_e32 v178, s61, v148
	ds_read_b128 v[150:153], v162
	ds_read_b128 v[154:157], v162 offset:1024
	ds_read_b128 v[158:161], v162 offset:2048
	ds_read_b128 v[162:165], v162 offset:3072
	ds_read_b128 v[166:169], v178
	ds_read_b128 v[170:173], v178 offset:1024
	ds_read_b128 v[174:177], v178 offset:2048
	ds_read_b128 v[178:181], v178 offset:3072
	s_add_u32 s34, s34, 0xb0000
	s_addc_u32 s35, s35, 0
	s_mov_b32 m0, s42
	v_lshl_add_u64 v[224:225], s[34:35], 0, v[130:131]
	ds_read_b128 v[182:185], v149 offset:32768
	ds_read_b128 v[188:191], v149 offset:33792
	ds_read_b128 v[192:195], v149 offset:34816
	ds_read_b128 v[196:199], v149 offset:35840
	ds_read_b128 v[200:203], v149 offset:36864
	ds_read_b128 v[204:207], v149 offset:37888
	ds_read_b128 v[208:211], v149 offset:38912
	ds_read_b128 v[212:215], v149 offset:39936
	global_load_lds_dwordx4 v[224:225], off
	v_lshl_add_u64 v[224:225], s[34:35], 0, v[132:133]
	s_mov_b32 m0, s46
	s_nop 0
	global_load_lds_dwordx4 v[224:225], off
	s_waitcnt vmcnt(8)
	s_waitcnt lgkmcnt(0)
	s_barrier
	s_setprio 1
	s_waitcnt lgkmcnt(0)
	v_mfma_f32_16x16x32_bf16 v[114:117], v[150:153], v[182:185], v[114:117]
	v_mfma_f32_16x16x32_bf16 v[82:85], v[158:161], v[182:185], v[82:85]
	v_mfma_f32_16x16x32_bf16 v[122:125], v[150:153], v[192:195], v[122:125]
	v_mfma_f32_16x16x32_bf16 v[86:89], v[158:161], v[192:195], v[86:89]
	v_mfma_f32_16x16x32_bf16 v[126:129], v[150:153], v[200:203], v[126:129]
	v_mfma_f32_16x16x32_bf16 v[90:93], v[158:161], v[200:203], v[90:93]
	v_mfma_f32_16x16x32_bf16 v[118:121], v[150:153], v[208:211], v[118:121]
	v_mfma_f32_16x16x32_bf16 v[102:105], v[158:161], v[208:211], v[102:105]
	v_mfma_f32_16x16x32_bf16 v[114:117], v[154:157], v[188:191], v[114:117]
	v_mfma_f32_16x16x32_bf16 v[82:85], v[162:165], v[188:191], v[82:85]
	v_mfma_f32_16x16x32_bf16 v[122:125], v[154:157], v[196:199], v[122:125]
	v_mfma_f32_16x16x32_bf16 v[86:89], v[162:165], v[196:199], v[86:89]
	v_mfma_f32_16x16x32_bf16 v[126:129], v[154:157], v[204:207], v[126:129]
	v_mfma_f32_16x16x32_bf16 v[90:93], v[162:165], v[204:207], v[90:93]
	v_mfma_f32_16x16x32_bf16 v[118:121], v[154:157], v[212:215], v[118:121]
	v_mfma_f32_16x16x32_bf16 v[102:105], v[162:165], v[212:215], v[102:105]
	s_setprio 0
	s_setprio 1
	v_mfma_f32_16x16x32_bf16 v[26:29], v[166:169], v[182:185], v[26:29]
	v_mfma_f32_16x16x32_bf16 v[2:5], v[174:177], v[182:185], v[2:5]
	v_mfma_f32_16x16x32_bf16 v[30:33], v[166:169], v[192:195], v[30:33]
	v_mfma_f32_16x16x32_bf16 v[6:9], v[174:177], v[192:195], v[6:9]
	v_mfma_f32_16x16x32_bf16 v[42:45], v[166:169], v[200:203], v[42:45]
	v_mfma_f32_16x16x32_bf16 v[10:13], v[174:177], v[200:203], v[10:13]
	v_mfma_f32_16x16x32_bf16 v[58:61], v[166:169], v[208:211], v[58:61]
	v_mfma_f32_16x16x32_bf16 v[14:17], v[174:177], v[208:211], v[14:17]
	v_mfma_f32_16x16x32_bf16 v[26:29], v[170:173], v[188:191], v[26:29]
	v_mfma_f32_16x16x32_bf16 v[2:5], v[178:181], v[188:191], v[2:5]
	v_mfma_f32_16x16x32_bf16 v[30:33], v[170:173], v[196:199], v[30:33]
	v_mfma_f32_16x16x32_bf16 v[6:9], v[178:181], v[196:199], v[6:9]
	v_mfma_f32_16x16x32_bf16 v[42:45], v[170:173], v[204:207], v[42:45]
	v_mfma_f32_16x16x32_bf16 v[10:13], v[178:181], v[204:207], v[10:13]
	v_mfma_f32_16x16x32_bf16 v[58:61], v[170:173], v[212:215], v[58:61]
	v_mfma_f32_16x16x32_bf16 v[14:17], v[178:181], v[212:215], v[14:17]
	s_barrier
; #define PG8_STAGE(bufoff, gbase, voff) do { _Pragma("unroll") for (int _i = 0; _i < 2; ++_i) \
;         __builtin_amdgcn_global_load_lds((const unsigned*)((const char*)(gbase) + (voff)[_i]), (PG8_LAS unsigned*)(lds + (bufoff) + ldsw + _i * 8192), 16, 0, 0); } while (0)
; #define PG8_LDA(dst, b, h) do { _Pragma("unroll") for (int m = 0; m < 4; ++m) _Pragma("unroll") for (int k = 0; k < 2; ++k) dst[m][k] = *(const PG8_LAS bf16x8*)(lds + PG8_SA(b, h) + aoff + m * 2048 + k * 1024); } while (0)
; #define PG8_MMA(ai, bj, At, Bt) do { __builtin_amdgcn_s_setprio(1); _Pragma("unroll") for (int m = 0; m < 4; ++m) _Pragma("unroll") for (int n = 0; n < 2; ++n) _Pragma("unroll") for (int k = 0; k < 2; ++k) \
;         acc[ai][bj][m][n] = __builtin_amdgcn_mfma_f32_16x16x32_bf16(Bt[n][k], At[m][k], acc[ai][bj][m][n], 0, 0, 0); __builtin_amdgcn_s_setprio(0); } while (0)
; #define PG8_WAIT_V(n) asm volatile("s_waitcnt vmcnt(" #n ")" ::: "memory")
; #define PG8_WAIT_L(n) asm volatile("s_waitcnt lgkmcnt(" #n ")" ::: "memory")
; #define PG8_BAR __builtin_amdgcn_s_barrier()
; #define PG8_SCHED __builtin_amdgcn_sched_barrier(0)
; template <class Epi, class Sched, bool ALIGN_EPI = false, bool SP2 = false>
; __device__ __forceinline__ void gemm_phase(PG8_LAS unsigned char* lds, const Gemm g, const Sched& S, const Epi& E) {
;     ...
;             PG8_LDA(At, 1, 1); PG8_STAGE(PG8_SB(1, 0), b3, voffB); PG8_STAGE(PG8_SB(1, 1), b3 + hstep, voffB); PG8_STAGE(PG8_SA(1, 0), a3, voffA);
;             PG8_WAIT_V(8); PG8_WAIT_L(0); PG8_BAR; PG8_MMA(1, 0, At, B0); PG8_MMA(1, 1, At, B1); PG8_BAR; PG8_SCHED;
	s_setprio 0
	s_add_i32 s34, s60, s39
	v_lshl_add_u64 v[216:217], v[216:217], 0, s[24:25]
	s_mov_b32 m0, s34
	ds_read_b128 v[182:185], v149 offset:49152
	ds_read_b128 v[188:191], v149 offset:50176
	ds_read_b128 v[192:195], v149 offset:51200
	ds_read_b128 v[196:199], v149 offset:52224
	ds_read_b128 v[200:203], v149 offset:53248
	ds_read_b128 v[204:207], v149 offset:54272
	ds_read_b128 v[208:211], v149 offset:55296
	ds_read_b128 v[212:215], v149 offset:56320
	global_load_lds_dwordx4 v[216:217], off
	s_add_i32 m0, s34, 0x2000
	s_add_u32 s30, s30, 0xb0080
	v_lshl_add_u64 v[216:217], v[218:219], 0, s[24:25]
	s_addc_u32 s31, s31, 0
	s_add_i32 s34, s61, s39
	global_load_lds_dwordx4 v[216:217], off
	v_lshl_add_u64 v[216:217], s[30:31], 0, v[130:131]
	s_mov_b32 m0, s34
	s_nop 0
	global_load_lds_dwordx4 v[216:217], off
	v_lshl_add_u64 v[216:217], s[30:31], 0, v[132:133]
	s_add_i32 m0, s34, 0x2000
	s_nop 0
	global_load_lds_dwordx4 v[216:217], off
	v_lshl_add_u64 v[216:217], v[220:221], 0, s[24:25]
	s_mov_b32 m0, s49
	s_nop 0
	global_load_lds_dwordx4 v[216:217], off
	v_lshl_add_u64 v[216:217], v[222:223], 0, s[24:25]
	s_mov_b32 m0, s50
	s_nop 0
	global_load_lds_dwordx4 v[216:217], off
	s_waitcnt vmcnt(8)
	s_waitcnt lgkmcnt(0)
	s_barrier
	s_setprio 1
	s_waitcnt lgkmcnt(0)
	v_mfma_f32_16x16x32_bf16 v[110:113], v[150:153], v[182:185], v[110:113]
	v_mfma_f32_16x16x32_bf16 v[106:109], v[158:161], v[182:185], v[106:109]
	v_mfma_f32_16x16x32_bf16 v[98:101], v[150:153], v[192:195], v[98:101]
	v_mfma_f32_16x16x32_bf16 v[94:97], v[158:161], v[192:195], v[94:97]
	v_mfma_f32_16x16x32_bf16 v[74:77], v[150:153], v[200:203], v[74:77]
	v_mfma_f32_16x16x32_bf16 v[70:73], v[158:161], v[200:203], v[70:73]
	v_mfma_f32_16x16x32_bf16 v[54:57], v[150:153], v[208:211], v[54:57]
	v_mfma_f32_16x16x32_bf16 v[50:53], v[158:161], v[208:211], v[50:53]
	v_mfma_f32_16x16x32_bf16 v[110:113], v[154:157], v[188:191], v[110:113]
	v_mfma_f32_16x16x32_bf16 v[106:109], v[162:165], v[188:191], v[106:109]
	v_mfma_f32_16x16x32_bf16 v[98:101], v[154:157], v[196:199], v[98:101]
	v_mfma_f32_16x16x32_bf16 v[94:97], v[162:165], v[196:199], v[94:97]
	v_mfma_f32_16x16x32_bf16 v[74:77], v[154:157], v[204:207], v[74:77]
	v_mfma_f32_16x16x32_bf16 v[70:73], v[162:165], v[204:207], v[70:73]
	v_mfma_f32_16x16x32_bf16 v[54:57], v[154:157], v[212:215], v[54:57]
	v_mfma_f32_16x16x32_bf16 v[50:53], v[162:165], v[212:215], v[50:53]
	s_setprio 0
	s_setprio 1
	v_mfma_f32_16x16x32_bf16 v[66:69], v[166:169], v[182:185], v[66:69]
	v_mfma_f32_16x16x32_bf16 v[18:21], v[174:177], v[182:185], v[18:21]
	v_mfma_f32_16x16x32_bf16 v[78:81], v[166:169], v[192:195], v[78:81]
	v_mfma_f32_16x16x32_bf16 v[22:25], v[174:177], v[192:195], v[22:25]
	v_mfma_f32_16x16x32_bf16 v[62:65], v[166:169], v[200:203], v[62:65]
	v_mfma_f32_16x16x32_bf16 v[46:49], v[174:177], v[200:203], v[46:49]
	v_mfma_f32_16x16x32_bf16 v[38:41], v[166:169], v[208:211], v[38:41]
	v_mfma_f32_16x16x32_bf16 v[34:37], v[174:177], v[208:211], v[34:37]
	v_mfma_f32_16x16x32_bf16 v[66:69], v[170:173], v[188:191], v[66:69]
	v_mfma_f32_16x16x32_bf16 v[18:21], v[178:181], v[188:191], v[18:21]
	v_mfma_f32_16x16x32_bf16 v[78:81], v[170:173], v[196:199], v[78:81]
	v_mfma_f32_16x16x32_bf16 v[22:25], v[178:181], v[196:199], v[22:25]
	v_mfma_f32_16x16x32_bf16 v[62:65], v[170:173], v[204:207], v[62:65]
	v_mfma_f32_16x16x32_bf16 v[46:49], v[178:181], v[204:207], v[46:49]
	v_mfma_f32_16x16x32_bf16 v[38:41], v[170:173], v[212:215], v[38:41]
	v_mfma_f32_16x16x32_bf16 v[34:37], v[178:181], v[212:215], v[34:37]
	s_barrier
; template <class Epi, class Sched, bool ALIGN_EPI = false, bool SP2 = false>
; __device__ __forceinline__ void gemm_phase(PG8_LAS unsigned char* lds, const Gemm g, const Sched& S, const Epi& E) {
;     ...
;         for (int t = 0; t < nt; t += 2) {
;             const bool last = (t == nt - 2);
;             const char* a1 = cA + (size_t)(t + 1) * kstep;
;             const char* a2 = last ? nA : cA + (size_t)(t + 2) * kstep; const char* b2 = last ? nB : cB + (size_t)(t + 2) * kstep;
;             const char* a3 = a2 + kstep; const char* b3 = b2 + kstep;
;     ...
;         if (!has_next) break;
; #pragma unroll
;         for (int a = 0; a < 2; ++a)
; #pragma unroll
;             for (int b = 0; b < 2; ++b)
; #pragma unroll
;                 for (int m = 0; m < 4; ++m)
; #pragma unroll
;                     for (int n = 0; n < 2; ++n) acc[a][b][m][n] = (f32x4){0.f, 0.f, 0.f, 0.f};
;         cur = nxt; cA = nA; cB = nB; ++ui;
	s_setprio 0
	s_add_i32 s59, s59, 2
	s_add_u32 s28, s28, 0x100
	s_addc_u32 s29, s29, 0
	s_cmp_gt_u32 s59, 41
	s_cbranch_scc0 .LBB0_1778
	s_add_u32 s28, s57, 0xffffff00
	s_addc_u32 s29, s58, -1
	s_and_b64 vcc, exec, s[6:7]
	s_cbranch_vccnz .LBB0_1781
	v_mov_b32_e32 v34, 0
	s_mov_b32 s20, s54
	s_mov_b32 s37, s55
	s_mov_b64 s[22:23], s[26:27]
	s_mov_b32 s48, s56
	v_mov_b32_e32 v35, v34
	v_mov_b32_e32 v36, v34
	v_mov_b32_e32 v37, v34
	v_mov_b32_e32 v38, v34
	v_mov_b32_e32 v39, v34
	v_mov_b32_e32 v40, v34
	v_mov_b32_e32 v41, v34
	v_mov_b32_e32 v46, v34
	v_mov_b32_e32 v47, v34
	v_mov_b32_e32 v48, v34
	v_mov_b32_e32 v49, v34
	v_mov_b32_e32 v62, v34
	v_mov_b32_e32 v63, v34
	v_mov_b32_e32 v64, v34
	v_mov_b32_e32 v65, v34
	v_mov_b32_e32 v22, v34
	v_mov_b32_e32 v23, v34
	v_mov_b32_e32 v24, v34
	v_mov_b32_e32 v25, v34
	v_mov_b32_e32 v78, v34
	v_mov_b32_e32 v79, v34
	v_mov_b32_e32 v80, v34
	v_mov_b32_e32 v81, v34
	v_mov_b32_e32 v18, v34
	v_mov_b32_e32 v19, v34
	v_mov_b32_e32 v20, v34
	v_mov_b32_e32 v21, v34
	v_mov_b32_e32 v66, v34
	v_mov_b32_e32 v67, v34
	v_mov_b32_e32 v68, v34
	v_mov_b32_e32 v69, v34
	v_mov_b32_e32 v50, v34
	v_mov_b32_e32 v51, v34
	v_mov_b32_e32 v52, v34
	v_mov_b32_e32 v53, v34
	v_mov_b32_e32 v54, v34
	v_mov_b32_e32 v55, v34
	v_mov_b32_e32 v56, v34
	v_mov_b32_e32 v57, v34
	v_mov_b32_e32 v70, v34
	v_mov_b32_e32 v71, v34
	v_mov_b32_e32 v72, v34
	v_mov_b32_e32 v73, v34
	v_mov_b32_e32 v74, v34
	v_mov_b32_e32 v75, v34
	v_mov_b32_e32 v76, v34
	v_mov_b32_e32 v77, v34
	v_mov_b32_e32 v94, v34
	v_mov_b32_e32 v95, v34
	v_mov_b32_e32 v96, v34
	v_mov_b32_e32 v97, v34
	v_mov_b32_e32 v98, v34
	v_mov_b32_e32 v99, v34
	v_mov_b32_e32 v100, v34
	v_mov_b32_e32 v101, v34
	v_mov_b32_e32 v106, v34
	v_mov_b32_e32 v107, v34
	v_mov_b32_e32 v108, v34
	v_mov_b32_e32 v109, v34
	v_mov_b32_e32 v110, v34
	v_mov_b32_e32 v111, v34
	v_mov_b32_e32 v112, v34
	v_mov_b32_e32 v113, v34
	v_mov_b32_e32 v14, v34
	v_mov_b32_e32 v15, v34
	v_mov_b32_e32 v16, v34
	v_mov_b32_e32 v17, v34
	v_mov_b32_e32 v58, v34
	v_mov_b32_e32 v59, v34
	v_mov_b32_e32 v60, v34
	v_mov_b32_e32 v61, v34
	v_mov_b32_e32 v10, v34
	v_mov_b32_e32 v11, v34
	v_mov_b32_e32 v12, v34
	v_mov_b32_e32 v13, v34
	v_mov_b32_e32 v42, v34
	v_mov_b32_e32 v43, v34
	v_mov_b32_e32 v44, v34
	v_mov_b32_e32 v45, v34
	v_mov_b32_e32 v6, v34
	v_mov_b32_e32 v7, v34
	v_mov_b32_e32 v8, v34
	v_mov_b32_e32 v9, v34
	v_mov_b32_e32 v30, v34
	v_mov_b32_e32 v31, v34
	v_mov_b32_e32 v32, v34
	v_mov_b32_e32 v33, v34
	v_mov_b32_e32 v2, v34
	v_mov_b32_e32 v3, v34
	v_mov_b32_e32 v4, v34
	v_mov_b32_e32 v5, v34
	v_mov_b32_e32 v26, v34
	v_mov_b32_e32 v27, v34
	v_mov_b32_e32 v28, v34
	v_mov_b32_e32 v29, v34
	v_mov_b32_e32 v102, v34
	v_mov_b32_e32 v103, v34
	v_mov_b32_e32 v104, v34
	v_mov_b32_e32 v105, v34
	v_mov_b32_e32 v118, v34
	v_mov_b32_e32 v119, v34
	v_mov_b32_e32 v120, v34
	v_mov_b32_e32 v121, v34
	v_mov_b32_e32 v90, v34
	v_mov_b32_e32 v91, v34
	v_mov_b32_e32 v92, v34
	v_mov_b32_e32 v93, v34
	v_mov_b32_e32 v126, v34
	v_mov_b32_e32 v127, v34
	v_mov_b32_e32 v128, v34
	v_mov_b32_e32 v129, v34
	v_mov_b32_e32 v86, v34
	v_mov_b32_e32 v87, v34
	v_mov_b32_e32 v88, v34
	v_mov_b32_e32 v89, v34
	v_mov_b32_e32 v122, v34
	v_mov_b32_e32 v123, v34
	v_mov_b32_e32 v124, v34
	v_mov_b32_e32 v125, v34
	v_mov_b32_e32 v82, v34
	v_mov_b32_e32 v83, v34
	v_mov_b32_e32 v84, v34
	v_mov_b32_e32 v85, v34
	v_mov_b32_e32 v114, v34
	v_mov_b32_e32 v115, v34
	v_mov_b32_e32 v116, v34
	v_mov_b32_e32 v117, v34
	s_andn2_b64 vcc, exec, s[4:5]
	s_cbranch_vccnz .LBB0_1782
	s_branch .LBB0_1783

; #define PG8_STAGE(bufoff, gbase, voff) do { _Pragma("unroll") for (int _i = 0; _i < 2; ++_i) \
;         __builtin_amdgcn_global_load_lds((const unsigned*)((const char*)(gbase) + (voff)[_i]), (PG8_LAS unsigned*)(lds + (bufoff) + ldsw + _i * 8192), 16, 0, 0); } while (0)
; #define PG8_LDA(dst, b, h) do { _Pragma("unroll") for (int m = 0; m < 4; ++m) _Pragma("unroll") for (int k = 0; k < 2; ++k) dst[m][k] = *(const PG8_LAS bf16x8*)(lds + PG8_SA(b, h) + aoff + m * 2048 + k * 1024); } while (0)
; #define PG8_LDB(dst, b, h) do { _Pragma("unroll") for (int n = 0; n < 2; ++n) _Pragma("unroll") for (int k = 0; k < 2; ++k) dst[n][k] = *(const PG8_LAS bf16x8*)(lds + PG8_SB(b, h) + boff + n * 2048 + k * 1024); } while (0)
; #define PG8_MMA(ai, bj, At, Bt) do { __builtin_amdgcn_s_setprio(1); _Pragma("unroll") for (int m = 0; m < 4; ++m) _Pragma("unroll") for (int n = 0; n < 2; ++n) _Pragma("unroll") for (int k = 0; k < 2; ++k) \
;         acc[ai][bj][m][n] = __builtin_amdgcn_mfma_f32_16x16x32_bf16(Bt[n][k], At[m][k], acc[ai][bj][m][n], 0, 0, 0); __builtin_amdgcn_s_setprio(0); } while (0)
; #define PG8_WAIT_V(n) asm volatile("s_waitcnt vmcnt(" #n ")" ::: "memory")
; #define PG8_BAR __builtin_amdgcn_s_barrier()
; template <class Epi, class Sched, bool ALIGN_EPI = false, bool SP2 = false>
; __device__ __forceinline__ void gemm_phase(PG8_LAS unsigned char* lds, const Gemm g, const Sched& S, const Epi& E) {
;     ...
;         for (int t = 0; t < nt; t += 2) {
;             const bool last = (t == nt - 2);
;             const char* a1 = cA + (size_t)(t + 1) * kstep;
;             const char* a2 = last ? nA : cA + (size_t)(t + 2) * kstep; const char* b2 = last ? nB : cB + (size_t)(t + 2) * kstep;
;             const char* a3 = a2 + kstep; const char* b3 = b2 + kstep;
;             if (last && has_next) S.a_ready(nxt);
;             if constexpr (SP2) {
;             PG8_LDB(B0, 0, 0); PG8_LDB(B1, 0, 1); PG8_SCHED; PG8_LDA(At, 0, 0); PG8_STAGE(PG8_SA(1, 1), a1 + hstep, voffA);
;             PG8_WAIT_V(8); PG8_WAIT_L(0); PG8_BAR; PG8_MMA(0, 0, At, B0); PG8_MMA(0, 1, At, B1); PG8_BAR; PG8_SCHED;
;             PG8_LDA(At, 0, 1); PG8_STAGE(PG8_SB(0, 0), b2, voffB); PG8_STAGE(PG8_SB(0, 1), b2 + hstep, voffB); PG8_STAGE(PG8_SA(0, 0), a2, voffA);
;             PG8_WAIT_V(8); PG8_WAIT_L(0); PG8_BAR; PG8_MMA(1, 0, At, B0); PG8_MMA(1, 1, At, B1); PG8_BAR; PG8_SCHED;
.LBB0_1940:
	v_add_u32_e32 v149, s54, v147
	ds_read_b128 v[150:153], v149
	ds_read_b128 v[154:157], v149 offset:1024
	ds_read_b128 v[158:161], v149 offset:2048
	ds_read_b128 v[162:165], v149 offset:3072
	v_add_u32_e32 v149, s55, v147
	s_add_u32 s28, s20, s26
	ds_read_b128 v[166:169], v149
	ds_read_b128 v[170:173], v149 offset:1024
	ds_read_b128 v[174:177], v149 offset:2048
	ds_read_b128 v[178:181], v149 offset:3072
	s_addc_u32 s29, s21, s27
	s_add_u32 s28, s28, 0x100
	s_addc_u32 s29, s29, 0
	s_add_u32 s60, s0, s26
	s_addc_u32 s61, s1, s27
	s_cmpk_eq_i32 s26, 0x1500
	s_cselect_b32 s31, s25, s29
	s_cselect_b32 s30, s24, s28
	s_cselect_b32 s29, s9, s61
	s_cselect_b32 s28, s8, s60
	v_lshl_add_u64 v[216:217], v[142:143], 0, s[26:27]
	s_add_i32 m0, s42, 0xc000
	ds_read_b128 v[182:185], v148
	ds_read_b128 v[188:191], v148 offset:1024
	ds_read_b128 v[192:195], v148 offset:2048
	ds_read_b128 v[196:199], v148 offset:3072
	ds_read_b128 v[200:203], v148 offset:4096
	ds_read_b128 v[204:207], v148 offset:5120
	ds_read_b128 v[208:211], v148 offset:6144
	ds_read_b128 v[212:215], v148 offset:7168
	global_load_lds_dwordx4 v[216:217], off
	v_lshl_add_u64 v[216:217], v[144:145], 0, s[26:27]
	s_add_i32 m0, s42, 0xe000
	s_nop 0
	global_load_lds_dwordx4 v[216:217], off
	s_waitcnt vmcnt(8)
	s_waitcnt lgkmcnt(0)
	s_barrier
	s_setprio 1
	s_waitcnt lgkmcnt(0)
	v_mfma_f32_16x16x32_bf16 v[114:117], v[150:153], v[182:185], v[114:117]
	v_mfma_f32_16x16x32_bf16 v[82:85], v[158:161], v[182:185], v[82:85]
	v_mfma_f32_16x16x32_bf16 v[122:125], v[150:153], v[192:195], v[122:125]
	v_mfma_f32_16x16x32_bf16 v[86:89], v[158:161], v[192:195], v[86:89]
	v_mfma_f32_16x16x32_bf16 v[126:129], v[150:153], v[200:203], v[126:129]
	v_mfma_f32_16x16x32_bf16 v[90:93], v[158:161], v[200:203], v[90:93]
	v_mfma_f32_16x16x32_bf16 v[118:121], v[150:153], v[208:211], v[118:121]
	v_mfma_f32_16x16x32_bf16 v[102:105], v[158:161], v[208:211], v[102:105]
	v_mfma_f32_16x16x32_bf16 v[114:117], v[154:157], v[188:191], v[114:117]
	v_mfma_f32_16x16x32_bf16 v[82:85], v[162:165], v[188:191], v[82:85]
	v_mfma_f32_16x16x32_bf16 v[122:125], v[154:157], v[196:199], v[122:125]
	v_mfma_f32_16x16x32_bf16 v[86:89], v[162:165], v[196:199], v[86:89]
	v_mfma_f32_16x16x32_bf16 v[126:129], v[154:157], v[204:207], v[126:129]
	v_mfma_f32_16x16x32_bf16 v[90:93], v[162:165], v[204:207], v[90:93]
	v_mfma_f32_16x16x32_bf16 v[118:121], v[154:157], v[212:215], v[118:121]
	v_mfma_f32_16x16x32_bf16 v[102:105], v[162:165], v[212:215], v[102:105]
	s_setprio 0
	s_setprio 1
	v_mfma_f32_16x16x32_bf16 v[26:29], v[166:169], v[182:185], v[26:29]
	v_mfma_f32_16x16x32_bf16 v[2:5], v[174:177], v[182:185], v[2:5]
	v_mfma_f32_16x16x32_bf16 v[30:33], v[166:169], v[192:195], v[30:33]
	v_mfma_f32_16x16x32_bf16 v[6:9], v[174:177], v[192:195], v[6:9]
	v_mfma_f32_16x16x32_bf16 v[42:45], v[166:169], v[200:203], v[42:45]
	v_mfma_f32_16x16x32_bf16 v[10:13], v[174:177], v[200:203], v[10:13]
	v_mfma_f32_16x16x32_bf16 v[58:61], v[166:169], v[208:211], v[58:61]
	v_mfma_f32_16x16x32_bf16 v[14:17], v[174:177], v[208:211], v[14:17]
	v_mfma_f32_16x16x32_bf16 v[26:29], v[170:173], v[188:191], v[26:29]
	v_mfma_f32_16x16x32_bf16 v[2:5], v[178:181], v[188:191], v[2:5]
	v_mfma_f32_16x16x32_bf16 v[30:33], v[170:173], v[196:199], v[30:33]
	v_mfma_f32_16x16x32_bf16 v[6:9], v[178:181], v[196:199], v[6:9]
	v_mfma_f32_16x16x32_bf16 v[42:45], v[170:173], v[204:207], v[42:45]
	v_mfma_f32_16x16x32_bf16 v[10:13], v[178:181], v[204:207], v[10:13]
	v_mfma_f32_16x16x32_bf16 v[58:61], v[170:173], v[212:215], v[58:61]
	v_mfma_f32_16x16x32_bf16 v[14:17], v[178:181], v[212:215], v[14:17]
	s_barrier
	s_setprio 0
	s_add_i32 s60, s54, s41
	v_lshl_add_u64 v[216:217], s[28:29], 0, v[130:131]
	s_mov_b32 m0, s60
	ds_read_b128 v[182:185], v148 offset:16384
	ds_read_b128 v[188:191], v148 offset:17408
	ds_read_b128 v[192:195], v148 offset:18432
	ds_read_b128 v[196:199], v148 offset:19456
	ds_read_b128 v[200:203], v148 offset:20480
	ds_read_b128 v[204:207], v148 offset:21504
	ds_read_b128 v[208:211], v148 offset:22528
	ds_read_b128 v[212:215], v148 offset:23552
	global_load_lds_dwordx4 v[216:217], off
	s_add_i32 m0, s60, 0x2000
	s_add_u32 s60, s28, 0xb0000
	v_lshl_add_u64 v[218:219], s[28:29], 0, v[132:133]
	s_addc_u32 s61, s29, 0
	s_add_i32 s62, s55, s41
	global_load_lds_dwordx4 v[218:219], off
	v_lshl_add_u64 v[220:221], s[60:61], 0, v[130:131]
	s_mov_b32 m0, s62
	v_lshl_add_u64 v[222:223], s[30:31], 0, v[132:133]
	global_load_lds_dwordx4 v[220:221], off
	v_lshl_add_u64 v[220:221], s[60:61], 0, v[132:133]
	s_add_i32 m0, s62, 0x2000
	s_nop 0
	global_load_lds_dwordx4 v[220:221], off
	v_lshl_add_u64 v[220:221], s[30:31], 0, v[130:131]
	s_mov_b32 m0, s42
	s_nop 0
	global_load_lds_dwordx4 v[220:221], off
	s_mov_b32 m0, s46
	s_nop 0
	global_load_lds_dwordx4 v[222:223], off
	s_waitcnt vmcnt(8)
	s_waitcnt lgkmcnt(0)
	s_barrier
; #define PG8_STAGE(bufoff, gbase, voff) do { _Pragma("unroll") for (int _i = 0; _i < 2; ++_i) \
;         __builtin_amdgcn_global_load_lds((const unsigned*)((const char*)(gbase) + (voff)[_i]), (PG8_LAS unsigned*)(lds + (bufoff) + ldsw + _i * 8192), 16, 0, 0); } while (0)
; #define PG8_LDA(dst, b, h) do { _Pragma("unroll") for (int m = 0; m < 4; ++m) _Pragma("unroll") for (int k = 0; k < 2; ++k) dst[m][k] = *(const PG8_LAS bf16x8*)(lds + PG8_SA(b, h) + aoff + m * 2048 + k * 1024); } while (0)
; #define PG8_LDB(dst, b, h) do { _Pragma("unroll") for (int n = 0; n < 2; ++n) _Pragma("unroll") for (int k = 0; k < 2; ++k) dst[n][k] = *(const PG8_LAS bf16x8*)(lds + PG8_SB(b, h) + boff + n * 2048 + k * 1024); } while (0)
; #define PG8_MMA(ai, bj, At, Bt) do { __builtin_amdgcn_s_setprio(1); _Pragma("unroll") for (int m = 0; m < 4; ++m) _Pragma("unroll") for (int n = 0; n < 2; ++n) _Pragma("unroll") for (int k = 0; k < 2; ++k) \
;         acc[ai][bj][m][n] = __builtin_amdgcn_mfma_f32_16x16x32_bf16(Bt[n][k], At[m][k], acc[ai][bj][m][n], 0, 0, 0); __builtin_amdgcn_s_setprio(0); } while (0)
; #define PG8_WAIT_V(n) asm volatile("s_waitcnt vmcnt(" #n ")" ::: "memory")
; #define PG8_WAIT_L(n) asm volatile("s_waitcnt lgkmcnt(" #n ")" ::: "memory")
; #define PG8_BAR __builtin_amdgcn_s_barrier()
; #define PG8_SCHED __builtin_amdgcn_sched_barrier(0)
; template <class Epi, class Sched, bool ALIGN_EPI = false, bool SP2 = false>
; __device__ __forceinline__ void gemm_phase(PG8_LAS unsigned char* lds, const Gemm g, const Sched& S, const Epi& E) {
;     ...
;             PG8_WAIT_V(8); PG8_WAIT_L(0); PG8_BAR; PG8_MMA(1, 0, At, B0); PG8_MMA(1, 1, At, B1); PG8_BAR; PG8_SCHED;
;             PG8_LDB(B0, 1, 0); PG8_LDB(B1, 1, 1); PG8_SCHED; PG8_LDA(At, 1, 0); PG8_STAGE(PG8_SA(0, 1), a2 + hstep, voffA);
;             PG8_WAIT_V(8); PG8_WAIT_L(0); PG8_BAR; PG8_MMA(0, 0, At, B0); PG8_MMA(0, 1, At, B1); PG8_BAR; PG8_SCHED;
	s_setprio 1
	s_waitcnt lgkmcnt(0)
	v_mfma_f32_16x16x32_bf16 v[110:113], v[150:153], v[182:185], v[110:113]
	v_mfma_f32_16x16x32_bf16 v[106:109], v[158:161], v[182:185], v[106:109]
	v_mfma_f32_16x16x32_bf16 v[98:101], v[150:153], v[192:195], v[98:101]
	v_mfma_f32_16x16x32_bf16 v[94:97], v[158:161], v[192:195], v[94:97]
	v_mfma_f32_16x16x32_bf16 v[74:77], v[150:153], v[200:203], v[74:77]
	v_mfma_f32_16x16x32_bf16 v[70:73], v[158:161], v[200:203], v[70:73]
	v_mfma_f32_16x16x32_bf16 v[54:57], v[150:153], v[208:211], v[54:57]
	v_mfma_f32_16x16x32_bf16 v[50:53], v[158:161], v[208:211], v[50:53]
	v_mfma_f32_16x16x32_bf16 v[110:113], v[154:157], v[188:191], v[110:113]
	v_mfma_f32_16x16x32_bf16 v[106:109], v[162:165], v[188:191], v[106:109]
	v_mfma_f32_16x16x32_bf16 v[98:101], v[154:157], v[196:199], v[98:101]
	v_mfma_f32_16x16x32_bf16 v[94:97], v[162:165], v[196:199], v[94:97]
	v_mfma_f32_16x16x32_bf16 v[74:77], v[154:157], v[204:207], v[74:77]
	v_mfma_f32_16x16x32_bf16 v[70:73], v[162:165], v[204:207], v[70:73]
	v_mfma_f32_16x16x32_bf16 v[54:57], v[154:157], v[212:215], v[54:57]
	v_mfma_f32_16x16x32_bf16 v[50:53], v[162:165], v[212:215], v[50:53]
	s_setprio 0
	s_setprio 1
	v_mfma_f32_16x16x32_bf16 v[66:69], v[166:169], v[182:185], v[66:69]
	v_mfma_f32_16x16x32_bf16 v[18:21], v[174:177], v[182:185], v[18:21]
	v_mfma_f32_16x16x32_bf16 v[78:81], v[166:169], v[192:195], v[78:81]
	v_mfma_f32_16x16x32_bf16 v[22:25], v[174:177], v[192:195], v[22:25]
	v_mfma_f32_16x16x32_bf16 v[62:65], v[166:169], v[200:203], v[62:65]
	v_mfma_f32_16x16x32_bf16 v[46:49], v[174:177], v[200:203], v[46:49]
	v_mfma_f32_16x16x32_bf16 v[38:41], v[166:169], v[208:211], v[38:41]
	v_mfma_f32_16x16x32_bf16 v[34:37], v[174:177], v[208:211], v[34:37]
	v_mfma_f32_16x16x32_bf16 v[66:69], v[170:173], v[188:191], v[66:69]
	v_mfma_f32_16x16x32_bf16 v[18:21], v[178:181], v[188:191], v[18:21]
	v_mfma_f32_16x16x32_bf16 v[78:81], v[170:173], v[196:199], v[78:81]
	v_mfma_f32_16x16x32_bf16 v[22:25], v[178:181], v[196:199], v[22:25]
	v_mfma_f32_16x16x32_bf16 v[62:65], v[170:173], v[204:207], v[62:65]
	v_mfma_f32_16x16x32_bf16 v[46:49], v[178:181], v[204:207], v[46:49]
	v_mfma_f32_16x16x32_bf16 v[38:41], v[170:173], v[212:215], v[38:41]
	v_mfma_f32_16x16x32_bf16 v[34:37], v[178:181], v[212:215], v[34:37]
	s_barrier
	s_setprio 0
	s_add_i32 s60, 0, 0x18000
	v_add_u32_e32 v149, s60, v147
	s_add_i32 s61, 0, 0x1c000
	ds_read_b128 v[150:153], v149
	ds_read_b128 v[154:157], v149 offset:1024
	ds_read_b128 v[158:161], v149 offset:2048
	ds_read_b128 v[162:165], v149 offset:3072
	v_add_u32_e32 v149, s61, v147
	ds_read_b128 v[166:169], v149
	ds_read_b128 v[170:173], v149 offset:1024
	ds_read_b128 v[174:177], v149 offset:2048
	ds_read_b128 v[178:181], v149 offset:3072
	s_add_u32 s30, s30, 0xb0000
	s_addc_u32 s31, s31, 0
	s_mov_b32 m0, s47
	v_lshl_add_u64 v[224:225], s[30:31], 0, v[130:131]
	ds_read_b128 v[182:185], v148 offset:32768
	ds_read_b128 v[188:191], v148 offset:33792
	ds_read_b128 v[192:195], v148 offset:34816
	ds_read_b128 v[196:199], v148 offset:35840
	ds_read_b128 v[200:203], v148 offset:36864
	ds_read_b128 v[204:207], v148 offset:37888
	ds_read_b128 v[208:211], v148 offset:38912
	ds_read_b128 v[212:215], v148 offset:39936
	global_load_lds_dwordx4 v[224:225], off
	v_lshl_add_u64 v[224:225], s[30:31], 0, v[132:133]
	s_mov_b32 m0, s48
	s_nop 0
	global_load_lds_dwordx4 v[224:225], off
	s_waitcnt vmcnt(8)
	s_waitcnt lgkmcnt(0)
	s_barrier
	s_setprio 1
	s_waitcnt lgkmcnt(0)
	v_mfma_f32_16x16x32_bf16 v[114:117], v[150:153], v[182:185], v[114:117]
	v_mfma_f32_16x16x32_bf16 v[82:85], v[158:161], v[182:185], v[82:85]
	v_mfma_f32_16x16x32_bf16 v[122:125], v[150:153], v[192:195], v[122:125]
	v_mfma_f32_16x16x32_bf16 v[86:89], v[158:161], v[192:195], v[86:89]
	v_mfma_f32_16x16x32_bf16 v[126:129], v[150:153], v[200:203], v[126:129]
	v_mfma_f32_16x16x32_bf16 v[90:93], v[158:161], v[200:203], v[90:93]
	v_mfma_f32_16x16x32_bf16 v[118:121], v[150:153], v[208:211], v[118:121]
	v_mfma_f32_16x16x32_bf16 v[102:105], v[158:161], v[208:211], v[102:105]
	v_mfma_f32_16x16x32_bf16 v[114:117], v[154:157], v[188:191], v[114:117]
	v_mfma_f32_16x16x32_bf16 v[82:85], v[162:165], v[188:191], v[82:85]
	v_mfma_f32_16x16x32_bf16 v[122:125], v[154:157], v[196:199], v[122:125]
	v_mfma_f32_16x16x32_bf16 v[86:89], v[162:165], v[196:199], v[86:89]
	v_mfma_f32_16x16x32_bf16 v[126:129], v[154:157], v[204:207], v[126:129]
	v_mfma_f32_16x16x32_bf16 v[90:93], v[162:165], v[204:207], v[90:93]
	v_mfma_f32_16x16x32_bf16 v[118:121], v[154:157], v[212:215], v[118:121]
	v_mfma_f32_16x16x32_bf16 v[102:105], v[162:165], v[212:215], v[102:105]
	s_setprio 0
	s_setprio 1
	v_mfma_f32_16x16x32_bf16 v[26:29], v[166:169], v[182:185], v[26:29]
	v_mfma_f32_16x16x32_bf16 v[2:5], v[174:177], v[182:185], v[2:5]
	v_mfma_f32_16x16x32_bf16 v[30:33], v[166:169], v[192:195], v[30:33]
	v_mfma_f32_16x16x32_bf16 v[6:9], v[174:177], v[192:195], v[6:9]
	v_mfma_f32_16x16x32_bf16 v[42:45], v[166:169], v[200:203], v[42:45]
	v_mfma_f32_16x16x32_bf16 v[10:13], v[174:177], v[200:203], v[10:13]
	v_mfma_f32_16x16x32_bf16 v[58:61], v[166:169], v[208:211], v[58:61]
	v_mfma_f32_16x16x32_bf16 v[14:17], v[174:177], v[208:211], v[14:17]
	v_mfma_f32_16x16x32_bf16 v[26:29], v[170:173], v[188:191], v[26:29]
	v_mfma_f32_16x16x32_bf16 v[2:5], v[178:181], v[188:191], v[2:5]
	v_mfma_f32_16x16x32_bf16 v[30:33], v[170:173], v[196:199], v[30:33]
	v_mfma_f32_16x16x32_bf16 v[6:9], v[178:181], v[196:199], v[6:9]
	v_mfma_f32_16x16x32_bf16 v[42:45], v[170:173], v[204:207], v[42:45]
	v_mfma_f32_16x16x32_bf16 v[10:13], v[178:181], v[204:207], v[10:13]
	v_mfma_f32_16x16x32_bf16 v[58:61], v[170:173], v[212:215], v[58:61]
	v_mfma_f32_16x16x32_bf16 v[14:17], v[178:181], v[212:215], v[14:17]
	s_barrier
; #define PG8_STAGE(bufoff, gbase, voff) do { _Pragma("unroll") for (int _i = 0; _i < 2; ++_i) \
;         __builtin_amdgcn_global_load_lds((const unsigned*)((const char*)(gbase) + (voff)[_i]), (PG8_LAS unsigned*)(lds + (bufoff) + ldsw + _i * 8192), 16, 0, 0); } while (0)
; #define PG8_LDA(dst, b, h) do { _Pragma("unroll") for (int m = 0; m < 4; ++m) _Pragma("unroll") for (int k = 0; k < 2; ++k) dst[m][k] = *(const PG8_LAS bf16x8*)(lds + PG8_SA(b, h) + aoff + m * 2048 + k * 1024); } while (0)
; #define PG8_MMA(ai, bj, At, Bt) do { __builtin_amdgcn_s_setprio(1); _Pragma("unroll") for (int m = 0; m < 4; ++m) _Pragma("unroll") for (int n = 0; n < 2; ++n) _Pragma("unroll") for (int k = 0; k < 2; ++k) \
;         acc[ai][bj][m][n] = __builtin_amdgcn_mfma_f32_16x16x32_bf16(Bt[n][k], At[m][k], acc[ai][bj][m][n], 0, 0, 0); __builtin_amdgcn_s_setprio(0); } while (0)
; #define PG8_WAIT_V(n) asm volatile("s_waitcnt vmcnt(" #n ")" ::: "memory")
; #define PG8_WAIT_L(n) asm volatile("s_waitcnt lgkmcnt(" #n ")" ::: "memory")
; #define PG8_BAR __builtin_amdgcn_s_barrier()
; #define PG8_SCHED __builtin_amdgcn_sched_barrier(0)
; template <class Epi, class Sched, bool ALIGN_EPI = false, bool SP2 = false>
; __device__ __forceinline__ void gemm_phase(PG8_LAS unsigned char* lds, const Gemm g, const Sched& S, const Epi& E) {
;     ...
;             PG8_LDA(At, 1, 1); PG8_STAGE(PG8_SB(1, 0), b3, voffB); PG8_STAGE(PG8_SB(1, 1), b3 + hstep, voffB); PG8_STAGE(PG8_SA(1, 0), a3, voffA);
;             PG8_WAIT_V(8); PG8_WAIT_L(0); PG8_BAR; PG8_MMA(1, 0, At, B0); PG8_MMA(1, 1, At, B1); PG8_BAR; PG8_SCHED;
	s_setprio 0
	s_add_i32 s30, s60, s41
	v_lshl_add_u64 v[216:217], v[216:217], 0, s[22:23]
	s_mov_b32 m0, s30
	ds_read_b128 v[182:185], v148 offset:49152
	ds_read_b128 v[188:191], v148 offset:50176
	ds_read_b128 v[192:195], v148 offset:51200
	ds_read_b128 v[196:199], v148 offset:52224
	ds_read_b128 v[200:203], v148 offset:53248
	ds_read_b128 v[204:207], v148 offset:54272
	ds_read_b128 v[208:211], v148 offset:55296
	ds_read_b128 v[212:215], v148 offset:56320
	global_load_lds_dwordx4 v[216:217], off
	s_add_i32 m0, s30, 0x2000
	s_add_u32 s28, s28, 0xb0080
	v_lshl_add_u64 v[216:217], v[218:219], 0, s[22:23]
	s_addc_u32 s29, s29, 0
	s_add_i32 s30, s61, s41
	global_load_lds_dwordx4 v[216:217], off
	v_lshl_add_u64 v[216:217], s[28:29], 0, v[130:131]
	s_mov_b32 m0, s30
	s_nop 0
	global_load_lds_dwordx4 v[216:217], off
	v_lshl_add_u64 v[216:217], s[28:29], 0, v[132:133]
	s_add_i32 m0, s30, 0x2000
	s_nop 0
	global_load_lds_dwordx4 v[216:217], off
	v_lshl_add_u64 v[216:217], v[220:221], 0, s[22:23]
	s_mov_b32 m0, s51
	s_nop 0
	global_load_lds_dwordx4 v[216:217], off
	v_lshl_add_u64 v[216:217], v[222:223], 0, s[22:23]
	s_mov_b32 m0, s52
	s_nop 0
	global_load_lds_dwordx4 v[216:217], off
	s_waitcnt vmcnt(8)
	s_waitcnt lgkmcnt(0)
	s_barrier
	s_setprio 1
	s_waitcnt lgkmcnt(0)
	v_mfma_f32_16x16x32_bf16 v[110:113], v[150:153], v[182:185], v[110:113]
	v_mfma_f32_16x16x32_bf16 v[106:109], v[158:161], v[182:185], v[106:109]
	v_mfma_f32_16x16x32_bf16 v[98:101], v[150:153], v[192:195], v[98:101]
	v_mfma_f32_16x16x32_bf16 v[94:97], v[158:161], v[192:195], v[94:97]
	v_mfma_f32_16x16x32_bf16 v[74:77], v[150:153], v[200:203], v[74:77]
	v_mfma_f32_16x16x32_bf16 v[70:73], v[158:161], v[200:203], v[70:73]
	v_mfma_f32_16x16x32_bf16 v[54:57], v[150:153], v[208:211], v[54:57]
	v_mfma_f32_16x16x32_bf16 v[50:53], v[158:161], v[208:211], v[50:53]
	v_mfma_f32_16x16x32_bf16 v[110:113], v[154:157], v[188:191], v[110:113]
	v_mfma_f32_16x16x32_bf16 v[106:109], v[162:165], v[188:191], v[106:109]
	v_mfma_f32_16x16x32_bf16 v[98:101], v[154:157], v[196:199], v[98:101]
	v_mfma_f32_16x16x32_bf16 v[94:97], v[162:165], v[196:199], v[94:97]
	v_mfma_f32_16x16x32_bf16 v[74:77], v[154:157], v[204:207], v[74:77]
	v_mfma_f32_16x16x32_bf16 v[70:73], v[162:165], v[204:207], v[70:73]
	v_mfma_f32_16x16x32_bf16 v[54:57], v[154:157], v[212:215], v[54:57]
	v_mfma_f32_16x16x32_bf16 v[50:53], v[162:165], v[212:215], v[50:53]
	s_setprio 0
	s_setprio 1
	v_mfma_f32_16x16x32_bf16 v[66:69], v[166:169], v[182:185], v[66:69]
	v_mfma_f32_16x16x32_bf16 v[18:21], v[174:177], v[182:185], v[18:21]
	v_mfma_f32_16x16x32_bf16 v[78:81], v[166:169], v[192:195], v[78:81]
	v_mfma_f32_16x16x32_bf16 v[22:25], v[174:177], v[192:195], v[22:25]
	v_mfma_f32_16x16x32_bf16 v[62:65], v[166:169], v[200:203], v[62:65]
	v_mfma_f32_16x16x32_bf16 v[46:49], v[174:177], v[200:203], v[46:49]
	v_mfma_f32_16x16x32_bf16 v[38:41], v[166:169], v[208:211], v[38:41]
	v_mfma_f32_16x16x32_bf16 v[34:37], v[174:177], v[208:211], v[34:37]
	v_mfma_f32_16x16x32_bf16 v[66:69], v[170:173], v[188:191], v[66:69]
	v_mfma_f32_16x16x32_bf16 v[18:21], v[178:181], v[188:191], v[18:21]
	v_mfma_f32_16x16x32_bf16 v[78:81], v[170:173], v[196:199], v[78:81]
	v_mfma_f32_16x16x32_bf16 v[22:25], v[178:181], v[196:199], v[22:25]
	v_mfma_f32_16x16x32_bf16 v[62:65], v[170:173], v[204:207], v[62:65]
	v_mfma_f32_16x16x32_bf16 v[46:49], v[178:181], v[204:207], v[46:49]
	v_mfma_f32_16x16x32_bf16 v[38:41], v[170:173], v[212:215], v[38:41]
	v_mfma_f32_16x16x32_bf16 v[34:37], v[178:181], v[212:215], v[34:37]
	s_barrier
; template <class Epi, class Sched, bool ALIGN_EPI = false, bool SP2 = false>
; __device__ __forceinline__ void gemm_phase(PG8_LAS unsigned char* lds, const Gemm g, const Sched& S, const Epi& E) {
;     ...
;         for (int t = 0; t < nt; t += 2) {
;     ...
;         if (!has_next) break;
; #pragma unroll
;         for (int a = 0; a < 2; ++a)
; #pragma unroll
;             for (int b = 0; b < 2; ++b)
; #pragma unroll
;                 for (int m = 0; m < 4; ++m)
; #pragma unroll
;                     for (int n = 0; n < 2; ++n) acc[a][b][m][n] = (f32x4){0.f, 0.f, 0.f, 0.f};
;         cur = nxt; cA = nA; cB = nB; ++ui;
	s_setprio 0
	s_add_i32 s59, s59, 2
	s_add_u32 s26, s26, 0x100
	s_addc_u32 s27, s27, 0
	s_cmp_gt_u32 s59, 41
	s_cbranch_scc0 .LBB0_1940
	s_add_u32 s0, s0, 0xffffff00
	s_addc_u32 s1, s1, -1
	s_and_b64 vcc, exec, s[6:7]
	s_cbranch_vccnz .LBB0_1943
	v_mov_b32_e32 v34, 0
	s_mov_b32 s18, s56
	s_mov_b32 s35, s57
	s_mov_b64 s[20:21], s[24:25]
	s_mov_b32 s50, s58
	v_mov_b32_e32 v35, v34
	v_mov_b32_e32 v36, v34
	v_mov_b32_e32 v37, v34
	v_mov_b32_e32 v38, v34
	v_mov_b32_e32 v39, v34
	v_mov_b32_e32 v40, v34
	v_mov_b32_e32 v41, v34
	v_mov_b32_e32 v46, v34
	v_mov_b32_e32 v47, v34
	v_mov_b32_e32 v48, v34
	v_mov_b32_e32 v49, v34
	v_mov_b32_e32 v62, v34
	v_mov_b32_e32 v63, v34
	v_mov_b32_e32 v64, v34
	v_mov_b32_e32 v65, v34
	v_mov_b32_e32 v22, v34
	v_mov_b32_e32 v23, v34
	v_mov_b32_e32 v24, v34
	v_mov_b32_e32 v25, v34
	v_mov_b32_e32 v78, v34
	v_mov_b32_e32 v79, v34
	v_mov_b32_e32 v80, v34
	v_mov_b32_e32 v81, v34
	v_mov_b32_e32 v18, v34
	v_mov_b32_e32 v19, v34
	v_mov_b32_e32 v20, v34
	v_mov_b32_e32 v21, v34
	v_mov_b32_e32 v66, v34
	v_mov_b32_e32 v67, v34
	v_mov_b32_e32 v68, v34
	v_mov_b32_e32 v69, v34
	v_mov_b32_e32 v50, v34
	v_mov_b32_e32 v51, v34
	v_mov_b32_e32 v52, v34
	v_mov_b32_e32 v53, v34
	v_mov_b32_e32 v54, v34
	v_mov_b32_e32 v55, v34
	v_mov_b32_e32 v56, v34
	v_mov_b32_e32 v57, v34
	v_mov_b32_e32 v70, v34
	v_mov_b32_e32 v71, v34
	v_mov_b32_e32 v72, v34
	v_mov_b32_e32 v73, v34
	v_mov_b32_e32 v74, v34
	v_mov_b32_e32 v75, v34
	v_mov_b32_e32 v76, v34
	v_mov_b32_e32 v77, v34
	v_mov_b32_e32 v94, v34
	v_mov_b32_e32 v95, v34
	v_mov_b32_e32 v96, v34
	v_mov_b32_e32 v97, v34
	v_mov_b32_e32 v98, v34
	v_mov_b32_e32 v99, v34
	v_mov_b32_e32 v100, v34
	v_mov_b32_e32 v101, v34
	v_mov_b32_e32 v106, v34
	v_mov_b32_e32 v107, v34
	v_mov_b32_e32 v108, v34
	v_mov_b32_e32 v109, v34
	v_mov_b32_e32 v110, v34
	v_mov_b32_e32 v111, v34
	v_mov_b32_e32 v112, v34
	v_mov_b32_e32 v113, v34
	v_mov_b32_e32 v14, v34
	v_mov_b32_e32 v15, v34
	v_mov_b32_e32 v16, v34
	v_mov_b32_e32 v17, v34
	v_mov_b32_e32 v58, v34
	v_mov_b32_e32 v59, v34
	v_mov_b32_e32 v60, v34
	v_mov_b32_e32 v61, v34
	v_mov_b32_e32 v10, v34
	v_mov_b32_e32 v11, v34
	v_mov_b32_e32 v12, v34
	v_mov_b32_e32 v13, v34
	v_mov_b32_e32 v42, v34
	v_mov_b32_e32 v43, v34
	v_mov_b32_e32 v44, v34
	v_mov_b32_e32 v45, v34
	v_mov_b32_e32 v6, v34
	v_mov_b32_e32 v7, v34
	v_mov_b32_e32 v8, v34
	v_mov_b32_e32 v9, v34
	v_mov_b32_e32 v30, v34
	v_mov_b32_e32 v31, v34
	v_mov_b32_e32 v32, v34
	v_mov_b32_e32 v33, v34
	v_mov_b32_e32 v2, v34
	v_mov_b32_e32 v3, v34
	v_mov_b32_e32 v4, v34
	v_mov_b32_e32 v5, v34
	v_mov_b32_e32 v26, v34
	v_mov_b32_e32 v27, v34
	v_mov_b32_e32 v28, v34
	v_mov_b32_e32 v29, v34
	v_mov_b32_e32 v102, v34
	v_mov_b32_e32 v103, v34
	v_mov_b32_e32 v104, v34
	v_mov_b32_e32 v105, v34
	v_mov_b32_e32 v118, v34
	v_mov_b32_e32 v119, v34
	v_mov_b32_e32 v120, v34
	v_mov_b32_e32 v121, v34
	v_mov_b32_e32 v90, v34
	v_mov_b32_e32 v91, v34
	v_mov_b32_e32 v92, v34
	v_mov_b32_e32 v93, v34
	v_mov_b32_e32 v126, v34
	v_mov_b32_e32 v127, v34
	v_mov_b32_e32 v128, v34
	v_mov_b32_e32 v129, v34
	v_mov_b32_e32 v86, v34
	v_mov_b32_e32 v87, v34
	v_mov_b32_e32 v88, v34
	v_mov_b32_e32 v89, v34
	v_mov_b32_e32 v122, v34
	v_mov_b32_e32 v123, v34
	v_mov_b32_e32 v124, v34
	v_mov_b32_e32 v125, v34
	v_mov_b32_e32 v82, v34
	v_mov_b32_e32 v83, v34
	v_mov_b32_e32 v84, v34
	v_mov_b32_e32 v85, v34
	v_mov_b32_e32 v114, v34
	v_mov_b32_e32 v115, v34
	v_mov_b32_e32 v116, v34
	v_mov_b32_e32 v117, v34
	s_andn2_b64 vcc, exec, s[4:5]
	s_cbranch_vccnz .LBB0_1944
	s_branch .LBB0_1945
